# K-loops: LDS fragment-read addresses hoisted out of the loop, loop test on the scalar unit (no VALU left in load phases)
# baseline (speedup 1.0000x reference)
.LBB0_169:
	v_cmp_gt_i32_e32 vcc, 1, v138
	s_cbranch_vccnz .LBB0_231
	v_lshl_add_u64 v[152:153], v[2:3], 0, s[22:23]
	v_add_u32_e32 v154, -2, v138
	s_waitcnt lgkmcnt(0)
	v_lshl_add_u64 v[150:151], v[4:5], 0, s[28:29]
	s_mov_b32 s7, 0
	s_nop 0
	v_readfirstlane_b32 s86, v152
	v_readfirstlane_b32 s87, v153
	v_readfirstlane_b32 s88, v150
	v_readfirstlane_b32 s89, v151
	v_readfirstlane_b32 s90, v146
	v_readfirstlane_b32 s91, v147
	v_readfirstlane_b32 s92, v148
	v_readfirstlane_b32 s93, v149
	v_readfirstlane_b32 s100, v154
	v_readfirstlane_b32 s101, v138
	v_add_u32_e32 v230, s76, v141
	v_add_u32_e32 v231, s77, v141
	v_add_u32_e32 v232, 0x18000, v141
	v_add_u32_e32 v233, 0x1c000, v141
	s_add_u32 s98, s86, 0xfffc0080
	s_addc_u32 s99, s87, -1
	s_cmp_eq_u32 s7, s100
	s_cselect_b64 s[94:95], s[90:91], s[98:99]
	s_cselect_b64 s[96:97], s[92:93], s[88:89]
	ds_read_b128 v[164:167], v230
	ds_read_b128 v[168:171], v230 offset:1024
	ds_read_b128 v[172:175], v230 offset:2048
	ds_read_b128 v[176:179], v230 offset:3072
	ds_read_b128 v[180:183], v231
	ds_read_b128 v[184:187], v231 offset:1024
	ds_read_b128 v[188:191], v231 offset:2048
	ds_read_b128 v[192:195], v231 offset:3072
	s_add_i32 s51, s7, 2
	s_nop 0
	s_mov_b32 m0, s78
	ds_read_b128 v[196:199], v160
	ds_read_b128 v[200:203], v160 offset:1024
	ds_read_b128 v[204:207], v160 offset:2048
	ds_read_b128 v[208:211], v160 offset:3072
	ds_read_b128 v[212:215], v160 offset:4096
	ds_read_b128 v[216:219], v160 offset:5120
	ds_read_b128 v[220:223], v160 offset:6144
	ds_read_b128 v[224:227], v160 offset:7168
	global_load_lds_dwordx4 v144, s[86:87]
	s_mov_b32 m0, s79
	s_nop 0
	global_load_lds_dwordx4 v142, s[86:87]
	s_waitcnt vmcnt(8)
	s_waitcnt lgkmcnt(0)
	s_barrier
	s_setprio 1
	s_waitcnt lgkmcnt(0)
	v_mfma_f32_16x16x32_bf16 v[122:125], v[164:167], v[196:199], 0
	v_mfma_f32_16x16x32_bf16 v[118:121], v[172:175], v[196:199], 0
	v_mfma_f32_16x16x32_bf16 v[110:113], v[164:167], v[204:207], 0
	v_mfma_f32_16x16x32_bf16 v[102:105], v[172:175], v[204:207], 0
	v_mfma_f32_16x16x32_bf16 v[94:97], v[164:167], v[212:215], 0
	v_mfma_f32_16x16x32_bf16 v[86:89], v[172:175], v[212:215], 0
	v_mfma_f32_16x16x32_bf16 v[78:81], v[164:167], v[220:223], 0
	v_mfma_f32_16x16x32_bf16 v[70:73], v[172:175], v[220:223], 0
	v_mfma_f32_16x16x32_bf16 v[122:125], v[168:171], v[200:203], v[122:125]
	v_mfma_f32_16x16x32_bf16 v[118:121], v[176:179], v[200:203], v[118:121]
	v_mfma_f32_16x16x32_bf16 v[110:113], v[168:171], v[208:211], v[110:113]
	v_mfma_f32_16x16x32_bf16 v[102:105], v[176:179], v[208:211], v[102:105]
	v_mfma_f32_16x16x32_bf16 v[94:97], v[168:171], v[216:219], v[94:97]
	v_mfma_f32_16x16x32_bf16 v[86:89], v[176:179], v[216:219], v[86:89]
	v_mfma_f32_16x16x32_bf16 v[78:81], v[168:171], v[224:227], v[78:81]
	v_mfma_f32_16x16x32_bf16 v[70:73], v[176:179], v[224:227], v[70:73]
	s_setprio 0
	s_setprio 1
	v_mfma_f32_16x16x32_bf16 v[126:129], v[180:183], v[196:199], 0
	v_mfma_f32_16x16x32_bf16 v[114:117], v[188:191], v[196:199], 0
	v_mfma_f32_16x16x32_bf16 v[106:109], v[180:183], v[204:207], 0
	v_mfma_f32_16x16x32_bf16 v[98:101], v[188:191], v[204:207], 0
	v_mfma_f32_16x16x32_bf16 v[90:93], v[180:183], v[212:215], 0
	v_mfma_f32_16x16x32_bf16 v[82:85], v[188:191], v[212:215], 0
	v_mfma_f32_16x16x32_bf16 v[74:77], v[180:183], v[220:223], 0
	v_mfma_f32_16x16x32_bf16 v[66:69], v[188:191], v[220:223], 0
	v_mfma_f32_16x16x32_bf16 v[126:129], v[184:187], v[200:203], v[126:129]
	v_mfma_f32_16x16x32_bf16 v[114:117], v[192:195], v[200:203], v[114:117]
	v_mfma_f32_16x16x32_bf16 v[106:109], v[184:187], v[208:211], v[106:109]
	v_mfma_f32_16x16x32_bf16 v[98:101], v[192:195], v[208:211], v[98:101]
	v_mfma_f32_16x16x32_bf16 v[90:93], v[184:187], v[216:219], v[90:93]
	v_mfma_f32_16x16x32_bf16 v[82:85], v[192:195], v[216:219], v[82:85]
	v_mfma_f32_16x16x32_bf16 v[74:77], v[184:187], v[224:227], v[74:77]
	v_mfma_f32_16x16x32_bf16 v[66:69], v[192:195], v[224:227], v[66:69]
	s_setprio 0
	s_barrier
	s_add_u32 s98, s96, 0x40000
	s_addc_u32 s99, s97, 0
	s_mov_b32 m0, s80
	ds_read_b128 v[196:199], v160 offset:16384
	ds_read_b128 v[200:203], v160 offset:17408
	ds_read_b128 v[204:207], v160 offset:18432
	ds_read_b128 v[208:211], v160 offset:19456
	ds_read_b128 v[212:215], v160 offset:20480
	ds_read_b128 v[216:219], v160 offset:21504
	ds_read_b128 v[220:223], v160 offset:22528
	ds_read_b128 v[224:227], v160 offset:23552
	global_load_lds_dwordx4 v132, s[96:97]
	s_mov_b32 m0, s81
	s_add_i32 s7, s77, s47
	global_load_lds_dwordx4 v136, s[96:97]
	s_mov_b32 m0, s7
	s_nop 0
	global_load_lds_dwordx4 v132, s[98:99]
	s_add_i32 m0, s7, 0x2000
	s_nop 0
	global_load_lds_dwordx4 v136, s[98:99]
	s_mov_b32 m0, s57
	s_nop 0
	global_load_lds_dwordx4 v130, s[94:95]
	s_mov_b32 m0, s62
	s_nop 0
	global_load_lds_dwordx4 v134, s[94:95]
	s_waitcnt vmcnt(8)
	s_waitcnt lgkmcnt(0)
	s_barrier
	s_setprio 1
	s_waitcnt lgkmcnt(0)
	v_mfma_f32_16x16x32_bf16 v[62:65], v[164:167], v[196:199], 0
	v_mfma_f32_16x16x32_bf16 v[54:57], v[172:175], v[196:199], 0
	v_mfma_f32_16x16x32_bf16 v[46:49], v[164:167], v[204:207], 0
	v_mfma_f32_16x16x32_bf16 v[38:41], v[172:175], v[204:207], 0
	v_mfma_f32_16x16x32_bf16 v[30:33], v[164:167], v[212:215], 0
	v_mfma_f32_16x16x32_bf16 v[22:25], v[172:175], v[212:215], 0
	v_mfma_f32_16x16x32_bf16 v[14:17], v[164:167], v[220:223], 0
	v_mfma_f32_16x16x32_bf16 v[6:9], v[172:175], v[220:223], 0
	v_mfma_f32_16x16x32_bf16 v[62:65], v[168:171], v[200:203], v[62:65]
	v_mfma_f32_16x16x32_bf16 v[54:57], v[176:179], v[200:203], v[54:57]
	v_mfma_f32_16x16x32_bf16 v[46:49], v[168:171], v[208:211], v[46:49]
	v_mfma_f32_16x16x32_bf16 v[38:41], v[176:179], v[208:211], v[38:41]
	v_mfma_f32_16x16x32_bf16 v[30:33], v[168:171], v[216:219], v[30:33]
	v_mfma_f32_16x16x32_bf16 v[22:25], v[176:179], v[216:219], v[22:25]
	v_mfma_f32_16x16x32_bf16 v[14:17], v[168:171], v[224:227], v[14:17]
	v_mfma_f32_16x16x32_bf16 v[6:9], v[176:179], v[224:227], v[6:9]
	s_setprio 0
	s_setprio 1
	v_mfma_f32_16x16x32_bf16 v[58:61], v[180:183], v[196:199], 0
	v_mfma_f32_16x16x32_bf16 v[50:53], v[188:191], v[196:199], 0
	v_mfma_f32_16x16x32_bf16 v[42:45], v[180:183], v[204:207], 0
	v_mfma_f32_16x16x32_bf16 v[34:37], v[188:191], v[204:207], 0
	v_mfma_f32_16x16x32_bf16 v[26:29], v[180:183], v[212:215], 0
	v_mfma_f32_16x16x32_bf16 v[18:21], v[188:191], v[212:215], 0
	v_mfma_f32_16x16x32_bf16 v[10:13], v[180:183], v[220:223], 0
	v_mfma_f32_16x16x32_bf16 v[2:5], v[188:191], v[220:223], 0
	v_mfma_f32_16x16x32_bf16 v[58:61], v[184:187], v[200:203], v[58:61]
	v_mfma_f32_16x16x32_bf16 v[50:53], v[192:195], v[200:203], v[50:53]
	v_mfma_f32_16x16x32_bf16 v[42:45], v[184:187], v[208:211], v[42:45]
	v_mfma_f32_16x16x32_bf16 v[34:37], v[192:195], v[208:211], v[34:37]
	v_mfma_f32_16x16x32_bf16 v[26:29], v[184:187], v[216:219], v[26:29]
	v_mfma_f32_16x16x32_bf16 v[18:21], v[192:195], v[216:219], v[18:21]
	v_mfma_f32_16x16x32_bf16 v[10:13], v[184:187], v[224:227], v[10:13]
	v_mfma_f32_16x16x32_bf16 v[2:5], v[192:195], v[224:227], v[2:5]
	s_setprio 0
	s_barrier
	s_add_u32 s98, s94, 0x40000
	s_addc_u32 s99, s95, 0
	s_add_i32 s7, 0, 0x18000
	s_add_i32 s55, 0, 0x1c000
	ds_read_b128 v[164:167], v232
	ds_read_b128 v[168:171], v232 offset:1024
	ds_read_b128 v[172:175], v232 offset:2048
	ds_read_b128 v[176:179], v232 offset:3072
	ds_read_b128 v[180:183], v233
	ds_read_b128 v[184:187], v233 offset:1024
	ds_read_b128 v[188:191], v233 offset:2048
	ds_read_b128 v[192:195], v233 offset:3072
	s_mov_b32 m0, s63
	ds_read_b128 v[196:199], v160 offset:32768
	ds_read_b128 v[200:203], v160 offset:33792
	ds_read_b128 v[204:207], v160 offset:34816
	ds_read_b128 v[208:211], v160 offset:35840
	ds_read_b128 v[212:215], v160 offset:36864
	ds_read_b128 v[216:219], v160 offset:37888
	ds_read_b128 v[220:223], v160 offset:38912
	ds_read_b128 v[224:227], v160 offset:39936
	global_load_lds_dwordx4 v130, s[98:99]
	s_mov_b32 m0, s64
	s_nop 0
	global_load_lds_dwordx4 v134, s[98:99]
	s_waitcnt vmcnt(8)
	s_waitcnt lgkmcnt(0)
	s_barrier
	s_setprio 1
	s_waitcnt lgkmcnt(0)
	v_mfma_f32_16x16x32_bf16 v[122:125], v[164:167], v[196:199], v[122:125]
	v_mfma_f32_16x16x32_bf16 v[118:121], v[172:175], v[196:199], v[118:121]
	v_mfma_f32_16x16x32_bf16 v[110:113], v[164:167], v[204:207], v[110:113]
	v_mfma_f32_16x16x32_bf16 v[102:105], v[172:175], v[204:207], v[102:105]
	v_mfma_f32_16x16x32_bf16 v[94:97], v[164:167], v[212:215], v[94:97]
	v_mfma_f32_16x16x32_bf16 v[86:89], v[172:175], v[212:215], v[86:89]
	v_mfma_f32_16x16x32_bf16 v[78:81], v[164:167], v[220:223], v[78:81]
	v_mfma_f32_16x16x32_bf16 v[70:73], v[172:175], v[220:223], v[70:73]
	v_mfma_f32_16x16x32_bf16 v[122:125], v[168:171], v[200:203], v[122:125]
	v_mfma_f32_16x16x32_bf16 v[118:121], v[176:179], v[200:203], v[118:121]
	v_mfma_f32_16x16x32_bf16 v[110:113], v[168:171], v[208:211], v[110:113]
	v_mfma_f32_16x16x32_bf16 v[102:105], v[176:179], v[208:211], v[102:105]
	v_mfma_f32_16x16x32_bf16 v[94:97], v[168:171], v[216:219], v[94:97]
	v_mfma_f32_16x16x32_bf16 v[86:89], v[176:179], v[216:219], v[86:89]
	v_mfma_f32_16x16x32_bf16 v[78:81], v[168:171], v[224:227], v[78:81]
	v_mfma_f32_16x16x32_bf16 v[70:73], v[176:179], v[224:227], v[70:73]
	s_setprio 0
	s_setprio 1
	v_mfma_f32_16x16x32_bf16 v[126:129], v[180:183], v[196:199], v[126:129]
	v_mfma_f32_16x16x32_bf16 v[114:117], v[188:191], v[196:199], v[114:117]
	v_mfma_f32_16x16x32_bf16 v[106:109], v[180:183], v[204:207], v[106:109]
	v_mfma_f32_16x16x32_bf16 v[98:101], v[188:191], v[204:207], v[98:101]
	v_mfma_f32_16x16x32_bf16 v[90:93], v[180:183], v[212:215], v[90:93]
	v_mfma_f32_16x16x32_bf16 v[82:85], v[188:191], v[212:215], v[82:85]
	v_mfma_f32_16x16x32_bf16 v[74:77], v[180:183], v[220:223], v[74:77]
	v_mfma_f32_16x16x32_bf16 v[66:69], v[188:191], v[220:223], v[66:69]
	v_mfma_f32_16x16x32_bf16 v[126:129], v[184:187], v[200:203], v[126:129]
	v_mfma_f32_16x16x32_bf16 v[114:117], v[192:195], v[200:203], v[114:117]
	v_mfma_f32_16x16x32_bf16 v[106:109], v[184:187], v[208:211], v[106:109]
	v_mfma_f32_16x16x32_bf16 v[98:101], v[192:195], v[208:211], v[98:101]
	v_mfma_f32_16x16x32_bf16 v[90:93], v[184:187], v[216:219], v[90:93]
	v_mfma_f32_16x16x32_bf16 v[82:85], v[192:195], v[216:219], v[82:85]
	v_mfma_f32_16x16x32_bf16 v[74:77], v[184:187], v[224:227], v[74:77]
	v_mfma_f32_16x16x32_bf16 v[66:69], v[192:195], v[224:227], v[66:69]
	s_setprio 0
	s_barrier
	s_add_u32 s96, s96, 0x80
	s_addc_u32 s97, s97, 0
	s_add_u32 s98, s96, 0x40000
	s_addc_u32 s99, s97, 0
	s_add_u32 s94, s94, 0x80
	s_addc_u32 s95, s95, 0
	s_add_i32 s7, s7, s47
	s_mov_b32 m0, s7
	ds_read_b128 v[196:199], v160 offset:49152
	ds_read_b128 v[200:203], v160 offset:50176
	ds_read_b128 v[204:207], v160 offset:51200
	ds_read_b128 v[208:211], v160 offset:52224
	ds_read_b128 v[212:215], v160 offset:53248
	ds_read_b128 v[216:219], v160 offset:54272
	ds_read_b128 v[220:223], v160 offset:55296
	ds_read_b128 v[224:227], v160 offset:56320
	global_load_lds_dwordx4 v132, s[96:97]
	s_add_i32 m0, s7, 0x2000
	s_add_i32 s7, s55, s47
	global_load_lds_dwordx4 v136, s[96:97]
	s_mov_b32 m0, s7
	s_nop 0
	global_load_lds_dwordx4 v132, s[98:99]
	s_add_i32 m0, s7, 0x2000
	s_nop 0
	global_load_lds_dwordx4 v136, s[98:99]
	s_mov_b32 m0, s65
	s_nop 0
	global_load_lds_dwordx4 v130, s[94:95]
	s_mov_b32 m0, s66
	s_nop 0
	global_load_lds_dwordx4 v134, s[94:95]
	s_waitcnt vmcnt(8)
	s_waitcnt lgkmcnt(0)
	s_barrier
	s_setprio 1
	s_waitcnt lgkmcnt(0)
	v_mfma_f32_16x16x32_bf16 v[62:65], v[164:167], v[196:199], v[62:65]
	v_mfma_f32_16x16x32_bf16 v[54:57], v[172:175], v[196:199], v[54:57]
	v_mfma_f32_16x16x32_bf16 v[46:49], v[164:167], v[204:207], v[46:49]
	v_mfma_f32_16x16x32_bf16 v[38:41], v[172:175], v[204:207], v[38:41]
	v_mfma_f32_16x16x32_bf16 v[30:33], v[164:167], v[212:215], v[30:33]
	v_mfma_f32_16x16x32_bf16 v[22:25], v[172:175], v[212:215], v[22:25]
	v_mfma_f32_16x16x32_bf16 v[14:17], v[164:167], v[220:223], v[14:17]
	v_mfma_f32_16x16x32_bf16 v[6:9], v[172:175], v[220:223], v[6:9]
	v_mfma_f32_16x16x32_bf16 v[62:65], v[168:171], v[200:203], v[62:65]
	v_mfma_f32_16x16x32_bf16 v[54:57], v[176:179], v[200:203], v[54:57]
	v_mfma_f32_16x16x32_bf16 v[46:49], v[168:171], v[208:211], v[46:49]
	v_mfma_f32_16x16x32_bf16 v[38:41], v[176:179], v[208:211], v[38:41]
	v_mfma_f32_16x16x32_bf16 v[30:33], v[168:171], v[216:219], v[30:33]
	v_mfma_f32_16x16x32_bf16 v[22:25], v[176:179], v[216:219], v[22:25]
	v_mfma_f32_16x16x32_bf16 v[14:17], v[168:171], v[224:227], v[14:17]
	v_mfma_f32_16x16x32_bf16 v[6:9], v[176:179], v[224:227], v[6:9]
	s_setprio 0
	s_setprio 1
	v_mfma_f32_16x16x32_bf16 v[58:61], v[180:183], v[196:199], v[58:61]
	v_mfma_f32_16x16x32_bf16 v[50:53], v[188:191], v[196:199], v[50:53]
	v_mfma_f32_16x16x32_bf16 v[42:45], v[180:183], v[204:207], v[42:45]
	v_mfma_f32_16x16x32_bf16 v[34:37], v[188:191], v[204:207], v[34:37]
	v_mfma_f32_16x16x32_bf16 v[26:29], v[180:183], v[212:215], v[26:29]
	v_mfma_f32_16x16x32_bf16 v[18:21], v[188:191], v[212:215], v[18:21]
	v_mfma_f32_16x16x32_bf16 v[10:13], v[180:183], v[220:223], v[10:13]
	v_mfma_f32_16x16x32_bf16 v[2:5], v[188:191], v[220:223], v[2:5]
	v_mfma_f32_16x16x32_bf16 v[58:61], v[184:187], v[200:203], v[58:61]
	v_mfma_f32_16x16x32_bf16 v[50:53], v[192:195], v[200:203], v[50:53]
	v_mfma_f32_16x16x32_bf16 v[42:45], v[184:187], v[208:211], v[42:45]
	v_mfma_f32_16x16x32_bf16 v[34:37], v[192:195], v[208:211], v[34:37]
	v_mfma_f32_16x16x32_bf16 v[26:29], v[184:187], v[216:219], v[26:29]
	v_mfma_f32_16x16x32_bf16 v[18:21], v[192:195], v[216:219], v[18:21]
	v_mfma_f32_16x16x32_bf16 v[10:13], v[184:187], v[224:227], v[10:13]
	v_mfma_f32_16x16x32_bf16 v[2:5], v[192:195], v[224:227], v[2:5]
	s_setprio 0
	s_barrier
	s_mov_b32 s7, s51
	s_add_u32 s88, s88, 0x100
	s_addc_u32 s89, s89, 0
	s_add_u32 s86, s86, 0x100
	s_addc_u32 s87, s87, 0
	s_cmp_ge_i32 s51, s101
	s_cbranch_scc1 .Lmy_kexit_0
.LBB0_171:
	s_add_u32 s98, s86, 0xfffc0080
	s_addc_u32 s99, s87, -1
	s_cmp_eq_u32 s7, s100
	s_cselect_b64 s[94:95], s[90:91], s[98:99]
	s_cselect_b64 s[96:97], s[92:93], s[88:89]
	ds_read_b128 v[164:167], v230
	ds_read_b128 v[168:171], v230 offset:1024
	ds_read_b128 v[172:175], v230 offset:2048
	ds_read_b128 v[176:179], v230 offset:3072
	ds_read_b128 v[180:183], v231
	ds_read_b128 v[184:187], v231 offset:1024
	ds_read_b128 v[188:191], v231 offset:2048
	ds_read_b128 v[192:195], v231 offset:3072
	s_add_i32 s51, s7, 2
	s_nop 0
	s_mov_b32 m0, s78
	ds_read_b128 v[196:199], v160
	ds_read_b128 v[200:203], v160 offset:1024
	ds_read_b128 v[204:207], v160 offset:2048
	ds_read_b128 v[208:211], v160 offset:3072
	ds_read_b128 v[212:215], v160 offset:4096
	ds_read_b128 v[216:219], v160 offset:5120
	ds_read_b128 v[220:223], v160 offset:6144
	ds_read_b128 v[224:227], v160 offset:7168
	global_load_lds_dwordx4 v144, s[86:87]
	s_mov_b32 m0, s79
	s_nop 0
	global_load_lds_dwordx4 v142, s[86:87]
	s_waitcnt vmcnt(8)
	s_waitcnt lgkmcnt(0)
	s_barrier
	s_setprio 1
	s_waitcnt lgkmcnt(0)
	v_mfma_f32_16x16x32_bf16 v[122:125], v[164:167], v[196:199], v[122:125]
	v_mfma_f32_16x16x32_bf16 v[118:121], v[172:175], v[196:199], v[118:121]
	v_mfma_f32_16x16x32_bf16 v[110:113], v[164:167], v[204:207], v[110:113]
	v_mfma_f32_16x16x32_bf16 v[102:105], v[172:175], v[204:207], v[102:105]
	v_mfma_f32_16x16x32_bf16 v[94:97], v[164:167], v[212:215], v[94:97]
	v_mfma_f32_16x16x32_bf16 v[86:89], v[172:175], v[212:215], v[86:89]
	v_mfma_f32_16x16x32_bf16 v[78:81], v[164:167], v[220:223], v[78:81]
	v_mfma_f32_16x16x32_bf16 v[70:73], v[172:175], v[220:223], v[70:73]
	v_mfma_f32_16x16x32_bf16 v[122:125], v[168:171], v[200:203], v[122:125]
	v_mfma_f32_16x16x32_bf16 v[118:121], v[176:179], v[200:203], v[118:121]
	v_mfma_f32_16x16x32_bf16 v[110:113], v[168:171], v[208:211], v[110:113]
	v_mfma_f32_16x16x32_bf16 v[102:105], v[176:179], v[208:211], v[102:105]
	v_mfma_f32_16x16x32_bf16 v[94:97], v[168:171], v[216:219], v[94:97]
	v_mfma_f32_16x16x32_bf16 v[86:89], v[176:179], v[216:219], v[86:89]
	v_mfma_f32_16x16x32_bf16 v[78:81], v[168:171], v[224:227], v[78:81]
	v_mfma_f32_16x16x32_bf16 v[70:73], v[176:179], v[224:227], v[70:73]
	s_setprio 0
	s_setprio 1
	v_mfma_f32_16x16x32_bf16 v[126:129], v[180:183], v[196:199], v[126:129]
	v_mfma_f32_16x16x32_bf16 v[114:117], v[188:191], v[196:199], v[114:117]
	v_mfma_f32_16x16x32_bf16 v[106:109], v[180:183], v[204:207], v[106:109]
	v_mfma_f32_16x16x32_bf16 v[98:101], v[188:191], v[204:207], v[98:101]
	v_mfma_f32_16x16x32_bf16 v[90:93], v[180:183], v[212:215], v[90:93]
	v_mfma_f32_16x16x32_bf16 v[82:85], v[188:191], v[212:215], v[82:85]
	v_mfma_f32_16x16x32_bf16 v[74:77], v[180:183], v[220:223], v[74:77]
	v_mfma_f32_16x16x32_bf16 v[66:69], v[188:191], v[220:223], v[66:69]
	v_mfma_f32_16x16x32_bf16 v[126:129], v[184:187], v[200:203], v[126:129]
	v_mfma_f32_16x16x32_bf16 v[114:117], v[192:195], v[200:203], v[114:117]
	v_mfma_f32_16x16x32_bf16 v[106:109], v[184:187], v[208:211], v[106:109]
	v_mfma_f32_16x16x32_bf16 v[98:101], v[192:195], v[208:211], v[98:101]
	v_mfma_f32_16x16x32_bf16 v[90:93], v[184:187], v[216:219], v[90:93]
	v_mfma_f32_16x16x32_bf16 v[82:85], v[192:195], v[216:219], v[82:85]
	v_mfma_f32_16x16x32_bf16 v[74:77], v[184:187], v[224:227], v[74:77]
	v_mfma_f32_16x16x32_bf16 v[66:69], v[192:195], v[224:227], v[66:69]
	s_setprio 0
	s_barrier
	s_add_u32 s98, s96, 0x40000
	s_addc_u32 s99, s97, 0
	s_mov_b32 m0, s80
	ds_read_b128 v[196:199], v160 offset:16384
	ds_read_b128 v[200:203], v160 offset:17408
	ds_read_b128 v[204:207], v160 offset:18432
	ds_read_b128 v[208:211], v160 offset:19456
	ds_read_b128 v[212:215], v160 offset:20480
	ds_read_b128 v[216:219], v160 offset:21504
	ds_read_b128 v[220:223], v160 offset:22528
	ds_read_b128 v[224:227], v160 offset:23552
	global_load_lds_dwordx4 v132, s[96:97]
	s_mov_b32 m0, s81
	s_add_i32 s7, s77, s47
	global_load_lds_dwordx4 v136, s[96:97]
	s_mov_b32 m0, s7
	s_nop 0
	global_load_lds_dwordx4 v132, s[98:99]
	s_add_i32 m0, s7, 0x2000
	s_nop 0
	global_load_lds_dwordx4 v136, s[98:99]
	s_mov_b32 m0, s57
	s_nop 0
	global_load_lds_dwordx4 v130, s[94:95]
	s_mov_b32 m0, s62
	s_nop 0
	global_load_lds_dwordx4 v134, s[94:95]
	s_waitcnt vmcnt(8)
	s_waitcnt lgkmcnt(0)
	s_barrier
	s_setprio 1
	s_waitcnt lgkmcnt(0)
	v_mfma_f32_16x16x32_bf16 v[62:65], v[164:167], v[196:199], v[62:65]
	v_mfma_f32_16x16x32_bf16 v[54:57], v[172:175], v[196:199], v[54:57]
	v_mfma_f32_16x16x32_bf16 v[46:49], v[164:167], v[204:207], v[46:49]
	v_mfma_f32_16x16x32_bf16 v[38:41], v[172:175], v[204:207], v[38:41]
	v_mfma_f32_16x16x32_bf16 v[30:33], v[164:167], v[212:215], v[30:33]
	v_mfma_f32_16x16x32_bf16 v[22:25], v[172:175], v[212:215], v[22:25]
	v_mfma_f32_16x16x32_bf16 v[14:17], v[164:167], v[220:223], v[14:17]
	v_mfma_f32_16x16x32_bf16 v[6:9], v[172:175], v[220:223], v[6:9]
	v_mfma_f32_16x16x32_bf16 v[62:65], v[168:171], v[200:203], v[62:65]
	v_mfma_f32_16x16x32_bf16 v[54:57], v[176:179], v[200:203], v[54:57]
	v_mfma_f32_16x16x32_bf16 v[46:49], v[168:171], v[208:211], v[46:49]
	v_mfma_f32_16x16x32_bf16 v[38:41], v[176:179], v[208:211], v[38:41]
	v_mfma_f32_16x16x32_bf16 v[30:33], v[168:171], v[216:219], v[30:33]
	v_mfma_f32_16x16x32_bf16 v[22:25], v[176:179], v[216:219], v[22:25]
	v_mfma_f32_16x16x32_bf16 v[14:17], v[168:171], v[224:227], v[14:17]
	v_mfma_f32_16x16x32_bf16 v[6:9], v[176:179], v[224:227], v[6:9]
	s_setprio 0
	s_setprio 1
	v_mfma_f32_16x16x32_bf16 v[58:61], v[180:183], v[196:199], v[58:61]
	v_mfma_f32_16x16x32_bf16 v[50:53], v[188:191], v[196:199], v[50:53]
	v_mfma_f32_16x16x32_bf16 v[42:45], v[180:183], v[204:207], v[42:45]
	v_mfma_f32_16x16x32_bf16 v[34:37], v[188:191], v[204:207], v[34:37]
	v_mfma_f32_16x16x32_bf16 v[26:29], v[180:183], v[212:215], v[26:29]
	v_mfma_f32_16x16x32_bf16 v[18:21], v[188:191], v[212:215], v[18:21]
	v_mfma_f32_16x16x32_bf16 v[10:13], v[180:183], v[220:223], v[10:13]
	v_mfma_f32_16x16x32_bf16 v[2:5], v[188:191], v[220:223], v[2:5]
	v_mfma_f32_16x16x32_bf16 v[58:61], v[184:187], v[200:203], v[58:61]
	v_mfma_f32_16x16x32_bf16 v[50:53], v[192:195], v[200:203], v[50:53]
	v_mfma_f32_16x16x32_bf16 v[42:45], v[184:187], v[208:211], v[42:45]
	v_mfma_f32_16x16x32_bf16 v[34:37], v[192:195], v[208:211], v[34:37]
	v_mfma_f32_16x16x32_bf16 v[26:29], v[184:187], v[216:219], v[26:29]
	v_mfma_f32_16x16x32_bf16 v[18:21], v[192:195], v[216:219], v[18:21]
	v_mfma_f32_16x16x32_bf16 v[10:13], v[184:187], v[224:227], v[10:13]
	v_mfma_f32_16x16x32_bf16 v[2:5], v[192:195], v[224:227], v[2:5]
	s_setprio 0
	s_barrier
	s_add_u32 s98, s94, 0x40000
	s_addc_u32 s99, s95, 0
	s_add_i32 s7, 0, 0x18000
	s_add_i32 s55, 0, 0x1c000
	ds_read_b128 v[164:167], v232
	ds_read_b128 v[168:171], v232 offset:1024
	ds_read_b128 v[172:175], v232 offset:2048
	ds_read_b128 v[176:179], v232 offset:3072
	ds_read_b128 v[180:183], v233
	ds_read_b128 v[184:187], v233 offset:1024
	ds_read_b128 v[188:191], v233 offset:2048
	ds_read_b128 v[192:195], v233 offset:3072
	s_mov_b32 m0, s63
	ds_read_b128 v[196:199], v160 offset:32768
	ds_read_b128 v[200:203], v160 offset:33792
	ds_read_b128 v[204:207], v160 offset:34816
	ds_read_b128 v[208:211], v160 offset:35840
	ds_read_b128 v[212:215], v160 offset:36864
	ds_read_b128 v[216:219], v160 offset:37888
	ds_read_b128 v[220:223], v160 offset:38912
	ds_read_b128 v[224:227], v160 offset:39936
	global_load_lds_dwordx4 v130, s[98:99]
	s_mov_b32 m0, s64
	s_nop 0
	global_load_lds_dwordx4 v134, s[98:99]
	s_waitcnt vmcnt(8)
	s_waitcnt lgkmcnt(0)
	s_barrier
	s_setprio 1
	s_waitcnt lgkmcnt(0)
	v_mfma_f32_16x16x32_bf16 v[122:125], v[164:167], v[196:199], v[122:125]
	v_mfma_f32_16x16x32_bf16 v[118:121], v[172:175], v[196:199], v[118:121]
	v_mfma_f32_16x16x32_bf16 v[110:113], v[164:167], v[204:207], v[110:113]
	v_mfma_f32_16x16x32_bf16 v[102:105], v[172:175], v[204:207], v[102:105]
	v_mfma_f32_16x16x32_bf16 v[94:97], v[164:167], v[212:215], v[94:97]
	v_mfma_f32_16x16x32_bf16 v[86:89], v[172:175], v[212:215], v[86:89]
	v_mfma_f32_16x16x32_bf16 v[78:81], v[164:167], v[220:223], v[78:81]
	v_mfma_f32_16x16x32_bf16 v[70:73], v[172:175], v[220:223], v[70:73]
	v_mfma_f32_16x16x32_bf16 v[122:125], v[168:171], v[200:203], v[122:125]
	v_mfma_f32_16x16x32_bf16 v[118:121], v[176:179], v[200:203], v[118:121]
	v_mfma_f32_16x16x32_bf16 v[110:113], v[168:171], v[208:211], v[110:113]
	v_mfma_f32_16x16x32_bf16 v[102:105], v[176:179], v[208:211], v[102:105]
	v_mfma_f32_16x16x32_bf16 v[94:97], v[168:171], v[216:219], v[94:97]
	v_mfma_f32_16x16x32_bf16 v[86:89], v[176:179], v[216:219], v[86:89]
	v_mfma_f32_16x16x32_bf16 v[78:81], v[168:171], v[224:227], v[78:81]
	v_mfma_f32_16x16x32_bf16 v[70:73], v[176:179], v[224:227], v[70:73]
	s_setprio 0
	s_setprio 1
	v_mfma_f32_16x16x32_bf16 v[126:129], v[180:183], v[196:199], v[126:129]
	v_mfma_f32_16x16x32_bf16 v[114:117], v[188:191], v[196:199], v[114:117]
	v_mfma_f32_16x16x32_bf16 v[106:109], v[180:183], v[204:207], v[106:109]
	v_mfma_f32_16x16x32_bf16 v[98:101], v[188:191], v[204:207], v[98:101]
	v_mfma_f32_16x16x32_bf16 v[90:93], v[180:183], v[212:215], v[90:93]
	v_mfma_f32_16x16x32_bf16 v[82:85], v[188:191], v[212:215], v[82:85]
	v_mfma_f32_16x16x32_bf16 v[74:77], v[180:183], v[220:223], v[74:77]
	v_mfma_f32_16x16x32_bf16 v[66:69], v[188:191], v[220:223], v[66:69]
	v_mfma_f32_16x16x32_bf16 v[126:129], v[184:187], v[200:203], v[126:129]
	v_mfma_f32_16x16x32_bf16 v[114:117], v[192:195], v[200:203], v[114:117]
	v_mfma_f32_16x16x32_bf16 v[106:109], v[184:187], v[208:211], v[106:109]
	v_mfma_f32_16x16x32_bf16 v[98:101], v[192:195], v[208:211], v[98:101]
	v_mfma_f32_16x16x32_bf16 v[90:93], v[184:187], v[216:219], v[90:93]
	v_mfma_f32_16x16x32_bf16 v[82:85], v[192:195], v[216:219], v[82:85]
	v_mfma_f32_16x16x32_bf16 v[74:77], v[184:187], v[224:227], v[74:77]
	v_mfma_f32_16x16x32_bf16 v[66:69], v[192:195], v[224:227], v[66:69]
	s_setprio 0
	s_barrier
	s_add_u32 s96, s96, 0x80
	s_addc_u32 s97, s97, 0
	s_add_u32 s98, s96, 0x40000
	s_addc_u32 s99, s97, 0
	s_add_u32 s94, s94, 0x80
	s_addc_u32 s95, s95, 0
	s_add_i32 s7, s7, s47
	s_mov_b32 m0, s7
	ds_read_b128 v[196:199], v160 offset:49152
	ds_read_b128 v[200:203], v160 offset:50176
	ds_read_b128 v[204:207], v160 offset:51200
	ds_read_b128 v[208:211], v160 offset:52224
	ds_read_b128 v[212:215], v160 offset:53248
	ds_read_b128 v[216:219], v160 offset:54272
	ds_read_b128 v[220:223], v160 offset:55296
	ds_read_b128 v[224:227], v160 offset:56320
	global_load_lds_dwordx4 v132, s[96:97]
	s_add_i32 m0, s7, 0x2000
	s_add_i32 s7, s55, s47
	global_load_lds_dwordx4 v136, s[96:97]
	s_mov_b32 m0, s7
	s_nop 0
	global_load_lds_dwordx4 v132, s[98:99]
	s_add_i32 m0, s7, 0x2000
	s_nop 0
	global_load_lds_dwordx4 v136, s[98:99]
	s_mov_b32 m0, s65
	s_nop 0
	global_load_lds_dwordx4 v130, s[94:95]
	s_mov_b32 m0, s66
	s_nop 0
	global_load_lds_dwordx4 v134, s[94:95]
	s_waitcnt vmcnt(8)
	s_waitcnt lgkmcnt(0)
	s_barrier
	s_setprio 1
	s_waitcnt lgkmcnt(0)
	v_mfma_f32_16x16x32_bf16 v[62:65], v[164:167], v[196:199], v[62:65]
	v_mfma_f32_16x16x32_bf16 v[54:57], v[172:175], v[196:199], v[54:57]
	v_mfma_f32_16x16x32_bf16 v[46:49], v[164:167], v[204:207], v[46:49]
	v_mfma_f32_16x16x32_bf16 v[38:41], v[172:175], v[204:207], v[38:41]
	v_mfma_f32_16x16x32_bf16 v[30:33], v[164:167], v[212:215], v[30:33]
	v_mfma_f32_16x16x32_bf16 v[22:25], v[172:175], v[212:215], v[22:25]
	v_mfma_f32_16x16x32_bf16 v[14:17], v[164:167], v[220:223], v[14:17]
	v_mfma_f32_16x16x32_bf16 v[6:9], v[172:175], v[220:223], v[6:9]
	v_mfma_f32_16x16x32_bf16 v[62:65], v[168:171], v[200:203], v[62:65]
	v_mfma_f32_16x16x32_bf16 v[54:57], v[176:179], v[200:203], v[54:57]
	v_mfma_f32_16x16x32_bf16 v[46:49], v[168:171], v[208:211], v[46:49]
	v_mfma_f32_16x16x32_bf16 v[38:41], v[176:179], v[208:211], v[38:41]
	v_mfma_f32_16x16x32_bf16 v[30:33], v[168:171], v[216:219], v[30:33]
	v_mfma_f32_16x16x32_bf16 v[22:25], v[176:179], v[216:219], v[22:25]
	v_mfma_f32_16x16x32_bf16 v[14:17], v[168:171], v[224:227], v[14:17]
	v_mfma_f32_16x16x32_bf16 v[6:9], v[176:179], v[224:227], v[6:9]
	s_setprio 0
	s_setprio 1
	v_mfma_f32_16x16x32_bf16 v[58:61], v[180:183], v[196:199], v[58:61]
	v_mfma_f32_16x16x32_bf16 v[50:53], v[188:191], v[196:199], v[50:53]
	v_mfma_f32_16x16x32_bf16 v[42:45], v[180:183], v[204:207], v[42:45]
	v_mfma_f32_16x16x32_bf16 v[34:37], v[188:191], v[204:207], v[34:37]
	v_mfma_f32_16x16x32_bf16 v[26:29], v[180:183], v[212:215], v[26:29]
	v_mfma_f32_16x16x32_bf16 v[18:21], v[188:191], v[212:215], v[18:21]
	v_mfma_f32_16x16x32_bf16 v[10:13], v[180:183], v[220:223], v[10:13]
	v_mfma_f32_16x16x32_bf16 v[2:5], v[188:191], v[220:223], v[2:5]
	v_mfma_f32_16x16x32_bf16 v[58:61], v[184:187], v[200:203], v[58:61]
	v_mfma_f32_16x16x32_bf16 v[50:53], v[192:195], v[200:203], v[50:53]
	v_mfma_f32_16x16x32_bf16 v[42:45], v[184:187], v[208:211], v[42:45]
	v_mfma_f32_16x16x32_bf16 v[34:37], v[192:195], v[208:211], v[34:37]
	v_mfma_f32_16x16x32_bf16 v[26:29], v[184:187], v[216:219], v[26:29]
	v_mfma_f32_16x16x32_bf16 v[18:21], v[192:195], v[216:219], v[18:21]
	v_mfma_f32_16x16x32_bf16 v[10:13], v[184:187], v[224:227], v[10:13]
	v_mfma_f32_16x16x32_bf16 v[2:5], v[192:195], v[224:227], v[2:5]
	s_setprio 0
	s_barrier
	s_mov_b32 s7, s51
	s_add_u32 s88, s88, 0x100
	s_addc_u32 s89, s89, 0
	s_add_u32 s86, s86, 0x100
	s_addc_u32 s87, s87, 0
	s_cmp_ge_i32 s51, s101
	s_cbranch_scc0 .LBB0_171

.LBB0_308:
	v_cmp_gt_i32_e32 vcc, 1, v141
	s_cbranch_vccnz .LBB0_370
	v_lshl_add_u64 v[154:155], v[2:3], 0, s[28:29]
	v_add_u32_e32 v138, -2, v141
	s_mov_b32 s8, 0
	s_nop 0
	v_readfirstlane_b32 s86, v152
	v_readfirstlane_b32 s87, v153
	v_readfirstlane_b32 s88, v154
	v_readfirstlane_b32 s89, v155
	v_readfirstlane_b32 s90, v148
	v_readfirstlane_b32 s91, v149
	v_readfirstlane_b32 s92, v150
	v_readfirstlane_b32 s93, v151
	v_readfirstlane_b32 s100, v138
	v_readfirstlane_b32 s101, v141
	v_add_u32_e32 v230, s69, v160
	v_add_u32_e32 v231, s72, v160
	v_add_u32_e32 v232, 0x18000, v160
	v_add_u32_e32 v233, 0x1c000, v160
	s_add_u32 s98, s86, 0x100
	s_addc_u32 s99, s87, 0
	s_cmp_eq_u32 s8, s100
	s_cselect_b64 s[94:95], s[90:91], s[98:99]
	s_cselect_b64 s[96:97], s[92:93], s[88:89]
	ds_read_b128 v[166:169], v230
	ds_read_b128 v[170:173], v230 offset:1024
	ds_read_b128 v[174:177], v230 offset:2048
	ds_read_b128 v[178:181], v230 offset:3072
	ds_read_b128 v[182:185], v231
	ds_read_b128 v[186:189], v231 offset:1024
	ds_read_b128 v[190:193], v231 offset:2048
	ds_read_b128 v[194:197], v231 offset:3072
	s_add_i32 s9, s8, 2
	s_nop 0
	s_add_i32 m0, s55, 0xc000
	ds_read_b128 v[198:201], v163
	ds_read_b128 v[202:205], v163 offset:1024
	ds_read_b128 v[206:209], v163 offset:2048
	ds_read_b128 v[210:213], v163 offset:3072
	ds_read_b128 v[214:217], v163 offset:4096
	ds_read_b128 v[218:221], v163 offset:5120
	ds_read_b128 v[222:225], v163 offset:6144
	ds_read_b128 v[226:229], v163 offset:7168
	global_load_lds_dwordx4 v144, s[86:87]
	s_add_i32 m0, s55, 0xe000
	s_nop 0
	global_load_lds_dwordx4 v142, s[86:87]
	s_waitcnt vmcnt(8)
	s_waitcnt lgkmcnt(0)
	s_barrier
	s_setprio 1
	s_waitcnt lgkmcnt(0)
	v_mfma_f32_16x16x32_bf16 v[122:125], v[166:169], v[198:201], 0
	v_mfma_f32_16x16x32_bf16 v[118:121], v[174:177], v[198:201], 0
	v_mfma_f32_16x16x32_bf16 v[110:113], v[166:169], v[206:209], 0
	v_mfma_f32_16x16x32_bf16 v[102:105], v[174:177], v[206:209], 0
	v_mfma_f32_16x16x32_bf16 v[94:97], v[166:169], v[214:217], 0
	v_mfma_f32_16x16x32_bf16 v[86:89], v[174:177], v[214:217], 0
	v_mfma_f32_16x16x32_bf16 v[78:81], v[166:169], v[222:225], 0
	v_mfma_f32_16x16x32_bf16 v[70:73], v[174:177], v[222:225], 0
	v_mfma_f32_16x16x32_bf16 v[122:125], v[170:173], v[202:205], v[122:125]
	v_mfma_f32_16x16x32_bf16 v[118:121], v[178:181], v[202:205], v[118:121]
	v_mfma_f32_16x16x32_bf16 v[110:113], v[170:173], v[210:213], v[110:113]
	v_mfma_f32_16x16x32_bf16 v[102:105], v[178:181], v[210:213], v[102:105]
	v_mfma_f32_16x16x32_bf16 v[94:97], v[170:173], v[218:221], v[94:97]
	v_mfma_f32_16x16x32_bf16 v[86:89], v[178:181], v[218:221], v[86:89]
	v_mfma_f32_16x16x32_bf16 v[78:81], v[170:173], v[226:229], v[78:81]
	v_mfma_f32_16x16x32_bf16 v[70:73], v[178:181], v[226:229], v[70:73]
	s_setprio 0
	s_setprio 1
	v_mfma_f32_16x16x32_bf16 v[126:129], v[182:185], v[198:201], 0
	v_mfma_f32_16x16x32_bf16 v[114:117], v[190:193], v[198:201], 0
	v_mfma_f32_16x16x32_bf16 v[106:109], v[182:185], v[206:209], 0
	v_mfma_f32_16x16x32_bf16 v[98:101], v[190:193], v[206:209], 0
	v_mfma_f32_16x16x32_bf16 v[90:93], v[182:185], v[214:217], 0
	v_mfma_f32_16x16x32_bf16 v[82:85], v[190:193], v[214:217], 0
	v_mfma_f32_16x16x32_bf16 v[74:77], v[182:185], v[222:225], 0
	v_mfma_f32_16x16x32_bf16 v[66:69], v[190:193], v[222:225], 0
	v_mfma_f32_16x16x32_bf16 v[126:129], v[186:189], v[202:205], v[126:129]
	v_mfma_f32_16x16x32_bf16 v[114:117], v[194:197], v[202:205], v[114:117]
	v_mfma_f32_16x16x32_bf16 v[106:109], v[186:189], v[210:213], v[106:109]
	v_mfma_f32_16x16x32_bf16 v[98:101], v[194:197], v[210:213], v[98:101]
	v_mfma_f32_16x16x32_bf16 v[90:93], v[186:189], v[218:221], v[90:93]
	v_mfma_f32_16x16x32_bf16 v[82:85], v[194:197], v[218:221], v[82:85]
	v_mfma_f32_16x16x32_bf16 v[74:77], v[186:189], v[226:229], v[74:77]
	v_mfma_f32_16x16x32_bf16 v[66:69], v[194:197], v[226:229], v[66:69]
	s_setprio 0
	s_barrier
	s_add_u32 s98, s96, 0xb0000
	s_addc_u32 s99, s97, 0
	s_add_i32 s8, s69, s54
	s_mov_b32 m0, s8
	ds_read_b128 v[198:201], v163 offset:16384
	ds_read_b128 v[202:205], v163 offset:17408
	ds_read_b128 v[206:209], v163 offset:18432
	ds_read_b128 v[210:213], v163 offset:19456
	ds_read_b128 v[214:217], v163 offset:20480
	ds_read_b128 v[218:221], v163 offset:21504
	ds_read_b128 v[222:225], v163 offset:22528
	ds_read_b128 v[226:229], v163 offset:23552
	global_load_lds_dwordx4 v132, s[96:97]
	s_add_i32 m0, s8, 0x2000
	s_add_i32 s8, s72, s54
	global_load_lds_dwordx4 v136, s[96:97]
	s_mov_b32 m0, s8
	s_nop 0
	global_load_lds_dwordx4 v132, s[98:99]
	s_add_i32 m0, s8, 0x2000
	s_nop 0
	global_load_lds_dwordx4 v136, s[98:99]
	s_mov_b32 m0, s55
	s_nop 0
	global_load_lds_dwordx4 v130, s[94:95]
	s_mov_b32 m0, s56
	s_nop 0
	global_load_lds_dwordx4 v134, s[94:95]
	s_waitcnt vmcnt(8)
	s_waitcnt lgkmcnt(0)
	s_barrier
	s_setprio 1
	s_waitcnt lgkmcnt(0)
	v_mfma_f32_16x16x32_bf16 v[62:65], v[166:169], v[198:201], 0
	v_mfma_f32_16x16x32_bf16 v[54:57], v[174:177], v[198:201], 0
	v_mfma_f32_16x16x32_bf16 v[46:49], v[166:169], v[206:209], 0
	v_mfma_f32_16x16x32_bf16 v[38:41], v[174:177], v[206:209], 0
	v_mfma_f32_16x16x32_bf16 v[30:33], v[166:169], v[214:217], 0
	v_mfma_f32_16x16x32_bf16 v[22:25], v[174:177], v[214:217], 0
	v_mfma_f32_16x16x32_bf16 v[14:17], v[166:169], v[222:225], 0
	v_mfma_f32_16x16x32_bf16 v[6:9], v[174:177], v[222:225], 0
	v_mfma_f32_16x16x32_bf16 v[62:65], v[170:173], v[202:205], v[62:65]
	v_mfma_f32_16x16x32_bf16 v[54:57], v[178:181], v[202:205], v[54:57]
	v_mfma_f32_16x16x32_bf16 v[46:49], v[170:173], v[210:213], v[46:49]
	v_mfma_f32_16x16x32_bf16 v[38:41], v[178:181], v[210:213], v[38:41]
	v_mfma_f32_16x16x32_bf16 v[30:33], v[170:173], v[218:221], v[30:33]
	v_mfma_f32_16x16x32_bf16 v[22:25], v[178:181], v[218:221], v[22:25]
	v_mfma_f32_16x16x32_bf16 v[14:17], v[170:173], v[226:229], v[14:17]
	v_mfma_f32_16x16x32_bf16 v[6:9], v[178:181], v[226:229], v[6:9]
	s_setprio 0
	s_setprio 1
	v_mfma_f32_16x16x32_bf16 v[58:61], v[182:185], v[198:201], 0
	v_mfma_f32_16x16x32_bf16 v[50:53], v[190:193], v[198:201], 0
	v_mfma_f32_16x16x32_bf16 v[42:45], v[182:185], v[206:209], 0
	v_mfma_f32_16x16x32_bf16 v[34:37], v[190:193], v[206:209], 0
	v_mfma_f32_16x16x32_bf16 v[26:29], v[182:185], v[214:217], 0
	v_mfma_f32_16x16x32_bf16 v[18:21], v[190:193], v[214:217], 0
	v_mfma_f32_16x16x32_bf16 v[10:13], v[182:185], v[222:225], 0
	v_mfma_f32_16x16x32_bf16 v[2:5], v[190:193], v[222:225], 0
	v_mfma_f32_16x16x32_bf16 v[58:61], v[186:189], v[202:205], v[58:61]
	v_mfma_f32_16x16x32_bf16 v[50:53], v[194:197], v[202:205], v[50:53]
	v_mfma_f32_16x16x32_bf16 v[42:45], v[186:189], v[210:213], v[42:45]
	v_mfma_f32_16x16x32_bf16 v[34:37], v[194:197], v[210:213], v[34:37]
	v_mfma_f32_16x16x32_bf16 v[26:29], v[186:189], v[218:221], v[26:29]
	v_mfma_f32_16x16x32_bf16 v[18:21], v[194:197], v[218:221], v[18:21]
	v_mfma_f32_16x16x32_bf16 v[10:13], v[186:189], v[226:229], v[10:13]
	v_mfma_f32_16x16x32_bf16 v[2:5], v[194:197], v[226:229], v[2:5]
	s_setprio 0
	s_barrier
	s_add_u32 s98, s94, 0xb0000
	s_addc_u32 s99, s95, 0
	s_add_i32 s8, 0, 0x18000
	s_add_i32 s50, 0, 0x1c000
	ds_read_b128 v[166:169], v232
	ds_read_b128 v[170:173], v232 offset:1024
	ds_read_b128 v[174:177], v232 offset:2048
	ds_read_b128 v[178:181], v232 offset:3072
	ds_read_b128 v[182:185], v233
	ds_read_b128 v[186:189], v233 offset:1024
	ds_read_b128 v[190:193], v233 offset:2048
	ds_read_b128 v[194:197], v233 offset:3072
	s_mov_b32 m0, s57
	ds_read_b128 v[198:201], v163 offset:32768
	ds_read_b128 v[202:205], v163 offset:33792
	ds_read_b128 v[206:209], v163 offset:34816
	ds_read_b128 v[210:213], v163 offset:35840
	ds_read_b128 v[214:217], v163 offset:36864
	ds_read_b128 v[218:221], v163 offset:37888
	ds_read_b128 v[222:225], v163 offset:38912
	ds_read_b128 v[226:229], v163 offset:39936
	global_load_lds_dwordx4 v130, s[98:99]
	s_mov_b32 m0, s58
	s_nop 0
	global_load_lds_dwordx4 v134, s[98:99]
	s_waitcnt vmcnt(8)
	s_waitcnt lgkmcnt(0)
	s_barrier
	s_setprio 1
	s_waitcnt lgkmcnt(0)
	v_mfma_f32_16x16x32_bf16 v[122:125], v[166:169], v[198:201], v[122:125]
	v_mfma_f32_16x16x32_bf16 v[118:121], v[174:177], v[198:201], v[118:121]
	v_mfma_f32_16x16x32_bf16 v[110:113], v[166:169], v[206:209], v[110:113]
	v_mfma_f32_16x16x32_bf16 v[102:105], v[174:177], v[206:209], v[102:105]
	v_mfma_f32_16x16x32_bf16 v[94:97], v[166:169], v[214:217], v[94:97]
	v_mfma_f32_16x16x32_bf16 v[86:89], v[174:177], v[214:217], v[86:89]
	v_mfma_f32_16x16x32_bf16 v[78:81], v[166:169], v[222:225], v[78:81]
	v_mfma_f32_16x16x32_bf16 v[70:73], v[174:177], v[222:225], v[70:73]
	v_mfma_f32_16x16x32_bf16 v[122:125], v[170:173], v[202:205], v[122:125]
	v_mfma_f32_16x16x32_bf16 v[118:121], v[178:181], v[202:205], v[118:121]
	v_mfma_f32_16x16x32_bf16 v[110:113], v[170:173], v[210:213], v[110:113]
	v_mfma_f32_16x16x32_bf16 v[102:105], v[178:181], v[210:213], v[102:105]
	v_mfma_f32_16x16x32_bf16 v[94:97], v[170:173], v[218:221], v[94:97]
	v_mfma_f32_16x16x32_bf16 v[86:89], v[178:181], v[218:221], v[86:89]
	v_mfma_f32_16x16x32_bf16 v[78:81], v[170:173], v[226:229], v[78:81]
	v_mfma_f32_16x16x32_bf16 v[70:73], v[178:181], v[226:229], v[70:73]
	s_setprio 0
	s_setprio 1
	v_mfma_f32_16x16x32_bf16 v[126:129], v[182:185], v[198:201], v[126:129]
	v_mfma_f32_16x16x32_bf16 v[114:117], v[190:193], v[198:201], v[114:117]
	v_mfma_f32_16x16x32_bf16 v[106:109], v[182:185], v[206:209], v[106:109]
	v_mfma_f32_16x16x32_bf16 v[98:101], v[190:193], v[206:209], v[98:101]
	v_mfma_f32_16x16x32_bf16 v[90:93], v[182:185], v[214:217], v[90:93]
	v_mfma_f32_16x16x32_bf16 v[82:85], v[190:193], v[214:217], v[82:85]
	v_mfma_f32_16x16x32_bf16 v[74:77], v[182:185], v[222:225], v[74:77]
	v_mfma_f32_16x16x32_bf16 v[66:69], v[190:193], v[222:225], v[66:69]
	v_mfma_f32_16x16x32_bf16 v[126:129], v[186:189], v[202:205], v[126:129]
	v_mfma_f32_16x16x32_bf16 v[114:117], v[194:197], v[202:205], v[114:117]
	v_mfma_f32_16x16x32_bf16 v[106:109], v[186:189], v[210:213], v[106:109]
	v_mfma_f32_16x16x32_bf16 v[98:101], v[194:197], v[210:213], v[98:101]
	v_mfma_f32_16x16x32_bf16 v[90:93], v[186:189], v[218:221], v[90:93]
	v_mfma_f32_16x16x32_bf16 v[82:85], v[194:197], v[218:221], v[82:85]
	v_mfma_f32_16x16x32_bf16 v[74:77], v[186:189], v[226:229], v[74:77]
	v_mfma_f32_16x16x32_bf16 v[66:69], v[194:197], v[226:229], v[66:69]
	s_setprio 0
	s_barrier
	s_add_u32 s96, s96, 0x80
	s_addc_u32 s97, s97, 0
	s_add_u32 s98, s96, 0xb0000
	s_addc_u32 s99, s97, 0
	s_add_u32 s94, s94, 0x80
	s_addc_u32 s95, s95, 0
	s_add_i32 s8, s8, s54
	s_mov_b32 m0, s8
	ds_read_b128 v[198:201], v163 offset:49152
	ds_read_b128 v[202:205], v163 offset:50176
	ds_read_b128 v[206:209], v163 offset:51200
	ds_read_b128 v[210:213], v163 offset:52224
	ds_read_b128 v[214:217], v163 offset:53248
	ds_read_b128 v[218:221], v163 offset:54272
	ds_read_b128 v[222:225], v163 offset:55296
	ds_read_b128 v[226:229], v163 offset:56320
	global_load_lds_dwordx4 v132, s[96:97]
	s_add_i32 m0, s8, 0x2000
	s_add_i32 s8, s50, s54
	global_load_lds_dwordx4 v136, s[96:97]
	s_mov_b32 m0, s8
	s_nop 0
	global_load_lds_dwordx4 v132, s[98:99]
	s_add_i32 m0, s8, 0x2000
	s_nop 0
	global_load_lds_dwordx4 v136, s[98:99]
	s_mov_b32 m0, s64
	s_nop 0
	global_load_lds_dwordx4 v130, s[94:95]
	s_mov_b32 m0, s65
	s_nop 0
	global_load_lds_dwordx4 v134, s[94:95]
	s_waitcnt vmcnt(8)
	s_waitcnt lgkmcnt(0)
	s_barrier
	s_setprio 1
	s_waitcnt lgkmcnt(0)
	v_mfma_f32_16x16x32_bf16 v[62:65], v[166:169], v[198:201], v[62:65]
	v_mfma_f32_16x16x32_bf16 v[54:57], v[174:177], v[198:201], v[54:57]
	v_mfma_f32_16x16x32_bf16 v[46:49], v[166:169], v[206:209], v[46:49]
	v_mfma_f32_16x16x32_bf16 v[38:41], v[174:177], v[206:209], v[38:41]
	v_mfma_f32_16x16x32_bf16 v[30:33], v[166:169], v[214:217], v[30:33]
	v_mfma_f32_16x16x32_bf16 v[22:25], v[174:177], v[214:217], v[22:25]
	v_mfma_f32_16x16x32_bf16 v[14:17], v[166:169], v[222:225], v[14:17]
	v_mfma_f32_16x16x32_bf16 v[6:9], v[174:177], v[222:225], v[6:9]
	v_mfma_f32_16x16x32_bf16 v[62:65], v[170:173], v[202:205], v[62:65]
	v_mfma_f32_16x16x32_bf16 v[54:57], v[178:181], v[202:205], v[54:57]
	v_mfma_f32_16x16x32_bf16 v[46:49], v[170:173], v[210:213], v[46:49]
	v_mfma_f32_16x16x32_bf16 v[38:41], v[178:181], v[210:213], v[38:41]
	v_mfma_f32_16x16x32_bf16 v[30:33], v[170:173], v[218:221], v[30:33]
	v_mfma_f32_16x16x32_bf16 v[22:25], v[178:181], v[218:221], v[22:25]
	v_mfma_f32_16x16x32_bf16 v[14:17], v[170:173], v[226:229], v[14:17]
	v_mfma_f32_16x16x32_bf16 v[6:9], v[178:181], v[226:229], v[6:9]
	s_setprio 0
	s_setprio 1
	v_mfma_f32_16x16x32_bf16 v[58:61], v[182:185], v[198:201], v[58:61]
	v_mfma_f32_16x16x32_bf16 v[50:53], v[190:193], v[198:201], v[50:53]
	v_mfma_f32_16x16x32_bf16 v[42:45], v[182:185], v[206:209], v[42:45]
	v_mfma_f32_16x16x32_bf16 v[34:37], v[190:193], v[206:209], v[34:37]
	v_mfma_f32_16x16x32_bf16 v[26:29], v[182:185], v[214:217], v[26:29]
	v_mfma_f32_16x16x32_bf16 v[18:21], v[190:193], v[214:217], v[18:21]
	v_mfma_f32_16x16x32_bf16 v[10:13], v[182:185], v[222:225], v[10:13]
	v_mfma_f32_16x16x32_bf16 v[2:5], v[190:193], v[222:225], v[2:5]
	v_mfma_f32_16x16x32_bf16 v[58:61], v[186:189], v[202:205], v[58:61]
	v_mfma_f32_16x16x32_bf16 v[50:53], v[194:197], v[202:205], v[50:53]
	v_mfma_f32_16x16x32_bf16 v[42:45], v[186:189], v[210:213], v[42:45]
	v_mfma_f32_16x16x32_bf16 v[34:37], v[194:197], v[210:213], v[34:37]
	v_mfma_f32_16x16x32_bf16 v[26:29], v[186:189], v[218:221], v[26:29]
	v_mfma_f32_16x16x32_bf16 v[18:21], v[194:197], v[218:221], v[18:21]
	v_mfma_f32_16x16x32_bf16 v[10:13], v[186:189], v[226:229], v[10:13]
	v_mfma_f32_16x16x32_bf16 v[2:5], v[194:197], v[226:229], v[2:5]
	s_setprio 0
	s_barrier
	s_mov_b32 s8, s9
	s_add_u32 s88, s88, 0x100
	s_addc_u32 s89, s89, 0
	s_add_u32 s86, s86, 0x100
	s_addc_u32 s87, s87, 0
	s_cmp_ge_i32 s9, s101
	s_cbranch_scc1 .Lmy_kexit_1
.LBB0_310:
	s_add_u32 s98, s86, 0x100
	s_addc_u32 s99, s87, 0
	s_cmp_eq_u32 s8, s100
	s_cselect_b64 s[94:95], s[90:91], s[98:99]
	s_cselect_b64 s[96:97], s[92:93], s[88:89]
	ds_read_b128 v[166:169], v230
	ds_read_b128 v[170:173], v230 offset:1024
	ds_read_b128 v[174:177], v230 offset:2048
	ds_read_b128 v[178:181], v230 offset:3072
	ds_read_b128 v[182:185], v231
	ds_read_b128 v[186:189], v231 offset:1024
	ds_read_b128 v[190:193], v231 offset:2048
	ds_read_b128 v[194:197], v231 offset:3072
	s_add_i32 s9, s8, 2
	s_nop 0
	s_add_i32 m0, s55, 0xc000
	ds_read_b128 v[198:201], v163
	ds_read_b128 v[202:205], v163 offset:1024
	ds_read_b128 v[206:209], v163 offset:2048
	ds_read_b128 v[210:213], v163 offset:3072
	ds_read_b128 v[214:217], v163 offset:4096
	ds_read_b128 v[218:221], v163 offset:5120
	ds_read_b128 v[222:225], v163 offset:6144
	ds_read_b128 v[226:229], v163 offset:7168
	global_load_lds_dwordx4 v144, s[86:87]
	s_add_i32 m0, s55, 0xe000
	s_nop 0
	global_load_lds_dwordx4 v142, s[86:87]
	s_waitcnt vmcnt(8)
	s_waitcnt lgkmcnt(0)
	s_barrier
	s_setprio 1
	s_waitcnt lgkmcnt(0)
	v_mfma_f32_16x16x32_bf16 v[122:125], v[166:169], v[198:201], v[122:125]
	v_mfma_f32_16x16x32_bf16 v[118:121], v[174:177], v[198:201], v[118:121]
	v_mfma_f32_16x16x32_bf16 v[110:113], v[166:169], v[206:209], v[110:113]
	v_mfma_f32_16x16x32_bf16 v[102:105], v[174:177], v[206:209], v[102:105]
	v_mfma_f32_16x16x32_bf16 v[94:97], v[166:169], v[214:217], v[94:97]
	v_mfma_f32_16x16x32_bf16 v[86:89], v[174:177], v[214:217], v[86:89]
	v_mfma_f32_16x16x32_bf16 v[78:81], v[166:169], v[222:225], v[78:81]
	v_mfma_f32_16x16x32_bf16 v[70:73], v[174:177], v[222:225], v[70:73]
	v_mfma_f32_16x16x32_bf16 v[122:125], v[170:173], v[202:205], v[122:125]
	v_mfma_f32_16x16x32_bf16 v[118:121], v[178:181], v[202:205], v[118:121]
	v_mfma_f32_16x16x32_bf16 v[110:113], v[170:173], v[210:213], v[110:113]
	v_mfma_f32_16x16x32_bf16 v[102:105], v[178:181], v[210:213], v[102:105]
	v_mfma_f32_16x16x32_bf16 v[94:97], v[170:173], v[218:221], v[94:97]
	v_mfma_f32_16x16x32_bf16 v[86:89], v[178:181], v[218:221], v[86:89]
	v_mfma_f32_16x16x32_bf16 v[78:81], v[170:173], v[226:229], v[78:81]
	v_mfma_f32_16x16x32_bf16 v[70:73], v[178:181], v[226:229], v[70:73]
	s_setprio 0
	s_setprio 1
	v_mfma_f32_16x16x32_bf16 v[126:129], v[182:185], v[198:201], v[126:129]
	v_mfma_f32_16x16x32_bf16 v[114:117], v[190:193], v[198:201], v[114:117]
	v_mfma_f32_16x16x32_bf16 v[106:109], v[182:185], v[206:209], v[106:109]
	v_mfma_f32_16x16x32_bf16 v[98:101], v[190:193], v[206:209], v[98:101]
	v_mfma_f32_16x16x32_bf16 v[90:93], v[182:185], v[214:217], v[90:93]
	v_mfma_f32_16x16x32_bf16 v[82:85], v[190:193], v[214:217], v[82:85]
	v_mfma_f32_16x16x32_bf16 v[74:77], v[182:185], v[222:225], v[74:77]
	v_mfma_f32_16x16x32_bf16 v[66:69], v[190:193], v[222:225], v[66:69]
	v_mfma_f32_16x16x32_bf16 v[126:129], v[186:189], v[202:205], v[126:129]
	v_mfma_f32_16x16x32_bf16 v[114:117], v[194:197], v[202:205], v[114:117]
	v_mfma_f32_16x16x32_bf16 v[106:109], v[186:189], v[210:213], v[106:109]
	v_mfma_f32_16x16x32_bf16 v[98:101], v[194:197], v[210:213], v[98:101]
	v_mfma_f32_16x16x32_bf16 v[90:93], v[186:189], v[218:221], v[90:93]
	v_mfma_f32_16x16x32_bf16 v[82:85], v[194:197], v[218:221], v[82:85]
	v_mfma_f32_16x16x32_bf16 v[74:77], v[186:189], v[226:229], v[74:77]
	v_mfma_f32_16x16x32_bf16 v[66:69], v[194:197], v[226:229], v[66:69]
	s_setprio 0
	s_barrier
	s_add_u32 s98, s96, 0xb0000
	s_addc_u32 s99, s97, 0
	s_add_i32 s8, s69, s54
	s_mov_b32 m0, s8
	ds_read_b128 v[198:201], v163 offset:16384
	ds_read_b128 v[202:205], v163 offset:17408
	ds_read_b128 v[206:209], v163 offset:18432
	ds_read_b128 v[210:213], v163 offset:19456
	ds_read_b128 v[214:217], v163 offset:20480
	ds_read_b128 v[218:221], v163 offset:21504
	ds_read_b128 v[222:225], v163 offset:22528
	ds_read_b128 v[226:229], v163 offset:23552
	global_load_lds_dwordx4 v132, s[96:97]
	s_add_i32 m0, s8, 0x2000
	s_add_i32 s8, s72, s54
	global_load_lds_dwordx4 v136, s[96:97]
	s_mov_b32 m0, s8
	s_nop 0
	global_load_lds_dwordx4 v132, s[98:99]
	s_add_i32 m0, s8, 0x2000
	s_nop 0
	global_load_lds_dwordx4 v136, s[98:99]
	s_mov_b32 m0, s55
	s_nop 0
	global_load_lds_dwordx4 v130, s[94:95]
	s_mov_b32 m0, s56
	s_nop 0
	global_load_lds_dwordx4 v134, s[94:95]
	s_waitcnt vmcnt(8)
	s_waitcnt lgkmcnt(0)
	s_barrier
	s_setprio 1
	s_waitcnt lgkmcnt(0)
	v_mfma_f32_16x16x32_bf16 v[62:65], v[166:169], v[198:201], v[62:65]
	v_mfma_f32_16x16x32_bf16 v[54:57], v[174:177], v[198:201], v[54:57]
	v_mfma_f32_16x16x32_bf16 v[46:49], v[166:169], v[206:209], v[46:49]
	v_mfma_f32_16x16x32_bf16 v[38:41], v[174:177], v[206:209], v[38:41]
	v_mfma_f32_16x16x32_bf16 v[30:33], v[166:169], v[214:217], v[30:33]
	v_mfma_f32_16x16x32_bf16 v[22:25], v[174:177], v[214:217], v[22:25]
	v_mfma_f32_16x16x32_bf16 v[14:17], v[166:169], v[222:225], v[14:17]
	v_mfma_f32_16x16x32_bf16 v[6:9], v[174:177], v[222:225], v[6:9]
	v_mfma_f32_16x16x32_bf16 v[62:65], v[170:173], v[202:205], v[62:65]
	v_mfma_f32_16x16x32_bf16 v[54:57], v[178:181], v[202:205], v[54:57]
	v_mfma_f32_16x16x32_bf16 v[46:49], v[170:173], v[210:213], v[46:49]
	v_mfma_f32_16x16x32_bf16 v[38:41], v[178:181], v[210:213], v[38:41]
	v_mfma_f32_16x16x32_bf16 v[30:33], v[170:173], v[218:221], v[30:33]
	v_mfma_f32_16x16x32_bf16 v[22:25], v[178:181], v[218:221], v[22:25]
	v_mfma_f32_16x16x32_bf16 v[14:17], v[170:173], v[226:229], v[14:17]
	v_mfma_f32_16x16x32_bf16 v[6:9], v[178:181], v[226:229], v[6:9]
	s_setprio 0
	s_setprio 1
	v_mfma_f32_16x16x32_bf16 v[58:61], v[182:185], v[198:201], v[58:61]
	v_mfma_f32_16x16x32_bf16 v[50:53], v[190:193], v[198:201], v[50:53]
	v_mfma_f32_16x16x32_bf16 v[42:45], v[182:185], v[206:209], v[42:45]
	v_mfma_f32_16x16x32_bf16 v[34:37], v[190:193], v[206:209], v[34:37]
	v_mfma_f32_16x16x32_bf16 v[26:29], v[182:185], v[214:217], v[26:29]
	v_mfma_f32_16x16x32_bf16 v[18:21], v[190:193], v[214:217], v[18:21]
	v_mfma_f32_16x16x32_bf16 v[10:13], v[182:185], v[222:225], v[10:13]
	v_mfma_f32_16x16x32_bf16 v[2:5], v[190:193], v[222:225], v[2:5]
	v_mfma_f32_16x16x32_bf16 v[58:61], v[186:189], v[202:205], v[58:61]
	v_mfma_f32_16x16x32_bf16 v[50:53], v[194:197], v[202:205], v[50:53]
	v_mfma_f32_16x16x32_bf16 v[42:45], v[186:189], v[210:213], v[42:45]
	v_mfma_f32_16x16x32_bf16 v[34:37], v[194:197], v[210:213], v[34:37]
	v_mfma_f32_16x16x32_bf16 v[26:29], v[186:189], v[218:221], v[26:29]
	v_mfma_f32_16x16x32_bf16 v[18:21], v[194:197], v[218:221], v[18:21]
	v_mfma_f32_16x16x32_bf16 v[10:13], v[186:189], v[226:229], v[10:13]
	v_mfma_f32_16x16x32_bf16 v[2:5], v[194:197], v[226:229], v[2:5]
	s_setprio 0
	s_barrier
	s_add_u32 s98, s94, 0xb0000
	s_addc_u32 s99, s95, 0
	s_add_i32 s8, 0, 0x18000
	s_add_i32 s50, 0, 0x1c000
	ds_read_b128 v[166:169], v232
	ds_read_b128 v[170:173], v232 offset:1024
	ds_read_b128 v[174:177], v232 offset:2048
	ds_read_b128 v[178:181], v232 offset:3072
	ds_read_b128 v[182:185], v233
	ds_read_b128 v[186:189], v233 offset:1024
	ds_read_b128 v[190:193], v233 offset:2048
	ds_read_b128 v[194:197], v233 offset:3072
	s_mov_b32 m0, s57
	ds_read_b128 v[198:201], v163 offset:32768
	ds_read_b128 v[202:205], v163 offset:33792
	ds_read_b128 v[206:209], v163 offset:34816
	ds_read_b128 v[210:213], v163 offset:35840
	ds_read_b128 v[214:217], v163 offset:36864
	ds_read_b128 v[218:221], v163 offset:37888
	ds_read_b128 v[222:225], v163 offset:38912
	ds_read_b128 v[226:229], v163 offset:39936
	global_load_lds_dwordx4 v130, s[98:99]
	s_mov_b32 m0, s58
	s_nop 0
	global_load_lds_dwordx4 v134, s[98:99]
	s_waitcnt vmcnt(8)
	s_waitcnt lgkmcnt(0)
	s_barrier
	s_setprio 1
	s_waitcnt lgkmcnt(0)
	v_mfma_f32_16x16x32_bf16 v[122:125], v[166:169], v[198:201], v[122:125]
	v_mfma_f32_16x16x32_bf16 v[118:121], v[174:177], v[198:201], v[118:121]
	v_mfma_f32_16x16x32_bf16 v[110:113], v[166:169], v[206:209], v[110:113]
	v_mfma_f32_16x16x32_bf16 v[102:105], v[174:177], v[206:209], v[102:105]
	v_mfma_f32_16x16x32_bf16 v[94:97], v[166:169], v[214:217], v[94:97]
	v_mfma_f32_16x16x32_bf16 v[86:89], v[174:177], v[214:217], v[86:89]
	v_mfma_f32_16x16x32_bf16 v[78:81], v[166:169], v[222:225], v[78:81]
	v_mfma_f32_16x16x32_bf16 v[70:73], v[174:177], v[222:225], v[70:73]
	v_mfma_f32_16x16x32_bf16 v[122:125], v[170:173], v[202:205], v[122:125]
	v_mfma_f32_16x16x32_bf16 v[118:121], v[178:181], v[202:205], v[118:121]
	v_mfma_f32_16x16x32_bf16 v[110:113], v[170:173], v[210:213], v[110:113]
	v_mfma_f32_16x16x32_bf16 v[102:105], v[178:181], v[210:213], v[102:105]
	v_mfma_f32_16x16x32_bf16 v[94:97], v[170:173], v[218:221], v[94:97]
	v_mfma_f32_16x16x32_bf16 v[86:89], v[178:181], v[218:221], v[86:89]
	v_mfma_f32_16x16x32_bf16 v[78:81], v[170:173], v[226:229], v[78:81]
	v_mfma_f32_16x16x32_bf16 v[70:73], v[178:181], v[226:229], v[70:73]
	s_setprio 0
	s_setprio 1
	v_mfma_f32_16x16x32_bf16 v[126:129], v[182:185], v[198:201], v[126:129]
	v_mfma_f32_16x16x32_bf16 v[114:117], v[190:193], v[198:201], v[114:117]
	v_mfma_f32_16x16x32_bf16 v[106:109], v[182:185], v[206:209], v[106:109]
	v_mfma_f32_16x16x32_bf16 v[98:101], v[190:193], v[206:209], v[98:101]
	v_mfma_f32_16x16x32_bf16 v[90:93], v[182:185], v[214:217], v[90:93]
	v_mfma_f32_16x16x32_bf16 v[82:85], v[190:193], v[214:217], v[82:85]
	v_mfma_f32_16x16x32_bf16 v[74:77], v[182:185], v[222:225], v[74:77]
	v_mfma_f32_16x16x32_bf16 v[66:69], v[190:193], v[222:225], v[66:69]
	v_mfma_f32_16x16x32_bf16 v[126:129], v[186:189], v[202:205], v[126:129]
	v_mfma_f32_16x16x32_bf16 v[114:117], v[194:197], v[202:205], v[114:117]
	v_mfma_f32_16x16x32_bf16 v[106:109], v[186:189], v[210:213], v[106:109]
	v_mfma_f32_16x16x32_bf16 v[98:101], v[194:197], v[210:213], v[98:101]
	v_mfma_f32_16x16x32_bf16 v[90:93], v[186:189], v[218:221], v[90:93]
	v_mfma_f32_16x16x32_bf16 v[82:85], v[194:197], v[218:221], v[82:85]
	v_mfma_f32_16x16x32_bf16 v[74:77], v[186:189], v[226:229], v[74:77]
	v_mfma_f32_16x16x32_bf16 v[66:69], v[194:197], v[226:229], v[66:69]
	s_setprio 0
	s_barrier
	s_add_u32 s96, s96, 0x80
	s_addc_u32 s97, s97, 0
	s_add_u32 s98, s96, 0xb0000
	s_addc_u32 s99, s97, 0
	s_add_u32 s94, s94, 0x80
	s_addc_u32 s95, s95, 0
	s_add_i32 s8, s8, s54
	s_mov_b32 m0, s8
	ds_read_b128 v[198:201], v163 offset:49152
	ds_read_b128 v[202:205], v163 offset:50176
	ds_read_b128 v[206:209], v163 offset:51200
	ds_read_b128 v[210:213], v163 offset:52224
	ds_read_b128 v[214:217], v163 offset:53248
	ds_read_b128 v[218:221], v163 offset:54272
	ds_read_b128 v[222:225], v163 offset:55296
	ds_read_b128 v[226:229], v163 offset:56320
	global_load_lds_dwordx4 v132, s[96:97]
	s_add_i32 m0, s8, 0x2000
	s_add_i32 s8, s50, s54
	global_load_lds_dwordx4 v136, s[96:97]
	s_mov_b32 m0, s8
	s_nop 0
	global_load_lds_dwordx4 v132, s[98:99]
	s_add_i32 m0, s8, 0x2000
	s_nop 0
	global_load_lds_dwordx4 v136, s[98:99]
	s_mov_b32 m0, s64
	s_nop 0
	global_load_lds_dwordx4 v130, s[94:95]
	s_mov_b32 m0, s65
	s_nop 0
	global_load_lds_dwordx4 v134, s[94:95]
	s_waitcnt vmcnt(8)
	s_waitcnt lgkmcnt(0)
	s_barrier
	s_setprio 1
	s_waitcnt lgkmcnt(0)
	v_mfma_f32_16x16x32_bf16 v[62:65], v[166:169], v[198:201], v[62:65]
	v_mfma_f32_16x16x32_bf16 v[54:57], v[174:177], v[198:201], v[54:57]
	v_mfma_f32_16x16x32_bf16 v[46:49], v[166:169], v[206:209], v[46:49]
	v_mfma_f32_16x16x32_bf16 v[38:41], v[174:177], v[206:209], v[38:41]
	v_mfma_f32_16x16x32_bf16 v[30:33], v[166:169], v[214:217], v[30:33]
	v_mfma_f32_16x16x32_bf16 v[22:25], v[174:177], v[214:217], v[22:25]
	v_mfma_f32_16x16x32_bf16 v[14:17], v[166:169], v[222:225], v[14:17]
	v_mfma_f32_16x16x32_bf16 v[6:9], v[174:177], v[222:225], v[6:9]
	v_mfma_f32_16x16x32_bf16 v[62:65], v[170:173], v[202:205], v[62:65]
	v_mfma_f32_16x16x32_bf16 v[54:57], v[178:181], v[202:205], v[54:57]
	v_mfma_f32_16x16x32_bf16 v[46:49], v[170:173], v[210:213], v[46:49]
	v_mfma_f32_16x16x32_bf16 v[38:41], v[178:181], v[210:213], v[38:41]
	v_mfma_f32_16x16x32_bf16 v[30:33], v[170:173], v[218:221], v[30:33]
	v_mfma_f32_16x16x32_bf16 v[22:25], v[178:181], v[218:221], v[22:25]
	v_mfma_f32_16x16x32_bf16 v[14:17], v[170:173], v[226:229], v[14:17]
	v_mfma_f32_16x16x32_bf16 v[6:9], v[178:181], v[226:229], v[6:9]
	s_setprio 0
	s_setprio 1
	v_mfma_f32_16x16x32_bf16 v[58:61], v[182:185], v[198:201], v[58:61]
	v_mfma_f32_16x16x32_bf16 v[50:53], v[190:193], v[198:201], v[50:53]
	v_mfma_f32_16x16x32_bf16 v[42:45], v[182:185], v[206:209], v[42:45]
	v_mfma_f32_16x16x32_bf16 v[34:37], v[190:193], v[206:209], v[34:37]
	v_mfma_f32_16x16x32_bf16 v[26:29], v[182:185], v[214:217], v[26:29]
	v_mfma_f32_16x16x32_bf16 v[18:21], v[190:193], v[214:217], v[18:21]
	v_mfma_f32_16x16x32_bf16 v[10:13], v[182:185], v[222:225], v[10:13]
	v_mfma_f32_16x16x32_bf16 v[2:5], v[190:193], v[222:225], v[2:5]
	v_mfma_f32_16x16x32_bf16 v[58:61], v[186:189], v[202:205], v[58:61]
	v_mfma_f32_16x16x32_bf16 v[50:53], v[194:197], v[202:205], v[50:53]
	v_mfma_f32_16x16x32_bf16 v[42:45], v[186:189], v[210:213], v[42:45]
	v_mfma_f32_16x16x32_bf16 v[34:37], v[194:197], v[210:213], v[34:37]
	v_mfma_f32_16x16x32_bf16 v[26:29], v[186:189], v[218:221], v[26:29]
	v_mfma_f32_16x16x32_bf16 v[18:21], v[194:197], v[218:221], v[18:21]
	v_mfma_f32_16x16x32_bf16 v[10:13], v[186:189], v[226:229], v[10:13]
	v_mfma_f32_16x16x32_bf16 v[2:5], v[194:197], v[226:229], v[2:5]
	s_setprio 0
	s_barrier
	s_mov_b32 s8, s9
	s_add_u32 s88, s88, 0x100
	s_addc_u32 s89, s89, 0
	s_add_u32 s86, s86, 0x100
	s_addc_u32 s87, s87, 0
	s_cmp_ge_i32 s9, s101
	s_cbranch_scc0 .LBB0_310

.LBB0_497:
	v_cmp_gt_i32_e32 vcc, 1, v141
	s_cbranch_vccnz .LBB0_559
	v_lshl_add_u64 v[154:155], v[2:3], 0, s[16:17]
	v_add_u32_e32 v138, -2, v141
	v_lshl_add_u64 v[152:153], v[4:5], 0, s[20:21]
	s_mov_b32 s7, 0
	s_nop 0
	v_readfirstlane_b32 s86, v154
	v_readfirstlane_b32 s87, v155
	v_readfirstlane_b32 s88, v152
	v_readfirstlane_b32 s89, v153
	v_readfirstlane_b32 s90, v148
	v_readfirstlane_b32 s91, v149
	v_readfirstlane_b32 s92, v150
	v_readfirstlane_b32 s93, v151
	v_readfirstlane_b32 s100, v138
	v_readfirstlane_b32 s101, v141
	v_add_u32_e32 v230, s77, v160
	v_add_u32_e32 v231, s78, v160
	v_add_u32_e32 v232, 0x18000, v160
	v_add_u32_e32 v233, 0x1c000, v160
	s_add_u32 s98, s86, 0xfffc0080
	s_addc_u32 s99, s87, -1
	s_cmp_eq_u32 s7, s100
	s_cselect_b64 s[94:95], s[90:91], s[98:99]
	s_cselect_b64 s[96:97], s[92:93], s[88:89]
	ds_read_b128 v[156:159], v230
	ds_read_b128 v[166:169], v230 offset:1024
	ds_read_b128 v[170:173], v230 offset:2048
	ds_read_b128 v[174:177], v230 offset:3072
	ds_read_b128 v[178:181], v231
	ds_read_b128 v[182:185], v231 offset:1024
	ds_read_b128 v[186:189], v231 offset:2048
	ds_read_b128 v[190:193], v231 offset:3072
	s_add_i32 s45, s7, 2
	s_nop 0
	s_add_i32 m0, s49, 0xc000
	ds_read_b128 v[194:197], v163
	ds_read_b128 v[198:201], v163 offset:1024
	ds_read_b128 v[202:205], v163 offset:2048
	ds_read_b128 v[206:209], v163 offset:3072
	ds_read_b128 v[210:213], v163 offset:4096
	ds_read_b128 v[214:217], v163 offset:5120
	ds_read_b128 v[218:221], v163 offset:6144
	ds_read_b128 v[222:225], v163 offset:7168
	global_load_lds_dwordx4 v144, s[86:87]
	s_add_i32 m0, s49, 0xe000
	s_nop 0
	global_load_lds_dwordx4 v142, s[86:87]
	s_waitcnt vmcnt(8)
	s_waitcnt lgkmcnt(0)
	s_barrier
	s_setprio 1
	s_waitcnt lgkmcnt(0)
	v_mfma_f32_16x16x32_bf16 v[122:125], v[156:159], v[194:197], 0
	v_mfma_f32_16x16x32_bf16 v[118:121], v[170:173], v[194:197], 0
	v_mfma_f32_16x16x32_bf16 v[110:113], v[156:159], v[202:205], 0
	v_mfma_f32_16x16x32_bf16 v[102:105], v[170:173], v[202:205], 0
	v_mfma_f32_16x16x32_bf16 v[94:97], v[156:159], v[210:213], 0
	v_mfma_f32_16x16x32_bf16 v[86:89], v[170:173], v[210:213], 0
	v_mfma_f32_16x16x32_bf16 v[78:81], v[156:159], v[218:221], 0
	v_mfma_f32_16x16x32_bf16 v[70:73], v[170:173], v[218:221], 0
	v_mfma_f32_16x16x32_bf16 v[122:125], v[166:169], v[198:201], v[122:125]
	v_mfma_f32_16x16x32_bf16 v[118:121], v[174:177], v[198:201], v[118:121]
	v_mfma_f32_16x16x32_bf16 v[110:113], v[166:169], v[206:209], v[110:113]
	v_mfma_f32_16x16x32_bf16 v[102:105], v[174:177], v[206:209], v[102:105]
	v_mfma_f32_16x16x32_bf16 v[94:97], v[166:169], v[214:217], v[94:97]
	v_mfma_f32_16x16x32_bf16 v[86:89], v[174:177], v[214:217], v[86:89]
	v_mfma_f32_16x16x32_bf16 v[78:81], v[166:169], v[222:225], v[78:81]
	v_mfma_f32_16x16x32_bf16 v[70:73], v[174:177], v[222:225], v[70:73]
	s_setprio 0
	s_setprio 1
	v_mfma_f32_16x16x32_bf16 v[126:129], v[178:181], v[194:197], 0
	v_mfma_f32_16x16x32_bf16 v[114:117], v[186:189], v[194:197], 0
	v_mfma_f32_16x16x32_bf16 v[106:109], v[178:181], v[202:205], 0
	v_mfma_f32_16x16x32_bf16 v[98:101], v[186:189], v[202:205], 0
	v_mfma_f32_16x16x32_bf16 v[90:93], v[178:181], v[210:213], 0
	v_mfma_f32_16x16x32_bf16 v[82:85], v[186:189], v[210:213], 0
	v_mfma_f32_16x16x32_bf16 v[74:77], v[178:181], v[218:221], 0
	v_mfma_f32_16x16x32_bf16 v[66:69], v[186:189], v[218:221], 0
	v_mfma_f32_16x16x32_bf16 v[126:129], v[182:185], v[198:201], v[126:129]
	v_mfma_f32_16x16x32_bf16 v[114:117], v[190:193], v[198:201], v[114:117]
	v_mfma_f32_16x16x32_bf16 v[106:109], v[182:185], v[206:209], v[106:109]
	v_mfma_f32_16x16x32_bf16 v[98:101], v[190:193], v[206:209], v[98:101]
	v_mfma_f32_16x16x32_bf16 v[90:93], v[182:185], v[214:217], v[90:93]
	v_mfma_f32_16x16x32_bf16 v[82:85], v[190:193], v[214:217], v[82:85]
	v_mfma_f32_16x16x32_bf16 v[74:77], v[182:185], v[222:225], v[74:77]
	v_mfma_f32_16x16x32_bf16 v[66:69], v[190:193], v[222:225], v[66:69]
	s_setprio 0
	s_barrier
	s_add_u32 s98, s96, 0x40000
	s_addc_u32 s99, s97, 0
	s_add_i32 s7, s77, s25
	s_mov_b32 m0, s7
	ds_read_b128 v[194:197], v163 offset:16384
	ds_read_b128 v[198:201], v163 offset:17408
	ds_read_b128 v[202:205], v163 offset:18432
	ds_read_b128 v[206:209], v163 offset:19456
	ds_read_b128 v[210:213], v163 offset:20480
	ds_read_b128 v[214:217], v163 offset:21504
	ds_read_b128 v[218:221], v163 offset:22528
	ds_read_b128 v[222:225], v163 offset:23552
	global_load_lds_dwordx4 v132, s[96:97]
	s_add_i32 m0, s7, 0x2000
	s_add_i32 s7, s78, s25
	global_load_lds_dwordx4 v136, s[96:97]
	s_mov_b32 m0, s7
	s_nop 0
	global_load_lds_dwordx4 v132, s[98:99]
	s_add_i32 m0, s7, 0x2000
	s_nop 0
	global_load_lds_dwordx4 v136, s[98:99]
	s_mov_b32 m0, s49
	s_nop 0
	global_load_lds_dwordx4 v130, s[94:95]
	s_mov_b32 m0, s58
	s_nop 0
	global_load_lds_dwordx4 v134, s[94:95]
	s_waitcnt vmcnt(8)
	s_waitcnt lgkmcnt(0)
	s_barrier
	s_setprio 1
	s_waitcnt lgkmcnt(0)
	v_mfma_f32_16x16x32_bf16 v[62:65], v[156:159], v[194:197], 0
	v_mfma_f32_16x16x32_bf16 v[54:57], v[170:173], v[194:197], 0
	v_mfma_f32_16x16x32_bf16 v[46:49], v[156:159], v[202:205], 0
	v_mfma_f32_16x16x32_bf16 v[38:41], v[170:173], v[202:205], 0
	v_mfma_f32_16x16x32_bf16 v[30:33], v[156:159], v[210:213], 0
	v_mfma_f32_16x16x32_bf16 v[22:25], v[170:173], v[210:213], 0
	v_mfma_f32_16x16x32_bf16 v[14:17], v[156:159], v[218:221], 0
	v_mfma_f32_16x16x32_bf16 v[6:9], v[170:173], v[218:221], 0
	v_mfma_f32_16x16x32_bf16 v[62:65], v[166:169], v[198:201], v[62:65]
	v_mfma_f32_16x16x32_bf16 v[54:57], v[174:177], v[198:201], v[54:57]
	v_mfma_f32_16x16x32_bf16 v[46:49], v[166:169], v[206:209], v[46:49]
	v_mfma_f32_16x16x32_bf16 v[38:41], v[174:177], v[206:209], v[38:41]
	v_mfma_f32_16x16x32_bf16 v[30:33], v[166:169], v[214:217], v[30:33]
	v_mfma_f32_16x16x32_bf16 v[22:25], v[174:177], v[214:217], v[22:25]
	v_mfma_f32_16x16x32_bf16 v[14:17], v[166:169], v[222:225], v[14:17]
	v_mfma_f32_16x16x32_bf16 v[6:9], v[174:177], v[222:225], v[6:9]
	s_setprio 0
	s_setprio 1
	v_mfma_f32_16x16x32_bf16 v[58:61], v[178:181], v[194:197], 0
	v_mfma_f32_16x16x32_bf16 v[50:53], v[186:189], v[194:197], 0
	v_mfma_f32_16x16x32_bf16 v[42:45], v[178:181], v[202:205], 0
	v_mfma_f32_16x16x32_bf16 v[34:37], v[186:189], v[202:205], 0
	v_mfma_f32_16x16x32_bf16 v[26:29], v[178:181], v[210:213], 0
	v_mfma_f32_16x16x32_bf16 v[18:21], v[186:189], v[210:213], 0
	v_mfma_f32_16x16x32_bf16 v[10:13], v[178:181], v[218:221], 0
	v_mfma_f32_16x16x32_bf16 v[2:5], v[186:189], v[218:221], 0
	v_mfma_f32_16x16x32_bf16 v[58:61], v[182:185], v[198:201], v[58:61]
	v_mfma_f32_16x16x32_bf16 v[50:53], v[190:193], v[198:201], v[50:53]
	v_mfma_f32_16x16x32_bf16 v[42:45], v[182:185], v[206:209], v[42:45]
	v_mfma_f32_16x16x32_bf16 v[34:37], v[190:193], v[206:209], v[34:37]
	v_mfma_f32_16x16x32_bf16 v[26:29], v[182:185], v[214:217], v[26:29]
	v_mfma_f32_16x16x32_bf16 v[18:21], v[190:193], v[214:217], v[18:21]
	v_mfma_f32_16x16x32_bf16 v[10:13], v[182:185], v[222:225], v[10:13]
	v_mfma_f32_16x16x32_bf16 v[2:5], v[190:193], v[222:225], v[2:5]
	s_setprio 0
	s_barrier
	s_add_u32 s98, s94, 0x40000
	s_addc_u32 s99, s95, 0
	s_add_i32 s7, 0, 0x18000
	s_add_i32 s47, 0, 0x1c000
	ds_read_b128 v[156:159], v232
	ds_read_b128 v[166:169], v232 offset:1024
	ds_read_b128 v[170:173], v232 offset:2048
	ds_read_b128 v[174:177], v232 offset:3072
	ds_read_b128 v[178:181], v233
	ds_read_b128 v[182:185], v233 offset:1024
	ds_read_b128 v[186:189], v233 offset:2048
	ds_read_b128 v[190:193], v233 offset:3072
	s_mov_b32 m0, s59
	ds_read_b128 v[194:197], v163 offset:32768
	ds_read_b128 v[198:201], v163 offset:33792
	ds_read_b128 v[202:205], v163 offset:34816
	ds_read_b128 v[206:209], v163 offset:35840
	ds_read_b128 v[210:213], v163 offset:36864
	ds_read_b128 v[214:217], v163 offset:37888
	ds_read_b128 v[218:221], v163 offset:38912
	ds_read_b128 v[222:225], v163 offset:39936
	global_load_lds_dwordx4 v130, s[98:99]
	s_mov_b32 m0, s60
	s_nop 0
	global_load_lds_dwordx4 v134, s[98:99]
	s_waitcnt vmcnt(8)
	s_waitcnt lgkmcnt(0)
	s_barrier
	s_setprio 1
	s_waitcnt lgkmcnt(0)
	v_mfma_f32_16x16x32_bf16 v[122:125], v[156:159], v[194:197], v[122:125]
	v_mfma_f32_16x16x32_bf16 v[118:121], v[170:173], v[194:197], v[118:121]
	v_mfma_f32_16x16x32_bf16 v[110:113], v[156:159], v[202:205], v[110:113]
	v_mfma_f32_16x16x32_bf16 v[102:105], v[170:173], v[202:205], v[102:105]
	v_mfma_f32_16x16x32_bf16 v[94:97], v[156:159], v[210:213], v[94:97]
	v_mfma_f32_16x16x32_bf16 v[86:89], v[170:173], v[210:213], v[86:89]
	v_mfma_f32_16x16x32_bf16 v[78:81], v[156:159], v[218:221], v[78:81]
	v_mfma_f32_16x16x32_bf16 v[70:73], v[170:173], v[218:221], v[70:73]
	v_mfma_f32_16x16x32_bf16 v[122:125], v[166:169], v[198:201], v[122:125]
	v_mfma_f32_16x16x32_bf16 v[118:121], v[174:177], v[198:201], v[118:121]
	v_mfma_f32_16x16x32_bf16 v[110:113], v[166:169], v[206:209], v[110:113]
	v_mfma_f32_16x16x32_bf16 v[102:105], v[174:177], v[206:209], v[102:105]
	v_mfma_f32_16x16x32_bf16 v[94:97], v[166:169], v[214:217], v[94:97]
	v_mfma_f32_16x16x32_bf16 v[86:89], v[174:177], v[214:217], v[86:89]
	v_mfma_f32_16x16x32_bf16 v[78:81], v[166:169], v[222:225], v[78:81]
	v_mfma_f32_16x16x32_bf16 v[70:73], v[174:177], v[222:225], v[70:73]
	s_setprio 0
	s_setprio 1
	v_mfma_f32_16x16x32_bf16 v[126:129], v[178:181], v[194:197], v[126:129]
	v_mfma_f32_16x16x32_bf16 v[114:117], v[186:189], v[194:197], v[114:117]
	v_mfma_f32_16x16x32_bf16 v[106:109], v[178:181], v[202:205], v[106:109]
	v_mfma_f32_16x16x32_bf16 v[98:101], v[186:189], v[202:205], v[98:101]
	v_mfma_f32_16x16x32_bf16 v[90:93], v[178:181], v[210:213], v[90:93]
	v_mfma_f32_16x16x32_bf16 v[82:85], v[186:189], v[210:213], v[82:85]
	v_mfma_f32_16x16x32_bf16 v[74:77], v[178:181], v[218:221], v[74:77]
	v_mfma_f32_16x16x32_bf16 v[66:69], v[186:189], v[218:221], v[66:69]
	v_mfma_f32_16x16x32_bf16 v[126:129], v[182:185], v[198:201], v[126:129]
	v_mfma_f32_16x16x32_bf16 v[114:117], v[190:193], v[198:201], v[114:117]
	v_mfma_f32_16x16x32_bf16 v[106:109], v[182:185], v[206:209], v[106:109]
	v_mfma_f32_16x16x32_bf16 v[98:101], v[190:193], v[206:209], v[98:101]
	v_mfma_f32_16x16x32_bf16 v[90:93], v[182:185], v[214:217], v[90:93]
	v_mfma_f32_16x16x32_bf16 v[82:85], v[190:193], v[214:217], v[82:85]
	v_mfma_f32_16x16x32_bf16 v[74:77], v[182:185], v[222:225], v[74:77]
	v_mfma_f32_16x16x32_bf16 v[66:69], v[190:193], v[222:225], v[66:69]
	s_setprio 0
	s_barrier
	s_add_u32 s96, s96, 0x80
	s_addc_u32 s97, s97, 0
	s_add_u32 s98, s96, 0x40000
	s_addc_u32 s99, s97, 0
	s_add_u32 s94, s94, 0x80
	s_addc_u32 s95, s95, 0
	s_add_i32 s7, s7, s25
	s_mov_b32 m0, s7
	ds_read_b128 v[194:197], v163 offset:49152
	ds_read_b128 v[198:201], v163 offset:50176
	ds_read_b128 v[202:205], v163 offset:51200
	ds_read_b128 v[206:209], v163 offset:52224
	ds_read_b128 v[210:213], v163 offset:53248
	ds_read_b128 v[214:217], v163 offset:54272
	ds_read_b128 v[218:221], v163 offset:55296
	ds_read_b128 v[222:225], v163 offset:56320
	global_load_lds_dwordx4 v132, s[96:97]
	s_add_i32 m0, s7, 0x2000
	s_add_i32 s7, s47, s25
	global_load_lds_dwordx4 v136, s[96:97]
	s_mov_b32 m0, s7
	s_nop 0
	global_load_lds_dwordx4 v132, s[98:99]
	s_add_i32 m0, s7, 0x2000
	s_nop 0
	global_load_lds_dwordx4 v136, s[98:99]
	s_mov_b32 m0, s66
	s_nop 0
	global_load_lds_dwordx4 v130, s[94:95]
	s_mov_b32 m0, s67
	s_nop 0
	global_load_lds_dwordx4 v134, s[94:95]
	s_waitcnt vmcnt(8)
	s_waitcnt lgkmcnt(0)
	s_barrier
	s_setprio 1
	s_waitcnt lgkmcnt(0)
	v_mfma_f32_16x16x32_bf16 v[62:65], v[156:159], v[194:197], v[62:65]
	v_mfma_f32_16x16x32_bf16 v[54:57], v[170:173], v[194:197], v[54:57]
	v_mfma_f32_16x16x32_bf16 v[46:49], v[156:159], v[202:205], v[46:49]
	v_mfma_f32_16x16x32_bf16 v[38:41], v[170:173], v[202:205], v[38:41]
	v_mfma_f32_16x16x32_bf16 v[30:33], v[156:159], v[210:213], v[30:33]
	v_mfma_f32_16x16x32_bf16 v[22:25], v[170:173], v[210:213], v[22:25]
	v_mfma_f32_16x16x32_bf16 v[14:17], v[156:159], v[218:221], v[14:17]
	v_mfma_f32_16x16x32_bf16 v[6:9], v[170:173], v[218:221], v[6:9]
	v_mfma_f32_16x16x32_bf16 v[62:65], v[166:169], v[198:201], v[62:65]
	v_mfma_f32_16x16x32_bf16 v[54:57], v[174:177], v[198:201], v[54:57]
	v_mfma_f32_16x16x32_bf16 v[46:49], v[166:169], v[206:209], v[46:49]
	v_mfma_f32_16x16x32_bf16 v[38:41], v[174:177], v[206:209], v[38:41]
	v_mfma_f32_16x16x32_bf16 v[30:33], v[166:169], v[214:217], v[30:33]
	v_mfma_f32_16x16x32_bf16 v[22:25], v[174:177], v[214:217], v[22:25]
	v_mfma_f32_16x16x32_bf16 v[14:17], v[166:169], v[222:225], v[14:17]
	v_mfma_f32_16x16x32_bf16 v[6:9], v[174:177], v[222:225], v[6:9]
	s_setprio 0
	s_setprio 1
	v_mfma_f32_16x16x32_bf16 v[58:61], v[178:181], v[194:197], v[58:61]
	v_mfma_f32_16x16x32_bf16 v[50:53], v[186:189], v[194:197], v[50:53]
	v_mfma_f32_16x16x32_bf16 v[42:45], v[178:181], v[202:205], v[42:45]
	v_mfma_f32_16x16x32_bf16 v[34:37], v[186:189], v[202:205], v[34:37]
	v_mfma_f32_16x16x32_bf16 v[26:29], v[178:181], v[210:213], v[26:29]
	v_mfma_f32_16x16x32_bf16 v[18:21], v[186:189], v[210:213], v[18:21]
	v_mfma_f32_16x16x32_bf16 v[10:13], v[178:181], v[218:221], v[10:13]
	v_mfma_f32_16x16x32_bf16 v[2:5], v[186:189], v[218:221], v[2:5]
	v_mfma_f32_16x16x32_bf16 v[58:61], v[182:185], v[198:201], v[58:61]
	v_mfma_f32_16x16x32_bf16 v[50:53], v[190:193], v[198:201], v[50:53]
	v_mfma_f32_16x16x32_bf16 v[42:45], v[182:185], v[206:209], v[42:45]
	v_mfma_f32_16x16x32_bf16 v[34:37], v[190:193], v[206:209], v[34:37]
	v_mfma_f32_16x16x32_bf16 v[26:29], v[182:185], v[214:217], v[26:29]
	v_mfma_f32_16x16x32_bf16 v[18:21], v[190:193], v[214:217], v[18:21]
	v_mfma_f32_16x16x32_bf16 v[10:13], v[182:185], v[222:225], v[10:13]
	v_mfma_f32_16x16x32_bf16 v[2:5], v[190:193], v[222:225], v[2:5]
	s_setprio 0
	s_barrier
	s_mov_b32 s7, s45
	s_add_u32 s88, s88, 0x100
	s_addc_u32 s89, s89, 0
	s_add_u32 s86, s86, 0x100
	s_addc_u32 s87, s87, 0
	s_cmp_ge_i32 s45, s101
	s_cbranch_scc1 .Lmy_kexit_2
.LBB0_499:
	s_add_u32 s98, s86, 0xfffc0080
	s_addc_u32 s99, s87, -1
	s_cmp_eq_u32 s7, s100
	s_cselect_b64 s[94:95], s[90:91], s[98:99]
	s_cselect_b64 s[96:97], s[92:93], s[88:89]
	ds_read_b128 v[156:159], v230
	ds_read_b128 v[166:169], v230 offset:1024
	ds_read_b128 v[170:173], v230 offset:2048
	ds_read_b128 v[174:177], v230 offset:3072
	ds_read_b128 v[178:181], v231
	ds_read_b128 v[182:185], v231 offset:1024
	ds_read_b128 v[186:189], v231 offset:2048
	ds_read_b128 v[190:193], v231 offset:3072
	s_add_i32 s45, s7, 2
	s_nop 0
	s_add_i32 m0, s49, 0xc000
	ds_read_b128 v[194:197], v163
	ds_read_b128 v[198:201], v163 offset:1024
	ds_read_b128 v[202:205], v163 offset:2048
	ds_read_b128 v[206:209], v163 offset:3072
	ds_read_b128 v[210:213], v163 offset:4096
	ds_read_b128 v[214:217], v163 offset:5120
	ds_read_b128 v[218:221], v163 offset:6144
	ds_read_b128 v[222:225], v163 offset:7168
	global_load_lds_dwordx4 v144, s[86:87]
	s_add_i32 m0, s49, 0xe000
	s_nop 0
	global_load_lds_dwordx4 v142, s[86:87]
	s_waitcnt vmcnt(8)
	s_waitcnt lgkmcnt(0)
	s_barrier
	s_setprio 1
	s_waitcnt lgkmcnt(0)
	v_mfma_f32_16x16x32_bf16 v[122:125], v[156:159], v[194:197], v[122:125]
	v_mfma_f32_16x16x32_bf16 v[118:121], v[170:173], v[194:197], v[118:121]
	v_mfma_f32_16x16x32_bf16 v[110:113], v[156:159], v[202:205], v[110:113]
	v_mfma_f32_16x16x32_bf16 v[102:105], v[170:173], v[202:205], v[102:105]
	v_mfma_f32_16x16x32_bf16 v[94:97], v[156:159], v[210:213], v[94:97]
	v_mfma_f32_16x16x32_bf16 v[86:89], v[170:173], v[210:213], v[86:89]
	v_mfma_f32_16x16x32_bf16 v[78:81], v[156:159], v[218:221], v[78:81]
	v_mfma_f32_16x16x32_bf16 v[70:73], v[170:173], v[218:221], v[70:73]
	v_mfma_f32_16x16x32_bf16 v[122:125], v[166:169], v[198:201], v[122:125]
	v_mfma_f32_16x16x32_bf16 v[118:121], v[174:177], v[198:201], v[118:121]
	v_mfma_f32_16x16x32_bf16 v[110:113], v[166:169], v[206:209], v[110:113]
	v_mfma_f32_16x16x32_bf16 v[102:105], v[174:177], v[206:209], v[102:105]
	v_mfma_f32_16x16x32_bf16 v[94:97], v[166:169], v[214:217], v[94:97]
	v_mfma_f32_16x16x32_bf16 v[86:89], v[174:177], v[214:217], v[86:89]
	v_mfma_f32_16x16x32_bf16 v[78:81], v[166:169], v[222:225], v[78:81]
	v_mfma_f32_16x16x32_bf16 v[70:73], v[174:177], v[222:225], v[70:73]
	s_setprio 0
	s_setprio 1
	v_mfma_f32_16x16x32_bf16 v[126:129], v[178:181], v[194:197], v[126:129]
	v_mfma_f32_16x16x32_bf16 v[114:117], v[186:189], v[194:197], v[114:117]
	v_mfma_f32_16x16x32_bf16 v[106:109], v[178:181], v[202:205], v[106:109]
	v_mfma_f32_16x16x32_bf16 v[98:101], v[186:189], v[202:205], v[98:101]
	v_mfma_f32_16x16x32_bf16 v[90:93], v[178:181], v[210:213], v[90:93]
	v_mfma_f32_16x16x32_bf16 v[82:85], v[186:189], v[210:213], v[82:85]
	v_mfma_f32_16x16x32_bf16 v[74:77], v[178:181], v[218:221], v[74:77]
	v_mfma_f32_16x16x32_bf16 v[66:69], v[186:189], v[218:221], v[66:69]
	v_mfma_f32_16x16x32_bf16 v[126:129], v[182:185], v[198:201], v[126:129]
	v_mfma_f32_16x16x32_bf16 v[114:117], v[190:193], v[198:201], v[114:117]
	v_mfma_f32_16x16x32_bf16 v[106:109], v[182:185], v[206:209], v[106:109]
	v_mfma_f32_16x16x32_bf16 v[98:101], v[190:193], v[206:209], v[98:101]
	v_mfma_f32_16x16x32_bf16 v[90:93], v[182:185], v[214:217], v[90:93]
	v_mfma_f32_16x16x32_bf16 v[82:85], v[190:193], v[214:217], v[82:85]
	v_mfma_f32_16x16x32_bf16 v[74:77], v[182:185], v[222:225], v[74:77]
	v_mfma_f32_16x16x32_bf16 v[66:69], v[190:193], v[222:225], v[66:69]
	s_setprio 0
	s_barrier
	s_add_u32 s98, s96, 0x40000
	s_addc_u32 s99, s97, 0
	s_add_i32 s7, s77, s25
	s_mov_b32 m0, s7
	ds_read_b128 v[194:197], v163 offset:16384
	ds_read_b128 v[198:201], v163 offset:17408
	ds_read_b128 v[202:205], v163 offset:18432
	ds_read_b128 v[206:209], v163 offset:19456
	ds_read_b128 v[210:213], v163 offset:20480
	ds_read_b128 v[214:217], v163 offset:21504
	ds_read_b128 v[218:221], v163 offset:22528
	ds_read_b128 v[222:225], v163 offset:23552
	global_load_lds_dwordx4 v132, s[96:97]
	s_add_i32 m0, s7, 0x2000
	s_add_i32 s7, s78, s25
	global_load_lds_dwordx4 v136, s[96:97]
	s_mov_b32 m0, s7
	s_nop 0
	global_load_lds_dwordx4 v132, s[98:99]
	s_add_i32 m0, s7, 0x2000
	s_nop 0
	global_load_lds_dwordx4 v136, s[98:99]
	s_mov_b32 m0, s49
	s_nop 0
	global_load_lds_dwordx4 v130, s[94:95]
	s_mov_b32 m0, s58
	s_nop 0
	global_load_lds_dwordx4 v134, s[94:95]
	s_waitcnt vmcnt(8)
	s_waitcnt lgkmcnt(0)
	s_barrier
	s_setprio 1
	s_waitcnt lgkmcnt(0)
	v_mfma_f32_16x16x32_bf16 v[62:65], v[156:159], v[194:197], v[62:65]
	v_mfma_f32_16x16x32_bf16 v[54:57], v[170:173], v[194:197], v[54:57]
	v_mfma_f32_16x16x32_bf16 v[46:49], v[156:159], v[202:205], v[46:49]
	v_mfma_f32_16x16x32_bf16 v[38:41], v[170:173], v[202:205], v[38:41]
	v_mfma_f32_16x16x32_bf16 v[30:33], v[156:159], v[210:213], v[30:33]
	v_mfma_f32_16x16x32_bf16 v[22:25], v[170:173], v[210:213], v[22:25]
	v_mfma_f32_16x16x32_bf16 v[14:17], v[156:159], v[218:221], v[14:17]
	v_mfma_f32_16x16x32_bf16 v[6:9], v[170:173], v[218:221], v[6:9]
	v_mfma_f32_16x16x32_bf16 v[62:65], v[166:169], v[198:201], v[62:65]
	v_mfma_f32_16x16x32_bf16 v[54:57], v[174:177], v[198:201], v[54:57]
	v_mfma_f32_16x16x32_bf16 v[46:49], v[166:169], v[206:209], v[46:49]
	v_mfma_f32_16x16x32_bf16 v[38:41], v[174:177], v[206:209], v[38:41]
	v_mfma_f32_16x16x32_bf16 v[30:33], v[166:169], v[214:217], v[30:33]
	v_mfma_f32_16x16x32_bf16 v[22:25], v[174:177], v[214:217], v[22:25]
	v_mfma_f32_16x16x32_bf16 v[14:17], v[166:169], v[222:225], v[14:17]
	v_mfma_f32_16x16x32_bf16 v[6:9], v[174:177], v[222:225], v[6:9]
	s_setprio 0
	s_setprio 1
	v_mfma_f32_16x16x32_bf16 v[58:61], v[178:181], v[194:197], v[58:61]
	v_mfma_f32_16x16x32_bf16 v[50:53], v[186:189], v[194:197], v[50:53]
	v_mfma_f32_16x16x32_bf16 v[42:45], v[178:181], v[202:205], v[42:45]
	v_mfma_f32_16x16x32_bf16 v[34:37], v[186:189], v[202:205], v[34:37]
	v_mfma_f32_16x16x32_bf16 v[26:29], v[178:181], v[210:213], v[26:29]
	v_mfma_f32_16x16x32_bf16 v[18:21], v[186:189], v[210:213], v[18:21]
	v_mfma_f32_16x16x32_bf16 v[10:13], v[178:181], v[218:221], v[10:13]
	v_mfma_f32_16x16x32_bf16 v[2:5], v[186:189], v[218:221], v[2:5]
	v_mfma_f32_16x16x32_bf16 v[58:61], v[182:185], v[198:201], v[58:61]
	v_mfma_f32_16x16x32_bf16 v[50:53], v[190:193], v[198:201], v[50:53]
	v_mfma_f32_16x16x32_bf16 v[42:45], v[182:185], v[206:209], v[42:45]
	v_mfma_f32_16x16x32_bf16 v[34:37], v[190:193], v[206:209], v[34:37]
	v_mfma_f32_16x16x32_bf16 v[26:29], v[182:185], v[214:217], v[26:29]
	v_mfma_f32_16x16x32_bf16 v[18:21], v[190:193], v[214:217], v[18:21]
	v_mfma_f32_16x16x32_bf16 v[10:13], v[182:185], v[222:225], v[10:13]
	v_mfma_f32_16x16x32_bf16 v[2:5], v[190:193], v[222:225], v[2:5]
	s_setprio 0
	s_barrier
	s_add_u32 s98, s94, 0x40000
	s_addc_u32 s99, s95, 0
	s_add_i32 s7, 0, 0x18000
	s_add_i32 s47, 0, 0x1c000
	ds_read_b128 v[156:159], v232
	ds_read_b128 v[166:169], v232 offset:1024
	ds_read_b128 v[170:173], v232 offset:2048
	ds_read_b128 v[174:177], v232 offset:3072
	ds_read_b128 v[178:181], v233
	ds_read_b128 v[182:185], v233 offset:1024
	ds_read_b128 v[186:189], v233 offset:2048
	ds_read_b128 v[190:193], v233 offset:3072
	s_mov_b32 m0, s59
	ds_read_b128 v[194:197], v163 offset:32768
	ds_read_b128 v[198:201], v163 offset:33792
	ds_read_b128 v[202:205], v163 offset:34816
	ds_read_b128 v[206:209], v163 offset:35840
	ds_read_b128 v[210:213], v163 offset:36864
	ds_read_b128 v[214:217], v163 offset:37888
	ds_read_b128 v[218:221], v163 offset:38912
	ds_read_b128 v[222:225], v163 offset:39936
	global_load_lds_dwordx4 v130, s[98:99]
	s_mov_b32 m0, s60
	s_nop 0
	global_load_lds_dwordx4 v134, s[98:99]
	s_waitcnt vmcnt(8)
	s_waitcnt lgkmcnt(0)
	s_barrier
	s_setprio 1
	s_waitcnt lgkmcnt(0)
	v_mfma_f32_16x16x32_bf16 v[122:125], v[156:159], v[194:197], v[122:125]
	v_mfma_f32_16x16x32_bf16 v[118:121], v[170:173], v[194:197], v[118:121]
	v_mfma_f32_16x16x32_bf16 v[110:113], v[156:159], v[202:205], v[110:113]
	v_mfma_f32_16x16x32_bf16 v[102:105], v[170:173], v[202:205], v[102:105]
	v_mfma_f32_16x16x32_bf16 v[94:97], v[156:159], v[210:213], v[94:97]
	v_mfma_f32_16x16x32_bf16 v[86:89], v[170:173], v[210:213], v[86:89]
	v_mfma_f32_16x16x32_bf16 v[78:81], v[156:159], v[218:221], v[78:81]
	v_mfma_f32_16x16x32_bf16 v[70:73], v[170:173], v[218:221], v[70:73]
	v_mfma_f32_16x16x32_bf16 v[122:125], v[166:169], v[198:201], v[122:125]
	v_mfma_f32_16x16x32_bf16 v[118:121], v[174:177], v[198:201], v[118:121]
	v_mfma_f32_16x16x32_bf16 v[110:113], v[166:169], v[206:209], v[110:113]
	v_mfma_f32_16x16x32_bf16 v[102:105], v[174:177], v[206:209], v[102:105]
	v_mfma_f32_16x16x32_bf16 v[94:97], v[166:169], v[214:217], v[94:97]
	v_mfma_f32_16x16x32_bf16 v[86:89], v[174:177], v[214:217], v[86:89]
	v_mfma_f32_16x16x32_bf16 v[78:81], v[166:169], v[222:225], v[78:81]
	v_mfma_f32_16x16x32_bf16 v[70:73], v[174:177], v[222:225], v[70:73]
	s_setprio 0
	s_setprio 1
	v_mfma_f32_16x16x32_bf16 v[126:129], v[178:181], v[194:197], v[126:129]
	v_mfma_f32_16x16x32_bf16 v[114:117], v[186:189], v[194:197], v[114:117]
	v_mfma_f32_16x16x32_bf16 v[106:109], v[178:181], v[202:205], v[106:109]
	v_mfma_f32_16x16x32_bf16 v[98:101], v[186:189], v[202:205], v[98:101]
	v_mfma_f32_16x16x32_bf16 v[90:93], v[178:181], v[210:213], v[90:93]
	v_mfma_f32_16x16x32_bf16 v[82:85], v[186:189], v[210:213], v[82:85]
	v_mfma_f32_16x16x32_bf16 v[74:77], v[178:181], v[218:221], v[74:77]
	v_mfma_f32_16x16x32_bf16 v[66:69], v[186:189], v[218:221], v[66:69]
	v_mfma_f32_16x16x32_bf16 v[126:129], v[182:185], v[198:201], v[126:129]
	v_mfma_f32_16x16x32_bf16 v[114:117], v[190:193], v[198:201], v[114:117]
	v_mfma_f32_16x16x32_bf16 v[106:109], v[182:185], v[206:209], v[106:109]
	v_mfma_f32_16x16x32_bf16 v[98:101], v[190:193], v[206:209], v[98:101]
	v_mfma_f32_16x16x32_bf16 v[90:93], v[182:185], v[214:217], v[90:93]
	v_mfma_f32_16x16x32_bf16 v[82:85], v[190:193], v[214:217], v[82:85]
	v_mfma_f32_16x16x32_bf16 v[74:77], v[182:185], v[222:225], v[74:77]
	v_mfma_f32_16x16x32_bf16 v[66:69], v[190:193], v[222:225], v[66:69]
	s_setprio 0
	s_barrier
	s_add_u32 s96, s96, 0x80
	s_addc_u32 s97, s97, 0
	s_add_u32 s98, s96, 0x40000
	s_addc_u32 s99, s97, 0
	s_add_u32 s94, s94, 0x80
	s_addc_u32 s95, s95, 0
	s_add_i32 s7, s7, s25
	s_mov_b32 m0, s7
	ds_read_b128 v[194:197], v163 offset:49152
	ds_read_b128 v[198:201], v163 offset:50176
	ds_read_b128 v[202:205], v163 offset:51200
	ds_read_b128 v[206:209], v163 offset:52224
	ds_read_b128 v[210:213], v163 offset:53248
	ds_read_b128 v[214:217], v163 offset:54272
	ds_read_b128 v[218:221], v163 offset:55296
	ds_read_b128 v[222:225], v163 offset:56320
	global_load_lds_dwordx4 v132, s[96:97]
	s_add_i32 m0, s7, 0x2000
	s_add_i32 s7, s47, s25
	global_load_lds_dwordx4 v136, s[96:97]
	s_mov_b32 m0, s7
	s_nop 0
	global_load_lds_dwordx4 v132, s[98:99]
	s_add_i32 m0, s7, 0x2000
	s_nop 0
	global_load_lds_dwordx4 v136, s[98:99]
	s_mov_b32 m0, s66
	s_nop 0
	global_load_lds_dwordx4 v130, s[94:95]
	s_mov_b32 m0, s67
	s_nop 0
	global_load_lds_dwordx4 v134, s[94:95]
	s_waitcnt vmcnt(8)
	s_waitcnt lgkmcnt(0)
	s_barrier
	s_setprio 1
	s_waitcnt lgkmcnt(0)
	v_mfma_f32_16x16x32_bf16 v[62:65], v[156:159], v[194:197], v[62:65]
	v_mfma_f32_16x16x32_bf16 v[54:57], v[170:173], v[194:197], v[54:57]
	v_mfma_f32_16x16x32_bf16 v[46:49], v[156:159], v[202:205], v[46:49]
	v_mfma_f32_16x16x32_bf16 v[38:41], v[170:173], v[202:205], v[38:41]
	v_mfma_f32_16x16x32_bf16 v[30:33], v[156:159], v[210:213], v[30:33]
	v_mfma_f32_16x16x32_bf16 v[22:25], v[170:173], v[210:213], v[22:25]
	v_mfma_f32_16x16x32_bf16 v[14:17], v[156:159], v[218:221], v[14:17]
	v_mfma_f32_16x16x32_bf16 v[6:9], v[170:173], v[218:221], v[6:9]
	v_mfma_f32_16x16x32_bf16 v[62:65], v[166:169], v[198:201], v[62:65]
	v_mfma_f32_16x16x32_bf16 v[54:57], v[174:177], v[198:201], v[54:57]
	v_mfma_f32_16x16x32_bf16 v[46:49], v[166:169], v[206:209], v[46:49]
	v_mfma_f32_16x16x32_bf16 v[38:41], v[174:177], v[206:209], v[38:41]
	v_mfma_f32_16x16x32_bf16 v[30:33], v[166:169], v[214:217], v[30:33]
	v_mfma_f32_16x16x32_bf16 v[22:25], v[174:177], v[214:217], v[22:25]
	v_mfma_f32_16x16x32_bf16 v[14:17], v[166:169], v[222:225], v[14:17]
	v_mfma_f32_16x16x32_bf16 v[6:9], v[174:177], v[222:225], v[6:9]
	s_setprio 0
	s_setprio 1
	v_mfma_f32_16x16x32_bf16 v[58:61], v[178:181], v[194:197], v[58:61]
	v_mfma_f32_16x16x32_bf16 v[50:53], v[186:189], v[194:197], v[50:53]
	v_mfma_f32_16x16x32_bf16 v[42:45], v[178:181], v[202:205], v[42:45]
	v_mfma_f32_16x16x32_bf16 v[34:37], v[186:189], v[202:205], v[34:37]
	v_mfma_f32_16x16x32_bf16 v[26:29], v[178:181], v[210:213], v[26:29]
	v_mfma_f32_16x16x32_bf16 v[18:21], v[186:189], v[210:213], v[18:21]
	v_mfma_f32_16x16x32_bf16 v[10:13], v[178:181], v[218:221], v[10:13]
	v_mfma_f32_16x16x32_bf16 v[2:5], v[186:189], v[218:221], v[2:5]
	v_mfma_f32_16x16x32_bf16 v[58:61], v[182:185], v[198:201], v[58:61]
	v_mfma_f32_16x16x32_bf16 v[50:53], v[190:193], v[198:201], v[50:53]
	v_mfma_f32_16x16x32_bf16 v[42:45], v[182:185], v[206:209], v[42:45]
	v_mfma_f32_16x16x32_bf16 v[34:37], v[190:193], v[206:209], v[34:37]
	v_mfma_f32_16x16x32_bf16 v[26:29], v[182:185], v[214:217], v[26:29]
	v_mfma_f32_16x16x32_bf16 v[18:21], v[190:193], v[214:217], v[18:21]
	v_mfma_f32_16x16x32_bf16 v[10:13], v[182:185], v[222:225], v[10:13]
	v_mfma_f32_16x16x32_bf16 v[2:5], v[190:193], v[222:225], v[2:5]
	s_setprio 0
	s_barrier
	s_mov_b32 s7, s45
	s_add_u32 s88, s88, 0x100
	s_addc_u32 s89, s89, 0
	s_add_u32 s86, s86, 0x100
	s_addc_u32 s87, s87, 0
	s_cmp_ge_i32 s45, s101
	s_cbranch_scc0 .LBB0_499

.LBB0_766:
	v_cmp_gt_i32_e32 vcc, 1, v138
	s_cbranch_vccnz .LBB0_828
	v_lshl_add_u64 v[152:153], v[2:3], 0, s[16:17]
	v_add_u32_e32 v154, -2, v138
	s_waitcnt lgkmcnt(0)
	v_lshl_add_u64 v[150:151], v[4:5], 0, s[20:21]
	s_mov_b32 s7, 0
	s_nop 0
	v_readfirstlane_b32 s86, v152
	v_readfirstlane_b32 s87, v153
	v_readfirstlane_b32 s88, v150
	v_readfirstlane_b32 s89, v151
	v_readfirstlane_b32 s90, v146
	v_readfirstlane_b32 s91, v147
	v_readfirstlane_b32 s92, v148
	v_readfirstlane_b32 s93, v149
	v_readfirstlane_b32 s100, v154
	v_readfirstlane_b32 s101, v138
	v_add_u32_e32 v230, s76, v141
	v_add_u32_e32 v231, s77, v141
	v_add_u32_e32 v232, 0x18000, v141
	v_add_u32_e32 v233, 0x1c000, v141
	s_add_u32 s98, s86, 0xfffc0080
	s_addc_u32 s99, s87, -1
	s_cmp_eq_u32 s7, s100
	s_cselect_b64 s[94:95], s[90:91], s[98:99]
	s_cselect_b64 s[96:97], s[92:93], s[88:89]
	ds_read_b128 v[164:167], v230
	ds_read_b128 v[168:171], v230 offset:1024
	ds_read_b128 v[172:175], v230 offset:2048
	ds_read_b128 v[176:179], v230 offset:3072
	ds_read_b128 v[180:183], v231
	ds_read_b128 v[184:187], v231 offset:1024
	ds_read_b128 v[188:191], v231 offset:2048
	ds_read_b128 v[192:195], v231 offset:3072
	s_add_i32 s45, s7, 2
	s_nop 0
	s_add_i32 m0, s49, 0xc000
	ds_read_b128 v[196:199], v160
	ds_read_b128 v[200:203], v160 offset:1024
	ds_read_b128 v[204:207], v160 offset:2048
	ds_read_b128 v[208:211], v160 offset:3072
	ds_read_b128 v[212:215], v160 offset:4096
	ds_read_b128 v[216:219], v160 offset:5120
	ds_read_b128 v[220:223], v160 offset:6144
	ds_read_b128 v[224:227], v160 offset:7168
	global_load_lds_dwordx4 v144, s[86:87]
	s_add_i32 m0, s49, 0xe000
	s_nop 0
	global_load_lds_dwordx4 v142, s[86:87]
	s_waitcnt vmcnt(8)
	s_waitcnt lgkmcnt(0)
	s_barrier
	s_setprio 1
	s_waitcnt lgkmcnt(0)
	v_mfma_f32_16x16x32_bf16 v[122:125], v[164:167], v[196:199], 0
	v_mfma_f32_16x16x32_bf16 v[118:121], v[172:175], v[196:199], 0
	v_mfma_f32_16x16x32_bf16 v[110:113], v[164:167], v[204:207], 0
	v_mfma_f32_16x16x32_bf16 v[102:105], v[172:175], v[204:207], 0
	v_mfma_f32_16x16x32_bf16 v[94:97], v[164:167], v[212:215], 0
	v_mfma_f32_16x16x32_bf16 v[86:89], v[172:175], v[212:215], 0
	v_mfma_f32_16x16x32_bf16 v[78:81], v[164:167], v[220:223], 0
	v_mfma_f32_16x16x32_bf16 v[70:73], v[172:175], v[220:223], 0
	v_mfma_f32_16x16x32_bf16 v[122:125], v[168:171], v[200:203], v[122:125]
	v_mfma_f32_16x16x32_bf16 v[118:121], v[176:179], v[200:203], v[118:121]
	v_mfma_f32_16x16x32_bf16 v[110:113], v[168:171], v[208:211], v[110:113]
	v_mfma_f32_16x16x32_bf16 v[102:105], v[176:179], v[208:211], v[102:105]
	v_mfma_f32_16x16x32_bf16 v[94:97], v[168:171], v[216:219], v[94:97]
	v_mfma_f32_16x16x32_bf16 v[86:89], v[176:179], v[216:219], v[86:89]
	v_mfma_f32_16x16x32_bf16 v[78:81], v[168:171], v[224:227], v[78:81]
	v_mfma_f32_16x16x32_bf16 v[70:73], v[176:179], v[224:227], v[70:73]
	s_setprio 0
	s_setprio 1
	v_mfma_f32_16x16x32_bf16 v[126:129], v[180:183], v[196:199], 0
	v_mfma_f32_16x16x32_bf16 v[114:117], v[188:191], v[196:199], 0
	v_mfma_f32_16x16x32_bf16 v[106:109], v[180:183], v[204:207], 0
	v_mfma_f32_16x16x32_bf16 v[98:101], v[188:191], v[204:207], 0
	v_mfma_f32_16x16x32_bf16 v[90:93], v[180:183], v[212:215], 0
	v_mfma_f32_16x16x32_bf16 v[82:85], v[188:191], v[212:215], 0
	v_mfma_f32_16x16x32_bf16 v[74:77], v[180:183], v[220:223], 0
	v_mfma_f32_16x16x32_bf16 v[66:69], v[188:191], v[220:223], 0
	v_mfma_f32_16x16x32_bf16 v[126:129], v[184:187], v[200:203], v[126:129]
	v_mfma_f32_16x16x32_bf16 v[114:117], v[192:195], v[200:203], v[114:117]
	v_mfma_f32_16x16x32_bf16 v[106:109], v[184:187], v[208:211], v[106:109]
	v_mfma_f32_16x16x32_bf16 v[98:101], v[192:195], v[208:211], v[98:101]
	v_mfma_f32_16x16x32_bf16 v[90:93], v[184:187], v[216:219], v[90:93]
	v_mfma_f32_16x16x32_bf16 v[82:85], v[192:195], v[216:219], v[82:85]
	v_mfma_f32_16x16x32_bf16 v[74:77], v[184:187], v[224:227], v[74:77]
	v_mfma_f32_16x16x32_bf16 v[66:69], v[192:195], v[224:227], v[66:69]
	s_setprio 0
	s_barrier
	s_add_u32 s98, s96, 0x40000
	s_addc_u32 s99, s97, 0
	s_add_i32 s7, s76, s25
	s_mov_b32 m0, s7
	ds_read_b128 v[196:199], v160 offset:16384
	ds_read_b128 v[200:203], v160 offset:17408
	ds_read_b128 v[204:207], v160 offset:18432
	ds_read_b128 v[208:211], v160 offset:19456
	ds_read_b128 v[212:215], v160 offset:20480
	ds_read_b128 v[216:219], v160 offset:21504
	ds_read_b128 v[220:223], v160 offset:22528
	ds_read_b128 v[224:227], v160 offset:23552
	global_load_lds_dwordx4 v132, s[96:97]
	s_add_i32 m0, s7, 0x2000
	s_add_i32 s7, s77, s25
	global_load_lds_dwordx4 v136, s[96:97]
	s_mov_b32 m0, s7
	s_nop 0
	global_load_lds_dwordx4 v132, s[98:99]
	s_add_i32 m0, s7, 0x2000
	s_nop 0
	global_load_lds_dwordx4 v136, s[98:99]
	s_mov_b32 m0, s49
	s_nop 0
	global_load_lds_dwordx4 v130, s[94:95]
	s_mov_b32 m0, s58
	s_nop 0
	global_load_lds_dwordx4 v134, s[94:95]
	s_waitcnt vmcnt(8)
	s_waitcnt lgkmcnt(0)
	s_barrier
	s_setprio 1
	s_waitcnt lgkmcnt(0)
	v_mfma_f32_16x16x32_bf16 v[62:65], v[164:167], v[196:199], 0
	v_mfma_f32_16x16x32_bf16 v[54:57], v[172:175], v[196:199], 0
	v_mfma_f32_16x16x32_bf16 v[46:49], v[164:167], v[204:207], 0
	v_mfma_f32_16x16x32_bf16 v[38:41], v[172:175], v[204:207], 0
	v_mfma_f32_16x16x32_bf16 v[30:33], v[164:167], v[212:215], 0
	v_mfma_f32_16x16x32_bf16 v[22:25], v[172:175], v[212:215], 0
	v_mfma_f32_16x16x32_bf16 v[14:17], v[164:167], v[220:223], 0
	v_mfma_f32_16x16x32_bf16 v[6:9], v[172:175], v[220:223], 0
	v_mfma_f32_16x16x32_bf16 v[62:65], v[168:171], v[200:203], v[62:65]
	v_mfma_f32_16x16x32_bf16 v[54:57], v[176:179], v[200:203], v[54:57]
	v_mfma_f32_16x16x32_bf16 v[46:49], v[168:171], v[208:211], v[46:49]
	v_mfma_f32_16x16x32_bf16 v[38:41], v[176:179], v[208:211], v[38:41]
	v_mfma_f32_16x16x32_bf16 v[30:33], v[168:171], v[216:219], v[30:33]
	v_mfma_f32_16x16x32_bf16 v[22:25], v[176:179], v[216:219], v[22:25]
	v_mfma_f32_16x16x32_bf16 v[14:17], v[168:171], v[224:227], v[14:17]
	v_mfma_f32_16x16x32_bf16 v[6:9], v[176:179], v[224:227], v[6:9]
	s_setprio 0
	s_setprio 1
	v_mfma_f32_16x16x32_bf16 v[58:61], v[180:183], v[196:199], 0
	v_mfma_f32_16x16x32_bf16 v[50:53], v[188:191], v[196:199], 0
	v_mfma_f32_16x16x32_bf16 v[42:45], v[180:183], v[204:207], 0
	v_mfma_f32_16x16x32_bf16 v[34:37], v[188:191], v[204:207], 0
	v_mfma_f32_16x16x32_bf16 v[26:29], v[180:183], v[212:215], 0
	v_mfma_f32_16x16x32_bf16 v[18:21], v[188:191], v[212:215], 0
	v_mfma_f32_16x16x32_bf16 v[10:13], v[180:183], v[220:223], 0
	v_mfma_f32_16x16x32_bf16 v[2:5], v[188:191], v[220:223], 0
	v_mfma_f32_16x16x32_bf16 v[58:61], v[184:187], v[200:203], v[58:61]
	v_mfma_f32_16x16x32_bf16 v[50:53], v[192:195], v[200:203], v[50:53]
	v_mfma_f32_16x16x32_bf16 v[42:45], v[184:187], v[208:211], v[42:45]
	v_mfma_f32_16x16x32_bf16 v[34:37], v[192:195], v[208:211], v[34:37]
	v_mfma_f32_16x16x32_bf16 v[26:29], v[184:187], v[216:219], v[26:29]
	v_mfma_f32_16x16x32_bf16 v[18:21], v[192:195], v[216:219], v[18:21]
	v_mfma_f32_16x16x32_bf16 v[10:13], v[184:187], v[224:227], v[10:13]
	v_mfma_f32_16x16x32_bf16 v[2:5], v[192:195], v[224:227], v[2:5]
	s_setprio 0
	s_barrier
	s_add_u32 s98, s94, 0x40000
	s_addc_u32 s99, s95, 0
	s_add_i32 s7, 0, 0x18000
	s_add_i32 s47, 0, 0x1c000
	ds_read_b128 v[164:167], v232
	ds_read_b128 v[168:171], v232 offset:1024
	ds_read_b128 v[172:175], v232 offset:2048
	ds_read_b128 v[176:179], v232 offset:3072
	ds_read_b128 v[180:183], v233
	ds_read_b128 v[184:187], v233 offset:1024
	ds_read_b128 v[188:191], v233 offset:2048
	ds_read_b128 v[192:195], v233 offset:3072
	s_mov_b32 m0, s59
	ds_read_b128 v[196:199], v160 offset:32768
	ds_read_b128 v[200:203], v160 offset:33792
	ds_read_b128 v[204:207], v160 offset:34816
	ds_read_b128 v[208:211], v160 offset:35840
	ds_read_b128 v[212:215], v160 offset:36864
	ds_read_b128 v[216:219], v160 offset:37888
	ds_read_b128 v[220:223], v160 offset:38912
	ds_read_b128 v[224:227], v160 offset:39936
	global_load_lds_dwordx4 v130, s[98:99]
	s_mov_b32 m0, s60
	s_nop 0
	global_load_lds_dwordx4 v134, s[98:99]
	s_waitcnt vmcnt(8)
	s_waitcnt lgkmcnt(0)
	s_barrier
	s_setprio 1
	s_waitcnt lgkmcnt(0)
	v_mfma_f32_16x16x32_bf16 v[122:125], v[164:167], v[196:199], v[122:125]
	v_mfma_f32_16x16x32_bf16 v[118:121], v[172:175], v[196:199], v[118:121]
	v_mfma_f32_16x16x32_bf16 v[110:113], v[164:167], v[204:207], v[110:113]
	v_mfma_f32_16x16x32_bf16 v[102:105], v[172:175], v[204:207], v[102:105]
	v_mfma_f32_16x16x32_bf16 v[94:97], v[164:167], v[212:215], v[94:97]
	v_mfma_f32_16x16x32_bf16 v[86:89], v[172:175], v[212:215], v[86:89]
	v_mfma_f32_16x16x32_bf16 v[78:81], v[164:167], v[220:223], v[78:81]
	v_mfma_f32_16x16x32_bf16 v[70:73], v[172:175], v[220:223], v[70:73]
	v_mfma_f32_16x16x32_bf16 v[122:125], v[168:171], v[200:203], v[122:125]
	v_mfma_f32_16x16x32_bf16 v[118:121], v[176:179], v[200:203], v[118:121]
	v_mfma_f32_16x16x32_bf16 v[110:113], v[168:171], v[208:211], v[110:113]
	v_mfma_f32_16x16x32_bf16 v[102:105], v[176:179], v[208:211], v[102:105]
	v_mfma_f32_16x16x32_bf16 v[94:97], v[168:171], v[216:219], v[94:97]
	v_mfma_f32_16x16x32_bf16 v[86:89], v[176:179], v[216:219], v[86:89]
	v_mfma_f32_16x16x32_bf16 v[78:81], v[168:171], v[224:227], v[78:81]
	v_mfma_f32_16x16x32_bf16 v[70:73], v[176:179], v[224:227], v[70:73]
	s_setprio 0
	s_setprio 1
	v_mfma_f32_16x16x32_bf16 v[126:129], v[180:183], v[196:199], v[126:129]
	v_mfma_f32_16x16x32_bf16 v[114:117], v[188:191], v[196:199], v[114:117]
	v_mfma_f32_16x16x32_bf16 v[106:109], v[180:183], v[204:207], v[106:109]
	v_mfma_f32_16x16x32_bf16 v[98:101], v[188:191], v[204:207], v[98:101]
	v_mfma_f32_16x16x32_bf16 v[90:93], v[180:183], v[212:215], v[90:93]
	v_mfma_f32_16x16x32_bf16 v[82:85], v[188:191], v[212:215], v[82:85]
	v_mfma_f32_16x16x32_bf16 v[74:77], v[180:183], v[220:223], v[74:77]
	v_mfma_f32_16x16x32_bf16 v[66:69], v[188:191], v[220:223], v[66:69]
	v_mfma_f32_16x16x32_bf16 v[126:129], v[184:187], v[200:203], v[126:129]
	v_mfma_f32_16x16x32_bf16 v[114:117], v[192:195], v[200:203], v[114:117]
	v_mfma_f32_16x16x32_bf16 v[106:109], v[184:187], v[208:211], v[106:109]
	v_mfma_f32_16x16x32_bf16 v[98:101], v[192:195], v[208:211], v[98:101]
	v_mfma_f32_16x16x32_bf16 v[90:93], v[184:187], v[216:219], v[90:93]
	v_mfma_f32_16x16x32_bf16 v[82:85], v[192:195], v[216:219], v[82:85]
	v_mfma_f32_16x16x32_bf16 v[74:77], v[184:187], v[224:227], v[74:77]
	v_mfma_f32_16x16x32_bf16 v[66:69], v[192:195], v[224:227], v[66:69]
	s_setprio 0
	s_barrier
	s_add_u32 s96, s96, 0x80
	s_addc_u32 s97, s97, 0
	s_add_u32 s98, s96, 0x40000
	s_addc_u32 s99, s97, 0
	s_add_u32 s94, s94, 0x80
	s_addc_u32 s95, s95, 0
	s_add_i32 s7, s7, s25
	s_mov_b32 m0, s7
	ds_read_b128 v[196:199], v160 offset:49152
	ds_read_b128 v[200:203], v160 offset:50176
	ds_read_b128 v[204:207], v160 offset:51200
	ds_read_b128 v[208:211], v160 offset:52224
	ds_read_b128 v[212:215], v160 offset:53248
	ds_read_b128 v[216:219], v160 offset:54272
	ds_read_b128 v[220:223], v160 offset:55296
	ds_read_b128 v[224:227], v160 offset:56320
	global_load_lds_dwordx4 v132, s[96:97]
	s_add_i32 m0, s7, 0x2000
	s_add_i32 s7, s47, s25
	global_load_lds_dwordx4 v136, s[96:97]
	s_mov_b32 m0, s7
	s_nop 0
	global_load_lds_dwordx4 v132, s[98:99]
	s_add_i32 m0, s7, 0x2000
	s_nop 0
	global_load_lds_dwordx4 v136, s[98:99]
	s_mov_b32 m0, s66
	s_nop 0
	global_load_lds_dwordx4 v130, s[94:95]
	s_mov_b32 m0, s67
	s_nop 0
	global_load_lds_dwordx4 v134, s[94:95]
	s_waitcnt vmcnt(8)
	s_waitcnt lgkmcnt(0)
	s_barrier
	s_setprio 1
	s_waitcnt lgkmcnt(0)
	v_mfma_f32_16x16x32_bf16 v[62:65], v[164:167], v[196:199], v[62:65]
	v_mfma_f32_16x16x32_bf16 v[54:57], v[172:175], v[196:199], v[54:57]
	v_mfma_f32_16x16x32_bf16 v[46:49], v[164:167], v[204:207], v[46:49]
	v_mfma_f32_16x16x32_bf16 v[38:41], v[172:175], v[204:207], v[38:41]
	v_mfma_f32_16x16x32_bf16 v[30:33], v[164:167], v[212:215], v[30:33]
	v_mfma_f32_16x16x32_bf16 v[22:25], v[172:175], v[212:215], v[22:25]
	v_mfma_f32_16x16x32_bf16 v[14:17], v[164:167], v[220:223], v[14:17]
	v_mfma_f32_16x16x32_bf16 v[6:9], v[172:175], v[220:223], v[6:9]
	v_mfma_f32_16x16x32_bf16 v[62:65], v[168:171], v[200:203], v[62:65]
	v_mfma_f32_16x16x32_bf16 v[54:57], v[176:179], v[200:203], v[54:57]
	v_mfma_f32_16x16x32_bf16 v[46:49], v[168:171], v[208:211], v[46:49]
	v_mfma_f32_16x16x32_bf16 v[38:41], v[176:179], v[208:211], v[38:41]
	v_mfma_f32_16x16x32_bf16 v[30:33], v[168:171], v[216:219], v[30:33]
	v_mfma_f32_16x16x32_bf16 v[22:25], v[176:179], v[216:219], v[22:25]
	v_mfma_f32_16x16x32_bf16 v[14:17], v[168:171], v[224:227], v[14:17]
	v_mfma_f32_16x16x32_bf16 v[6:9], v[176:179], v[224:227], v[6:9]
	s_setprio 0
	s_setprio 1
	v_mfma_f32_16x16x32_bf16 v[58:61], v[180:183], v[196:199], v[58:61]
	v_mfma_f32_16x16x32_bf16 v[50:53], v[188:191], v[196:199], v[50:53]
	v_mfma_f32_16x16x32_bf16 v[42:45], v[180:183], v[204:207], v[42:45]
	v_mfma_f32_16x16x32_bf16 v[34:37], v[188:191], v[204:207], v[34:37]
	v_mfma_f32_16x16x32_bf16 v[26:29], v[180:183], v[212:215], v[26:29]
	v_mfma_f32_16x16x32_bf16 v[18:21], v[188:191], v[212:215], v[18:21]
	v_mfma_f32_16x16x32_bf16 v[10:13], v[180:183], v[220:223], v[10:13]
	v_mfma_f32_16x16x32_bf16 v[2:5], v[188:191], v[220:223], v[2:5]
	v_mfma_f32_16x16x32_bf16 v[58:61], v[184:187], v[200:203], v[58:61]
	v_mfma_f32_16x16x32_bf16 v[50:53], v[192:195], v[200:203], v[50:53]
	v_mfma_f32_16x16x32_bf16 v[42:45], v[184:187], v[208:211], v[42:45]
	v_mfma_f32_16x16x32_bf16 v[34:37], v[192:195], v[208:211], v[34:37]
	v_mfma_f32_16x16x32_bf16 v[26:29], v[184:187], v[216:219], v[26:29]
	v_mfma_f32_16x16x32_bf16 v[18:21], v[192:195], v[216:219], v[18:21]
	v_mfma_f32_16x16x32_bf16 v[10:13], v[184:187], v[224:227], v[10:13]
	v_mfma_f32_16x16x32_bf16 v[2:5], v[192:195], v[224:227], v[2:5]
	s_setprio 0
	s_barrier
	s_mov_b32 s7, s45
	s_add_u32 s88, s88, 0x100
	s_addc_u32 s89, s89, 0
	s_add_u32 s86, s86, 0x100
	s_addc_u32 s87, s87, 0
	s_cmp_ge_i32 s45, s101
	s_cbranch_scc1 .Lmy_kexit_3
.LBB0_768:
	s_add_u32 s98, s86, 0xfffc0080
	s_addc_u32 s99, s87, -1
	s_cmp_eq_u32 s7, s100
	s_cselect_b64 s[94:95], s[90:91], s[98:99]
	s_cselect_b64 s[96:97], s[92:93], s[88:89]
	ds_read_b128 v[164:167], v230
	ds_read_b128 v[168:171], v230 offset:1024
	ds_read_b128 v[172:175], v230 offset:2048
	ds_read_b128 v[176:179], v230 offset:3072
	ds_read_b128 v[180:183], v231
	ds_read_b128 v[184:187], v231 offset:1024
	ds_read_b128 v[188:191], v231 offset:2048
	ds_read_b128 v[192:195], v231 offset:3072
	s_add_i32 s45, s7, 2
	s_nop 0
	s_add_i32 m0, s49, 0xc000
	ds_read_b128 v[196:199], v160
	ds_read_b128 v[200:203], v160 offset:1024
	ds_read_b128 v[204:207], v160 offset:2048
	ds_read_b128 v[208:211], v160 offset:3072
	ds_read_b128 v[212:215], v160 offset:4096
	ds_read_b128 v[216:219], v160 offset:5120
	ds_read_b128 v[220:223], v160 offset:6144
	ds_read_b128 v[224:227], v160 offset:7168
	global_load_lds_dwordx4 v144, s[86:87]
	s_add_i32 m0, s49, 0xe000
	s_nop 0
	global_load_lds_dwordx4 v142, s[86:87]
	s_waitcnt vmcnt(8)
	s_waitcnt lgkmcnt(0)
	s_barrier
	s_setprio 1
	s_waitcnt lgkmcnt(0)
	v_mfma_f32_16x16x32_bf16 v[122:125], v[164:167], v[196:199], v[122:125]
	v_mfma_f32_16x16x32_bf16 v[118:121], v[172:175], v[196:199], v[118:121]
	v_mfma_f32_16x16x32_bf16 v[110:113], v[164:167], v[204:207], v[110:113]
	v_mfma_f32_16x16x32_bf16 v[102:105], v[172:175], v[204:207], v[102:105]
	v_mfma_f32_16x16x32_bf16 v[94:97], v[164:167], v[212:215], v[94:97]
	v_mfma_f32_16x16x32_bf16 v[86:89], v[172:175], v[212:215], v[86:89]
	v_mfma_f32_16x16x32_bf16 v[78:81], v[164:167], v[220:223], v[78:81]
	v_mfma_f32_16x16x32_bf16 v[70:73], v[172:175], v[220:223], v[70:73]
	v_mfma_f32_16x16x32_bf16 v[122:125], v[168:171], v[200:203], v[122:125]
	v_mfma_f32_16x16x32_bf16 v[118:121], v[176:179], v[200:203], v[118:121]
	v_mfma_f32_16x16x32_bf16 v[110:113], v[168:171], v[208:211], v[110:113]
	v_mfma_f32_16x16x32_bf16 v[102:105], v[176:179], v[208:211], v[102:105]
	v_mfma_f32_16x16x32_bf16 v[94:97], v[168:171], v[216:219], v[94:97]
	v_mfma_f32_16x16x32_bf16 v[86:89], v[176:179], v[216:219], v[86:89]
	v_mfma_f32_16x16x32_bf16 v[78:81], v[168:171], v[224:227], v[78:81]
	v_mfma_f32_16x16x32_bf16 v[70:73], v[176:179], v[224:227], v[70:73]
	s_setprio 0
	s_setprio 1
	v_mfma_f32_16x16x32_bf16 v[126:129], v[180:183], v[196:199], v[126:129]
	v_mfma_f32_16x16x32_bf16 v[114:117], v[188:191], v[196:199], v[114:117]
	v_mfma_f32_16x16x32_bf16 v[106:109], v[180:183], v[204:207], v[106:109]
	v_mfma_f32_16x16x32_bf16 v[98:101], v[188:191], v[204:207], v[98:101]
	v_mfma_f32_16x16x32_bf16 v[90:93], v[180:183], v[212:215], v[90:93]
	v_mfma_f32_16x16x32_bf16 v[82:85], v[188:191], v[212:215], v[82:85]
	v_mfma_f32_16x16x32_bf16 v[74:77], v[180:183], v[220:223], v[74:77]
	v_mfma_f32_16x16x32_bf16 v[66:69], v[188:191], v[220:223], v[66:69]
	v_mfma_f32_16x16x32_bf16 v[126:129], v[184:187], v[200:203], v[126:129]
	v_mfma_f32_16x16x32_bf16 v[114:117], v[192:195], v[200:203], v[114:117]
	v_mfma_f32_16x16x32_bf16 v[106:109], v[184:187], v[208:211], v[106:109]
	v_mfma_f32_16x16x32_bf16 v[98:101], v[192:195], v[208:211], v[98:101]
	v_mfma_f32_16x16x32_bf16 v[90:93], v[184:187], v[216:219], v[90:93]
	v_mfma_f32_16x16x32_bf16 v[82:85], v[192:195], v[216:219], v[82:85]
	v_mfma_f32_16x16x32_bf16 v[74:77], v[184:187], v[224:227], v[74:77]
	v_mfma_f32_16x16x32_bf16 v[66:69], v[192:195], v[224:227], v[66:69]
	s_setprio 0
	s_barrier
	s_add_u32 s98, s96, 0x40000
	s_addc_u32 s99, s97, 0
	s_add_i32 s7, s76, s25
	s_mov_b32 m0, s7
	ds_read_b128 v[196:199], v160 offset:16384
	ds_read_b128 v[200:203], v160 offset:17408
	ds_read_b128 v[204:207], v160 offset:18432
	ds_read_b128 v[208:211], v160 offset:19456
	ds_read_b128 v[212:215], v160 offset:20480
	ds_read_b128 v[216:219], v160 offset:21504
	ds_read_b128 v[220:223], v160 offset:22528
	ds_read_b128 v[224:227], v160 offset:23552
	global_load_lds_dwordx4 v132, s[96:97]
	s_add_i32 m0, s7, 0x2000
	s_add_i32 s7, s77, s25
	global_load_lds_dwordx4 v136, s[96:97]
	s_mov_b32 m0, s7
	s_nop 0
	global_load_lds_dwordx4 v132, s[98:99]
	s_add_i32 m0, s7, 0x2000
	s_nop 0
	global_load_lds_dwordx4 v136, s[98:99]
	s_mov_b32 m0, s49
	s_nop 0
	global_load_lds_dwordx4 v130, s[94:95]
	s_mov_b32 m0, s58
	s_nop 0
	global_load_lds_dwordx4 v134, s[94:95]
	s_waitcnt vmcnt(8)
	s_waitcnt lgkmcnt(0)
	s_barrier
	s_setprio 1
	s_waitcnt lgkmcnt(0)
	v_mfma_f32_16x16x32_bf16 v[62:65], v[164:167], v[196:199], v[62:65]
	v_mfma_f32_16x16x32_bf16 v[54:57], v[172:175], v[196:199], v[54:57]
	v_mfma_f32_16x16x32_bf16 v[46:49], v[164:167], v[204:207], v[46:49]
	v_mfma_f32_16x16x32_bf16 v[38:41], v[172:175], v[204:207], v[38:41]
	v_mfma_f32_16x16x32_bf16 v[30:33], v[164:167], v[212:215], v[30:33]
	v_mfma_f32_16x16x32_bf16 v[22:25], v[172:175], v[212:215], v[22:25]
	v_mfma_f32_16x16x32_bf16 v[14:17], v[164:167], v[220:223], v[14:17]
	v_mfma_f32_16x16x32_bf16 v[6:9], v[172:175], v[220:223], v[6:9]
	v_mfma_f32_16x16x32_bf16 v[62:65], v[168:171], v[200:203], v[62:65]
	v_mfma_f32_16x16x32_bf16 v[54:57], v[176:179], v[200:203], v[54:57]
	v_mfma_f32_16x16x32_bf16 v[46:49], v[168:171], v[208:211], v[46:49]
	v_mfma_f32_16x16x32_bf16 v[38:41], v[176:179], v[208:211], v[38:41]
	v_mfma_f32_16x16x32_bf16 v[30:33], v[168:171], v[216:219], v[30:33]
	v_mfma_f32_16x16x32_bf16 v[22:25], v[176:179], v[216:219], v[22:25]
	v_mfma_f32_16x16x32_bf16 v[14:17], v[168:171], v[224:227], v[14:17]
	v_mfma_f32_16x16x32_bf16 v[6:9], v[176:179], v[224:227], v[6:9]
	s_setprio 0
	s_setprio 1
	v_mfma_f32_16x16x32_bf16 v[58:61], v[180:183], v[196:199], v[58:61]
	v_mfma_f32_16x16x32_bf16 v[50:53], v[188:191], v[196:199], v[50:53]
	v_mfma_f32_16x16x32_bf16 v[42:45], v[180:183], v[204:207], v[42:45]
	v_mfma_f32_16x16x32_bf16 v[34:37], v[188:191], v[204:207], v[34:37]
	v_mfma_f32_16x16x32_bf16 v[26:29], v[180:183], v[212:215], v[26:29]
	v_mfma_f32_16x16x32_bf16 v[18:21], v[188:191], v[212:215], v[18:21]
	v_mfma_f32_16x16x32_bf16 v[10:13], v[180:183], v[220:223], v[10:13]
	v_mfma_f32_16x16x32_bf16 v[2:5], v[188:191], v[220:223], v[2:5]
	v_mfma_f32_16x16x32_bf16 v[58:61], v[184:187], v[200:203], v[58:61]
	v_mfma_f32_16x16x32_bf16 v[50:53], v[192:195], v[200:203], v[50:53]
	v_mfma_f32_16x16x32_bf16 v[42:45], v[184:187], v[208:211], v[42:45]
	v_mfma_f32_16x16x32_bf16 v[34:37], v[192:195], v[208:211], v[34:37]
	v_mfma_f32_16x16x32_bf16 v[26:29], v[184:187], v[216:219], v[26:29]
	v_mfma_f32_16x16x32_bf16 v[18:21], v[192:195], v[216:219], v[18:21]
	v_mfma_f32_16x16x32_bf16 v[10:13], v[184:187], v[224:227], v[10:13]
	v_mfma_f32_16x16x32_bf16 v[2:5], v[192:195], v[224:227], v[2:5]
	s_setprio 0
	s_barrier
	s_add_u32 s98, s94, 0x40000
	s_addc_u32 s99, s95, 0
	s_add_i32 s7, 0, 0x18000
	s_add_i32 s47, 0, 0x1c000
	ds_read_b128 v[164:167], v232
	ds_read_b128 v[168:171], v232 offset:1024
	ds_read_b128 v[172:175], v232 offset:2048
	ds_read_b128 v[176:179], v232 offset:3072
	ds_read_b128 v[180:183], v233
	ds_read_b128 v[184:187], v233 offset:1024
	ds_read_b128 v[188:191], v233 offset:2048
	ds_read_b128 v[192:195], v233 offset:3072
	s_mov_b32 m0, s59
	ds_read_b128 v[196:199], v160 offset:32768
	ds_read_b128 v[200:203], v160 offset:33792
	ds_read_b128 v[204:207], v160 offset:34816
	ds_read_b128 v[208:211], v160 offset:35840
	ds_read_b128 v[212:215], v160 offset:36864
	ds_read_b128 v[216:219], v160 offset:37888
	ds_read_b128 v[220:223], v160 offset:38912
	ds_read_b128 v[224:227], v160 offset:39936
	global_load_lds_dwordx4 v130, s[98:99]
	s_mov_b32 m0, s60
	s_nop 0
	global_load_lds_dwordx4 v134, s[98:99]
	s_waitcnt vmcnt(8)
	s_waitcnt lgkmcnt(0)
	s_barrier
	s_setprio 1
	s_waitcnt lgkmcnt(0)
	v_mfma_f32_16x16x32_bf16 v[122:125], v[164:167], v[196:199], v[122:125]
	v_mfma_f32_16x16x32_bf16 v[118:121], v[172:175], v[196:199], v[118:121]
	v_mfma_f32_16x16x32_bf16 v[110:113], v[164:167], v[204:207], v[110:113]
	v_mfma_f32_16x16x32_bf16 v[102:105], v[172:175], v[204:207], v[102:105]
	v_mfma_f32_16x16x32_bf16 v[94:97], v[164:167], v[212:215], v[94:97]
	v_mfma_f32_16x16x32_bf16 v[86:89], v[172:175], v[212:215], v[86:89]
	v_mfma_f32_16x16x32_bf16 v[78:81], v[164:167], v[220:223], v[78:81]
	v_mfma_f32_16x16x32_bf16 v[70:73], v[172:175], v[220:223], v[70:73]
	v_mfma_f32_16x16x32_bf16 v[122:125], v[168:171], v[200:203], v[122:125]
	v_mfma_f32_16x16x32_bf16 v[118:121], v[176:179], v[200:203], v[118:121]
	v_mfma_f32_16x16x32_bf16 v[110:113], v[168:171], v[208:211], v[110:113]
	v_mfma_f32_16x16x32_bf16 v[102:105], v[176:179], v[208:211], v[102:105]
	v_mfma_f32_16x16x32_bf16 v[94:97], v[168:171], v[216:219], v[94:97]
	v_mfma_f32_16x16x32_bf16 v[86:89], v[176:179], v[216:219], v[86:89]
	v_mfma_f32_16x16x32_bf16 v[78:81], v[168:171], v[224:227], v[78:81]
	v_mfma_f32_16x16x32_bf16 v[70:73], v[176:179], v[224:227], v[70:73]
	s_setprio 0
	s_setprio 1
	v_mfma_f32_16x16x32_bf16 v[126:129], v[180:183], v[196:199], v[126:129]
	v_mfma_f32_16x16x32_bf16 v[114:117], v[188:191], v[196:199], v[114:117]
	v_mfma_f32_16x16x32_bf16 v[106:109], v[180:183], v[204:207], v[106:109]
	v_mfma_f32_16x16x32_bf16 v[98:101], v[188:191], v[204:207], v[98:101]
	v_mfma_f32_16x16x32_bf16 v[90:93], v[180:183], v[212:215], v[90:93]
	v_mfma_f32_16x16x32_bf16 v[82:85], v[188:191], v[212:215], v[82:85]
	v_mfma_f32_16x16x32_bf16 v[74:77], v[180:183], v[220:223], v[74:77]
	v_mfma_f32_16x16x32_bf16 v[66:69], v[188:191], v[220:223], v[66:69]
	v_mfma_f32_16x16x32_bf16 v[126:129], v[184:187], v[200:203], v[126:129]
	v_mfma_f32_16x16x32_bf16 v[114:117], v[192:195], v[200:203], v[114:117]
	v_mfma_f32_16x16x32_bf16 v[106:109], v[184:187], v[208:211], v[106:109]
	v_mfma_f32_16x16x32_bf16 v[98:101], v[192:195], v[208:211], v[98:101]
	v_mfma_f32_16x16x32_bf16 v[90:93], v[184:187], v[216:219], v[90:93]
	v_mfma_f32_16x16x32_bf16 v[82:85], v[192:195], v[216:219], v[82:85]
	v_mfma_f32_16x16x32_bf16 v[74:77], v[184:187], v[224:227], v[74:77]
	v_mfma_f32_16x16x32_bf16 v[66:69], v[192:195], v[224:227], v[66:69]
	s_setprio 0
	s_barrier
	s_add_u32 s96, s96, 0x80
	s_addc_u32 s97, s97, 0
	s_add_u32 s98, s96, 0x40000
	s_addc_u32 s99, s97, 0
	s_add_u32 s94, s94, 0x80
	s_addc_u32 s95, s95, 0
	s_add_i32 s7, s7, s25
	s_mov_b32 m0, s7
	ds_read_b128 v[196:199], v160 offset:49152
	ds_read_b128 v[200:203], v160 offset:50176
	ds_read_b128 v[204:207], v160 offset:51200
	ds_read_b128 v[208:211], v160 offset:52224
	ds_read_b128 v[212:215], v160 offset:53248
	ds_read_b128 v[216:219], v160 offset:54272
	ds_read_b128 v[220:223], v160 offset:55296
	ds_read_b128 v[224:227], v160 offset:56320
	global_load_lds_dwordx4 v132, s[96:97]
	s_add_i32 m0, s7, 0x2000
	s_add_i32 s7, s47, s25
	global_load_lds_dwordx4 v136, s[96:97]
	s_mov_b32 m0, s7
	s_nop 0
	global_load_lds_dwordx4 v132, s[98:99]
	s_add_i32 m0, s7, 0x2000
	s_nop 0
	global_load_lds_dwordx4 v136, s[98:99]
	s_mov_b32 m0, s66
	s_nop 0
	global_load_lds_dwordx4 v130, s[94:95]
	s_mov_b32 m0, s67
	s_nop 0
	global_load_lds_dwordx4 v134, s[94:95]
	s_waitcnt vmcnt(8)
	s_waitcnt lgkmcnt(0)
	s_barrier
	s_setprio 1
	s_waitcnt lgkmcnt(0)
	v_mfma_f32_16x16x32_bf16 v[62:65], v[164:167], v[196:199], v[62:65]
	v_mfma_f32_16x16x32_bf16 v[54:57], v[172:175], v[196:199], v[54:57]
	v_mfma_f32_16x16x32_bf16 v[46:49], v[164:167], v[204:207], v[46:49]
	v_mfma_f32_16x16x32_bf16 v[38:41], v[172:175], v[204:207], v[38:41]
	v_mfma_f32_16x16x32_bf16 v[30:33], v[164:167], v[212:215], v[30:33]
	v_mfma_f32_16x16x32_bf16 v[22:25], v[172:175], v[212:215], v[22:25]
	v_mfma_f32_16x16x32_bf16 v[14:17], v[164:167], v[220:223], v[14:17]
	v_mfma_f32_16x16x32_bf16 v[6:9], v[172:175], v[220:223], v[6:9]
	v_mfma_f32_16x16x32_bf16 v[62:65], v[168:171], v[200:203], v[62:65]
	v_mfma_f32_16x16x32_bf16 v[54:57], v[176:179], v[200:203], v[54:57]
	v_mfma_f32_16x16x32_bf16 v[46:49], v[168:171], v[208:211], v[46:49]
	v_mfma_f32_16x16x32_bf16 v[38:41], v[176:179], v[208:211], v[38:41]
	v_mfma_f32_16x16x32_bf16 v[30:33], v[168:171], v[216:219], v[30:33]
	v_mfma_f32_16x16x32_bf16 v[22:25], v[176:179], v[216:219], v[22:25]
	v_mfma_f32_16x16x32_bf16 v[14:17], v[168:171], v[224:227], v[14:17]
	v_mfma_f32_16x16x32_bf16 v[6:9], v[176:179], v[224:227], v[6:9]
	s_setprio 0
	s_setprio 1
	v_mfma_f32_16x16x32_bf16 v[58:61], v[180:183], v[196:199], v[58:61]
	v_mfma_f32_16x16x32_bf16 v[50:53], v[188:191], v[196:199], v[50:53]
	v_mfma_f32_16x16x32_bf16 v[42:45], v[180:183], v[204:207], v[42:45]
	v_mfma_f32_16x16x32_bf16 v[34:37], v[188:191], v[204:207], v[34:37]
	v_mfma_f32_16x16x32_bf16 v[26:29], v[180:183], v[212:215], v[26:29]
	v_mfma_f32_16x16x32_bf16 v[18:21], v[188:191], v[212:215], v[18:21]
	v_mfma_f32_16x16x32_bf16 v[10:13], v[180:183], v[220:223], v[10:13]
	v_mfma_f32_16x16x32_bf16 v[2:5], v[188:191], v[220:223], v[2:5]
	v_mfma_f32_16x16x32_bf16 v[58:61], v[184:187], v[200:203], v[58:61]
	v_mfma_f32_16x16x32_bf16 v[50:53], v[192:195], v[200:203], v[50:53]
	v_mfma_f32_16x16x32_bf16 v[42:45], v[184:187], v[208:211], v[42:45]
	v_mfma_f32_16x16x32_bf16 v[34:37], v[192:195], v[208:211], v[34:37]
	v_mfma_f32_16x16x32_bf16 v[26:29], v[184:187], v[216:219], v[26:29]
	v_mfma_f32_16x16x32_bf16 v[18:21], v[192:195], v[216:219], v[18:21]
	v_mfma_f32_16x16x32_bf16 v[10:13], v[184:187], v[224:227], v[10:13]
	v_mfma_f32_16x16x32_bf16 v[2:5], v[192:195], v[224:227], v[2:5]
	s_setprio 0
	s_barrier
	s_mov_b32 s7, s45
	s_add_u32 s88, s88, 0x100
	s_addc_u32 s89, s89, 0
	s_add_u32 s86, s86, 0x100
	s_addc_u32 s87, s87, 0
	s_cmp_ge_i32 s45, s101
	s_cbranch_scc0 .LBB0_768

.LBB0_947:
	v_cmp_gt_i32_e32 vcc, 1, v138
	s_cbranch_vccnz .LBB0_1009
	v_lshl_add_u64 v[152:153], v[2:3], 0, s[18:19]
	v_add_u32_e32 v154, -2, v138
	s_waitcnt lgkmcnt(0)
	v_lshl_add_u64 v[150:151], v[4:5], 0, s[22:23]
	s_mov_b32 s7, 0
	s_nop 0
	v_readfirstlane_b32 s86, v152
	v_readfirstlane_b32 s87, v153
	v_readfirstlane_b32 s88, v150
	v_readfirstlane_b32 s89, v151
	v_readfirstlane_b32 s90, v146
	v_readfirstlane_b32 s91, v147
	v_readfirstlane_b32 s92, v148
	v_readfirstlane_b32 s93, v149
	v_readfirstlane_b32 s100, v154
	v_readfirstlane_b32 s101, v138
	v_add_u32_e32 v230, s74, v141
	v_add_u32_e32 v231, s75, v141
	v_add_u32_e32 v232, 0x18000, v141
	v_add_u32_e32 v233, 0x1c000, v141
	s_add_u32 s98, s86, 0xfffc0080
	s_addc_u32 s99, s87, -1
	s_cmp_eq_u32 s7, s100
	s_cselect_b64 s[94:95], s[90:91], s[98:99]
	s_cselect_b64 s[96:97], s[92:93], s[88:89]
	ds_read_b128 v[164:167], v230
	ds_read_b128 v[168:171], v230 offset:1024
	ds_read_b128 v[172:175], v230 offset:2048
	ds_read_b128 v[176:179], v230 offset:3072
	ds_read_b128 v[180:183], v231
	ds_read_b128 v[184:187], v231 offset:1024
	ds_read_b128 v[188:191], v231 offset:2048
	ds_read_b128 v[192:195], v231 offset:3072
	s_add_i32 s47, s7, 2
	s_nop 0
	s_mov_b32 m0, s76
	ds_read_b128 v[196:199], v160
	ds_read_b128 v[200:203], v160 offset:1024
	ds_read_b128 v[204:207], v160 offset:2048
	ds_read_b128 v[208:211], v160 offset:3072
	ds_read_b128 v[212:215], v160 offset:4096
	ds_read_b128 v[216:219], v160 offset:5120
	ds_read_b128 v[220:223], v160 offset:6144
	ds_read_b128 v[224:227], v160 offset:7168
	global_load_lds_dwordx4 v144, s[86:87]
	s_mov_b32 m0, s77
	s_nop 0
	global_load_lds_dwordx4 v142, s[86:87]
	s_waitcnt vmcnt(8)
	s_waitcnt lgkmcnt(0)
	s_barrier
	s_setprio 1
	s_waitcnt lgkmcnt(0)
	v_mfma_f32_16x16x32_bf16 v[122:125], v[164:167], v[196:199], 0
	v_mfma_f32_16x16x32_bf16 v[118:121], v[172:175], v[196:199], 0
	v_mfma_f32_16x16x32_bf16 v[110:113], v[164:167], v[204:207], 0
	v_mfma_f32_16x16x32_bf16 v[102:105], v[172:175], v[204:207], 0
	v_mfma_f32_16x16x32_bf16 v[94:97], v[164:167], v[212:215], 0
	v_mfma_f32_16x16x32_bf16 v[86:89], v[172:175], v[212:215], 0
	v_mfma_f32_16x16x32_bf16 v[78:81], v[164:167], v[220:223], 0
	v_mfma_f32_16x16x32_bf16 v[70:73], v[172:175], v[220:223], 0
	v_mfma_f32_16x16x32_bf16 v[122:125], v[168:171], v[200:203], v[122:125]
	v_mfma_f32_16x16x32_bf16 v[118:121], v[176:179], v[200:203], v[118:121]
	v_mfma_f32_16x16x32_bf16 v[110:113], v[168:171], v[208:211], v[110:113]
	v_mfma_f32_16x16x32_bf16 v[102:105], v[176:179], v[208:211], v[102:105]
	v_mfma_f32_16x16x32_bf16 v[94:97], v[168:171], v[216:219], v[94:97]
	v_mfma_f32_16x16x32_bf16 v[86:89], v[176:179], v[216:219], v[86:89]
	v_mfma_f32_16x16x32_bf16 v[78:81], v[168:171], v[224:227], v[78:81]
	v_mfma_f32_16x16x32_bf16 v[70:73], v[176:179], v[224:227], v[70:73]
	s_setprio 0
	s_setprio 1
	v_mfma_f32_16x16x32_bf16 v[126:129], v[180:183], v[196:199], 0
	v_mfma_f32_16x16x32_bf16 v[114:117], v[188:191], v[196:199], 0
	v_mfma_f32_16x16x32_bf16 v[106:109], v[180:183], v[204:207], 0
	v_mfma_f32_16x16x32_bf16 v[98:101], v[188:191], v[204:207], 0
	v_mfma_f32_16x16x32_bf16 v[90:93], v[180:183], v[212:215], 0
	v_mfma_f32_16x16x32_bf16 v[82:85], v[188:191], v[212:215], 0
	v_mfma_f32_16x16x32_bf16 v[74:77], v[180:183], v[220:223], 0
	v_mfma_f32_16x16x32_bf16 v[66:69], v[188:191], v[220:223], 0
	v_mfma_f32_16x16x32_bf16 v[126:129], v[184:187], v[200:203], v[126:129]
	v_mfma_f32_16x16x32_bf16 v[114:117], v[192:195], v[200:203], v[114:117]
	v_mfma_f32_16x16x32_bf16 v[106:109], v[184:187], v[208:211], v[106:109]
	v_mfma_f32_16x16x32_bf16 v[98:101], v[192:195], v[208:211], v[98:101]
	v_mfma_f32_16x16x32_bf16 v[90:93], v[184:187], v[216:219], v[90:93]
	v_mfma_f32_16x16x32_bf16 v[82:85], v[192:195], v[216:219], v[82:85]
	v_mfma_f32_16x16x32_bf16 v[74:77], v[184:187], v[224:227], v[74:77]
	v_mfma_f32_16x16x32_bf16 v[66:69], v[192:195], v[224:227], v[66:69]
	s_setprio 0
	s_barrier
	s_add_u32 s98, s96, 0x40000
	s_addc_u32 s99, s97, 0
	s_mov_b32 m0, s78
	ds_read_b128 v[196:199], v160 offset:16384
	ds_read_b128 v[200:203], v160 offset:17408
	ds_read_b128 v[204:207], v160 offset:18432
	ds_read_b128 v[208:211], v160 offset:19456
	ds_read_b128 v[212:215], v160 offset:20480
	ds_read_b128 v[216:219], v160 offset:21504
	ds_read_b128 v[220:223], v160 offset:22528
	ds_read_b128 v[224:227], v160 offset:23552
	global_load_lds_dwordx4 v132, s[96:97]
	s_mov_b32 m0, s79
	s_add_i32 s7, s75, s29
	global_load_lds_dwordx4 v136, s[96:97]
	s_mov_b32 m0, s7
	s_nop 0
	global_load_lds_dwordx4 v132, s[98:99]
	s_add_i32 m0, s7, 0x2000
	s_nop 0
	global_load_lds_dwordx4 v136, s[98:99]
	s_mov_b32 m0, s51
	s_nop 0
	global_load_lds_dwordx4 v130, s[94:95]
	s_mov_b32 m0, s60
	s_nop 0
	global_load_lds_dwordx4 v134, s[94:95]
	s_waitcnt vmcnt(8)
	s_waitcnt lgkmcnt(0)
	s_barrier
	s_setprio 1
	s_waitcnt lgkmcnt(0)
	v_mfma_f32_16x16x32_bf16 v[62:65], v[164:167], v[196:199], 0
	v_mfma_f32_16x16x32_bf16 v[54:57], v[172:175], v[196:199], 0
	v_mfma_f32_16x16x32_bf16 v[46:49], v[164:167], v[204:207], 0
	v_mfma_f32_16x16x32_bf16 v[38:41], v[172:175], v[204:207], 0
	v_mfma_f32_16x16x32_bf16 v[30:33], v[164:167], v[212:215], 0
	v_mfma_f32_16x16x32_bf16 v[22:25], v[172:175], v[212:215], 0
	v_mfma_f32_16x16x32_bf16 v[14:17], v[164:167], v[220:223], 0
	v_mfma_f32_16x16x32_bf16 v[6:9], v[172:175], v[220:223], 0
	v_mfma_f32_16x16x32_bf16 v[62:65], v[168:171], v[200:203], v[62:65]
	v_mfma_f32_16x16x32_bf16 v[54:57], v[176:179], v[200:203], v[54:57]
	v_mfma_f32_16x16x32_bf16 v[46:49], v[168:171], v[208:211], v[46:49]
	v_mfma_f32_16x16x32_bf16 v[38:41], v[176:179], v[208:211], v[38:41]
	v_mfma_f32_16x16x32_bf16 v[30:33], v[168:171], v[216:219], v[30:33]
	v_mfma_f32_16x16x32_bf16 v[22:25], v[176:179], v[216:219], v[22:25]
	v_mfma_f32_16x16x32_bf16 v[14:17], v[168:171], v[224:227], v[14:17]
	v_mfma_f32_16x16x32_bf16 v[6:9], v[176:179], v[224:227], v[6:9]
	s_setprio 0
	s_setprio 1
	v_mfma_f32_16x16x32_bf16 v[58:61], v[180:183], v[196:199], 0
	v_mfma_f32_16x16x32_bf16 v[50:53], v[188:191], v[196:199], 0
	v_mfma_f32_16x16x32_bf16 v[42:45], v[180:183], v[204:207], 0
	v_mfma_f32_16x16x32_bf16 v[34:37], v[188:191], v[204:207], 0
	v_mfma_f32_16x16x32_bf16 v[26:29], v[180:183], v[212:215], 0
	v_mfma_f32_16x16x32_bf16 v[18:21], v[188:191], v[212:215], 0
	v_mfma_f32_16x16x32_bf16 v[10:13], v[180:183], v[220:223], 0
	v_mfma_f32_16x16x32_bf16 v[2:5], v[188:191], v[220:223], 0
	v_mfma_f32_16x16x32_bf16 v[58:61], v[184:187], v[200:203], v[58:61]
	v_mfma_f32_16x16x32_bf16 v[50:53], v[192:195], v[200:203], v[50:53]
	v_mfma_f32_16x16x32_bf16 v[42:45], v[184:187], v[208:211], v[42:45]
	v_mfma_f32_16x16x32_bf16 v[34:37], v[192:195], v[208:211], v[34:37]
	v_mfma_f32_16x16x32_bf16 v[26:29], v[184:187], v[216:219], v[26:29]
	v_mfma_f32_16x16x32_bf16 v[18:21], v[192:195], v[216:219], v[18:21]
	v_mfma_f32_16x16x32_bf16 v[10:13], v[184:187], v[224:227], v[10:13]
	v_mfma_f32_16x16x32_bf16 v[2:5], v[192:195], v[224:227], v[2:5]
	s_setprio 0
	s_barrier
	s_add_u32 s98, s94, 0x40000
	s_addc_u32 s99, s95, 0
	s_add_i32 s7, 0, 0x18000
	s_add_i32 s49, 0, 0x1c000
	ds_read_b128 v[164:167], v232
	ds_read_b128 v[168:171], v232 offset:1024
	ds_read_b128 v[172:175], v232 offset:2048
	ds_read_b128 v[176:179], v232 offset:3072
	ds_read_b128 v[180:183], v233
	ds_read_b128 v[184:187], v233 offset:1024
	ds_read_b128 v[188:191], v233 offset:2048
	ds_read_b128 v[192:195], v233 offset:3072
	s_mov_b32 m0, s61
	ds_read_b128 v[196:199], v160 offset:32768
	ds_read_b128 v[200:203], v160 offset:33792
	ds_read_b128 v[204:207], v160 offset:34816
	ds_read_b128 v[208:211], v160 offset:35840
	ds_read_b128 v[212:215], v160 offset:36864
	ds_read_b128 v[216:219], v160 offset:37888
	ds_read_b128 v[220:223], v160 offset:38912
	ds_read_b128 v[224:227], v160 offset:39936
	global_load_lds_dwordx4 v130, s[98:99]
	s_mov_b32 m0, s62
	s_nop 0
	global_load_lds_dwordx4 v134, s[98:99]
	s_waitcnt vmcnt(8)
	s_waitcnt lgkmcnt(0)
	s_barrier
	s_setprio 1
	s_waitcnt lgkmcnt(0)
	v_mfma_f32_16x16x32_bf16 v[122:125], v[164:167], v[196:199], v[122:125]
	v_mfma_f32_16x16x32_bf16 v[118:121], v[172:175], v[196:199], v[118:121]
	v_mfma_f32_16x16x32_bf16 v[110:113], v[164:167], v[204:207], v[110:113]
	v_mfma_f32_16x16x32_bf16 v[102:105], v[172:175], v[204:207], v[102:105]
	v_mfma_f32_16x16x32_bf16 v[94:97], v[164:167], v[212:215], v[94:97]
	v_mfma_f32_16x16x32_bf16 v[86:89], v[172:175], v[212:215], v[86:89]
	v_mfma_f32_16x16x32_bf16 v[78:81], v[164:167], v[220:223], v[78:81]
	v_mfma_f32_16x16x32_bf16 v[70:73], v[172:175], v[220:223], v[70:73]
	v_mfma_f32_16x16x32_bf16 v[122:125], v[168:171], v[200:203], v[122:125]
	v_mfma_f32_16x16x32_bf16 v[118:121], v[176:179], v[200:203], v[118:121]
	v_mfma_f32_16x16x32_bf16 v[110:113], v[168:171], v[208:211], v[110:113]
	v_mfma_f32_16x16x32_bf16 v[102:105], v[176:179], v[208:211], v[102:105]
	v_mfma_f32_16x16x32_bf16 v[94:97], v[168:171], v[216:219], v[94:97]
	v_mfma_f32_16x16x32_bf16 v[86:89], v[176:179], v[216:219], v[86:89]
	v_mfma_f32_16x16x32_bf16 v[78:81], v[168:171], v[224:227], v[78:81]
	v_mfma_f32_16x16x32_bf16 v[70:73], v[176:179], v[224:227], v[70:73]
	s_setprio 0
	s_setprio 1
	v_mfma_f32_16x16x32_bf16 v[126:129], v[180:183], v[196:199], v[126:129]
	v_mfma_f32_16x16x32_bf16 v[114:117], v[188:191], v[196:199], v[114:117]
	v_mfma_f32_16x16x32_bf16 v[106:109], v[180:183], v[204:207], v[106:109]
	v_mfma_f32_16x16x32_bf16 v[98:101], v[188:191], v[204:207], v[98:101]
	v_mfma_f32_16x16x32_bf16 v[90:93], v[180:183], v[212:215], v[90:93]
	v_mfma_f32_16x16x32_bf16 v[82:85], v[188:191], v[212:215], v[82:85]
	v_mfma_f32_16x16x32_bf16 v[74:77], v[180:183], v[220:223], v[74:77]
	v_mfma_f32_16x16x32_bf16 v[66:69], v[188:191], v[220:223], v[66:69]
	v_mfma_f32_16x16x32_bf16 v[126:129], v[184:187], v[200:203], v[126:129]
	v_mfma_f32_16x16x32_bf16 v[114:117], v[192:195], v[200:203], v[114:117]
	v_mfma_f32_16x16x32_bf16 v[106:109], v[184:187], v[208:211], v[106:109]
	v_mfma_f32_16x16x32_bf16 v[98:101], v[192:195], v[208:211], v[98:101]
	v_mfma_f32_16x16x32_bf16 v[90:93], v[184:187], v[216:219], v[90:93]
	v_mfma_f32_16x16x32_bf16 v[82:85], v[192:195], v[216:219], v[82:85]
	v_mfma_f32_16x16x32_bf16 v[74:77], v[184:187], v[224:227], v[74:77]
	v_mfma_f32_16x16x32_bf16 v[66:69], v[192:195], v[224:227], v[66:69]
	s_setprio 0
	s_barrier
	s_add_u32 s96, s96, 0x80
	s_addc_u32 s97, s97, 0
	s_add_u32 s98, s96, 0x40000
	s_addc_u32 s99, s97, 0
	s_add_u32 s94, s94, 0x80
	s_addc_u32 s95, s95, 0
	s_add_i32 s7, s7, s29
	s_mov_b32 m0, s7
	ds_read_b128 v[196:199], v160 offset:49152
	ds_read_b128 v[200:203], v160 offset:50176
	ds_read_b128 v[204:207], v160 offset:51200
	ds_read_b128 v[208:211], v160 offset:52224
	ds_read_b128 v[212:215], v160 offset:53248
	ds_read_b128 v[216:219], v160 offset:54272
	ds_read_b128 v[220:223], v160 offset:55296
	ds_read_b128 v[224:227], v160 offset:56320
	global_load_lds_dwordx4 v132, s[96:97]
	s_add_i32 m0, s7, 0x2000
	s_add_i32 s7, s49, s29
	global_load_lds_dwordx4 v136, s[96:97]
	s_mov_b32 m0, s7
	s_nop 0
	global_load_lds_dwordx4 v132, s[98:99]
	s_add_i32 m0, s7, 0x2000
	s_nop 0
	global_load_lds_dwordx4 v136, s[98:99]
	s_mov_b32 m0, s63
	s_nop 0
	global_load_lds_dwordx4 v130, s[94:95]
	s_mov_b32 m0, s64
	s_nop 0
	global_load_lds_dwordx4 v134, s[94:95]
	s_waitcnt vmcnt(8)
	s_waitcnt lgkmcnt(0)
	s_barrier
	s_setprio 1
	s_waitcnt lgkmcnt(0)
	v_mfma_f32_16x16x32_bf16 v[62:65], v[164:167], v[196:199], v[62:65]
	v_mfma_f32_16x16x32_bf16 v[54:57], v[172:175], v[196:199], v[54:57]
	v_mfma_f32_16x16x32_bf16 v[46:49], v[164:167], v[204:207], v[46:49]
	v_mfma_f32_16x16x32_bf16 v[38:41], v[172:175], v[204:207], v[38:41]
	v_mfma_f32_16x16x32_bf16 v[30:33], v[164:167], v[212:215], v[30:33]
	v_mfma_f32_16x16x32_bf16 v[22:25], v[172:175], v[212:215], v[22:25]
	v_mfma_f32_16x16x32_bf16 v[14:17], v[164:167], v[220:223], v[14:17]
	v_mfma_f32_16x16x32_bf16 v[6:9], v[172:175], v[220:223], v[6:9]
	v_mfma_f32_16x16x32_bf16 v[62:65], v[168:171], v[200:203], v[62:65]
	v_mfma_f32_16x16x32_bf16 v[54:57], v[176:179], v[200:203], v[54:57]
	v_mfma_f32_16x16x32_bf16 v[46:49], v[168:171], v[208:211], v[46:49]
	v_mfma_f32_16x16x32_bf16 v[38:41], v[176:179], v[208:211], v[38:41]
	v_mfma_f32_16x16x32_bf16 v[30:33], v[168:171], v[216:219], v[30:33]
	v_mfma_f32_16x16x32_bf16 v[22:25], v[176:179], v[216:219], v[22:25]
	v_mfma_f32_16x16x32_bf16 v[14:17], v[168:171], v[224:227], v[14:17]
	v_mfma_f32_16x16x32_bf16 v[6:9], v[176:179], v[224:227], v[6:9]
	s_setprio 0
	s_setprio 1
	v_mfma_f32_16x16x32_bf16 v[58:61], v[180:183], v[196:199], v[58:61]
	v_mfma_f32_16x16x32_bf16 v[50:53], v[188:191], v[196:199], v[50:53]
	v_mfma_f32_16x16x32_bf16 v[42:45], v[180:183], v[204:207], v[42:45]
	v_mfma_f32_16x16x32_bf16 v[34:37], v[188:191], v[204:207], v[34:37]
	v_mfma_f32_16x16x32_bf16 v[26:29], v[180:183], v[212:215], v[26:29]
	v_mfma_f32_16x16x32_bf16 v[18:21], v[188:191], v[212:215], v[18:21]
	v_mfma_f32_16x16x32_bf16 v[10:13], v[180:183], v[220:223], v[10:13]
	v_mfma_f32_16x16x32_bf16 v[2:5], v[188:191], v[220:223], v[2:5]
	v_mfma_f32_16x16x32_bf16 v[58:61], v[184:187], v[200:203], v[58:61]
	v_mfma_f32_16x16x32_bf16 v[50:53], v[192:195], v[200:203], v[50:53]
	v_mfma_f32_16x16x32_bf16 v[42:45], v[184:187], v[208:211], v[42:45]
	v_mfma_f32_16x16x32_bf16 v[34:37], v[192:195], v[208:211], v[34:37]
	v_mfma_f32_16x16x32_bf16 v[26:29], v[184:187], v[216:219], v[26:29]
	v_mfma_f32_16x16x32_bf16 v[18:21], v[192:195], v[216:219], v[18:21]
	v_mfma_f32_16x16x32_bf16 v[10:13], v[184:187], v[224:227], v[10:13]
	v_mfma_f32_16x16x32_bf16 v[2:5], v[192:195], v[224:227], v[2:5]
	s_setprio 0
	s_barrier
	s_mov_b32 s7, s47
	s_add_u32 s88, s88, 0x100
	s_addc_u32 s89, s89, 0
	s_add_u32 s86, s86, 0x100
	s_addc_u32 s87, s87, 0
	s_cmp_ge_i32 s47, s101
	s_cbranch_scc1 .Lmy_kexit_4
.LBB0_949:
	s_add_u32 s98, s86, 0xfffc0080
	s_addc_u32 s99, s87, -1
	s_cmp_eq_u32 s7, s100
	s_cselect_b64 s[94:95], s[90:91], s[98:99]
	s_cselect_b64 s[96:97], s[92:93], s[88:89]
	ds_read_b128 v[164:167], v230
	ds_read_b128 v[168:171], v230 offset:1024
	ds_read_b128 v[172:175], v230 offset:2048
	ds_read_b128 v[176:179], v230 offset:3072
	ds_read_b128 v[180:183], v231
	ds_read_b128 v[184:187], v231 offset:1024
	ds_read_b128 v[188:191], v231 offset:2048
	ds_read_b128 v[192:195], v231 offset:3072
	s_add_i32 s47, s7, 2
	s_nop 0
	s_mov_b32 m0, s76
	ds_read_b128 v[196:199], v160
	ds_read_b128 v[200:203], v160 offset:1024
	ds_read_b128 v[204:207], v160 offset:2048
	ds_read_b128 v[208:211], v160 offset:3072
	ds_read_b128 v[212:215], v160 offset:4096
	ds_read_b128 v[216:219], v160 offset:5120
	ds_read_b128 v[220:223], v160 offset:6144
	ds_read_b128 v[224:227], v160 offset:7168
	global_load_lds_dwordx4 v144, s[86:87]
	s_mov_b32 m0, s77
	s_nop 0
	global_load_lds_dwordx4 v142, s[86:87]
	s_waitcnt vmcnt(8)
	s_waitcnt lgkmcnt(0)
	s_barrier
	s_setprio 1
	s_waitcnt lgkmcnt(0)
	v_mfma_f32_16x16x32_bf16 v[122:125], v[164:167], v[196:199], v[122:125]
	v_mfma_f32_16x16x32_bf16 v[118:121], v[172:175], v[196:199], v[118:121]
	v_mfma_f32_16x16x32_bf16 v[110:113], v[164:167], v[204:207], v[110:113]
	v_mfma_f32_16x16x32_bf16 v[102:105], v[172:175], v[204:207], v[102:105]
	v_mfma_f32_16x16x32_bf16 v[94:97], v[164:167], v[212:215], v[94:97]
	v_mfma_f32_16x16x32_bf16 v[86:89], v[172:175], v[212:215], v[86:89]
	v_mfma_f32_16x16x32_bf16 v[78:81], v[164:167], v[220:223], v[78:81]
	v_mfma_f32_16x16x32_bf16 v[70:73], v[172:175], v[220:223], v[70:73]
	v_mfma_f32_16x16x32_bf16 v[122:125], v[168:171], v[200:203], v[122:125]
	v_mfma_f32_16x16x32_bf16 v[118:121], v[176:179], v[200:203], v[118:121]
	v_mfma_f32_16x16x32_bf16 v[110:113], v[168:171], v[208:211], v[110:113]
	v_mfma_f32_16x16x32_bf16 v[102:105], v[176:179], v[208:211], v[102:105]
	v_mfma_f32_16x16x32_bf16 v[94:97], v[168:171], v[216:219], v[94:97]
	v_mfma_f32_16x16x32_bf16 v[86:89], v[176:179], v[216:219], v[86:89]
	v_mfma_f32_16x16x32_bf16 v[78:81], v[168:171], v[224:227], v[78:81]
	v_mfma_f32_16x16x32_bf16 v[70:73], v[176:179], v[224:227], v[70:73]
	s_setprio 0
	s_setprio 1
	v_mfma_f32_16x16x32_bf16 v[126:129], v[180:183], v[196:199], v[126:129]
	v_mfma_f32_16x16x32_bf16 v[114:117], v[188:191], v[196:199], v[114:117]
	v_mfma_f32_16x16x32_bf16 v[106:109], v[180:183], v[204:207], v[106:109]
	v_mfma_f32_16x16x32_bf16 v[98:101], v[188:191], v[204:207], v[98:101]
	v_mfma_f32_16x16x32_bf16 v[90:93], v[180:183], v[212:215], v[90:93]
	v_mfma_f32_16x16x32_bf16 v[82:85], v[188:191], v[212:215], v[82:85]
	v_mfma_f32_16x16x32_bf16 v[74:77], v[180:183], v[220:223], v[74:77]
	v_mfma_f32_16x16x32_bf16 v[66:69], v[188:191], v[220:223], v[66:69]
	v_mfma_f32_16x16x32_bf16 v[126:129], v[184:187], v[200:203], v[126:129]
	v_mfma_f32_16x16x32_bf16 v[114:117], v[192:195], v[200:203], v[114:117]
	v_mfma_f32_16x16x32_bf16 v[106:109], v[184:187], v[208:211], v[106:109]
	v_mfma_f32_16x16x32_bf16 v[98:101], v[192:195], v[208:211], v[98:101]
	v_mfma_f32_16x16x32_bf16 v[90:93], v[184:187], v[216:219], v[90:93]
	v_mfma_f32_16x16x32_bf16 v[82:85], v[192:195], v[216:219], v[82:85]
	v_mfma_f32_16x16x32_bf16 v[74:77], v[184:187], v[224:227], v[74:77]
	v_mfma_f32_16x16x32_bf16 v[66:69], v[192:195], v[224:227], v[66:69]
	s_setprio 0
	s_barrier
	s_add_u32 s98, s96, 0x40000
	s_addc_u32 s99, s97, 0
	s_mov_b32 m0, s78
	ds_read_b128 v[196:199], v160 offset:16384
	ds_read_b128 v[200:203], v160 offset:17408
	ds_read_b128 v[204:207], v160 offset:18432
	ds_read_b128 v[208:211], v160 offset:19456
	ds_read_b128 v[212:215], v160 offset:20480
	ds_read_b128 v[216:219], v160 offset:21504
	ds_read_b128 v[220:223], v160 offset:22528
	ds_read_b128 v[224:227], v160 offset:23552
	global_load_lds_dwordx4 v132, s[96:97]
	s_mov_b32 m0, s79
	s_add_i32 s7, s75, s29
	global_load_lds_dwordx4 v136, s[96:97]
	s_mov_b32 m0, s7
	s_nop 0
	global_load_lds_dwordx4 v132, s[98:99]
	s_add_i32 m0, s7, 0x2000
	s_nop 0
	global_load_lds_dwordx4 v136, s[98:99]
	s_mov_b32 m0, s51
	s_nop 0
	global_load_lds_dwordx4 v130, s[94:95]
	s_mov_b32 m0, s60
	s_nop 0
	global_load_lds_dwordx4 v134, s[94:95]
	s_waitcnt vmcnt(8)
	s_waitcnt lgkmcnt(0)
	s_barrier
	s_setprio 1
	s_waitcnt lgkmcnt(0)
	v_mfma_f32_16x16x32_bf16 v[62:65], v[164:167], v[196:199], v[62:65]
	v_mfma_f32_16x16x32_bf16 v[54:57], v[172:175], v[196:199], v[54:57]
	v_mfma_f32_16x16x32_bf16 v[46:49], v[164:167], v[204:207], v[46:49]
	v_mfma_f32_16x16x32_bf16 v[38:41], v[172:175], v[204:207], v[38:41]
	v_mfma_f32_16x16x32_bf16 v[30:33], v[164:167], v[212:215], v[30:33]
	v_mfma_f32_16x16x32_bf16 v[22:25], v[172:175], v[212:215], v[22:25]
	v_mfma_f32_16x16x32_bf16 v[14:17], v[164:167], v[220:223], v[14:17]
	v_mfma_f32_16x16x32_bf16 v[6:9], v[172:175], v[220:223], v[6:9]
	v_mfma_f32_16x16x32_bf16 v[62:65], v[168:171], v[200:203], v[62:65]
	v_mfma_f32_16x16x32_bf16 v[54:57], v[176:179], v[200:203], v[54:57]
	v_mfma_f32_16x16x32_bf16 v[46:49], v[168:171], v[208:211], v[46:49]
	v_mfma_f32_16x16x32_bf16 v[38:41], v[176:179], v[208:211], v[38:41]
	v_mfma_f32_16x16x32_bf16 v[30:33], v[168:171], v[216:219], v[30:33]
	v_mfma_f32_16x16x32_bf16 v[22:25], v[176:179], v[216:219], v[22:25]
	v_mfma_f32_16x16x32_bf16 v[14:17], v[168:171], v[224:227], v[14:17]
	v_mfma_f32_16x16x32_bf16 v[6:9], v[176:179], v[224:227], v[6:9]
	s_setprio 0
	s_setprio 1
	v_mfma_f32_16x16x32_bf16 v[58:61], v[180:183], v[196:199], v[58:61]
	v_mfma_f32_16x16x32_bf16 v[50:53], v[188:191], v[196:199], v[50:53]
	v_mfma_f32_16x16x32_bf16 v[42:45], v[180:183], v[204:207], v[42:45]
	v_mfma_f32_16x16x32_bf16 v[34:37], v[188:191], v[204:207], v[34:37]
	v_mfma_f32_16x16x32_bf16 v[26:29], v[180:183], v[212:215], v[26:29]
	v_mfma_f32_16x16x32_bf16 v[18:21], v[188:191], v[212:215], v[18:21]
	v_mfma_f32_16x16x32_bf16 v[10:13], v[180:183], v[220:223], v[10:13]
	v_mfma_f32_16x16x32_bf16 v[2:5], v[188:191], v[220:223], v[2:5]
	v_mfma_f32_16x16x32_bf16 v[58:61], v[184:187], v[200:203], v[58:61]
	v_mfma_f32_16x16x32_bf16 v[50:53], v[192:195], v[200:203], v[50:53]
	v_mfma_f32_16x16x32_bf16 v[42:45], v[184:187], v[208:211], v[42:45]
	v_mfma_f32_16x16x32_bf16 v[34:37], v[192:195], v[208:211], v[34:37]
	v_mfma_f32_16x16x32_bf16 v[26:29], v[184:187], v[216:219], v[26:29]
	v_mfma_f32_16x16x32_bf16 v[18:21], v[192:195], v[216:219], v[18:21]
	v_mfma_f32_16x16x32_bf16 v[10:13], v[184:187], v[224:227], v[10:13]
	v_mfma_f32_16x16x32_bf16 v[2:5], v[192:195], v[224:227], v[2:5]
	s_setprio 0
	s_barrier
	s_add_u32 s98, s94, 0x40000
	s_addc_u32 s99, s95, 0
	s_add_i32 s7, 0, 0x18000
	s_add_i32 s49, 0, 0x1c000
	ds_read_b128 v[164:167], v232
	ds_read_b128 v[168:171], v232 offset:1024
	ds_read_b128 v[172:175], v232 offset:2048
	ds_read_b128 v[176:179], v232 offset:3072
	ds_read_b128 v[180:183], v233
	ds_read_b128 v[184:187], v233 offset:1024
	ds_read_b128 v[188:191], v233 offset:2048
	ds_read_b128 v[192:195], v233 offset:3072
	s_mov_b32 m0, s61
	ds_read_b128 v[196:199], v160 offset:32768
	ds_read_b128 v[200:203], v160 offset:33792
	ds_read_b128 v[204:207], v160 offset:34816
	ds_read_b128 v[208:211], v160 offset:35840
	ds_read_b128 v[212:215], v160 offset:36864
	ds_read_b128 v[216:219], v160 offset:37888
	ds_read_b128 v[220:223], v160 offset:38912
	ds_read_b128 v[224:227], v160 offset:39936
	global_load_lds_dwordx4 v130, s[98:99]
	s_mov_b32 m0, s62
	s_nop 0
	global_load_lds_dwordx4 v134, s[98:99]
	s_waitcnt vmcnt(8)
	s_waitcnt lgkmcnt(0)
	s_barrier
	s_setprio 1
	s_waitcnt lgkmcnt(0)
	v_mfma_f32_16x16x32_bf16 v[122:125], v[164:167], v[196:199], v[122:125]
	v_mfma_f32_16x16x32_bf16 v[118:121], v[172:175], v[196:199], v[118:121]
	v_mfma_f32_16x16x32_bf16 v[110:113], v[164:167], v[204:207], v[110:113]
	v_mfma_f32_16x16x32_bf16 v[102:105], v[172:175], v[204:207], v[102:105]
	v_mfma_f32_16x16x32_bf16 v[94:97], v[164:167], v[212:215], v[94:97]
	v_mfma_f32_16x16x32_bf16 v[86:89], v[172:175], v[212:215], v[86:89]
	v_mfma_f32_16x16x32_bf16 v[78:81], v[164:167], v[220:223], v[78:81]
	v_mfma_f32_16x16x32_bf16 v[70:73], v[172:175], v[220:223], v[70:73]
	v_mfma_f32_16x16x32_bf16 v[122:125], v[168:171], v[200:203], v[122:125]
	v_mfma_f32_16x16x32_bf16 v[118:121], v[176:179], v[200:203], v[118:121]
	v_mfma_f32_16x16x32_bf16 v[110:113], v[168:171], v[208:211], v[110:113]
	v_mfma_f32_16x16x32_bf16 v[102:105], v[176:179], v[208:211], v[102:105]
	v_mfma_f32_16x16x32_bf16 v[94:97], v[168:171], v[216:219], v[94:97]
	v_mfma_f32_16x16x32_bf16 v[86:89], v[176:179], v[216:219], v[86:89]
	v_mfma_f32_16x16x32_bf16 v[78:81], v[168:171], v[224:227], v[78:81]
	v_mfma_f32_16x16x32_bf16 v[70:73], v[176:179], v[224:227], v[70:73]
	s_setprio 0
	s_setprio 1
	v_mfma_f32_16x16x32_bf16 v[126:129], v[180:183], v[196:199], v[126:129]
	v_mfma_f32_16x16x32_bf16 v[114:117], v[188:191], v[196:199], v[114:117]
	v_mfma_f32_16x16x32_bf16 v[106:109], v[180:183], v[204:207], v[106:109]
	v_mfma_f32_16x16x32_bf16 v[98:101], v[188:191], v[204:207], v[98:101]
	v_mfma_f32_16x16x32_bf16 v[90:93], v[180:183], v[212:215], v[90:93]
	v_mfma_f32_16x16x32_bf16 v[82:85], v[188:191], v[212:215], v[82:85]
	v_mfma_f32_16x16x32_bf16 v[74:77], v[180:183], v[220:223], v[74:77]
	v_mfma_f32_16x16x32_bf16 v[66:69], v[188:191], v[220:223], v[66:69]
	v_mfma_f32_16x16x32_bf16 v[126:129], v[184:187], v[200:203], v[126:129]
	v_mfma_f32_16x16x32_bf16 v[114:117], v[192:195], v[200:203], v[114:117]
	v_mfma_f32_16x16x32_bf16 v[106:109], v[184:187], v[208:211], v[106:109]
	v_mfma_f32_16x16x32_bf16 v[98:101], v[192:195], v[208:211], v[98:101]
	v_mfma_f32_16x16x32_bf16 v[90:93], v[184:187], v[216:219], v[90:93]
	v_mfma_f32_16x16x32_bf16 v[82:85], v[192:195], v[216:219], v[82:85]
	v_mfma_f32_16x16x32_bf16 v[74:77], v[184:187], v[224:227], v[74:77]
	v_mfma_f32_16x16x32_bf16 v[66:69], v[192:195], v[224:227], v[66:69]
	s_setprio 0
	s_barrier
	s_add_u32 s96, s96, 0x80
	s_addc_u32 s97, s97, 0
	s_add_u32 s98, s96, 0x40000
	s_addc_u32 s99, s97, 0
	s_add_u32 s94, s94, 0x80
	s_addc_u32 s95, s95, 0
	s_add_i32 s7, s7, s29
	s_mov_b32 m0, s7
	ds_read_b128 v[196:199], v160 offset:49152
	ds_read_b128 v[200:203], v160 offset:50176
	ds_read_b128 v[204:207], v160 offset:51200
	ds_read_b128 v[208:211], v160 offset:52224
	ds_read_b128 v[212:215], v160 offset:53248
	ds_read_b128 v[216:219], v160 offset:54272
	ds_read_b128 v[220:223], v160 offset:55296
	ds_read_b128 v[224:227], v160 offset:56320
	global_load_lds_dwordx4 v132, s[96:97]
	s_add_i32 m0, s7, 0x2000
	s_add_i32 s7, s49, s29
	global_load_lds_dwordx4 v136, s[96:97]
	s_mov_b32 m0, s7
	s_nop 0
	global_load_lds_dwordx4 v132, s[98:99]
	s_add_i32 m0, s7, 0x2000
	s_nop 0
	global_load_lds_dwordx4 v136, s[98:99]
	s_mov_b32 m0, s63
	s_nop 0
	global_load_lds_dwordx4 v130, s[94:95]
	s_mov_b32 m0, s64
	s_nop 0
	global_load_lds_dwordx4 v134, s[94:95]
	s_waitcnt vmcnt(8)
	s_waitcnt lgkmcnt(0)
	s_barrier
	s_setprio 1
	s_waitcnt lgkmcnt(0)
	v_mfma_f32_16x16x32_bf16 v[62:65], v[164:167], v[196:199], v[62:65]
	v_mfma_f32_16x16x32_bf16 v[54:57], v[172:175], v[196:199], v[54:57]
	v_mfma_f32_16x16x32_bf16 v[46:49], v[164:167], v[204:207], v[46:49]
	v_mfma_f32_16x16x32_bf16 v[38:41], v[172:175], v[204:207], v[38:41]
	v_mfma_f32_16x16x32_bf16 v[30:33], v[164:167], v[212:215], v[30:33]
	v_mfma_f32_16x16x32_bf16 v[22:25], v[172:175], v[212:215], v[22:25]
	v_mfma_f32_16x16x32_bf16 v[14:17], v[164:167], v[220:223], v[14:17]
	v_mfma_f32_16x16x32_bf16 v[6:9], v[172:175], v[220:223], v[6:9]
	v_mfma_f32_16x16x32_bf16 v[62:65], v[168:171], v[200:203], v[62:65]
	v_mfma_f32_16x16x32_bf16 v[54:57], v[176:179], v[200:203], v[54:57]
	v_mfma_f32_16x16x32_bf16 v[46:49], v[168:171], v[208:211], v[46:49]
	v_mfma_f32_16x16x32_bf16 v[38:41], v[176:179], v[208:211], v[38:41]
	v_mfma_f32_16x16x32_bf16 v[30:33], v[168:171], v[216:219], v[30:33]
	v_mfma_f32_16x16x32_bf16 v[22:25], v[176:179], v[216:219], v[22:25]
	v_mfma_f32_16x16x32_bf16 v[14:17], v[168:171], v[224:227], v[14:17]
	v_mfma_f32_16x16x32_bf16 v[6:9], v[176:179], v[224:227], v[6:9]
	s_setprio 0
	s_setprio 1
	v_mfma_f32_16x16x32_bf16 v[58:61], v[180:183], v[196:199], v[58:61]
	v_mfma_f32_16x16x32_bf16 v[50:53], v[188:191], v[196:199], v[50:53]
	v_mfma_f32_16x16x32_bf16 v[42:45], v[180:183], v[204:207], v[42:45]
	v_mfma_f32_16x16x32_bf16 v[34:37], v[188:191], v[204:207], v[34:37]
	v_mfma_f32_16x16x32_bf16 v[26:29], v[180:183], v[212:215], v[26:29]
	v_mfma_f32_16x16x32_bf16 v[18:21], v[188:191], v[212:215], v[18:21]
	v_mfma_f32_16x16x32_bf16 v[10:13], v[180:183], v[220:223], v[10:13]
	v_mfma_f32_16x16x32_bf16 v[2:5], v[188:191], v[220:223], v[2:5]
	v_mfma_f32_16x16x32_bf16 v[58:61], v[184:187], v[200:203], v[58:61]
	v_mfma_f32_16x16x32_bf16 v[50:53], v[192:195], v[200:203], v[50:53]
	v_mfma_f32_16x16x32_bf16 v[42:45], v[184:187], v[208:211], v[42:45]
	v_mfma_f32_16x16x32_bf16 v[34:37], v[192:195], v[208:211], v[34:37]
	v_mfma_f32_16x16x32_bf16 v[26:29], v[184:187], v[216:219], v[26:29]
	v_mfma_f32_16x16x32_bf16 v[18:21], v[192:195], v[216:219], v[18:21]
	v_mfma_f32_16x16x32_bf16 v[10:13], v[184:187], v[224:227], v[10:13]
	v_mfma_f32_16x16x32_bf16 v[2:5], v[192:195], v[224:227], v[2:5]
	s_setprio 0
	s_barrier
	s_mov_b32 s7, s47
	s_add_u32 s88, s88, 0x100
	s_addc_u32 s89, s89, 0
	s_add_u32 s86, s86, 0x100
	s_addc_u32 s87, s87, 0
	s_cmp_ge_i32 s47, s101
	s_cbranch_scc0 .LBB0_949

.LBB0_1078:
	v_cmp_gt_i32_e32 vcc, 1, v156
	s_cbranch_vccnz .LBB0_1140
	v_lshl_add_u64 v[152:153], v[2:3], 0, s[20:21]
	v_add_u32_e32 v138, -2, v156
	s_mov_b32 s6, 0
	s_nop 0
	v_readfirstlane_b32 s86, v150
	v_readfirstlane_b32 s87, v151
	v_readfirstlane_b32 s88, v152
	v_readfirstlane_b32 s89, v153
	v_readfirstlane_b32 s90, v146
	v_readfirstlane_b32 s91, v147
	v_readfirstlane_b32 s92, v148
	v_readfirstlane_b32 s93, v149
	v_readfirstlane_b32 s100, v138
	v_readfirstlane_b32 s101, v156
	v_add_u32_e32 v230, s67, v141
	v_add_u32_e32 v231, s68, v141
	v_add_u32_e32 v232, 0x18000, v141
	v_add_u32_e32 v233, 0x1c000, v141
	s_add_u32 s98, s86, 0x100
	s_addc_u32 s99, s87, 0
	s_cmp_eq_u32 s6, s100
	s_cselect_b64 s[94:95], s[90:91], s[98:99]
	s_cselect_b64 s[96:97], s[92:93], s[88:89]
	ds_read_b128 v[164:167], v230
	ds_read_b128 v[168:171], v230 offset:1024
	ds_read_b128 v[172:175], v230 offset:2048
	ds_read_b128 v[176:179], v230 offset:3072
	ds_read_b128 v[180:183], v231
	ds_read_b128 v[184:187], v231 offset:1024
	ds_read_b128 v[188:191], v231 offset:2048
	ds_read_b128 v[192:195], v231 offset:3072
	s_add_i32 s7, s6, 2
	s_nop 0
	s_add_i32 m0, s46, 0xc000
	ds_read_b128 v[196:199], v160
	ds_read_b128 v[200:203], v160 offset:1024
	ds_read_b128 v[204:207], v160 offset:2048
	ds_read_b128 v[208:211], v160 offset:3072
	ds_read_b128 v[212:215], v160 offset:4096
	ds_read_b128 v[216:219], v160 offset:5120
	ds_read_b128 v[220:223], v160 offset:6144
	ds_read_b128 v[224:227], v160 offset:7168
	global_load_lds_dwordx4 v144, s[86:87]
	s_add_i32 m0, s46, 0xe000
	s_nop 0
	global_load_lds_dwordx4 v142, s[86:87]
	s_waitcnt vmcnt(8)
	s_waitcnt lgkmcnt(0)
	s_barrier
	s_setprio 1
	s_waitcnt lgkmcnt(0)
	v_mfma_f32_16x16x32_bf16 v[122:125], v[164:167], v[196:199], 0
	v_mfma_f32_16x16x32_bf16 v[118:121], v[172:175], v[196:199], 0
	v_mfma_f32_16x16x32_bf16 v[110:113], v[164:167], v[204:207], 0
	v_mfma_f32_16x16x32_bf16 v[102:105], v[172:175], v[204:207], 0
	v_mfma_f32_16x16x32_bf16 v[94:97], v[164:167], v[212:215], 0
	v_mfma_f32_16x16x32_bf16 v[86:89], v[172:175], v[212:215], 0
	v_mfma_f32_16x16x32_bf16 v[78:81], v[164:167], v[220:223], 0
	v_mfma_f32_16x16x32_bf16 v[70:73], v[172:175], v[220:223], 0
	v_mfma_f32_16x16x32_bf16 v[122:125], v[168:171], v[200:203], v[122:125]
	v_mfma_f32_16x16x32_bf16 v[118:121], v[176:179], v[200:203], v[118:121]
	v_mfma_f32_16x16x32_bf16 v[110:113], v[168:171], v[208:211], v[110:113]
	v_mfma_f32_16x16x32_bf16 v[102:105], v[176:179], v[208:211], v[102:105]
	v_mfma_f32_16x16x32_bf16 v[94:97], v[168:171], v[216:219], v[94:97]
	v_mfma_f32_16x16x32_bf16 v[86:89], v[176:179], v[216:219], v[86:89]
	v_mfma_f32_16x16x32_bf16 v[78:81], v[168:171], v[224:227], v[78:81]
	v_mfma_f32_16x16x32_bf16 v[70:73], v[176:179], v[224:227], v[70:73]
	s_setprio 0
	s_setprio 1
	v_mfma_f32_16x16x32_bf16 v[126:129], v[180:183], v[196:199], 0
	v_mfma_f32_16x16x32_bf16 v[114:117], v[188:191], v[196:199], 0
	v_mfma_f32_16x16x32_bf16 v[106:109], v[180:183], v[204:207], 0
	v_mfma_f32_16x16x32_bf16 v[98:101], v[188:191], v[204:207], 0
	v_mfma_f32_16x16x32_bf16 v[90:93], v[180:183], v[212:215], 0
	v_mfma_f32_16x16x32_bf16 v[82:85], v[188:191], v[212:215], 0
	v_mfma_f32_16x16x32_bf16 v[74:77], v[180:183], v[220:223], 0
	v_mfma_f32_16x16x32_bf16 v[66:69], v[188:191], v[220:223], 0
	v_mfma_f32_16x16x32_bf16 v[126:129], v[184:187], v[200:203], v[126:129]
	v_mfma_f32_16x16x32_bf16 v[114:117], v[192:195], v[200:203], v[114:117]
	v_mfma_f32_16x16x32_bf16 v[106:109], v[184:187], v[208:211], v[106:109]
	v_mfma_f32_16x16x32_bf16 v[98:101], v[192:195], v[208:211], v[98:101]
	v_mfma_f32_16x16x32_bf16 v[90:93], v[184:187], v[216:219], v[90:93]
	v_mfma_f32_16x16x32_bf16 v[82:85], v[192:195], v[216:219], v[82:85]
	v_mfma_f32_16x16x32_bf16 v[74:77], v[184:187], v[224:227], v[74:77]
	v_mfma_f32_16x16x32_bf16 v[66:69], v[192:195], v[224:227], v[66:69]
	s_setprio 0
	s_barrier
	s_add_u32 s98, s96, 0xb0000
	s_addc_u32 s99, s97, 0
	s_add_i32 s6, s67, s23
	s_mov_b32 m0, s6
	ds_read_b128 v[196:199], v160 offset:16384
	ds_read_b128 v[200:203], v160 offset:17408
	ds_read_b128 v[204:207], v160 offset:18432
	ds_read_b128 v[208:211], v160 offset:19456
	ds_read_b128 v[212:215], v160 offset:20480
	ds_read_b128 v[216:219], v160 offset:21504
	ds_read_b128 v[220:223], v160 offset:22528
	ds_read_b128 v[224:227], v160 offset:23552
	global_load_lds_dwordx4 v132, s[96:97]
	s_add_i32 m0, s6, 0x2000
	s_add_i32 s6, s68, s23
	global_load_lds_dwordx4 v136, s[96:97]
	s_mov_b32 m0, s6
	s_nop 0
	global_load_lds_dwordx4 v132, s[98:99]
	s_add_i32 m0, s6, 0x2000
	s_nop 0
	global_load_lds_dwordx4 v136, s[98:99]
	s_mov_b32 m0, s46
	s_nop 0
	global_load_lds_dwordx4 v130, s[94:95]
	s_mov_b32 m0, s47
	s_nop 0
	global_load_lds_dwordx4 v134, s[94:95]
	s_waitcnt vmcnt(8)
	s_waitcnt lgkmcnt(0)
	s_barrier
	s_setprio 1
	s_waitcnt lgkmcnt(0)
	v_mfma_f32_16x16x32_bf16 v[62:65], v[164:167], v[196:199], 0
	v_mfma_f32_16x16x32_bf16 v[54:57], v[172:175], v[196:199], 0
	v_mfma_f32_16x16x32_bf16 v[46:49], v[164:167], v[204:207], 0
	v_mfma_f32_16x16x32_bf16 v[38:41], v[172:175], v[204:207], 0
	v_mfma_f32_16x16x32_bf16 v[30:33], v[164:167], v[212:215], 0
	v_mfma_f32_16x16x32_bf16 v[22:25], v[172:175], v[212:215], 0
	v_mfma_f32_16x16x32_bf16 v[14:17], v[164:167], v[220:223], 0
	v_mfma_f32_16x16x32_bf16 v[6:9], v[172:175], v[220:223], 0
	v_mfma_f32_16x16x32_bf16 v[62:65], v[168:171], v[200:203], v[62:65]
	v_mfma_f32_16x16x32_bf16 v[54:57], v[176:179], v[200:203], v[54:57]
	v_mfma_f32_16x16x32_bf16 v[46:49], v[168:171], v[208:211], v[46:49]
	v_mfma_f32_16x16x32_bf16 v[38:41], v[176:179], v[208:211], v[38:41]
	v_mfma_f32_16x16x32_bf16 v[30:33], v[168:171], v[216:219], v[30:33]
	v_mfma_f32_16x16x32_bf16 v[22:25], v[176:179], v[216:219], v[22:25]
	v_mfma_f32_16x16x32_bf16 v[14:17], v[168:171], v[224:227], v[14:17]
	v_mfma_f32_16x16x32_bf16 v[6:9], v[176:179], v[224:227], v[6:9]
	s_setprio 0
	s_setprio 1
	v_mfma_f32_16x16x32_bf16 v[58:61], v[180:183], v[196:199], 0
	v_mfma_f32_16x16x32_bf16 v[50:53], v[188:191], v[196:199], 0
	v_mfma_f32_16x16x32_bf16 v[42:45], v[180:183], v[204:207], 0
	v_mfma_f32_16x16x32_bf16 v[34:37], v[188:191], v[204:207], 0
	v_mfma_f32_16x16x32_bf16 v[26:29], v[180:183], v[212:215], 0
	v_mfma_f32_16x16x32_bf16 v[18:21], v[188:191], v[212:215], 0
	v_mfma_f32_16x16x32_bf16 v[10:13], v[180:183], v[220:223], 0
	v_mfma_f32_16x16x32_bf16 v[2:5], v[188:191], v[220:223], 0
	v_mfma_f32_16x16x32_bf16 v[58:61], v[184:187], v[200:203], v[58:61]
	v_mfma_f32_16x16x32_bf16 v[50:53], v[192:195], v[200:203], v[50:53]
	v_mfma_f32_16x16x32_bf16 v[42:45], v[184:187], v[208:211], v[42:45]
	v_mfma_f32_16x16x32_bf16 v[34:37], v[192:195], v[208:211], v[34:37]
	v_mfma_f32_16x16x32_bf16 v[26:29], v[184:187], v[216:219], v[26:29]
	v_mfma_f32_16x16x32_bf16 v[18:21], v[192:195], v[216:219], v[18:21]
	v_mfma_f32_16x16x32_bf16 v[10:13], v[184:187], v[224:227], v[10:13]
	v_mfma_f32_16x16x32_bf16 v[2:5], v[192:195], v[224:227], v[2:5]
	s_setprio 0
	s_barrier
	s_add_u32 s98, s94, 0xb0000
	s_addc_u32 s99, s95, 0
	s_add_i32 s6, 0, 0x18000
	s_add_i32 s29, 0, 0x1c000
	ds_read_b128 v[164:167], v232
	ds_read_b128 v[168:171], v232 offset:1024
	ds_read_b128 v[172:175], v232 offset:2048
	ds_read_b128 v[176:179], v232 offset:3072
	ds_read_b128 v[180:183], v233
	ds_read_b128 v[184:187], v233 offset:1024
	ds_read_b128 v[188:191], v233 offset:2048
	ds_read_b128 v[192:195], v233 offset:3072
	s_mov_b32 m0, s48
	ds_read_b128 v[196:199], v160 offset:32768
	ds_read_b128 v[200:203], v160 offset:33792
	ds_read_b128 v[204:207], v160 offset:34816
	ds_read_b128 v[208:211], v160 offset:35840
	ds_read_b128 v[212:215], v160 offset:36864
	ds_read_b128 v[216:219], v160 offset:37888
	ds_read_b128 v[220:223], v160 offset:38912
	ds_read_b128 v[224:227], v160 offset:39936
	global_load_lds_dwordx4 v130, s[98:99]
	s_mov_b32 m0, s49
	s_nop 0
	global_load_lds_dwordx4 v134, s[98:99]
	s_waitcnt vmcnt(8)
	s_waitcnt lgkmcnt(0)
	s_barrier
	s_setprio 1
	s_waitcnt lgkmcnt(0)
	v_mfma_f32_16x16x32_bf16 v[122:125], v[164:167], v[196:199], v[122:125]
	v_mfma_f32_16x16x32_bf16 v[118:121], v[172:175], v[196:199], v[118:121]
	v_mfma_f32_16x16x32_bf16 v[110:113], v[164:167], v[204:207], v[110:113]
	v_mfma_f32_16x16x32_bf16 v[102:105], v[172:175], v[204:207], v[102:105]
	v_mfma_f32_16x16x32_bf16 v[94:97], v[164:167], v[212:215], v[94:97]
	v_mfma_f32_16x16x32_bf16 v[86:89], v[172:175], v[212:215], v[86:89]
	v_mfma_f32_16x16x32_bf16 v[78:81], v[164:167], v[220:223], v[78:81]
	v_mfma_f32_16x16x32_bf16 v[70:73], v[172:175], v[220:223], v[70:73]
	v_mfma_f32_16x16x32_bf16 v[122:125], v[168:171], v[200:203], v[122:125]
	v_mfma_f32_16x16x32_bf16 v[118:121], v[176:179], v[200:203], v[118:121]
	v_mfma_f32_16x16x32_bf16 v[110:113], v[168:171], v[208:211], v[110:113]
	v_mfma_f32_16x16x32_bf16 v[102:105], v[176:179], v[208:211], v[102:105]
	v_mfma_f32_16x16x32_bf16 v[94:97], v[168:171], v[216:219], v[94:97]
	v_mfma_f32_16x16x32_bf16 v[86:89], v[176:179], v[216:219], v[86:89]
	v_mfma_f32_16x16x32_bf16 v[78:81], v[168:171], v[224:227], v[78:81]
	v_mfma_f32_16x16x32_bf16 v[70:73], v[176:179], v[224:227], v[70:73]
	s_setprio 0
	s_setprio 1
	v_mfma_f32_16x16x32_bf16 v[126:129], v[180:183], v[196:199], v[126:129]
	v_mfma_f32_16x16x32_bf16 v[114:117], v[188:191], v[196:199], v[114:117]
	v_mfma_f32_16x16x32_bf16 v[106:109], v[180:183], v[204:207], v[106:109]
	v_mfma_f32_16x16x32_bf16 v[98:101], v[188:191], v[204:207], v[98:101]
	v_mfma_f32_16x16x32_bf16 v[90:93], v[180:183], v[212:215], v[90:93]
	v_mfma_f32_16x16x32_bf16 v[82:85], v[188:191], v[212:215], v[82:85]
	v_mfma_f32_16x16x32_bf16 v[74:77], v[180:183], v[220:223], v[74:77]
	v_mfma_f32_16x16x32_bf16 v[66:69], v[188:191], v[220:223], v[66:69]
	v_mfma_f32_16x16x32_bf16 v[126:129], v[184:187], v[200:203], v[126:129]
	v_mfma_f32_16x16x32_bf16 v[114:117], v[192:195], v[200:203], v[114:117]
	v_mfma_f32_16x16x32_bf16 v[106:109], v[184:187], v[208:211], v[106:109]
	v_mfma_f32_16x16x32_bf16 v[98:101], v[192:195], v[208:211], v[98:101]
	v_mfma_f32_16x16x32_bf16 v[90:93], v[184:187], v[216:219], v[90:93]
	v_mfma_f32_16x16x32_bf16 v[82:85], v[192:195], v[216:219], v[82:85]
	v_mfma_f32_16x16x32_bf16 v[74:77], v[184:187], v[224:227], v[74:77]
	v_mfma_f32_16x16x32_bf16 v[66:69], v[192:195], v[224:227], v[66:69]
	s_setprio 0
	s_barrier
	s_add_u32 s96, s96, 0x80
	s_addc_u32 s97, s97, 0
	s_add_u32 s98, s96, 0xb0000
	s_addc_u32 s99, s97, 0
	s_add_u32 s94, s94, 0x80
	s_addc_u32 s95, s95, 0
	s_add_i32 s6, s6, s23
	s_mov_b32 m0, s6
	ds_read_b128 v[196:199], v160 offset:49152
	ds_read_b128 v[200:203], v160 offset:50176
	ds_read_b128 v[204:207], v160 offset:51200
	ds_read_b128 v[208:211], v160 offset:52224
	ds_read_b128 v[212:215], v160 offset:53248
	ds_read_b128 v[216:219], v160 offset:54272
	ds_read_b128 v[220:223], v160 offset:55296
	ds_read_b128 v[224:227], v160 offset:56320
	global_load_lds_dwordx4 v132, s[96:97]
	s_add_i32 m0, s6, 0x2000
	s_add_i32 s6, s29, s23
	global_load_lds_dwordx4 v136, s[96:97]
	s_mov_b32 m0, s6
	s_nop 0
	global_load_lds_dwordx4 v132, s[98:99]
	s_add_i32 m0, s6, 0x2000
	s_nop 0
	global_load_lds_dwordx4 v136, s[98:99]
	s_mov_b32 m0, s59
	s_nop 0
	global_load_lds_dwordx4 v130, s[94:95]
	s_mov_b32 m0, s60
	s_nop 0
	global_load_lds_dwordx4 v134, s[94:95]
	s_waitcnt vmcnt(8)
	s_waitcnt lgkmcnt(0)
	s_barrier
	s_setprio 1
	s_waitcnt lgkmcnt(0)
	v_mfma_f32_16x16x32_bf16 v[62:65], v[164:167], v[196:199], v[62:65]
	v_mfma_f32_16x16x32_bf16 v[54:57], v[172:175], v[196:199], v[54:57]
	v_mfma_f32_16x16x32_bf16 v[46:49], v[164:167], v[204:207], v[46:49]
	v_mfma_f32_16x16x32_bf16 v[38:41], v[172:175], v[204:207], v[38:41]
	v_mfma_f32_16x16x32_bf16 v[30:33], v[164:167], v[212:215], v[30:33]
	v_mfma_f32_16x16x32_bf16 v[22:25], v[172:175], v[212:215], v[22:25]
	v_mfma_f32_16x16x32_bf16 v[14:17], v[164:167], v[220:223], v[14:17]
	v_mfma_f32_16x16x32_bf16 v[6:9], v[172:175], v[220:223], v[6:9]
	v_mfma_f32_16x16x32_bf16 v[62:65], v[168:171], v[200:203], v[62:65]
	v_mfma_f32_16x16x32_bf16 v[54:57], v[176:179], v[200:203], v[54:57]
	v_mfma_f32_16x16x32_bf16 v[46:49], v[168:171], v[208:211], v[46:49]
	v_mfma_f32_16x16x32_bf16 v[38:41], v[176:179], v[208:211], v[38:41]
	v_mfma_f32_16x16x32_bf16 v[30:33], v[168:171], v[216:219], v[30:33]
	v_mfma_f32_16x16x32_bf16 v[22:25], v[176:179], v[216:219], v[22:25]
	v_mfma_f32_16x16x32_bf16 v[14:17], v[168:171], v[224:227], v[14:17]
	v_mfma_f32_16x16x32_bf16 v[6:9], v[176:179], v[224:227], v[6:9]
	s_setprio 0
	s_setprio 1
	v_mfma_f32_16x16x32_bf16 v[58:61], v[180:183], v[196:199], v[58:61]
	v_mfma_f32_16x16x32_bf16 v[50:53], v[188:191], v[196:199], v[50:53]
	v_mfma_f32_16x16x32_bf16 v[42:45], v[180:183], v[204:207], v[42:45]
	v_mfma_f32_16x16x32_bf16 v[34:37], v[188:191], v[204:207], v[34:37]
	v_mfma_f32_16x16x32_bf16 v[26:29], v[180:183], v[212:215], v[26:29]
	v_mfma_f32_16x16x32_bf16 v[18:21], v[188:191], v[212:215], v[18:21]
	v_mfma_f32_16x16x32_bf16 v[10:13], v[180:183], v[220:223], v[10:13]
	v_mfma_f32_16x16x32_bf16 v[2:5], v[188:191], v[220:223], v[2:5]
	v_mfma_f32_16x16x32_bf16 v[58:61], v[184:187], v[200:203], v[58:61]
	v_mfma_f32_16x16x32_bf16 v[50:53], v[192:195], v[200:203], v[50:53]
	v_mfma_f32_16x16x32_bf16 v[42:45], v[184:187], v[208:211], v[42:45]
	v_mfma_f32_16x16x32_bf16 v[34:37], v[192:195], v[208:211], v[34:37]
	v_mfma_f32_16x16x32_bf16 v[26:29], v[184:187], v[216:219], v[26:29]
	v_mfma_f32_16x16x32_bf16 v[18:21], v[192:195], v[216:219], v[18:21]
	v_mfma_f32_16x16x32_bf16 v[10:13], v[184:187], v[224:227], v[10:13]
	v_mfma_f32_16x16x32_bf16 v[2:5], v[192:195], v[224:227], v[2:5]
	s_setprio 0
	s_barrier
	s_mov_b32 s6, s7
	s_add_u32 s88, s88, 0x100
	s_addc_u32 s89, s89, 0
	s_add_u32 s86, s86, 0x100
	s_addc_u32 s87, s87, 0
	s_cmp_ge_i32 s7, s101
	s_cbranch_scc1 .Lmy_kexit_5
.LBB0_1080:
	s_add_u32 s98, s86, 0x100
	s_addc_u32 s99, s87, 0
	s_cmp_eq_u32 s6, s100
	s_cselect_b64 s[94:95], s[90:91], s[98:99]
	s_cselect_b64 s[96:97], s[92:93], s[88:89]
	ds_read_b128 v[164:167], v230
	ds_read_b128 v[168:171], v230 offset:1024
	ds_read_b128 v[172:175], v230 offset:2048
	ds_read_b128 v[176:179], v230 offset:3072
	ds_read_b128 v[180:183], v231
	ds_read_b128 v[184:187], v231 offset:1024
	ds_read_b128 v[188:191], v231 offset:2048
	ds_read_b128 v[192:195], v231 offset:3072
	s_add_i32 s7, s6, 2
	s_nop 0
	s_add_i32 m0, s46, 0xc000
	ds_read_b128 v[196:199], v160
	ds_read_b128 v[200:203], v160 offset:1024
	ds_read_b128 v[204:207], v160 offset:2048
	ds_read_b128 v[208:211], v160 offset:3072
	ds_read_b128 v[212:215], v160 offset:4096
	ds_read_b128 v[216:219], v160 offset:5120
	ds_read_b128 v[220:223], v160 offset:6144
	ds_read_b128 v[224:227], v160 offset:7168
	global_load_lds_dwordx4 v144, s[86:87]
	s_add_i32 m0, s46, 0xe000
	s_nop 0
	global_load_lds_dwordx4 v142, s[86:87]
	s_waitcnt vmcnt(8)
	s_waitcnt lgkmcnt(0)
	s_barrier
	s_setprio 1
	s_waitcnt lgkmcnt(0)
	v_mfma_f32_16x16x32_bf16 v[122:125], v[164:167], v[196:199], v[122:125]
	v_mfma_f32_16x16x32_bf16 v[118:121], v[172:175], v[196:199], v[118:121]
	v_mfma_f32_16x16x32_bf16 v[110:113], v[164:167], v[204:207], v[110:113]
	v_mfma_f32_16x16x32_bf16 v[102:105], v[172:175], v[204:207], v[102:105]
	v_mfma_f32_16x16x32_bf16 v[94:97], v[164:167], v[212:215], v[94:97]
	v_mfma_f32_16x16x32_bf16 v[86:89], v[172:175], v[212:215], v[86:89]
	v_mfma_f32_16x16x32_bf16 v[78:81], v[164:167], v[220:223], v[78:81]
	v_mfma_f32_16x16x32_bf16 v[70:73], v[172:175], v[220:223], v[70:73]
	v_mfma_f32_16x16x32_bf16 v[122:125], v[168:171], v[200:203], v[122:125]
	v_mfma_f32_16x16x32_bf16 v[118:121], v[176:179], v[200:203], v[118:121]
	v_mfma_f32_16x16x32_bf16 v[110:113], v[168:171], v[208:211], v[110:113]
	v_mfma_f32_16x16x32_bf16 v[102:105], v[176:179], v[208:211], v[102:105]
	v_mfma_f32_16x16x32_bf16 v[94:97], v[168:171], v[216:219], v[94:97]
	v_mfma_f32_16x16x32_bf16 v[86:89], v[176:179], v[216:219], v[86:89]
	v_mfma_f32_16x16x32_bf16 v[78:81], v[168:171], v[224:227], v[78:81]
	v_mfma_f32_16x16x32_bf16 v[70:73], v[176:179], v[224:227], v[70:73]
	s_setprio 0
	s_setprio 1
	v_mfma_f32_16x16x32_bf16 v[126:129], v[180:183], v[196:199], v[126:129]
	v_mfma_f32_16x16x32_bf16 v[114:117], v[188:191], v[196:199], v[114:117]
	v_mfma_f32_16x16x32_bf16 v[106:109], v[180:183], v[204:207], v[106:109]
	v_mfma_f32_16x16x32_bf16 v[98:101], v[188:191], v[204:207], v[98:101]
	v_mfma_f32_16x16x32_bf16 v[90:93], v[180:183], v[212:215], v[90:93]
	v_mfma_f32_16x16x32_bf16 v[82:85], v[188:191], v[212:215], v[82:85]
	v_mfma_f32_16x16x32_bf16 v[74:77], v[180:183], v[220:223], v[74:77]
	v_mfma_f32_16x16x32_bf16 v[66:69], v[188:191], v[220:223], v[66:69]
	v_mfma_f32_16x16x32_bf16 v[126:129], v[184:187], v[200:203], v[126:129]
	v_mfma_f32_16x16x32_bf16 v[114:117], v[192:195], v[200:203], v[114:117]
	v_mfma_f32_16x16x32_bf16 v[106:109], v[184:187], v[208:211], v[106:109]
	v_mfma_f32_16x16x32_bf16 v[98:101], v[192:195], v[208:211], v[98:101]
	v_mfma_f32_16x16x32_bf16 v[90:93], v[184:187], v[216:219], v[90:93]
	v_mfma_f32_16x16x32_bf16 v[82:85], v[192:195], v[216:219], v[82:85]
	v_mfma_f32_16x16x32_bf16 v[74:77], v[184:187], v[224:227], v[74:77]
	v_mfma_f32_16x16x32_bf16 v[66:69], v[192:195], v[224:227], v[66:69]
	s_setprio 0
	s_barrier
	s_add_u32 s98, s96, 0xb0000
	s_addc_u32 s99, s97, 0
	s_add_i32 s6, s67, s23
	s_mov_b32 m0, s6
	ds_read_b128 v[196:199], v160 offset:16384
	ds_read_b128 v[200:203], v160 offset:17408
	ds_read_b128 v[204:207], v160 offset:18432
	ds_read_b128 v[208:211], v160 offset:19456
	ds_read_b128 v[212:215], v160 offset:20480
	ds_read_b128 v[216:219], v160 offset:21504
	ds_read_b128 v[220:223], v160 offset:22528
	ds_read_b128 v[224:227], v160 offset:23552
	global_load_lds_dwordx4 v132, s[96:97]
	s_add_i32 m0, s6, 0x2000
	s_add_i32 s6, s68, s23
	global_load_lds_dwordx4 v136, s[96:97]
	s_mov_b32 m0, s6
	s_nop 0
	global_load_lds_dwordx4 v132, s[98:99]
	s_add_i32 m0, s6, 0x2000
	s_nop 0
	global_load_lds_dwordx4 v136, s[98:99]
	s_mov_b32 m0, s46
	s_nop 0
	global_load_lds_dwordx4 v130, s[94:95]
	s_mov_b32 m0, s47
	s_nop 0
	global_load_lds_dwordx4 v134, s[94:95]
	s_waitcnt vmcnt(8)
	s_waitcnt lgkmcnt(0)
	s_barrier
	s_setprio 1
	s_waitcnt lgkmcnt(0)
	v_mfma_f32_16x16x32_bf16 v[62:65], v[164:167], v[196:199], v[62:65]
	v_mfma_f32_16x16x32_bf16 v[54:57], v[172:175], v[196:199], v[54:57]
	v_mfma_f32_16x16x32_bf16 v[46:49], v[164:167], v[204:207], v[46:49]
	v_mfma_f32_16x16x32_bf16 v[38:41], v[172:175], v[204:207], v[38:41]
	v_mfma_f32_16x16x32_bf16 v[30:33], v[164:167], v[212:215], v[30:33]
	v_mfma_f32_16x16x32_bf16 v[22:25], v[172:175], v[212:215], v[22:25]
	v_mfma_f32_16x16x32_bf16 v[14:17], v[164:167], v[220:223], v[14:17]
	v_mfma_f32_16x16x32_bf16 v[6:9], v[172:175], v[220:223], v[6:9]
	v_mfma_f32_16x16x32_bf16 v[62:65], v[168:171], v[200:203], v[62:65]
	v_mfma_f32_16x16x32_bf16 v[54:57], v[176:179], v[200:203], v[54:57]
	v_mfma_f32_16x16x32_bf16 v[46:49], v[168:171], v[208:211], v[46:49]
	v_mfma_f32_16x16x32_bf16 v[38:41], v[176:179], v[208:211], v[38:41]
	v_mfma_f32_16x16x32_bf16 v[30:33], v[168:171], v[216:219], v[30:33]
	v_mfma_f32_16x16x32_bf16 v[22:25], v[176:179], v[216:219], v[22:25]
	v_mfma_f32_16x16x32_bf16 v[14:17], v[168:171], v[224:227], v[14:17]
	v_mfma_f32_16x16x32_bf16 v[6:9], v[176:179], v[224:227], v[6:9]
	s_setprio 0
	s_setprio 1
	v_mfma_f32_16x16x32_bf16 v[58:61], v[180:183], v[196:199], v[58:61]
	v_mfma_f32_16x16x32_bf16 v[50:53], v[188:191], v[196:199], v[50:53]
	v_mfma_f32_16x16x32_bf16 v[42:45], v[180:183], v[204:207], v[42:45]
	v_mfma_f32_16x16x32_bf16 v[34:37], v[188:191], v[204:207], v[34:37]
	v_mfma_f32_16x16x32_bf16 v[26:29], v[180:183], v[212:215], v[26:29]
	v_mfma_f32_16x16x32_bf16 v[18:21], v[188:191], v[212:215], v[18:21]
	v_mfma_f32_16x16x32_bf16 v[10:13], v[180:183], v[220:223], v[10:13]
	v_mfma_f32_16x16x32_bf16 v[2:5], v[188:191], v[220:223], v[2:5]
	v_mfma_f32_16x16x32_bf16 v[58:61], v[184:187], v[200:203], v[58:61]
	v_mfma_f32_16x16x32_bf16 v[50:53], v[192:195], v[200:203], v[50:53]
	v_mfma_f32_16x16x32_bf16 v[42:45], v[184:187], v[208:211], v[42:45]
	v_mfma_f32_16x16x32_bf16 v[34:37], v[192:195], v[208:211], v[34:37]
	v_mfma_f32_16x16x32_bf16 v[26:29], v[184:187], v[216:219], v[26:29]
	v_mfma_f32_16x16x32_bf16 v[18:21], v[192:195], v[216:219], v[18:21]
	v_mfma_f32_16x16x32_bf16 v[10:13], v[184:187], v[224:227], v[10:13]
	v_mfma_f32_16x16x32_bf16 v[2:5], v[192:195], v[224:227], v[2:5]
	s_setprio 0
	s_barrier
	s_add_u32 s98, s94, 0xb0000
	s_addc_u32 s99, s95, 0
	s_add_i32 s6, 0, 0x18000
	s_add_i32 s29, 0, 0x1c000
	ds_read_b128 v[164:167], v232
	ds_read_b128 v[168:171], v232 offset:1024
	ds_read_b128 v[172:175], v232 offset:2048
	ds_read_b128 v[176:179], v232 offset:3072
	ds_read_b128 v[180:183], v233
	ds_read_b128 v[184:187], v233 offset:1024
	ds_read_b128 v[188:191], v233 offset:2048
	ds_read_b128 v[192:195], v233 offset:3072
	s_mov_b32 m0, s48
	ds_read_b128 v[196:199], v160 offset:32768
	ds_read_b128 v[200:203], v160 offset:33792
	ds_read_b128 v[204:207], v160 offset:34816
	ds_read_b128 v[208:211], v160 offset:35840
	ds_read_b128 v[212:215], v160 offset:36864
	ds_read_b128 v[216:219], v160 offset:37888
	ds_read_b128 v[220:223], v160 offset:38912
	ds_read_b128 v[224:227], v160 offset:39936
	global_load_lds_dwordx4 v130, s[98:99]
	s_mov_b32 m0, s49
	s_nop 0
	global_load_lds_dwordx4 v134, s[98:99]
	s_waitcnt vmcnt(8)
	s_waitcnt lgkmcnt(0)
	s_barrier
	s_setprio 1
	s_waitcnt lgkmcnt(0)
	v_mfma_f32_16x16x32_bf16 v[122:125], v[164:167], v[196:199], v[122:125]
	v_mfma_f32_16x16x32_bf16 v[118:121], v[172:175], v[196:199], v[118:121]
	v_mfma_f32_16x16x32_bf16 v[110:113], v[164:167], v[204:207], v[110:113]
	v_mfma_f32_16x16x32_bf16 v[102:105], v[172:175], v[204:207], v[102:105]
	v_mfma_f32_16x16x32_bf16 v[94:97], v[164:167], v[212:215], v[94:97]
	v_mfma_f32_16x16x32_bf16 v[86:89], v[172:175], v[212:215], v[86:89]
	v_mfma_f32_16x16x32_bf16 v[78:81], v[164:167], v[220:223], v[78:81]
	v_mfma_f32_16x16x32_bf16 v[70:73], v[172:175], v[220:223], v[70:73]
	v_mfma_f32_16x16x32_bf16 v[122:125], v[168:171], v[200:203], v[122:125]
	v_mfma_f32_16x16x32_bf16 v[118:121], v[176:179], v[200:203], v[118:121]
	v_mfma_f32_16x16x32_bf16 v[110:113], v[168:171], v[208:211], v[110:113]
	v_mfma_f32_16x16x32_bf16 v[102:105], v[176:179], v[208:211], v[102:105]
	v_mfma_f32_16x16x32_bf16 v[94:97], v[168:171], v[216:219], v[94:97]
	v_mfma_f32_16x16x32_bf16 v[86:89], v[176:179], v[216:219], v[86:89]
	v_mfma_f32_16x16x32_bf16 v[78:81], v[168:171], v[224:227], v[78:81]
	v_mfma_f32_16x16x32_bf16 v[70:73], v[176:179], v[224:227], v[70:73]
	s_setprio 0
	s_setprio 1
	v_mfma_f32_16x16x32_bf16 v[126:129], v[180:183], v[196:199], v[126:129]
	v_mfma_f32_16x16x32_bf16 v[114:117], v[188:191], v[196:199], v[114:117]
	v_mfma_f32_16x16x32_bf16 v[106:109], v[180:183], v[204:207], v[106:109]
	v_mfma_f32_16x16x32_bf16 v[98:101], v[188:191], v[204:207], v[98:101]
	v_mfma_f32_16x16x32_bf16 v[90:93], v[180:183], v[212:215], v[90:93]
	v_mfma_f32_16x16x32_bf16 v[82:85], v[188:191], v[212:215], v[82:85]
	v_mfma_f32_16x16x32_bf16 v[74:77], v[180:183], v[220:223], v[74:77]
	v_mfma_f32_16x16x32_bf16 v[66:69], v[188:191], v[220:223], v[66:69]
	v_mfma_f32_16x16x32_bf16 v[126:129], v[184:187], v[200:203], v[126:129]
	v_mfma_f32_16x16x32_bf16 v[114:117], v[192:195], v[200:203], v[114:117]
	v_mfma_f32_16x16x32_bf16 v[106:109], v[184:187], v[208:211], v[106:109]
	v_mfma_f32_16x16x32_bf16 v[98:101], v[192:195], v[208:211], v[98:101]
	v_mfma_f32_16x16x32_bf16 v[90:93], v[184:187], v[216:219], v[90:93]
	v_mfma_f32_16x16x32_bf16 v[82:85], v[192:195], v[216:219], v[82:85]
	v_mfma_f32_16x16x32_bf16 v[74:77], v[184:187], v[224:227], v[74:77]
	v_mfma_f32_16x16x32_bf16 v[66:69], v[192:195], v[224:227], v[66:69]
	s_setprio 0
	s_barrier
	s_add_u32 s96, s96, 0x80
	s_addc_u32 s97, s97, 0
	s_add_u32 s98, s96, 0xb0000
	s_addc_u32 s99, s97, 0
	s_add_u32 s94, s94, 0x80
	s_addc_u32 s95, s95, 0
	s_add_i32 s6, s6, s23
	s_mov_b32 m0, s6
	ds_read_b128 v[196:199], v160 offset:49152
	ds_read_b128 v[200:203], v160 offset:50176
	ds_read_b128 v[204:207], v160 offset:51200
	ds_read_b128 v[208:211], v160 offset:52224
	ds_read_b128 v[212:215], v160 offset:53248
	ds_read_b128 v[216:219], v160 offset:54272
	ds_read_b128 v[220:223], v160 offset:55296
	ds_read_b128 v[224:227], v160 offset:56320
	global_load_lds_dwordx4 v132, s[96:97]
	s_add_i32 m0, s6, 0x2000
	s_add_i32 s6, s29, s23
	global_load_lds_dwordx4 v136, s[96:97]
	s_mov_b32 m0, s6
	s_nop 0
	global_load_lds_dwordx4 v132, s[98:99]
	s_add_i32 m0, s6, 0x2000
	s_nop 0
	global_load_lds_dwordx4 v136, s[98:99]
	s_mov_b32 m0, s59
	s_nop 0
	global_load_lds_dwordx4 v130, s[94:95]
	s_mov_b32 m0, s60
	s_nop 0
	global_load_lds_dwordx4 v134, s[94:95]
	s_waitcnt vmcnt(8)
	s_waitcnt lgkmcnt(0)
	s_barrier
	s_setprio 1
	s_waitcnt lgkmcnt(0)
	v_mfma_f32_16x16x32_bf16 v[62:65], v[164:167], v[196:199], v[62:65]
	v_mfma_f32_16x16x32_bf16 v[54:57], v[172:175], v[196:199], v[54:57]
	v_mfma_f32_16x16x32_bf16 v[46:49], v[164:167], v[204:207], v[46:49]
	v_mfma_f32_16x16x32_bf16 v[38:41], v[172:175], v[204:207], v[38:41]
	v_mfma_f32_16x16x32_bf16 v[30:33], v[164:167], v[212:215], v[30:33]
	v_mfma_f32_16x16x32_bf16 v[22:25], v[172:175], v[212:215], v[22:25]
	v_mfma_f32_16x16x32_bf16 v[14:17], v[164:167], v[220:223], v[14:17]
	v_mfma_f32_16x16x32_bf16 v[6:9], v[172:175], v[220:223], v[6:9]
	v_mfma_f32_16x16x32_bf16 v[62:65], v[168:171], v[200:203], v[62:65]
	v_mfma_f32_16x16x32_bf16 v[54:57], v[176:179], v[200:203], v[54:57]
	v_mfma_f32_16x16x32_bf16 v[46:49], v[168:171], v[208:211], v[46:49]
	v_mfma_f32_16x16x32_bf16 v[38:41], v[176:179], v[208:211], v[38:41]
	v_mfma_f32_16x16x32_bf16 v[30:33], v[168:171], v[216:219], v[30:33]
	v_mfma_f32_16x16x32_bf16 v[22:25], v[176:179], v[216:219], v[22:25]
	v_mfma_f32_16x16x32_bf16 v[14:17], v[168:171], v[224:227], v[14:17]
	v_mfma_f32_16x16x32_bf16 v[6:9], v[176:179], v[224:227], v[6:9]
	s_setprio 0
	s_setprio 1
	v_mfma_f32_16x16x32_bf16 v[58:61], v[180:183], v[196:199], v[58:61]
	v_mfma_f32_16x16x32_bf16 v[50:53], v[188:191], v[196:199], v[50:53]
	v_mfma_f32_16x16x32_bf16 v[42:45], v[180:183], v[204:207], v[42:45]
	v_mfma_f32_16x16x32_bf16 v[34:37], v[188:191], v[204:207], v[34:37]
	v_mfma_f32_16x16x32_bf16 v[26:29], v[180:183], v[212:215], v[26:29]
	v_mfma_f32_16x16x32_bf16 v[18:21], v[188:191], v[212:215], v[18:21]
	v_mfma_f32_16x16x32_bf16 v[10:13], v[180:183], v[220:223], v[10:13]
	v_mfma_f32_16x16x32_bf16 v[2:5], v[188:191], v[220:223], v[2:5]
	v_mfma_f32_16x16x32_bf16 v[58:61], v[184:187], v[200:203], v[58:61]
	v_mfma_f32_16x16x32_bf16 v[50:53], v[192:195], v[200:203], v[50:53]
	v_mfma_f32_16x16x32_bf16 v[42:45], v[184:187], v[208:211], v[42:45]
	v_mfma_f32_16x16x32_bf16 v[34:37], v[192:195], v[208:211], v[34:37]
	v_mfma_f32_16x16x32_bf16 v[26:29], v[184:187], v[216:219], v[26:29]
	v_mfma_f32_16x16x32_bf16 v[18:21], v[192:195], v[216:219], v[18:21]
	v_mfma_f32_16x16x32_bf16 v[10:13], v[184:187], v[224:227], v[10:13]
	v_mfma_f32_16x16x32_bf16 v[2:5], v[192:195], v[224:227], v[2:5]
	s_setprio 0
	s_barrier
	s_mov_b32 s6, s7
	s_add_u32 s88, s88, 0x100
	s_addc_u32 s89, s89, 0
	s_add_u32 s86, s86, 0x100
	s_addc_u32 s87, s87, 0
	s_cmp_ge_i32 s7, s101
	s_cbranch_scc0 .LBB0_1080

.LBB0_1390:
	v_cmp_gt_i32_e32 vcc, 1, v156
	s_cbranch_vccnz .LBB0_1452
	v_lshl_add_u64 v[152:153], v[2:3], 0, s[20:21]
	v_add_u32_e32 v138, -2, v156
	s_mov_b32 s6, 0
	s_nop 0
	v_readfirstlane_b32 s86, v150
	v_readfirstlane_b32 s87, v151
	v_readfirstlane_b32 s88, v152
	v_readfirstlane_b32 s89, v153
	v_readfirstlane_b32 s90, v146
	v_readfirstlane_b32 s91, v147
	v_readfirstlane_b32 s92, v148
	v_readfirstlane_b32 s93, v149
	v_readfirstlane_b32 s100, v138
	v_readfirstlane_b32 s101, v156
	v_add_u32_e32 v230, s67, v141
	v_add_u32_e32 v231, s70, v141
	v_add_u32_e32 v232, 0x18000, v141
	v_add_u32_e32 v233, 0x1c000, v141
	s_add_u32 s98, s86, 0x100
	s_addc_u32 s99, s87, 0
	s_cmp_eq_u32 s6, s100
	s_cselect_b64 s[94:95], s[90:91], s[98:99]
	s_cselect_b64 s[96:97], s[92:93], s[88:89]
	ds_read_b128 v[164:167], v230
	ds_read_b128 v[168:171], v230 offset:1024
	ds_read_b128 v[172:175], v230 offset:2048
	ds_read_b128 v[176:179], v230 offset:3072
	ds_read_b128 v[180:183], v231
	ds_read_b128 v[184:187], v231 offset:1024
	ds_read_b128 v[188:191], v231 offset:2048
	ds_read_b128 v[192:195], v231 offset:3072
	s_add_i32 s7, s6, 2
	s_nop 0
	s_add_i32 m0, s46, 0xc000
	ds_read_b128 v[196:199], v160
	ds_read_b128 v[200:203], v160 offset:1024
	ds_read_b128 v[204:207], v160 offset:2048
	ds_read_b128 v[208:211], v160 offset:3072
	ds_read_b128 v[212:215], v160 offset:4096
	ds_read_b128 v[216:219], v160 offset:5120
	ds_read_b128 v[220:223], v160 offset:6144
	ds_read_b128 v[224:227], v160 offset:7168
	global_load_lds_dwordx4 v144, s[86:87]
	s_add_i32 m0, s46, 0xe000
	s_nop 0
	global_load_lds_dwordx4 v142, s[86:87]
	s_waitcnt vmcnt(8)
	s_waitcnt lgkmcnt(0)
	s_barrier
	s_setprio 1
	s_waitcnt lgkmcnt(0)
	v_mfma_f32_16x16x32_bf16 v[122:125], v[164:167], v[196:199], 0
	v_mfma_f32_16x16x32_bf16 v[118:121], v[172:175], v[196:199], 0
	v_mfma_f32_16x16x32_bf16 v[110:113], v[164:167], v[204:207], 0
	v_mfma_f32_16x16x32_bf16 v[102:105], v[172:175], v[204:207], 0
	v_mfma_f32_16x16x32_bf16 v[94:97], v[164:167], v[212:215], 0
	v_mfma_f32_16x16x32_bf16 v[86:89], v[172:175], v[212:215], 0
	v_mfma_f32_16x16x32_bf16 v[78:81], v[164:167], v[220:223], 0
	v_mfma_f32_16x16x32_bf16 v[70:73], v[172:175], v[220:223], 0
	v_mfma_f32_16x16x32_bf16 v[122:125], v[168:171], v[200:203], v[122:125]
	v_mfma_f32_16x16x32_bf16 v[118:121], v[176:179], v[200:203], v[118:121]
	v_mfma_f32_16x16x32_bf16 v[110:113], v[168:171], v[208:211], v[110:113]
	v_mfma_f32_16x16x32_bf16 v[102:105], v[176:179], v[208:211], v[102:105]
	v_mfma_f32_16x16x32_bf16 v[94:97], v[168:171], v[216:219], v[94:97]
	v_mfma_f32_16x16x32_bf16 v[86:89], v[176:179], v[216:219], v[86:89]
	v_mfma_f32_16x16x32_bf16 v[78:81], v[168:171], v[224:227], v[78:81]
	v_mfma_f32_16x16x32_bf16 v[70:73], v[176:179], v[224:227], v[70:73]
	s_setprio 0
	s_setprio 1
	v_mfma_f32_16x16x32_bf16 v[126:129], v[180:183], v[196:199], 0
	v_mfma_f32_16x16x32_bf16 v[114:117], v[188:191], v[196:199], 0
	v_mfma_f32_16x16x32_bf16 v[106:109], v[180:183], v[204:207], 0
	v_mfma_f32_16x16x32_bf16 v[98:101], v[188:191], v[204:207], 0
	v_mfma_f32_16x16x32_bf16 v[90:93], v[180:183], v[212:215], 0
	v_mfma_f32_16x16x32_bf16 v[82:85], v[188:191], v[212:215], 0
	v_mfma_f32_16x16x32_bf16 v[74:77], v[180:183], v[220:223], 0
	v_mfma_f32_16x16x32_bf16 v[66:69], v[188:191], v[220:223], 0
	v_mfma_f32_16x16x32_bf16 v[126:129], v[184:187], v[200:203], v[126:129]
	v_mfma_f32_16x16x32_bf16 v[114:117], v[192:195], v[200:203], v[114:117]
	v_mfma_f32_16x16x32_bf16 v[106:109], v[184:187], v[208:211], v[106:109]
	v_mfma_f32_16x16x32_bf16 v[98:101], v[192:195], v[208:211], v[98:101]
	v_mfma_f32_16x16x32_bf16 v[90:93], v[184:187], v[216:219], v[90:93]
	v_mfma_f32_16x16x32_bf16 v[82:85], v[192:195], v[216:219], v[82:85]
	v_mfma_f32_16x16x32_bf16 v[74:77], v[184:187], v[224:227], v[74:77]
	v_mfma_f32_16x16x32_bf16 v[66:69], v[192:195], v[224:227], v[66:69]
	s_setprio 0
	s_barrier
	s_add_u32 s98, s96, 0xb0000
	s_addc_u32 s99, s97, 0
	s_add_i32 s6, s67, s23
	s_mov_b32 m0, s6
	ds_read_b128 v[196:199], v160 offset:16384
	ds_read_b128 v[200:203], v160 offset:17408
	ds_read_b128 v[204:207], v160 offset:18432
	ds_read_b128 v[208:211], v160 offset:19456
	ds_read_b128 v[212:215], v160 offset:20480
	ds_read_b128 v[216:219], v160 offset:21504
	ds_read_b128 v[220:223], v160 offset:22528
	ds_read_b128 v[224:227], v160 offset:23552
	global_load_lds_dwordx4 v132, s[96:97]
	s_add_i32 m0, s6, 0x2000
	s_add_i32 s6, s70, s23
	global_load_lds_dwordx4 v136, s[96:97]
	s_mov_b32 m0, s6
	s_nop 0
	global_load_lds_dwordx4 v132, s[98:99]
	s_add_i32 m0, s6, 0x2000
	s_nop 0
	global_load_lds_dwordx4 v136, s[98:99]
	s_mov_b32 m0, s46
	s_nop 0
	global_load_lds_dwordx4 v130, s[94:95]
	s_mov_b32 m0, s47
	s_nop 0
	global_load_lds_dwordx4 v134, s[94:95]
	s_waitcnt vmcnt(8)
	s_waitcnt lgkmcnt(0)
	s_barrier
	s_setprio 1
	s_waitcnt lgkmcnt(0)
	v_mfma_f32_16x16x32_bf16 v[62:65], v[164:167], v[196:199], 0
	v_mfma_f32_16x16x32_bf16 v[54:57], v[172:175], v[196:199], 0
	v_mfma_f32_16x16x32_bf16 v[46:49], v[164:167], v[204:207], 0
	v_mfma_f32_16x16x32_bf16 v[38:41], v[172:175], v[204:207], 0
	v_mfma_f32_16x16x32_bf16 v[30:33], v[164:167], v[212:215], 0
	v_mfma_f32_16x16x32_bf16 v[22:25], v[172:175], v[212:215], 0
	v_mfma_f32_16x16x32_bf16 v[14:17], v[164:167], v[220:223], 0
	v_mfma_f32_16x16x32_bf16 v[6:9], v[172:175], v[220:223], 0
	v_mfma_f32_16x16x32_bf16 v[62:65], v[168:171], v[200:203], v[62:65]
	v_mfma_f32_16x16x32_bf16 v[54:57], v[176:179], v[200:203], v[54:57]
	v_mfma_f32_16x16x32_bf16 v[46:49], v[168:171], v[208:211], v[46:49]
	v_mfma_f32_16x16x32_bf16 v[38:41], v[176:179], v[208:211], v[38:41]
	v_mfma_f32_16x16x32_bf16 v[30:33], v[168:171], v[216:219], v[30:33]
	v_mfma_f32_16x16x32_bf16 v[22:25], v[176:179], v[216:219], v[22:25]
	v_mfma_f32_16x16x32_bf16 v[14:17], v[168:171], v[224:227], v[14:17]
	v_mfma_f32_16x16x32_bf16 v[6:9], v[176:179], v[224:227], v[6:9]
	s_setprio 0
	s_setprio 1
	v_mfma_f32_16x16x32_bf16 v[58:61], v[180:183], v[196:199], 0
	v_mfma_f32_16x16x32_bf16 v[50:53], v[188:191], v[196:199], 0
	v_mfma_f32_16x16x32_bf16 v[42:45], v[180:183], v[204:207], 0
	v_mfma_f32_16x16x32_bf16 v[34:37], v[188:191], v[204:207], 0
	v_mfma_f32_16x16x32_bf16 v[26:29], v[180:183], v[212:215], 0
	v_mfma_f32_16x16x32_bf16 v[18:21], v[188:191], v[212:215], 0
	v_mfma_f32_16x16x32_bf16 v[10:13], v[180:183], v[220:223], 0
	v_mfma_f32_16x16x32_bf16 v[2:5], v[188:191], v[220:223], 0
	v_mfma_f32_16x16x32_bf16 v[58:61], v[184:187], v[200:203], v[58:61]
	v_mfma_f32_16x16x32_bf16 v[50:53], v[192:195], v[200:203], v[50:53]
	v_mfma_f32_16x16x32_bf16 v[42:45], v[184:187], v[208:211], v[42:45]
	v_mfma_f32_16x16x32_bf16 v[34:37], v[192:195], v[208:211], v[34:37]
	v_mfma_f32_16x16x32_bf16 v[26:29], v[184:187], v[216:219], v[26:29]
	v_mfma_f32_16x16x32_bf16 v[18:21], v[192:195], v[216:219], v[18:21]
	v_mfma_f32_16x16x32_bf16 v[10:13], v[184:187], v[224:227], v[10:13]
	v_mfma_f32_16x16x32_bf16 v[2:5], v[192:195], v[224:227], v[2:5]
	s_setprio 0
	s_barrier
	s_add_u32 s98, s94, 0xb0000
	s_addc_u32 s99, s95, 0
	s_add_i32 s6, 0, 0x18000
	s_add_i32 s29, 0, 0x1c000
	ds_read_b128 v[164:167], v232
	ds_read_b128 v[168:171], v232 offset:1024
	ds_read_b128 v[172:175], v232 offset:2048
	ds_read_b128 v[176:179], v232 offset:3072
	ds_read_b128 v[180:183], v233
	ds_read_b128 v[184:187], v233 offset:1024
	ds_read_b128 v[188:191], v233 offset:2048
	ds_read_b128 v[192:195], v233 offset:3072
	s_mov_b32 m0, s48
	ds_read_b128 v[196:199], v160 offset:32768
	ds_read_b128 v[200:203], v160 offset:33792
	ds_read_b128 v[204:207], v160 offset:34816
	ds_read_b128 v[208:211], v160 offset:35840
	ds_read_b128 v[212:215], v160 offset:36864
	ds_read_b128 v[216:219], v160 offset:37888
	ds_read_b128 v[220:223], v160 offset:38912
	ds_read_b128 v[224:227], v160 offset:39936
	global_load_lds_dwordx4 v130, s[98:99]
	s_mov_b32 m0, s49
	s_nop 0
	global_load_lds_dwordx4 v134, s[98:99]
	s_waitcnt vmcnt(8)
	s_waitcnt lgkmcnt(0)
	s_barrier
	s_setprio 1
	s_waitcnt lgkmcnt(0)
	v_mfma_f32_16x16x32_bf16 v[122:125], v[164:167], v[196:199], v[122:125]
	v_mfma_f32_16x16x32_bf16 v[118:121], v[172:175], v[196:199], v[118:121]
	v_mfma_f32_16x16x32_bf16 v[110:113], v[164:167], v[204:207], v[110:113]
	v_mfma_f32_16x16x32_bf16 v[102:105], v[172:175], v[204:207], v[102:105]
	v_mfma_f32_16x16x32_bf16 v[94:97], v[164:167], v[212:215], v[94:97]
	v_mfma_f32_16x16x32_bf16 v[86:89], v[172:175], v[212:215], v[86:89]
	v_mfma_f32_16x16x32_bf16 v[78:81], v[164:167], v[220:223], v[78:81]
	v_mfma_f32_16x16x32_bf16 v[70:73], v[172:175], v[220:223], v[70:73]
	v_mfma_f32_16x16x32_bf16 v[122:125], v[168:171], v[200:203], v[122:125]
	v_mfma_f32_16x16x32_bf16 v[118:121], v[176:179], v[200:203], v[118:121]
	v_mfma_f32_16x16x32_bf16 v[110:113], v[168:171], v[208:211], v[110:113]
	v_mfma_f32_16x16x32_bf16 v[102:105], v[176:179], v[208:211], v[102:105]
	v_mfma_f32_16x16x32_bf16 v[94:97], v[168:171], v[216:219], v[94:97]
	v_mfma_f32_16x16x32_bf16 v[86:89], v[176:179], v[216:219], v[86:89]
	v_mfma_f32_16x16x32_bf16 v[78:81], v[168:171], v[224:227], v[78:81]
	v_mfma_f32_16x16x32_bf16 v[70:73], v[176:179], v[224:227], v[70:73]
	s_setprio 0
	s_setprio 1
	v_mfma_f32_16x16x32_bf16 v[126:129], v[180:183], v[196:199], v[126:129]
	v_mfma_f32_16x16x32_bf16 v[114:117], v[188:191], v[196:199], v[114:117]
	v_mfma_f32_16x16x32_bf16 v[106:109], v[180:183], v[204:207], v[106:109]
	v_mfma_f32_16x16x32_bf16 v[98:101], v[188:191], v[204:207], v[98:101]
	v_mfma_f32_16x16x32_bf16 v[90:93], v[180:183], v[212:215], v[90:93]
	v_mfma_f32_16x16x32_bf16 v[82:85], v[188:191], v[212:215], v[82:85]
	v_mfma_f32_16x16x32_bf16 v[74:77], v[180:183], v[220:223], v[74:77]
	v_mfma_f32_16x16x32_bf16 v[66:69], v[188:191], v[220:223], v[66:69]
	v_mfma_f32_16x16x32_bf16 v[126:129], v[184:187], v[200:203], v[126:129]
	v_mfma_f32_16x16x32_bf16 v[114:117], v[192:195], v[200:203], v[114:117]
	v_mfma_f32_16x16x32_bf16 v[106:109], v[184:187], v[208:211], v[106:109]
	v_mfma_f32_16x16x32_bf16 v[98:101], v[192:195], v[208:211], v[98:101]
	v_mfma_f32_16x16x32_bf16 v[90:93], v[184:187], v[216:219], v[90:93]
	v_mfma_f32_16x16x32_bf16 v[82:85], v[192:195], v[216:219], v[82:85]
	v_mfma_f32_16x16x32_bf16 v[74:77], v[184:187], v[224:227], v[74:77]
	v_mfma_f32_16x16x32_bf16 v[66:69], v[192:195], v[224:227], v[66:69]
	s_setprio 0
	s_barrier
	s_add_u32 s96, s96, 0x80
	s_addc_u32 s97, s97, 0
	s_add_u32 s98, s96, 0xb0000
	s_addc_u32 s99, s97, 0
	s_add_u32 s94, s94, 0x80
	s_addc_u32 s95, s95, 0
	s_add_i32 s6, s6, s23
	s_mov_b32 m0, s6
	ds_read_b128 v[196:199], v160 offset:49152
	ds_read_b128 v[200:203], v160 offset:50176
	ds_read_b128 v[204:207], v160 offset:51200
	ds_read_b128 v[208:211], v160 offset:52224
	ds_read_b128 v[212:215], v160 offset:53248
	ds_read_b128 v[216:219], v160 offset:54272
	ds_read_b128 v[220:223], v160 offset:55296
	ds_read_b128 v[224:227], v160 offset:56320
	global_load_lds_dwordx4 v132, s[96:97]
	s_add_i32 m0, s6, 0x2000
	s_add_i32 s6, s29, s23
	global_load_lds_dwordx4 v136, s[96:97]
	s_mov_b32 m0, s6
	s_nop 0
	global_load_lds_dwordx4 v132, s[98:99]
	s_add_i32 m0, s6, 0x2000
	s_nop 0
	global_load_lds_dwordx4 v136, s[98:99]
	s_mov_b32 m0, s59
	s_nop 0
	global_load_lds_dwordx4 v130, s[94:95]
	s_mov_b32 m0, s60
	s_nop 0
	global_load_lds_dwordx4 v134, s[94:95]
	s_waitcnt vmcnt(8)
	s_waitcnt lgkmcnt(0)
	s_barrier
	s_setprio 1
	s_waitcnt lgkmcnt(0)
	v_mfma_f32_16x16x32_bf16 v[62:65], v[164:167], v[196:199], v[62:65]
	v_mfma_f32_16x16x32_bf16 v[54:57], v[172:175], v[196:199], v[54:57]
	v_mfma_f32_16x16x32_bf16 v[46:49], v[164:167], v[204:207], v[46:49]
	v_mfma_f32_16x16x32_bf16 v[38:41], v[172:175], v[204:207], v[38:41]
	v_mfma_f32_16x16x32_bf16 v[30:33], v[164:167], v[212:215], v[30:33]
	v_mfma_f32_16x16x32_bf16 v[22:25], v[172:175], v[212:215], v[22:25]
	v_mfma_f32_16x16x32_bf16 v[14:17], v[164:167], v[220:223], v[14:17]
	v_mfma_f32_16x16x32_bf16 v[6:9], v[172:175], v[220:223], v[6:9]
	v_mfma_f32_16x16x32_bf16 v[62:65], v[168:171], v[200:203], v[62:65]
	v_mfma_f32_16x16x32_bf16 v[54:57], v[176:179], v[200:203], v[54:57]
	v_mfma_f32_16x16x32_bf16 v[46:49], v[168:171], v[208:211], v[46:49]
	v_mfma_f32_16x16x32_bf16 v[38:41], v[176:179], v[208:211], v[38:41]
	v_mfma_f32_16x16x32_bf16 v[30:33], v[168:171], v[216:219], v[30:33]
	v_mfma_f32_16x16x32_bf16 v[22:25], v[176:179], v[216:219], v[22:25]
	v_mfma_f32_16x16x32_bf16 v[14:17], v[168:171], v[224:227], v[14:17]
	v_mfma_f32_16x16x32_bf16 v[6:9], v[176:179], v[224:227], v[6:9]
	s_setprio 0
	s_setprio 1
	v_mfma_f32_16x16x32_bf16 v[58:61], v[180:183], v[196:199], v[58:61]
	v_mfma_f32_16x16x32_bf16 v[50:53], v[188:191], v[196:199], v[50:53]
	v_mfma_f32_16x16x32_bf16 v[42:45], v[180:183], v[204:207], v[42:45]
	v_mfma_f32_16x16x32_bf16 v[34:37], v[188:191], v[204:207], v[34:37]
	v_mfma_f32_16x16x32_bf16 v[26:29], v[180:183], v[212:215], v[26:29]
	v_mfma_f32_16x16x32_bf16 v[18:21], v[188:191], v[212:215], v[18:21]
	v_mfma_f32_16x16x32_bf16 v[10:13], v[180:183], v[220:223], v[10:13]
	v_mfma_f32_16x16x32_bf16 v[2:5], v[188:191], v[220:223], v[2:5]
	v_mfma_f32_16x16x32_bf16 v[58:61], v[184:187], v[200:203], v[58:61]
	v_mfma_f32_16x16x32_bf16 v[50:53], v[192:195], v[200:203], v[50:53]
	v_mfma_f32_16x16x32_bf16 v[42:45], v[184:187], v[208:211], v[42:45]
	v_mfma_f32_16x16x32_bf16 v[34:37], v[192:195], v[208:211], v[34:37]
	v_mfma_f32_16x16x32_bf16 v[26:29], v[184:187], v[216:219], v[26:29]
	v_mfma_f32_16x16x32_bf16 v[18:21], v[192:195], v[216:219], v[18:21]
	v_mfma_f32_16x16x32_bf16 v[10:13], v[184:187], v[224:227], v[10:13]
	v_mfma_f32_16x16x32_bf16 v[2:5], v[192:195], v[224:227], v[2:5]
	s_setprio 0
	s_barrier
	s_mov_b32 s6, s7
	s_add_u32 s88, s88, 0x100
	s_addc_u32 s89, s89, 0
	s_add_u32 s86, s86, 0x100
	s_addc_u32 s87, s87, 0
	s_cmp_ge_i32 s7, s101
	s_cbranch_scc1 .Lmy_kexit_7
.LBB0_1392:
	s_add_u32 s98, s86, 0x100
	s_addc_u32 s99, s87, 0
	s_cmp_eq_u32 s6, s100
	s_cselect_b64 s[94:95], s[90:91], s[98:99]
	s_cselect_b64 s[96:97], s[92:93], s[88:89]
	ds_read_b128 v[164:167], v230
	ds_read_b128 v[168:171], v230 offset:1024
	ds_read_b128 v[172:175], v230 offset:2048
	ds_read_b128 v[176:179], v230 offset:3072
	ds_read_b128 v[180:183], v231
	ds_read_b128 v[184:187], v231 offset:1024
	ds_read_b128 v[188:191], v231 offset:2048
	ds_read_b128 v[192:195], v231 offset:3072
	s_add_i32 s7, s6, 2
	s_nop 0
	s_add_i32 m0, s46, 0xc000
	ds_read_b128 v[196:199], v160
	ds_read_b128 v[200:203], v160 offset:1024
	ds_read_b128 v[204:207], v160 offset:2048
	ds_read_b128 v[208:211], v160 offset:3072
	ds_read_b128 v[212:215], v160 offset:4096
	ds_read_b128 v[216:219], v160 offset:5120
	ds_read_b128 v[220:223], v160 offset:6144
	ds_read_b128 v[224:227], v160 offset:7168
	global_load_lds_dwordx4 v144, s[86:87]
	s_add_i32 m0, s46, 0xe000
	s_nop 0
	global_load_lds_dwordx4 v142, s[86:87]
	s_waitcnt vmcnt(8)
	s_waitcnt lgkmcnt(0)
	s_barrier
	s_setprio 1
	s_waitcnt lgkmcnt(0)
	v_mfma_f32_16x16x32_bf16 v[122:125], v[164:167], v[196:199], v[122:125]
	v_mfma_f32_16x16x32_bf16 v[118:121], v[172:175], v[196:199], v[118:121]
	v_mfma_f32_16x16x32_bf16 v[110:113], v[164:167], v[204:207], v[110:113]
	v_mfma_f32_16x16x32_bf16 v[102:105], v[172:175], v[204:207], v[102:105]
	v_mfma_f32_16x16x32_bf16 v[94:97], v[164:167], v[212:215], v[94:97]
	v_mfma_f32_16x16x32_bf16 v[86:89], v[172:175], v[212:215], v[86:89]
	v_mfma_f32_16x16x32_bf16 v[78:81], v[164:167], v[220:223], v[78:81]
	v_mfma_f32_16x16x32_bf16 v[70:73], v[172:175], v[220:223], v[70:73]
	v_mfma_f32_16x16x32_bf16 v[122:125], v[168:171], v[200:203], v[122:125]
	v_mfma_f32_16x16x32_bf16 v[118:121], v[176:179], v[200:203], v[118:121]
	v_mfma_f32_16x16x32_bf16 v[110:113], v[168:171], v[208:211], v[110:113]
	v_mfma_f32_16x16x32_bf16 v[102:105], v[176:179], v[208:211], v[102:105]
	v_mfma_f32_16x16x32_bf16 v[94:97], v[168:171], v[216:219], v[94:97]
	v_mfma_f32_16x16x32_bf16 v[86:89], v[176:179], v[216:219], v[86:89]
	v_mfma_f32_16x16x32_bf16 v[78:81], v[168:171], v[224:227], v[78:81]
	v_mfma_f32_16x16x32_bf16 v[70:73], v[176:179], v[224:227], v[70:73]
	s_setprio 0
	s_setprio 1
	v_mfma_f32_16x16x32_bf16 v[126:129], v[180:183], v[196:199], v[126:129]
	v_mfma_f32_16x16x32_bf16 v[114:117], v[188:191], v[196:199], v[114:117]
	v_mfma_f32_16x16x32_bf16 v[106:109], v[180:183], v[204:207], v[106:109]
	v_mfma_f32_16x16x32_bf16 v[98:101], v[188:191], v[204:207], v[98:101]
	v_mfma_f32_16x16x32_bf16 v[90:93], v[180:183], v[212:215], v[90:93]
	v_mfma_f32_16x16x32_bf16 v[82:85], v[188:191], v[212:215], v[82:85]
	v_mfma_f32_16x16x32_bf16 v[74:77], v[180:183], v[220:223], v[74:77]
	v_mfma_f32_16x16x32_bf16 v[66:69], v[188:191], v[220:223], v[66:69]
	v_mfma_f32_16x16x32_bf16 v[126:129], v[184:187], v[200:203], v[126:129]
	v_mfma_f32_16x16x32_bf16 v[114:117], v[192:195], v[200:203], v[114:117]
	v_mfma_f32_16x16x32_bf16 v[106:109], v[184:187], v[208:211], v[106:109]
	v_mfma_f32_16x16x32_bf16 v[98:101], v[192:195], v[208:211], v[98:101]
	v_mfma_f32_16x16x32_bf16 v[90:93], v[184:187], v[216:219], v[90:93]
	v_mfma_f32_16x16x32_bf16 v[82:85], v[192:195], v[216:219], v[82:85]
	v_mfma_f32_16x16x32_bf16 v[74:77], v[184:187], v[224:227], v[74:77]
	v_mfma_f32_16x16x32_bf16 v[66:69], v[192:195], v[224:227], v[66:69]
	s_setprio 0
	s_barrier
	s_add_u32 s98, s96, 0xb0000
	s_addc_u32 s99, s97, 0
	s_add_i32 s6, s67, s23
	s_mov_b32 m0, s6
	ds_read_b128 v[196:199], v160 offset:16384
	ds_read_b128 v[200:203], v160 offset:17408
	ds_read_b128 v[204:207], v160 offset:18432
	ds_read_b128 v[208:211], v160 offset:19456
	ds_read_b128 v[212:215], v160 offset:20480
	ds_read_b128 v[216:219], v160 offset:21504
	ds_read_b128 v[220:223], v160 offset:22528
	ds_read_b128 v[224:227], v160 offset:23552
	global_load_lds_dwordx4 v132, s[96:97]
	s_add_i32 m0, s6, 0x2000
	s_add_i32 s6, s70, s23
	global_load_lds_dwordx4 v136, s[96:97]
	s_mov_b32 m0, s6
	s_nop 0
	global_load_lds_dwordx4 v132, s[98:99]
	s_add_i32 m0, s6, 0x2000
	s_nop 0
	global_load_lds_dwordx4 v136, s[98:99]
	s_mov_b32 m0, s46
	s_nop 0
	global_load_lds_dwordx4 v130, s[94:95]
	s_mov_b32 m0, s47
	s_nop 0
	global_load_lds_dwordx4 v134, s[94:95]
	s_waitcnt vmcnt(8)
	s_waitcnt lgkmcnt(0)
	s_barrier
	s_setprio 1
	s_waitcnt lgkmcnt(0)
	v_mfma_f32_16x16x32_bf16 v[62:65], v[164:167], v[196:199], v[62:65]
	v_mfma_f32_16x16x32_bf16 v[54:57], v[172:175], v[196:199], v[54:57]
	v_mfma_f32_16x16x32_bf16 v[46:49], v[164:167], v[204:207], v[46:49]
	v_mfma_f32_16x16x32_bf16 v[38:41], v[172:175], v[204:207], v[38:41]
	v_mfma_f32_16x16x32_bf16 v[30:33], v[164:167], v[212:215], v[30:33]
	v_mfma_f32_16x16x32_bf16 v[22:25], v[172:175], v[212:215], v[22:25]
	v_mfma_f32_16x16x32_bf16 v[14:17], v[164:167], v[220:223], v[14:17]
	v_mfma_f32_16x16x32_bf16 v[6:9], v[172:175], v[220:223], v[6:9]
	v_mfma_f32_16x16x32_bf16 v[62:65], v[168:171], v[200:203], v[62:65]
	v_mfma_f32_16x16x32_bf16 v[54:57], v[176:179], v[200:203], v[54:57]
	v_mfma_f32_16x16x32_bf16 v[46:49], v[168:171], v[208:211], v[46:49]
	v_mfma_f32_16x16x32_bf16 v[38:41], v[176:179], v[208:211], v[38:41]
	v_mfma_f32_16x16x32_bf16 v[30:33], v[168:171], v[216:219], v[30:33]
	v_mfma_f32_16x16x32_bf16 v[22:25], v[176:179], v[216:219], v[22:25]
	v_mfma_f32_16x16x32_bf16 v[14:17], v[168:171], v[224:227], v[14:17]
	v_mfma_f32_16x16x32_bf16 v[6:9], v[176:179], v[224:227], v[6:9]
	s_setprio 0
	s_setprio 1
	v_mfma_f32_16x16x32_bf16 v[58:61], v[180:183], v[196:199], v[58:61]
	v_mfma_f32_16x16x32_bf16 v[50:53], v[188:191], v[196:199], v[50:53]
	v_mfma_f32_16x16x32_bf16 v[42:45], v[180:183], v[204:207], v[42:45]
	v_mfma_f32_16x16x32_bf16 v[34:37], v[188:191], v[204:207], v[34:37]
	v_mfma_f32_16x16x32_bf16 v[26:29], v[180:183], v[212:215], v[26:29]
	v_mfma_f32_16x16x32_bf16 v[18:21], v[188:191], v[212:215], v[18:21]
	v_mfma_f32_16x16x32_bf16 v[10:13], v[180:183], v[220:223], v[10:13]
	v_mfma_f32_16x16x32_bf16 v[2:5], v[188:191], v[220:223], v[2:5]
	v_mfma_f32_16x16x32_bf16 v[58:61], v[184:187], v[200:203], v[58:61]
	v_mfma_f32_16x16x32_bf16 v[50:53], v[192:195], v[200:203], v[50:53]
	v_mfma_f32_16x16x32_bf16 v[42:45], v[184:187], v[208:211], v[42:45]
	v_mfma_f32_16x16x32_bf16 v[34:37], v[192:195], v[208:211], v[34:37]
	v_mfma_f32_16x16x32_bf16 v[26:29], v[184:187], v[216:219], v[26:29]
	v_mfma_f32_16x16x32_bf16 v[18:21], v[192:195], v[216:219], v[18:21]
	v_mfma_f32_16x16x32_bf16 v[10:13], v[184:187], v[224:227], v[10:13]
	v_mfma_f32_16x16x32_bf16 v[2:5], v[192:195], v[224:227], v[2:5]
	s_setprio 0
	s_barrier
	s_add_u32 s98, s94, 0xb0000
	s_addc_u32 s99, s95, 0
	s_add_i32 s6, 0, 0x18000
	s_add_i32 s29, 0, 0x1c000
	ds_read_b128 v[164:167], v232
	ds_read_b128 v[168:171], v232 offset:1024
	ds_read_b128 v[172:175], v232 offset:2048
	ds_read_b128 v[176:179], v232 offset:3072
	ds_read_b128 v[180:183], v233
	ds_read_b128 v[184:187], v233 offset:1024
	ds_read_b128 v[188:191], v233 offset:2048
	ds_read_b128 v[192:195], v233 offset:3072
	s_mov_b32 m0, s48
	ds_read_b128 v[196:199], v160 offset:32768
	ds_read_b128 v[200:203], v160 offset:33792
	ds_read_b128 v[204:207], v160 offset:34816
	ds_read_b128 v[208:211], v160 offset:35840
	ds_read_b128 v[212:215], v160 offset:36864
	ds_read_b128 v[216:219], v160 offset:37888
	ds_read_b128 v[220:223], v160 offset:38912
	ds_read_b128 v[224:227], v160 offset:39936
	global_load_lds_dwordx4 v130, s[98:99]
	s_mov_b32 m0, s49
	s_nop 0
	global_load_lds_dwordx4 v134, s[98:99]
	s_waitcnt vmcnt(8)
	s_waitcnt lgkmcnt(0)
	s_barrier
	s_setprio 1
	s_waitcnt lgkmcnt(0)
	v_mfma_f32_16x16x32_bf16 v[122:125], v[164:167], v[196:199], v[122:125]
	v_mfma_f32_16x16x32_bf16 v[118:121], v[172:175], v[196:199], v[118:121]
	v_mfma_f32_16x16x32_bf16 v[110:113], v[164:167], v[204:207], v[110:113]
	v_mfma_f32_16x16x32_bf16 v[102:105], v[172:175], v[204:207], v[102:105]
	v_mfma_f32_16x16x32_bf16 v[94:97], v[164:167], v[212:215], v[94:97]
	v_mfma_f32_16x16x32_bf16 v[86:89], v[172:175], v[212:215], v[86:89]
	v_mfma_f32_16x16x32_bf16 v[78:81], v[164:167], v[220:223], v[78:81]
	v_mfma_f32_16x16x32_bf16 v[70:73], v[172:175], v[220:223], v[70:73]
	v_mfma_f32_16x16x32_bf16 v[122:125], v[168:171], v[200:203], v[122:125]
	v_mfma_f32_16x16x32_bf16 v[118:121], v[176:179], v[200:203], v[118:121]
	v_mfma_f32_16x16x32_bf16 v[110:113], v[168:171], v[208:211], v[110:113]
	v_mfma_f32_16x16x32_bf16 v[102:105], v[176:179], v[208:211], v[102:105]
	v_mfma_f32_16x16x32_bf16 v[94:97], v[168:171], v[216:219], v[94:97]
	v_mfma_f32_16x16x32_bf16 v[86:89], v[176:179], v[216:219], v[86:89]
	v_mfma_f32_16x16x32_bf16 v[78:81], v[168:171], v[224:227], v[78:81]
	v_mfma_f32_16x16x32_bf16 v[70:73], v[176:179], v[224:227], v[70:73]
	s_setprio 0
	s_setprio 1
	v_mfma_f32_16x16x32_bf16 v[126:129], v[180:183], v[196:199], v[126:129]
	v_mfma_f32_16x16x32_bf16 v[114:117], v[188:191], v[196:199], v[114:117]
	v_mfma_f32_16x16x32_bf16 v[106:109], v[180:183], v[204:207], v[106:109]
	v_mfma_f32_16x16x32_bf16 v[98:101], v[188:191], v[204:207], v[98:101]
	v_mfma_f32_16x16x32_bf16 v[90:93], v[180:183], v[212:215], v[90:93]
	v_mfma_f32_16x16x32_bf16 v[82:85], v[188:191], v[212:215], v[82:85]
	v_mfma_f32_16x16x32_bf16 v[74:77], v[180:183], v[220:223], v[74:77]
	v_mfma_f32_16x16x32_bf16 v[66:69], v[188:191], v[220:223], v[66:69]
	v_mfma_f32_16x16x32_bf16 v[126:129], v[184:187], v[200:203], v[126:129]
	v_mfma_f32_16x16x32_bf16 v[114:117], v[192:195], v[200:203], v[114:117]
	v_mfma_f32_16x16x32_bf16 v[106:109], v[184:187], v[208:211], v[106:109]
	v_mfma_f32_16x16x32_bf16 v[98:101], v[192:195], v[208:211], v[98:101]
	v_mfma_f32_16x16x32_bf16 v[90:93], v[184:187], v[216:219], v[90:93]
	v_mfma_f32_16x16x32_bf16 v[82:85], v[192:195], v[216:219], v[82:85]
	v_mfma_f32_16x16x32_bf16 v[74:77], v[184:187], v[224:227], v[74:77]
	v_mfma_f32_16x16x32_bf16 v[66:69], v[192:195], v[224:227], v[66:69]
	s_setprio 0
	s_barrier
	s_add_u32 s96, s96, 0x80
	s_addc_u32 s97, s97, 0
	s_add_u32 s98, s96, 0xb0000
	s_addc_u32 s99, s97, 0
	s_add_u32 s94, s94, 0x80
	s_addc_u32 s95, s95, 0
	s_add_i32 s6, s6, s23
	s_mov_b32 m0, s6
	ds_read_b128 v[196:199], v160 offset:49152
	ds_read_b128 v[200:203], v160 offset:50176
	ds_read_b128 v[204:207], v160 offset:51200
	ds_read_b128 v[208:211], v160 offset:52224
	ds_read_b128 v[212:215], v160 offset:53248
	ds_read_b128 v[216:219], v160 offset:54272
	ds_read_b128 v[220:223], v160 offset:55296
	ds_read_b128 v[224:227], v160 offset:56320
	global_load_lds_dwordx4 v132, s[96:97]
	s_add_i32 m0, s6, 0x2000
	s_add_i32 s6, s29, s23
	global_load_lds_dwordx4 v136, s[96:97]
	s_mov_b32 m0, s6
	s_nop 0
	global_load_lds_dwordx4 v132, s[98:99]
	s_add_i32 m0, s6, 0x2000
	s_nop 0
	global_load_lds_dwordx4 v136, s[98:99]
	s_mov_b32 m0, s59
	s_nop 0
	global_load_lds_dwordx4 v130, s[94:95]
	s_mov_b32 m0, s60
	s_nop 0
	global_load_lds_dwordx4 v134, s[94:95]
	s_waitcnt vmcnt(8)
	s_waitcnt lgkmcnt(0)
	s_barrier
	s_setprio 1
	s_waitcnt lgkmcnt(0)
	v_mfma_f32_16x16x32_bf16 v[62:65], v[164:167], v[196:199], v[62:65]
	v_mfma_f32_16x16x32_bf16 v[54:57], v[172:175], v[196:199], v[54:57]
	v_mfma_f32_16x16x32_bf16 v[46:49], v[164:167], v[204:207], v[46:49]
	v_mfma_f32_16x16x32_bf16 v[38:41], v[172:175], v[204:207], v[38:41]
	v_mfma_f32_16x16x32_bf16 v[30:33], v[164:167], v[212:215], v[30:33]
	v_mfma_f32_16x16x32_bf16 v[22:25], v[172:175], v[212:215], v[22:25]
	v_mfma_f32_16x16x32_bf16 v[14:17], v[164:167], v[220:223], v[14:17]
	v_mfma_f32_16x16x32_bf16 v[6:9], v[172:175], v[220:223], v[6:9]
	v_mfma_f32_16x16x32_bf16 v[62:65], v[168:171], v[200:203], v[62:65]
	v_mfma_f32_16x16x32_bf16 v[54:57], v[176:179], v[200:203], v[54:57]
	v_mfma_f32_16x16x32_bf16 v[46:49], v[168:171], v[208:211], v[46:49]
	v_mfma_f32_16x16x32_bf16 v[38:41], v[176:179], v[208:211], v[38:41]
	v_mfma_f32_16x16x32_bf16 v[30:33], v[168:171], v[216:219], v[30:33]
	v_mfma_f32_16x16x32_bf16 v[22:25], v[176:179], v[216:219], v[22:25]
	v_mfma_f32_16x16x32_bf16 v[14:17], v[168:171], v[224:227], v[14:17]
	v_mfma_f32_16x16x32_bf16 v[6:9], v[176:179], v[224:227], v[6:9]
	s_setprio 0
	s_setprio 1
	v_mfma_f32_16x16x32_bf16 v[58:61], v[180:183], v[196:199], v[58:61]
	v_mfma_f32_16x16x32_bf16 v[50:53], v[188:191], v[196:199], v[50:53]
	v_mfma_f32_16x16x32_bf16 v[42:45], v[180:183], v[204:207], v[42:45]
	v_mfma_f32_16x16x32_bf16 v[34:37], v[188:191], v[204:207], v[34:37]
	v_mfma_f32_16x16x32_bf16 v[26:29], v[180:183], v[212:215], v[26:29]
	v_mfma_f32_16x16x32_bf16 v[18:21], v[188:191], v[212:215], v[18:21]
	v_mfma_f32_16x16x32_bf16 v[10:13], v[180:183], v[220:223], v[10:13]
	v_mfma_f32_16x16x32_bf16 v[2:5], v[188:191], v[220:223], v[2:5]
	v_mfma_f32_16x16x32_bf16 v[58:61], v[184:187], v[200:203], v[58:61]
	v_mfma_f32_16x16x32_bf16 v[50:53], v[192:195], v[200:203], v[50:53]
	v_mfma_f32_16x16x32_bf16 v[42:45], v[184:187], v[208:211], v[42:45]
	v_mfma_f32_16x16x32_bf16 v[34:37], v[192:195], v[208:211], v[34:37]
	v_mfma_f32_16x16x32_bf16 v[26:29], v[184:187], v[216:219], v[26:29]
	v_mfma_f32_16x16x32_bf16 v[18:21], v[192:195], v[216:219], v[18:21]
	v_mfma_f32_16x16x32_bf16 v[10:13], v[184:187], v[224:227], v[10:13]
	v_mfma_f32_16x16x32_bf16 v[2:5], v[192:195], v[224:227], v[2:5]
	s_setprio 0
	s_barrier
	s_mov_b32 s6, s7
	s_add_u32 s88, s88, 0x100
	s_addc_u32 s89, s89, 0
	s_add_u32 s86, s86, 0x100
	s_addc_u32 s87, s87, 0
	s_cmp_ge_i32 s7, s101
	s_cbranch_scc0 .LBB0_1392

.LBB0_1571:
	v_cmp_gt_i32_e32 vcc, 1, v141
	s_cbranch_vccnz .LBB0_1633
	v_lshl_add_u64 v[154:155], v[2:3], 0, s[18:19]
	v_add_u32_e32 v138, -2, v141
	v_lshl_add_u64 v[152:153], v[4:5], 0, s[22:23]
	s_mov_b32 s7, 0
	s_nop 0
	v_readfirstlane_b32 s86, v154
	v_readfirstlane_b32 s87, v155
	v_readfirstlane_b32 s88, v152
	v_readfirstlane_b32 s89, v153
	v_readfirstlane_b32 s90, v148
	v_readfirstlane_b32 s91, v149
	v_readfirstlane_b32 s92, v150
	v_readfirstlane_b32 s93, v151
	v_readfirstlane_b32 s100, v138
	v_readfirstlane_b32 s101, v141
	v_add_u32_e32 v230, s71, v160
	v_add_u32_e32 v231, s72, v160
	v_add_u32_e32 v232, 0x18000, v160
	v_add_u32_e32 v233, 0x1c000, v160
	s_add_u32 s98, s86, 0xfffc0080
	s_addc_u32 s99, s87, -1
	s_cmp_eq_u32 s7, s100
	s_cselect_b64 s[94:95], s[90:91], s[98:99]
	s_cselect_b64 s[96:97], s[92:93], s[88:89]
	ds_read_b128 v[156:159], v230
	ds_read_b128 v[166:169], v230 offset:1024
	ds_read_b128 v[170:173], v230 offset:2048
	ds_read_b128 v[174:177], v230 offset:3072
	ds_read_b128 v[178:181], v231
	ds_read_b128 v[182:185], v231 offset:1024
	ds_read_b128 v[186:189], v231 offset:2048
	ds_read_b128 v[190:193], v231 offset:3072
	s_add_i32 s47, s7, 2
	s_nop 0
	s_mov_b32 m0, s74
	ds_read_b128 v[194:197], v163
	ds_read_b128 v[198:201], v163 offset:1024
	ds_read_b128 v[202:205], v163 offset:2048
	ds_read_b128 v[206:209], v163 offset:3072
	ds_read_b128 v[210:213], v163 offset:4096
	ds_read_b128 v[214:217], v163 offset:5120
	ds_read_b128 v[218:221], v163 offset:6144
	ds_read_b128 v[222:225], v163 offset:7168
	global_load_lds_dwordx4 v144, s[86:87]
	s_mov_b32 m0, s75
	s_nop 0
	global_load_lds_dwordx4 v142, s[86:87]
	s_waitcnt vmcnt(8)
	s_waitcnt lgkmcnt(0)
	s_barrier
	s_setprio 1
	s_waitcnt lgkmcnt(0)
	v_mfma_f32_16x16x32_bf16 v[122:125], v[156:159], v[194:197], 0
	v_mfma_f32_16x16x32_bf16 v[118:121], v[170:173], v[194:197], 0
	v_mfma_f32_16x16x32_bf16 v[110:113], v[156:159], v[202:205], 0
	v_mfma_f32_16x16x32_bf16 v[102:105], v[170:173], v[202:205], 0
	v_mfma_f32_16x16x32_bf16 v[94:97], v[156:159], v[210:213], 0
	v_mfma_f32_16x16x32_bf16 v[86:89], v[170:173], v[210:213], 0
	v_mfma_f32_16x16x32_bf16 v[78:81], v[156:159], v[218:221], 0
	v_mfma_f32_16x16x32_bf16 v[70:73], v[170:173], v[218:221], 0
	v_mfma_f32_16x16x32_bf16 v[122:125], v[166:169], v[198:201], v[122:125]
	v_mfma_f32_16x16x32_bf16 v[118:121], v[174:177], v[198:201], v[118:121]
	v_mfma_f32_16x16x32_bf16 v[110:113], v[166:169], v[206:209], v[110:113]
	v_mfma_f32_16x16x32_bf16 v[102:105], v[174:177], v[206:209], v[102:105]
	v_mfma_f32_16x16x32_bf16 v[94:97], v[166:169], v[214:217], v[94:97]
	v_mfma_f32_16x16x32_bf16 v[86:89], v[174:177], v[214:217], v[86:89]
	v_mfma_f32_16x16x32_bf16 v[78:81], v[166:169], v[222:225], v[78:81]
	v_mfma_f32_16x16x32_bf16 v[70:73], v[174:177], v[222:225], v[70:73]
	s_setprio 0
	s_setprio 1
	v_mfma_f32_16x16x32_bf16 v[126:129], v[178:181], v[194:197], 0
	v_mfma_f32_16x16x32_bf16 v[114:117], v[186:189], v[194:197], 0
	v_mfma_f32_16x16x32_bf16 v[106:109], v[178:181], v[202:205], 0
	v_mfma_f32_16x16x32_bf16 v[98:101], v[186:189], v[202:205], 0
	v_mfma_f32_16x16x32_bf16 v[90:93], v[178:181], v[210:213], 0
	v_mfma_f32_16x16x32_bf16 v[82:85], v[186:189], v[210:213], 0
	v_mfma_f32_16x16x32_bf16 v[74:77], v[178:181], v[218:221], 0
	v_mfma_f32_16x16x32_bf16 v[66:69], v[186:189], v[218:221], 0
	v_mfma_f32_16x16x32_bf16 v[126:129], v[182:185], v[198:201], v[126:129]
	v_mfma_f32_16x16x32_bf16 v[114:117], v[190:193], v[198:201], v[114:117]
	v_mfma_f32_16x16x32_bf16 v[106:109], v[182:185], v[206:209], v[106:109]
	v_mfma_f32_16x16x32_bf16 v[98:101], v[190:193], v[206:209], v[98:101]
	v_mfma_f32_16x16x32_bf16 v[90:93], v[182:185], v[214:217], v[90:93]
	v_mfma_f32_16x16x32_bf16 v[82:85], v[190:193], v[214:217], v[82:85]
	v_mfma_f32_16x16x32_bf16 v[74:77], v[182:185], v[222:225], v[74:77]
	v_mfma_f32_16x16x32_bf16 v[66:69], v[190:193], v[222:225], v[66:69]
	s_setprio 0
	s_barrier
	s_add_u32 s98, s96, 0x40000
	s_addc_u32 s99, s97, 0
	s_add_i32 s7, s71, s29
	s_mov_b32 m0, s7
	ds_read_b128 v[194:197], v163 offset:16384
	ds_read_b128 v[198:201], v163 offset:17408
	ds_read_b128 v[202:205], v163 offset:18432
	ds_read_b128 v[206:209], v163 offset:19456
	ds_read_b128 v[210:213], v163 offset:20480
	ds_read_b128 v[214:217], v163 offset:21504
	ds_read_b128 v[218:221], v163 offset:22528
	ds_read_b128 v[222:225], v163 offset:23552
	global_load_lds_dwordx4 v132, s[96:97]
	s_add_i32 m0, s7, 0x2000
	s_add_i32 s7, s72, s29
	global_load_lds_dwordx4 v136, s[96:97]
	s_mov_b32 m0, s7
	s_nop 0
	global_load_lds_dwordx4 v132, s[98:99]
	s_add_i32 m0, s7, 0x2000
	s_nop 0
	global_load_lds_dwordx4 v136, s[98:99]
	s_mov_b32 m0, s51
	s_nop 0
	global_load_lds_dwordx4 v130, s[94:95]
	s_mov_b32 m0, s60
	s_nop 0
	global_load_lds_dwordx4 v134, s[94:95]
	s_waitcnt vmcnt(8)
	s_waitcnt lgkmcnt(0)
	s_barrier
	s_setprio 1
	s_waitcnt lgkmcnt(0)
	v_mfma_f32_16x16x32_bf16 v[62:65], v[156:159], v[194:197], 0
	v_mfma_f32_16x16x32_bf16 v[54:57], v[170:173], v[194:197], 0
	v_mfma_f32_16x16x32_bf16 v[46:49], v[156:159], v[202:205], 0
	v_mfma_f32_16x16x32_bf16 v[38:41], v[170:173], v[202:205], 0
	v_mfma_f32_16x16x32_bf16 v[30:33], v[156:159], v[210:213], 0
	v_mfma_f32_16x16x32_bf16 v[22:25], v[170:173], v[210:213], 0
	v_mfma_f32_16x16x32_bf16 v[14:17], v[156:159], v[218:221], 0
	v_mfma_f32_16x16x32_bf16 v[6:9], v[170:173], v[218:221], 0
	v_mfma_f32_16x16x32_bf16 v[62:65], v[166:169], v[198:201], v[62:65]
	v_mfma_f32_16x16x32_bf16 v[54:57], v[174:177], v[198:201], v[54:57]
	v_mfma_f32_16x16x32_bf16 v[46:49], v[166:169], v[206:209], v[46:49]
	v_mfma_f32_16x16x32_bf16 v[38:41], v[174:177], v[206:209], v[38:41]
	v_mfma_f32_16x16x32_bf16 v[30:33], v[166:169], v[214:217], v[30:33]
	v_mfma_f32_16x16x32_bf16 v[22:25], v[174:177], v[214:217], v[22:25]
	v_mfma_f32_16x16x32_bf16 v[14:17], v[166:169], v[222:225], v[14:17]
	v_mfma_f32_16x16x32_bf16 v[6:9], v[174:177], v[222:225], v[6:9]
	s_setprio 0
	s_setprio 1
	v_mfma_f32_16x16x32_bf16 v[58:61], v[178:181], v[194:197], 0
	v_mfma_f32_16x16x32_bf16 v[50:53], v[186:189], v[194:197], 0
	v_mfma_f32_16x16x32_bf16 v[42:45], v[178:181], v[202:205], 0
	v_mfma_f32_16x16x32_bf16 v[34:37], v[186:189], v[202:205], 0
	v_mfma_f32_16x16x32_bf16 v[26:29], v[178:181], v[210:213], 0
	v_mfma_f32_16x16x32_bf16 v[18:21], v[186:189], v[210:213], 0
	v_mfma_f32_16x16x32_bf16 v[10:13], v[178:181], v[218:221], 0
	v_mfma_f32_16x16x32_bf16 v[2:5], v[186:189], v[218:221], 0
	v_mfma_f32_16x16x32_bf16 v[58:61], v[182:185], v[198:201], v[58:61]
	v_mfma_f32_16x16x32_bf16 v[50:53], v[190:193], v[198:201], v[50:53]
	v_mfma_f32_16x16x32_bf16 v[42:45], v[182:185], v[206:209], v[42:45]
	v_mfma_f32_16x16x32_bf16 v[34:37], v[190:193], v[206:209], v[34:37]
	v_mfma_f32_16x16x32_bf16 v[26:29], v[182:185], v[214:217], v[26:29]
	v_mfma_f32_16x16x32_bf16 v[18:21], v[190:193], v[214:217], v[18:21]
	v_mfma_f32_16x16x32_bf16 v[10:13], v[182:185], v[222:225], v[10:13]
	v_mfma_f32_16x16x32_bf16 v[2:5], v[190:193], v[222:225], v[2:5]
	s_setprio 0
	s_barrier
	s_add_u32 s98, s94, 0x40000
	s_addc_u32 s99, s95, 0
	s_add_i32 s7, 0, 0x18000
	s_add_i32 s49, 0, 0x1c000
	ds_read_b128 v[156:159], v232
	ds_read_b128 v[166:169], v232 offset:1024
	ds_read_b128 v[170:173], v232 offset:2048
	ds_read_b128 v[174:177], v232 offset:3072
	ds_read_b128 v[178:181], v233
	ds_read_b128 v[182:185], v233 offset:1024
	ds_read_b128 v[186:189], v233 offset:2048
	ds_read_b128 v[190:193], v233 offset:3072
	s_mov_b32 m0, s61
	ds_read_b128 v[194:197], v163 offset:32768
	ds_read_b128 v[198:201], v163 offset:33792
	ds_read_b128 v[202:205], v163 offset:34816
	ds_read_b128 v[206:209], v163 offset:35840
	ds_read_b128 v[210:213], v163 offset:36864
	ds_read_b128 v[214:217], v163 offset:37888
	ds_read_b128 v[218:221], v163 offset:38912
	ds_read_b128 v[222:225], v163 offset:39936
	global_load_lds_dwordx4 v130, s[98:99]
	s_mov_b32 m0, s62
	s_nop 0
	global_load_lds_dwordx4 v134, s[98:99]
	s_waitcnt vmcnt(8)
	s_waitcnt lgkmcnt(0)
	s_barrier
	s_setprio 1
	s_waitcnt lgkmcnt(0)
	v_mfma_f32_16x16x32_bf16 v[122:125], v[156:159], v[194:197], v[122:125]
	v_mfma_f32_16x16x32_bf16 v[118:121], v[170:173], v[194:197], v[118:121]
	v_mfma_f32_16x16x32_bf16 v[110:113], v[156:159], v[202:205], v[110:113]
	v_mfma_f32_16x16x32_bf16 v[102:105], v[170:173], v[202:205], v[102:105]
	v_mfma_f32_16x16x32_bf16 v[94:97], v[156:159], v[210:213], v[94:97]
	v_mfma_f32_16x16x32_bf16 v[86:89], v[170:173], v[210:213], v[86:89]
	v_mfma_f32_16x16x32_bf16 v[78:81], v[156:159], v[218:221], v[78:81]
	v_mfma_f32_16x16x32_bf16 v[70:73], v[170:173], v[218:221], v[70:73]
	v_mfma_f32_16x16x32_bf16 v[122:125], v[166:169], v[198:201], v[122:125]
	v_mfma_f32_16x16x32_bf16 v[118:121], v[174:177], v[198:201], v[118:121]
	v_mfma_f32_16x16x32_bf16 v[110:113], v[166:169], v[206:209], v[110:113]
	v_mfma_f32_16x16x32_bf16 v[102:105], v[174:177], v[206:209], v[102:105]
	v_mfma_f32_16x16x32_bf16 v[94:97], v[166:169], v[214:217], v[94:97]
	v_mfma_f32_16x16x32_bf16 v[86:89], v[174:177], v[214:217], v[86:89]
	v_mfma_f32_16x16x32_bf16 v[78:81], v[166:169], v[222:225], v[78:81]
	v_mfma_f32_16x16x32_bf16 v[70:73], v[174:177], v[222:225], v[70:73]
	s_setprio 0
	s_setprio 1
	v_mfma_f32_16x16x32_bf16 v[126:129], v[178:181], v[194:197], v[126:129]
	v_mfma_f32_16x16x32_bf16 v[114:117], v[186:189], v[194:197], v[114:117]
	v_mfma_f32_16x16x32_bf16 v[106:109], v[178:181], v[202:205], v[106:109]
	v_mfma_f32_16x16x32_bf16 v[98:101], v[186:189], v[202:205], v[98:101]
	v_mfma_f32_16x16x32_bf16 v[90:93], v[178:181], v[210:213], v[90:93]
	v_mfma_f32_16x16x32_bf16 v[82:85], v[186:189], v[210:213], v[82:85]
	v_mfma_f32_16x16x32_bf16 v[74:77], v[178:181], v[218:221], v[74:77]
	v_mfma_f32_16x16x32_bf16 v[66:69], v[186:189], v[218:221], v[66:69]
	v_mfma_f32_16x16x32_bf16 v[126:129], v[182:185], v[198:201], v[126:129]
	v_mfma_f32_16x16x32_bf16 v[114:117], v[190:193], v[198:201], v[114:117]
	v_mfma_f32_16x16x32_bf16 v[106:109], v[182:185], v[206:209], v[106:109]
	v_mfma_f32_16x16x32_bf16 v[98:101], v[190:193], v[206:209], v[98:101]
	v_mfma_f32_16x16x32_bf16 v[90:93], v[182:185], v[214:217], v[90:93]
	v_mfma_f32_16x16x32_bf16 v[82:85], v[190:193], v[214:217], v[82:85]
	v_mfma_f32_16x16x32_bf16 v[74:77], v[182:185], v[222:225], v[74:77]
	v_mfma_f32_16x16x32_bf16 v[66:69], v[190:193], v[222:225], v[66:69]
	s_setprio 0
	s_barrier
	s_add_u32 s96, s96, 0x80
	s_addc_u32 s97, s97, 0
	s_add_u32 s98, s96, 0x40000
	s_addc_u32 s99, s97, 0
	s_add_u32 s94, s94, 0x80
	s_addc_u32 s95, s95, 0
	s_add_i32 s7, s7, s29
	s_mov_b32 m0, s7
	ds_read_b128 v[194:197], v163 offset:49152
	ds_read_b128 v[198:201], v163 offset:50176
	ds_read_b128 v[202:205], v163 offset:51200
	ds_read_b128 v[206:209], v163 offset:52224
	ds_read_b128 v[210:213], v163 offset:53248
	ds_read_b128 v[214:217], v163 offset:54272
	ds_read_b128 v[218:221], v163 offset:55296
	ds_read_b128 v[222:225], v163 offset:56320
	global_load_lds_dwordx4 v132, s[96:97]
	s_add_i32 m0, s7, 0x2000
	s_add_i32 s7, s49, s29
	global_load_lds_dwordx4 v136, s[96:97]
	s_mov_b32 m0, s7
	s_nop 0
	global_load_lds_dwordx4 v132, s[98:99]
	s_add_i32 m0, s7, 0x2000
	s_nop 0
	global_load_lds_dwordx4 v136, s[98:99]
	s_mov_b32 m0, s63
	s_nop 0
	global_load_lds_dwordx4 v130, s[94:95]
	s_mov_b32 m0, s64
	s_nop 0
	global_load_lds_dwordx4 v134, s[94:95]
	s_waitcnt vmcnt(8)
	s_waitcnt lgkmcnt(0)
	s_barrier
	s_setprio 1
	s_waitcnt lgkmcnt(0)
	v_mfma_f32_16x16x32_bf16 v[62:65], v[156:159], v[194:197], v[62:65]
	v_mfma_f32_16x16x32_bf16 v[54:57], v[170:173], v[194:197], v[54:57]
	v_mfma_f32_16x16x32_bf16 v[46:49], v[156:159], v[202:205], v[46:49]
	v_mfma_f32_16x16x32_bf16 v[38:41], v[170:173], v[202:205], v[38:41]
	v_mfma_f32_16x16x32_bf16 v[30:33], v[156:159], v[210:213], v[30:33]
	v_mfma_f32_16x16x32_bf16 v[22:25], v[170:173], v[210:213], v[22:25]
	v_mfma_f32_16x16x32_bf16 v[14:17], v[156:159], v[218:221], v[14:17]
	v_mfma_f32_16x16x32_bf16 v[6:9], v[170:173], v[218:221], v[6:9]
	v_mfma_f32_16x16x32_bf16 v[62:65], v[166:169], v[198:201], v[62:65]
	v_mfma_f32_16x16x32_bf16 v[54:57], v[174:177], v[198:201], v[54:57]
	v_mfma_f32_16x16x32_bf16 v[46:49], v[166:169], v[206:209], v[46:49]
	v_mfma_f32_16x16x32_bf16 v[38:41], v[174:177], v[206:209], v[38:41]
	v_mfma_f32_16x16x32_bf16 v[30:33], v[166:169], v[214:217], v[30:33]
	v_mfma_f32_16x16x32_bf16 v[22:25], v[174:177], v[214:217], v[22:25]
	v_mfma_f32_16x16x32_bf16 v[14:17], v[166:169], v[222:225], v[14:17]
	v_mfma_f32_16x16x32_bf16 v[6:9], v[174:177], v[222:225], v[6:9]
	s_setprio 0
	s_setprio 1
	v_mfma_f32_16x16x32_bf16 v[58:61], v[178:181], v[194:197], v[58:61]
	v_mfma_f32_16x16x32_bf16 v[50:53], v[186:189], v[194:197], v[50:53]
	v_mfma_f32_16x16x32_bf16 v[42:45], v[178:181], v[202:205], v[42:45]
	v_mfma_f32_16x16x32_bf16 v[34:37], v[186:189], v[202:205], v[34:37]
	v_mfma_f32_16x16x32_bf16 v[26:29], v[178:181], v[210:213], v[26:29]
	v_mfma_f32_16x16x32_bf16 v[18:21], v[186:189], v[210:213], v[18:21]
	v_mfma_f32_16x16x32_bf16 v[10:13], v[178:181], v[218:221], v[10:13]
	v_mfma_f32_16x16x32_bf16 v[2:5], v[186:189], v[218:221], v[2:5]
	v_mfma_f32_16x16x32_bf16 v[58:61], v[182:185], v[198:201], v[58:61]
	v_mfma_f32_16x16x32_bf16 v[50:53], v[190:193], v[198:201], v[50:53]
	v_mfma_f32_16x16x32_bf16 v[42:45], v[182:185], v[206:209], v[42:45]
	v_mfma_f32_16x16x32_bf16 v[34:37], v[190:193], v[206:209], v[34:37]
	v_mfma_f32_16x16x32_bf16 v[26:29], v[182:185], v[214:217], v[26:29]
	v_mfma_f32_16x16x32_bf16 v[18:21], v[190:193], v[214:217], v[18:21]
	v_mfma_f32_16x16x32_bf16 v[10:13], v[182:185], v[222:225], v[10:13]
	v_mfma_f32_16x16x32_bf16 v[2:5], v[190:193], v[222:225], v[2:5]
	s_setprio 0
	s_barrier
	s_mov_b32 s7, s47
	s_add_u32 s88, s88, 0x100
	s_addc_u32 s89, s89, 0
	s_add_u32 s86, s86, 0x100
	s_addc_u32 s87, s87, 0
	s_cmp_ge_i32 s47, s101
	s_cbranch_scc1 .Lmy_kexit_8
.LBB0_1573:
	s_add_u32 s98, s86, 0xfffc0080
	s_addc_u32 s99, s87, -1
	s_cmp_eq_u32 s7, s100
	s_cselect_b64 s[94:95], s[90:91], s[98:99]
	s_cselect_b64 s[96:97], s[92:93], s[88:89]
	ds_read_b128 v[156:159], v230
	ds_read_b128 v[166:169], v230 offset:1024
	ds_read_b128 v[170:173], v230 offset:2048
	ds_read_b128 v[174:177], v230 offset:3072
	ds_read_b128 v[178:181], v231
	ds_read_b128 v[182:185], v231 offset:1024
	ds_read_b128 v[186:189], v231 offset:2048
	ds_read_b128 v[190:193], v231 offset:3072
	s_add_i32 s47, s7, 2
	s_nop 0
	s_mov_b32 m0, s74
	ds_read_b128 v[194:197], v163
	ds_read_b128 v[198:201], v163 offset:1024
	ds_read_b128 v[202:205], v163 offset:2048
	ds_read_b128 v[206:209], v163 offset:3072
	ds_read_b128 v[210:213], v163 offset:4096
	ds_read_b128 v[214:217], v163 offset:5120
	ds_read_b128 v[218:221], v163 offset:6144
	ds_read_b128 v[222:225], v163 offset:7168
	global_load_lds_dwordx4 v144, s[86:87]
	s_mov_b32 m0, s75
	s_nop 0
	global_load_lds_dwordx4 v142, s[86:87]
	s_waitcnt vmcnt(8)
	s_waitcnt lgkmcnt(0)
	s_barrier
	s_setprio 1
	s_waitcnt lgkmcnt(0)
	v_mfma_f32_16x16x32_bf16 v[122:125], v[156:159], v[194:197], v[122:125]
	v_mfma_f32_16x16x32_bf16 v[118:121], v[170:173], v[194:197], v[118:121]
	v_mfma_f32_16x16x32_bf16 v[110:113], v[156:159], v[202:205], v[110:113]
	v_mfma_f32_16x16x32_bf16 v[102:105], v[170:173], v[202:205], v[102:105]
	v_mfma_f32_16x16x32_bf16 v[94:97], v[156:159], v[210:213], v[94:97]
	v_mfma_f32_16x16x32_bf16 v[86:89], v[170:173], v[210:213], v[86:89]
	v_mfma_f32_16x16x32_bf16 v[78:81], v[156:159], v[218:221], v[78:81]
	v_mfma_f32_16x16x32_bf16 v[70:73], v[170:173], v[218:221], v[70:73]
	v_mfma_f32_16x16x32_bf16 v[122:125], v[166:169], v[198:201], v[122:125]
	v_mfma_f32_16x16x32_bf16 v[118:121], v[174:177], v[198:201], v[118:121]
	v_mfma_f32_16x16x32_bf16 v[110:113], v[166:169], v[206:209], v[110:113]
	v_mfma_f32_16x16x32_bf16 v[102:105], v[174:177], v[206:209], v[102:105]
	v_mfma_f32_16x16x32_bf16 v[94:97], v[166:169], v[214:217], v[94:97]
	v_mfma_f32_16x16x32_bf16 v[86:89], v[174:177], v[214:217], v[86:89]
	v_mfma_f32_16x16x32_bf16 v[78:81], v[166:169], v[222:225], v[78:81]
	v_mfma_f32_16x16x32_bf16 v[70:73], v[174:177], v[222:225], v[70:73]
	s_setprio 0
	s_setprio 1
	v_mfma_f32_16x16x32_bf16 v[126:129], v[178:181], v[194:197], v[126:129]
	v_mfma_f32_16x16x32_bf16 v[114:117], v[186:189], v[194:197], v[114:117]
	v_mfma_f32_16x16x32_bf16 v[106:109], v[178:181], v[202:205], v[106:109]
	v_mfma_f32_16x16x32_bf16 v[98:101], v[186:189], v[202:205], v[98:101]
	v_mfma_f32_16x16x32_bf16 v[90:93], v[178:181], v[210:213], v[90:93]
	v_mfma_f32_16x16x32_bf16 v[82:85], v[186:189], v[210:213], v[82:85]
	v_mfma_f32_16x16x32_bf16 v[74:77], v[178:181], v[218:221], v[74:77]
	v_mfma_f32_16x16x32_bf16 v[66:69], v[186:189], v[218:221], v[66:69]
	v_mfma_f32_16x16x32_bf16 v[126:129], v[182:185], v[198:201], v[126:129]
	v_mfma_f32_16x16x32_bf16 v[114:117], v[190:193], v[198:201], v[114:117]
	v_mfma_f32_16x16x32_bf16 v[106:109], v[182:185], v[206:209], v[106:109]
	v_mfma_f32_16x16x32_bf16 v[98:101], v[190:193], v[206:209], v[98:101]
	v_mfma_f32_16x16x32_bf16 v[90:93], v[182:185], v[214:217], v[90:93]
	v_mfma_f32_16x16x32_bf16 v[82:85], v[190:193], v[214:217], v[82:85]
	v_mfma_f32_16x16x32_bf16 v[74:77], v[182:185], v[222:225], v[74:77]
	v_mfma_f32_16x16x32_bf16 v[66:69], v[190:193], v[222:225], v[66:69]
	s_setprio 0
	s_barrier
	s_add_u32 s98, s96, 0x40000
	s_addc_u32 s99, s97, 0
	s_add_i32 s7, s71, s29
	s_mov_b32 m0, s7
	ds_read_b128 v[194:197], v163 offset:16384
	ds_read_b128 v[198:201], v163 offset:17408
	ds_read_b128 v[202:205], v163 offset:18432
	ds_read_b128 v[206:209], v163 offset:19456
	ds_read_b128 v[210:213], v163 offset:20480
	ds_read_b128 v[214:217], v163 offset:21504
	ds_read_b128 v[218:221], v163 offset:22528
	ds_read_b128 v[222:225], v163 offset:23552
	global_load_lds_dwordx4 v132, s[96:97]
	s_add_i32 m0, s7, 0x2000
	s_add_i32 s7, s72, s29
	global_load_lds_dwordx4 v136, s[96:97]
	s_mov_b32 m0, s7
	s_nop 0
	global_load_lds_dwordx4 v132, s[98:99]
	s_add_i32 m0, s7, 0x2000
	s_nop 0
	global_load_lds_dwordx4 v136, s[98:99]
	s_mov_b32 m0, s51
	s_nop 0
	global_load_lds_dwordx4 v130, s[94:95]
	s_mov_b32 m0, s60
	s_nop 0
	global_load_lds_dwordx4 v134, s[94:95]
	s_waitcnt vmcnt(8)
	s_waitcnt lgkmcnt(0)
	s_barrier
	s_setprio 1
	s_waitcnt lgkmcnt(0)
	v_mfma_f32_16x16x32_bf16 v[62:65], v[156:159], v[194:197], v[62:65]
	v_mfma_f32_16x16x32_bf16 v[54:57], v[170:173], v[194:197], v[54:57]
	v_mfma_f32_16x16x32_bf16 v[46:49], v[156:159], v[202:205], v[46:49]
	v_mfma_f32_16x16x32_bf16 v[38:41], v[170:173], v[202:205], v[38:41]
	v_mfma_f32_16x16x32_bf16 v[30:33], v[156:159], v[210:213], v[30:33]
	v_mfma_f32_16x16x32_bf16 v[22:25], v[170:173], v[210:213], v[22:25]
	v_mfma_f32_16x16x32_bf16 v[14:17], v[156:159], v[218:221], v[14:17]
	v_mfma_f32_16x16x32_bf16 v[6:9], v[170:173], v[218:221], v[6:9]
	v_mfma_f32_16x16x32_bf16 v[62:65], v[166:169], v[198:201], v[62:65]
	v_mfma_f32_16x16x32_bf16 v[54:57], v[174:177], v[198:201], v[54:57]
	v_mfma_f32_16x16x32_bf16 v[46:49], v[166:169], v[206:209], v[46:49]
	v_mfma_f32_16x16x32_bf16 v[38:41], v[174:177], v[206:209], v[38:41]
	v_mfma_f32_16x16x32_bf16 v[30:33], v[166:169], v[214:217], v[30:33]
	v_mfma_f32_16x16x32_bf16 v[22:25], v[174:177], v[214:217], v[22:25]
	v_mfma_f32_16x16x32_bf16 v[14:17], v[166:169], v[222:225], v[14:17]
	v_mfma_f32_16x16x32_bf16 v[6:9], v[174:177], v[222:225], v[6:9]
	s_setprio 0
	s_setprio 1
	v_mfma_f32_16x16x32_bf16 v[58:61], v[178:181], v[194:197], v[58:61]
	v_mfma_f32_16x16x32_bf16 v[50:53], v[186:189], v[194:197], v[50:53]
	v_mfma_f32_16x16x32_bf16 v[42:45], v[178:181], v[202:205], v[42:45]
	v_mfma_f32_16x16x32_bf16 v[34:37], v[186:189], v[202:205], v[34:37]
	v_mfma_f32_16x16x32_bf16 v[26:29], v[178:181], v[210:213], v[26:29]
	v_mfma_f32_16x16x32_bf16 v[18:21], v[186:189], v[210:213], v[18:21]
	v_mfma_f32_16x16x32_bf16 v[10:13], v[178:181], v[218:221], v[10:13]
	v_mfma_f32_16x16x32_bf16 v[2:5], v[186:189], v[218:221], v[2:5]
	v_mfma_f32_16x16x32_bf16 v[58:61], v[182:185], v[198:201], v[58:61]
	v_mfma_f32_16x16x32_bf16 v[50:53], v[190:193], v[198:201], v[50:53]
	v_mfma_f32_16x16x32_bf16 v[42:45], v[182:185], v[206:209], v[42:45]
	v_mfma_f32_16x16x32_bf16 v[34:37], v[190:193], v[206:209], v[34:37]
	v_mfma_f32_16x16x32_bf16 v[26:29], v[182:185], v[214:217], v[26:29]
	v_mfma_f32_16x16x32_bf16 v[18:21], v[190:193], v[214:217], v[18:21]
	v_mfma_f32_16x16x32_bf16 v[10:13], v[182:185], v[222:225], v[10:13]
	v_mfma_f32_16x16x32_bf16 v[2:5], v[190:193], v[222:225], v[2:5]
	s_setprio 0
	s_barrier
	s_add_u32 s98, s94, 0x40000
	s_addc_u32 s99, s95, 0
	s_add_i32 s7, 0, 0x18000
	s_add_i32 s49, 0, 0x1c000
	ds_read_b128 v[156:159], v232
	ds_read_b128 v[166:169], v232 offset:1024
	ds_read_b128 v[170:173], v232 offset:2048
	ds_read_b128 v[174:177], v232 offset:3072
	ds_read_b128 v[178:181], v233
	ds_read_b128 v[182:185], v233 offset:1024
	ds_read_b128 v[186:189], v233 offset:2048
	ds_read_b128 v[190:193], v233 offset:3072
	s_mov_b32 m0, s61
	ds_read_b128 v[194:197], v163 offset:32768
	ds_read_b128 v[198:201], v163 offset:33792
	ds_read_b128 v[202:205], v163 offset:34816
	ds_read_b128 v[206:209], v163 offset:35840
	ds_read_b128 v[210:213], v163 offset:36864
	ds_read_b128 v[214:217], v163 offset:37888
	ds_read_b128 v[218:221], v163 offset:38912
	ds_read_b128 v[222:225], v163 offset:39936
	global_load_lds_dwordx4 v130, s[98:99]
	s_mov_b32 m0, s62
	s_nop 0
	global_load_lds_dwordx4 v134, s[98:99]
	s_waitcnt vmcnt(8)
	s_waitcnt lgkmcnt(0)
	s_barrier
	s_setprio 1
	s_waitcnt lgkmcnt(0)
	v_mfma_f32_16x16x32_bf16 v[122:125], v[156:159], v[194:197], v[122:125]
	v_mfma_f32_16x16x32_bf16 v[118:121], v[170:173], v[194:197], v[118:121]
	v_mfma_f32_16x16x32_bf16 v[110:113], v[156:159], v[202:205], v[110:113]
	v_mfma_f32_16x16x32_bf16 v[102:105], v[170:173], v[202:205], v[102:105]
	v_mfma_f32_16x16x32_bf16 v[94:97], v[156:159], v[210:213], v[94:97]
	v_mfma_f32_16x16x32_bf16 v[86:89], v[170:173], v[210:213], v[86:89]
	v_mfma_f32_16x16x32_bf16 v[78:81], v[156:159], v[218:221], v[78:81]
	v_mfma_f32_16x16x32_bf16 v[70:73], v[170:173], v[218:221], v[70:73]
	v_mfma_f32_16x16x32_bf16 v[122:125], v[166:169], v[198:201], v[122:125]
	v_mfma_f32_16x16x32_bf16 v[118:121], v[174:177], v[198:201], v[118:121]
	v_mfma_f32_16x16x32_bf16 v[110:113], v[166:169], v[206:209], v[110:113]
	v_mfma_f32_16x16x32_bf16 v[102:105], v[174:177], v[206:209], v[102:105]
	v_mfma_f32_16x16x32_bf16 v[94:97], v[166:169], v[214:217], v[94:97]
	v_mfma_f32_16x16x32_bf16 v[86:89], v[174:177], v[214:217], v[86:89]
	v_mfma_f32_16x16x32_bf16 v[78:81], v[166:169], v[222:225], v[78:81]
	v_mfma_f32_16x16x32_bf16 v[70:73], v[174:177], v[222:225], v[70:73]
	s_setprio 0
	s_setprio 1
	v_mfma_f32_16x16x32_bf16 v[126:129], v[178:181], v[194:197], v[126:129]
	v_mfma_f32_16x16x32_bf16 v[114:117], v[186:189], v[194:197], v[114:117]
	v_mfma_f32_16x16x32_bf16 v[106:109], v[178:181], v[202:205], v[106:109]
	v_mfma_f32_16x16x32_bf16 v[98:101], v[186:189], v[202:205], v[98:101]
	v_mfma_f32_16x16x32_bf16 v[90:93], v[178:181], v[210:213], v[90:93]
	v_mfma_f32_16x16x32_bf16 v[82:85], v[186:189], v[210:213], v[82:85]
	v_mfma_f32_16x16x32_bf16 v[74:77], v[178:181], v[218:221], v[74:77]
	v_mfma_f32_16x16x32_bf16 v[66:69], v[186:189], v[218:221], v[66:69]
	v_mfma_f32_16x16x32_bf16 v[126:129], v[182:185], v[198:201], v[126:129]
	v_mfma_f32_16x16x32_bf16 v[114:117], v[190:193], v[198:201], v[114:117]
	v_mfma_f32_16x16x32_bf16 v[106:109], v[182:185], v[206:209], v[106:109]
	v_mfma_f32_16x16x32_bf16 v[98:101], v[190:193], v[206:209], v[98:101]
	v_mfma_f32_16x16x32_bf16 v[90:93], v[182:185], v[214:217], v[90:93]
	v_mfma_f32_16x16x32_bf16 v[82:85], v[190:193], v[214:217], v[82:85]
	v_mfma_f32_16x16x32_bf16 v[74:77], v[182:185], v[222:225], v[74:77]
	v_mfma_f32_16x16x32_bf16 v[66:69], v[190:193], v[222:225], v[66:69]
	s_setprio 0
	s_barrier
	s_add_u32 s96, s96, 0x80
	s_addc_u32 s97, s97, 0
	s_add_u32 s98, s96, 0x40000
	s_addc_u32 s99, s97, 0
	s_add_u32 s94, s94, 0x80
	s_addc_u32 s95, s95, 0
	s_add_i32 s7, s7, s29
	s_mov_b32 m0, s7
	ds_read_b128 v[194:197], v163 offset:49152
	ds_read_b128 v[198:201], v163 offset:50176
	ds_read_b128 v[202:205], v163 offset:51200
	ds_read_b128 v[206:209], v163 offset:52224
	ds_read_b128 v[210:213], v163 offset:53248
	ds_read_b128 v[214:217], v163 offset:54272
	ds_read_b128 v[218:221], v163 offset:55296
	ds_read_b128 v[222:225], v163 offset:56320
	global_load_lds_dwordx4 v132, s[96:97]
	s_add_i32 m0, s7, 0x2000
	s_add_i32 s7, s49, s29
	global_load_lds_dwordx4 v136, s[96:97]
	s_mov_b32 m0, s7
	s_nop 0
	global_load_lds_dwordx4 v132, s[98:99]
	s_add_i32 m0, s7, 0x2000
	s_nop 0
	global_load_lds_dwordx4 v136, s[98:99]
	s_mov_b32 m0, s63
	s_nop 0
	global_load_lds_dwordx4 v130, s[94:95]
	s_mov_b32 m0, s64
	s_nop 0
	global_load_lds_dwordx4 v134, s[94:95]
	s_waitcnt vmcnt(8)
	s_waitcnt lgkmcnt(0)
	s_barrier
	s_setprio 1
	s_waitcnt lgkmcnt(0)
	v_mfma_f32_16x16x32_bf16 v[62:65], v[156:159], v[194:197], v[62:65]
	v_mfma_f32_16x16x32_bf16 v[54:57], v[170:173], v[194:197], v[54:57]
	v_mfma_f32_16x16x32_bf16 v[46:49], v[156:159], v[202:205], v[46:49]
	v_mfma_f32_16x16x32_bf16 v[38:41], v[170:173], v[202:205], v[38:41]
	v_mfma_f32_16x16x32_bf16 v[30:33], v[156:159], v[210:213], v[30:33]
	v_mfma_f32_16x16x32_bf16 v[22:25], v[170:173], v[210:213], v[22:25]
	v_mfma_f32_16x16x32_bf16 v[14:17], v[156:159], v[218:221], v[14:17]
	v_mfma_f32_16x16x32_bf16 v[6:9], v[170:173], v[218:221], v[6:9]
	v_mfma_f32_16x16x32_bf16 v[62:65], v[166:169], v[198:201], v[62:65]
	v_mfma_f32_16x16x32_bf16 v[54:57], v[174:177], v[198:201], v[54:57]
	v_mfma_f32_16x16x32_bf16 v[46:49], v[166:169], v[206:209], v[46:49]
	v_mfma_f32_16x16x32_bf16 v[38:41], v[174:177], v[206:209], v[38:41]
	v_mfma_f32_16x16x32_bf16 v[30:33], v[166:169], v[214:217], v[30:33]
	v_mfma_f32_16x16x32_bf16 v[22:25], v[174:177], v[214:217], v[22:25]
	v_mfma_f32_16x16x32_bf16 v[14:17], v[166:169], v[222:225], v[14:17]
	v_mfma_f32_16x16x32_bf16 v[6:9], v[174:177], v[222:225], v[6:9]
	s_setprio 0
	s_setprio 1
	v_mfma_f32_16x16x32_bf16 v[58:61], v[178:181], v[194:197], v[58:61]
	v_mfma_f32_16x16x32_bf16 v[50:53], v[186:189], v[194:197], v[50:53]
	v_mfma_f32_16x16x32_bf16 v[42:45], v[178:181], v[202:205], v[42:45]
	v_mfma_f32_16x16x32_bf16 v[34:37], v[186:189], v[202:205], v[34:37]
	v_mfma_f32_16x16x32_bf16 v[26:29], v[178:181], v[210:213], v[26:29]
	v_mfma_f32_16x16x32_bf16 v[18:21], v[186:189], v[210:213], v[18:21]
	v_mfma_f32_16x16x32_bf16 v[10:13], v[178:181], v[218:221], v[10:13]
	v_mfma_f32_16x16x32_bf16 v[2:5], v[186:189], v[218:221], v[2:5]
	v_mfma_f32_16x16x32_bf16 v[58:61], v[182:185], v[198:201], v[58:61]
	v_mfma_f32_16x16x32_bf16 v[50:53], v[190:193], v[198:201], v[50:53]
	v_mfma_f32_16x16x32_bf16 v[42:45], v[182:185], v[206:209], v[42:45]
	v_mfma_f32_16x16x32_bf16 v[34:37], v[190:193], v[206:209], v[34:37]
	v_mfma_f32_16x16x32_bf16 v[26:29], v[182:185], v[214:217], v[26:29]
	v_mfma_f32_16x16x32_bf16 v[18:21], v[190:193], v[214:217], v[18:21]
	v_mfma_f32_16x16x32_bf16 v[10:13], v[182:185], v[222:225], v[10:13]
	v_mfma_f32_16x16x32_bf16 v[2:5], v[190:193], v[222:225], v[2:5]
	s_setprio 0
	s_barrier
	s_mov_b32 s7, s47
	s_add_u32 s88, s88, 0x100
	s_addc_u32 s89, s89, 0
	s_add_u32 s86, s86, 0x100
	s_addc_u32 s87, s87, 0
	s_cmp_ge_i32 s47, s101
	s_cbranch_scc0 .LBB0_1573

.LBB0_1761:
	v_cmp_gt_i32_e32 vcc, 1, v138
	s_cbranch_vccnz .LBB0_1823
	v_lshl_add_u64 v[152:153], v[2:3], 0, s[14:15]
	v_add_u32_e32 v154, -2, v138
	s_waitcnt lgkmcnt(0)
	v_lshl_add_u64 v[150:151], v[4:5], 0, s[18:19]
	s_mov_b32 s5, 0
	s_nop 0
	v_readfirstlane_b32 s86, v152
	v_readfirstlane_b32 s87, v153
	v_readfirstlane_b32 s88, v150
	v_readfirstlane_b32 s89, v151
	v_readfirstlane_b32 s90, v146
	v_readfirstlane_b32 s91, v147
	v_readfirstlane_b32 s92, v148
	v_readfirstlane_b32 s93, v149
	v_readfirstlane_b32 s100, v154
	v_readfirstlane_b32 s101, v138
	v_add_u32_e32 v230, s74, v141
	v_add_u32_e32 v231, s75, v141
	v_add_u32_e32 v232, 0x18000, v141
	v_add_u32_e32 v233, 0x1c000, v141
	s_add_u32 s98, s86, 0xfffc0080
	s_addc_u32 s99, s87, -1
	s_cmp_eq_u32 s5, s100
	s_cselect_b64 s[94:95], s[90:91], s[98:99]
	s_cselect_b64 s[96:97], s[92:93], s[88:89]
	ds_read_b128 v[164:167], v230
	ds_read_b128 v[168:171], v230 offset:1024
	ds_read_b128 v[172:175], v230 offset:2048
	ds_read_b128 v[176:179], v230 offset:3072
	ds_read_b128 v[180:183], v231
	ds_read_b128 v[184:187], v231 offset:1024
	ds_read_b128 v[188:191], v231 offset:2048
	ds_read_b128 v[192:195], v231 offset:3072
	s_add_i32 s29, s5, 2
	s_nop 0
	s_add_i32 m0, s47, 0xc000
	ds_read_b128 v[196:199], v160
	ds_read_b128 v[200:203], v160 offset:1024
	ds_read_b128 v[204:207], v160 offset:2048
	ds_read_b128 v[208:211], v160 offset:3072
	ds_read_b128 v[212:215], v160 offset:4096
	ds_read_b128 v[216:219], v160 offset:5120
	ds_read_b128 v[220:223], v160 offset:6144
	ds_read_b128 v[224:227], v160 offset:7168
	global_load_lds_dwordx4 v144, s[86:87]
	s_add_i32 m0, s47, 0xe000
	s_nop 0
	global_load_lds_dwordx4 v142, s[86:87]
	s_waitcnt vmcnt(8)
	s_waitcnt lgkmcnt(0)
	s_barrier
	s_setprio 1
	s_waitcnt lgkmcnt(0)
	v_mfma_f32_16x16x32_bf16 v[122:125], v[164:167], v[196:199], 0
	v_mfma_f32_16x16x32_bf16 v[118:121], v[172:175], v[196:199], 0
	v_mfma_f32_16x16x32_bf16 v[110:113], v[164:167], v[204:207], 0
	v_mfma_f32_16x16x32_bf16 v[102:105], v[172:175], v[204:207], 0
	v_mfma_f32_16x16x32_bf16 v[94:97], v[164:167], v[212:215], 0
	v_mfma_f32_16x16x32_bf16 v[86:89], v[172:175], v[212:215], 0
	v_mfma_f32_16x16x32_bf16 v[78:81], v[164:167], v[220:223], 0
	v_mfma_f32_16x16x32_bf16 v[70:73], v[172:175], v[220:223], 0
	v_mfma_f32_16x16x32_bf16 v[122:125], v[168:171], v[200:203], v[122:125]
	v_mfma_f32_16x16x32_bf16 v[118:121], v[176:179], v[200:203], v[118:121]
	v_mfma_f32_16x16x32_bf16 v[110:113], v[168:171], v[208:211], v[110:113]
	v_mfma_f32_16x16x32_bf16 v[102:105], v[176:179], v[208:211], v[102:105]
	v_mfma_f32_16x16x32_bf16 v[94:97], v[168:171], v[216:219], v[94:97]
	v_mfma_f32_16x16x32_bf16 v[86:89], v[176:179], v[216:219], v[86:89]
	v_mfma_f32_16x16x32_bf16 v[78:81], v[168:171], v[224:227], v[78:81]
	v_mfma_f32_16x16x32_bf16 v[70:73], v[176:179], v[224:227], v[70:73]
	s_setprio 0
	s_setprio 1
	v_mfma_f32_16x16x32_bf16 v[126:129], v[180:183], v[196:199], 0
	v_mfma_f32_16x16x32_bf16 v[114:117], v[188:191], v[196:199], 0
	v_mfma_f32_16x16x32_bf16 v[106:109], v[180:183], v[204:207], 0
	v_mfma_f32_16x16x32_bf16 v[98:101], v[188:191], v[204:207], 0
	v_mfma_f32_16x16x32_bf16 v[90:93], v[180:183], v[212:215], 0
	v_mfma_f32_16x16x32_bf16 v[82:85], v[188:191], v[212:215], 0
	v_mfma_f32_16x16x32_bf16 v[74:77], v[180:183], v[220:223], 0
	v_mfma_f32_16x16x32_bf16 v[66:69], v[188:191], v[220:223], 0
	v_mfma_f32_16x16x32_bf16 v[126:129], v[184:187], v[200:203], v[126:129]
	v_mfma_f32_16x16x32_bf16 v[114:117], v[192:195], v[200:203], v[114:117]
	v_mfma_f32_16x16x32_bf16 v[106:109], v[184:187], v[208:211], v[106:109]
	v_mfma_f32_16x16x32_bf16 v[98:101], v[192:195], v[208:211], v[98:101]
	v_mfma_f32_16x16x32_bf16 v[90:93], v[184:187], v[216:219], v[90:93]
	v_mfma_f32_16x16x32_bf16 v[82:85], v[192:195], v[216:219], v[82:85]
	v_mfma_f32_16x16x32_bf16 v[74:77], v[184:187], v[224:227], v[74:77]
	v_mfma_f32_16x16x32_bf16 v[66:69], v[192:195], v[224:227], v[66:69]
	s_setprio 0
	s_barrier
	s_add_u32 s98, s96, 0x40000
	s_addc_u32 s99, s97, 0
	s_add_i32 s5, s74, s23
	s_mov_b32 m0, s5
	ds_read_b128 v[196:199], v160 offset:16384
	ds_read_b128 v[200:203], v160 offset:17408
	ds_read_b128 v[204:207], v160 offset:18432
	ds_read_b128 v[208:211], v160 offset:19456
	ds_read_b128 v[212:215], v160 offset:20480
	ds_read_b128 v[216:219], v160 offset:21504
	ds_read_b128 v[220:223], v160 offset:22528
	ds_read_b128 v[224:227], v160 offset:23552
	global_load_lds_dwordx4 v132, s[96:97]
	s_add_i32 m0, s5, 0x2000
	s_add_i32 s5, s75, s23
	global_load_lds_dwordx4 v136, s[96:97]
	s_mov_b32 m0, s5
	s_nop 0
	global_load_lds_dwordx4 v132, s[98:99]
	s_add_i32 m0, s5, 0x2000
	s_nop 0
	global_load_lds_dwordx4 v136, s[98:99]
	s_mov_b32 m0, s47
	s_nop 0
	global_load_lds_dwordx4 v130, s[94:95]
	s_mov_b32 m0, s56
	s_nop 0
	global_load_lds_dwordx4 v134, s[94:95]
	s_waitcnt vmcnt(8)
	s_waitcnt lgkmcnt(0)
	s_barrier
	s_setprio 1
	s_waitcnt lgkmcnt(0)
	v_mfma_f32_16x16x32_bf16 v[62:65], v[164:167], v[196:199], 0
	v_mfma_f32_16x16x32_bf16 v[54:57], v[172:175], v[196:199], 0
	v_mfma_f32_16x16x32_bf16 v[46:49], v[164:167], v[204:207], 0
	v_mfma_f32_16x16x32_bf16 v[38:41], v[172:175], v[204:207], 0
	v_mfma_f32_16x16x32_bf16 v[30:33], v[164:167], v[212:215], 0
	v_mfma_f32_16x16x32_bf16 v[22:25], v[172:175], v[212:215], 0
	v_mfma_f32_16x16x32_bf16 v[14:17], v[164:167], v[220:223], 0
	v_mfma_f32_16x16x32_bf16 v[6:9], v[172:175], v[220:223], 0
	v_mfma_f32_16x16x32_bf16 v[62:65], v[168:171], v[200:203], v[62:65]
	v_mfma_f32_16x16x32_bf16 v[54:57], v[176:179], v[200:203], v[54:57]
	v_mfma_f32_16x16x32_bf16 v[46:49], v[168:171], v[208:211], v[46:49]
	v_mfma_f32_16x16x32_bf16 v[38:41], v[176:179], v[208:211], v[38:41]
	v_mfma_f32_16x16x32_bf16 v[30:33], v[168:171], v[216:219], v[30:33]
	v_mfma_f32_16x16x32_bf16 v[22:25], v[176:179], v[216:219], v[22:25]
	v_mfma_f32_16x16x32_bf16 v[14:17], v[168:171], v[224:227], v[14:17]
	v_mfma_f32_16x16x32_bf16 v[6:9], v[176:179], v[224:227], v[6:9]
	s_setprio 0
	s_setprio 1
	v_mfma_f32_16x16x32_bf16 v[58:61], v[180:183], v[196:199], 0
	v_mfma_f32_16x16x32_bf16 v[50:53], v[188:191], v[196:199], 0
	v_mfma_f32_16x16x32_bf16 v[42:45], v[180:183], v[204:207], 0
	v_mfma_f32_16x16x32_bf16 v[34:37], v[188:191], v[204:207], 0
	v_mfma_f32_16x16x32_bf16 v[26:29], v[180:183], v[212:215], 0
	v_mfma_f32_16x16x32_bf16 v[18:21], v[188:191], v[212:215], 0
	v_mfma_f32_16x16x32_bf16 v[10:13], v[180:183], v[220:223], 0
	v_mfma_f32_16x16x32_bf16 v[2:5], v[188:191], v[220:223], 0
	v_mfma_f32_16x16x32_bf16 v[58:61], v[184:187], v[200:203], v[58:61]
	v_mfma_f32_16x16x32_bf16 v[50:53], v[192:195], v[200:203], v[50:53]
	v_mfma_f32_16x16x32_bf16 v[42:45], v[184:187], v[208:211], v[42:45]
	v_mfma_f32_16x16x32_bf16 v[34:37], v[192:195], v[208:211], v[34:37]
	v_mfma_f32_16x16x32_bf16 v[26:29], v[184:187], v[216:219], v[26:29]
	v_mfma_f32_16x16x32_bf16 v[18:21], v[192:195], v[216:219], v[18:21]
	v_mfma_f32_16x16x32_bf16 v[10:13], v[184:187], v[224:227], v[10:13]
	v_mfma_f32_16x16x32_bf16 v[2:5], v[192:195], v[224:227], v[2:5]
	s_setprio 0
	s_barrier
	s_add_u32 s98, s94, 0x40000
	s_addc_u32 s99, s95, 0
	s_add_i32 s5, 0, 0x18000
	s_add_i32 s45, 0, 0x1c000
	ds_read_b128 v[164:167], v232
	ds_read_b128 v[168:171], v232 offset:1024
	ds_read_b128 v[172:175], v232 offset:2048
	ds_read_b128 v[176:179], v232 offset:3072
	ds_read_b128 v[180:183], v233
	ds_read_b128 v[184:187], v233 offset:1024
	ds_read_b128 v[188:191], v233 offset:2048
	ds_read_b128 v[192:195], v233 offset:3072
	s_mov_b32 m0, s57
	ds_read_b128 v[196:199], v160 offset:32768
	ds_read_b128 v[200:203], v160 offset:33792
	ds_read_b128 v[204:207], v160 offset:34816
	ds_read_b128 v[208:211], v160 offset:35840
	ds_read_b128 v[212:215], v160 offset:36864
	ds_read_b128 v[216:219], v160 offset:37888
	ds_read_b128 v[220:223], v160 offset:38912
	ds_read_b128 v[224:227], v160 offset:39936
	global_load_lds_dwordx4 v130, s[98:99]
	s_mov_b32 m0, s58
	s_nop 0
	global_load_lds_dwordx4 v134, s[98:99]
	s_waitcnt vmcnt(8)
	s_waitcnt lgkmcnt(0)
	s_barrier
	s_setprio 1
	s_waitcnt lgkmcnt(0)
	v_mfma_f32_16x16x32_bf16 v[122:125], v[164:167], v[196:199], v[122:125]
	v_mfma_f32_16x16x32_bf16 v[118:121], v[172:175], v[196:199], v[118:121]
	v_mfma_f32_16x16x32_bf16 v[110:113], v[164:167], v[204:207], v[110:113]
	v_mfma_f32_16x16x32_bf16 v[102:105], v[172:175], v[204:207], v[102:105]
	v_mfma_f32_16x16x32_bf16 v[94:97], v[164:167], v[212:215], v[94:97]
	v_mfma_f32_16x16x32_bf16 v[86:89], v[172:175], v[212:215], v[86:89]
	v_mfma_f32_16x16x32_bf16 v[78:81], v[164:167], v[220:223], v[78:81]
	v_mfma_f32_16x16x32_bf16 v[70:73], v[172:175], v[220:223], v[70:73]
	v_mfma_f32_16x16x32_bf16 v[122:125], v[168:171], v[200:203], v[122:125]
	v_mfma_f32_16x16x32_bf16 v[118:121], v[176:179], v[200:203], v[118:121]
	v_mfma_f32_16x16x32_bf16 v[110:113], v[168:171], v[208:211], v[110:113]
	v_mfma_f32_16x16x32_bf16 v[102:105], v[176:179], v[208:211], v[102:105]
	v_mfma_f32_16x16x32_bf16 v[94:97], v[168:171], v[216:219], v[94:97]
	v_mfma_f32_16x16x32_bf16 v[86:89], v[176:179], v[216:219], v[86:89]
	v_mfma_f32_16x16x32_bf16 v[78:81], v[168:171], v[224:227], v[78:81]
	v_mfma_f32_16x16x32_bf16 v[70:73], v[176:179], v[224:227], v[70:73]
	s_setprio 0
	s_setprio 1
	v_mfma_f32_16x16x32_bf16 v[126:129], v[180:183], v[196:199], v[126:129]
	v_mfma_f32_16x16x32_bf16 v[114:117], v[188:191], v[196:199], v[114:117]
	v_mfma_f32_16x16x32_bf16 v[106:109], v[180:183], v[204:207], v[106:109]
	v_mfma_f32_16x16x32_bf16 v[98:101], v[188:191], v[204:207], v[98:101]
	v_mfma_f32_16x16x32_bf16 v[90:93], v[180:183], v[212:215], v[90:93]
	v_mfma_f32_16x16x32_bf16 v[82:85], v[188:191], v[212:215], v[82:85]
	v_mfma_f32_16x16x32_bf16 v[74:77], v[180:183], v[220:223], v[74:77]
	v_mfma_f32_16x16x32_bf16 v[66:69], v[188:191], v[220:223], v[66:69]
	v_mfma_f32_16x16x32_bf16 v[126:129], v[184:187], v[200:203], v[126:129]
	v_mfma_f32_16x16x32_bf16 v[114:117], v[192:195], v[200:203], v[114:117]
	v_mfma_f32_16x16x32_bf16 v[106:109], v[184:187], v[208:211], v[106:109]
	v_mfma_f32_16x16x32_bf16 v[98:101], v[192:195], v[208:211], v[98:101]
	v_mfma_f32_16x16x32_bf16 v[90:93], v[184:187], v[216:219], v[90:93]
	v_mfma_f32_16x16x32_bf16 v[82:85], v[192:195], v[216:219], v[82:85]
	v_mfma_f32_16x16x32_bf16 v[74:77], v[184:187], v[224:227], v[74:77]
	v_mfma_f32_16x16x32_bf16 v[66:69], v[192:195], v[224:227], v[66:69]
	s_setprio 0
	s_barrier
	s_add_u32 s96, s96, 0x80
	s_addc_u32 s97, s97, 0
	s_add_u32 s98, s96, 0x40000
	s_addc_u32 s99, s97, 0
	s_add_u32 s94, s94, 0x80
	s_addc_u32 s95, s95, 0
	s_add_i32 s5, s5, s23
	s_mov_b32 m0, s5
	ds_read_b128 v[196:199], v160 offset:49152
	ds_read_b128 v[200:203], v160 offset:50176
	ds_read_b128 v[204:207], v160 offset:51200
	ds_read_b128 v[208:211], v160 offset:52224
	ds_read_b128 v[212:215], v160 offset:53248
	ds_read_b128 v[216:219], v160 offset:54272
	ds_read_b128 v[220:223], v160 offset:55296
	ds_read_b128 v[224:227], v160 offset:56320
	global_load_lds_dwordx4 v132, s[96:97]
	s_add_i32 m0, s5, 0x2000
	s_add_i32 s5, s45, s23
	global_load_lds_dwordx4 v136, s[96:97]
	s_mov_b32 m0, s5
	s_nop 0
	global_load_lds_dwordx4 v132, s[98:99]
	s_add_i32 m0, s5, 0x2000
	s_nop 0
	global_load_lds_dwordx4 v136, s[98:99]
	s_mov_b32 m0, s64
	s_nop 0
	global_load_lds_dwordx4 v130, s[94:95]
	s_mov_b32 m0, s65
	s_nop 0
	global_load_lds_dwordx4 v134, s[94:95]
	s_waitcnt vmcnt(8)
	s_waitcnt lgkmcnt(0)
	s_barrier
	s_setprio 1
	s_waitcnt lgkmcnt(0)
	v_mfma_f32_16x16x32_bf16 v[62:65], v[164:167], v[196:199], v[62:65]
	v_mfma_f32_16x16x32_bf16 v[54:57], v[172:175], v[196:199], v[54:57]
	v_mfma_f32_16x16x32_bf16 v[46:49], v[164:167], v[204:207], v[46:49]
	v_mfma_f32_16x16x32_bf16 v[38:41], v[172:175], v[204:207], v[38:41]
	v_mfma_f32_16x16x32_bf16 v[30:33], v[164:167], v[212:215], v[30:33]
	v_mfma_f32_16x16x32_bf16 v[22:25], v[172:175], v[212:215], v[22:25]
	v_mfma_f32_16x16x32_bf16 v[14:17], v[164:167], v[220:223], v[14:17]
	v_mfma_f32_16x16x32_bf16 v[6:9], v[172:175], v[220:223], v[6:9]
	v_mfma_f32_16x16x32_bf16 v[62:65], v[168:171], v[200:203], v[62:65]
	v_mfma_f32_16x16x32_bf16 v[54:57], v[176:179], v[200:203], v[54:57]
	v_mfma_f32_16x16x32_bf16 v[46:49], v[168:171], v[208:211], v[46:49]
	v_mfma_f32_16x16x32_bf16 v[38:41], v[176:179], v[208:211], v[38:41]
	v_mfma_f32_16x16x32_bf16 v[30:33], v[168:171], v[216:219], v[30:33]
	v_mfma_f32_16x16x32_bf16 v[22:25], v[176:179], v[216:219], v[22:25]
	v_mfma_f32_16x16x32_bf16 v[14:17], v[168:171], v[224:227], v[14:17]
	v_mfma_f32_16x16x32_bf16 v[6:9], v[176:179], v[224:227], v[6:9]
	s_setprio 0
	s_setprio 1
	v_mfma_f32_16x16x32_bf16 v[58:61], v[180:183], v[196:199], v[58:61]
	v_mfma_f32_16x16x32_bf16 v[50:53], v[188:191], v[196:199], v[50:53]
	v_mfma_f32_16x16x32_bf16 v[42:45], v[180:183], v[204:207], v[42:45]
	v_mfma_f32_16x16x32_bf16 v[34:37], v[188:191], v[204:207], v[34:37]
	v_mfma_f32_16x16x32_bf16 v[26:29], v[180:183], v[212:215], v[26:29]
	v_mfma_f32_16x16x32_bf16 v[18:21], v[188:191], v[212:215], v[18:21]
	v_mfma_f32_16x16x32_bf16 v[10:13], v[180:183], v[220:223], v[10:13]
	v_mfma_f32_16x16x32_bf16 v[2:5], v[188:191], v[220:223], v[2:5]
	v_mfma_f32_16x16x32_bf16 v[58:61], v[184:187], v[200:203], v[58:61]
	v_mfma_f32_16x16x32_bf16 v[50:53], v[192:195], v[200:203], v[50:53]
	v_mfma_f32_16x16x32_bf16 v[42:45], v[184:187], v[208:211], v[42:45]
	v_mfma_f32_16x16x32_bf16 v[34:37], v[192:195], v[208:211], v[34:37]
	v_mfma_f32_16x16x32_bf16 v[26:29], v[184:187], v[216:219], v[26:29]
	v_mfma_f32_16x16x32_bf16 v[18:21], v[192:195], v[216:219], v[18:21]
	v_mfma_f32_16x16x32_bf16 v[10:13], v[184:187], v[224:227], v[10:13]
	v_mfma_f32_16x16x32_bf16 v[2:5], v[192:195], v[224:227], v[2:5]
	s_setprio 0
	s_barrier
	s_mov_b32 s5, s29
	s_add_u32 s88, s88, 0x100
	s_addc_u32 s89, s89, 0
	s_add_u32 s86, s86, 0x100
	s_addc_u32 s87, s87, 0
	s_cmp_ge_i32 s29, s101
	s_cbranch_scc1 .Lmy_kexit_9
.LBB0_1763:
	s_add_u32 s98, s86, 0xfffc0080
	s_addc_u32 s99, s87, -1
	s_cmp_eq_u32 s5, s100
	s_cselect_b64 s[94:95], s[90:91], s[98:99]
	s_cselect_b64 s[96:97], s[92:93], s[88:89]
	ds_read_b128 v[164:167], v230
	ds_read_b128 v[168:171], v230 offset:1024
	ds_read_b128 v[172:175], v230 offset:2048
	ds_read_b128 v[176:179], v230 offset:3072
	ds_read_b128 v[180:183], v231
	ds_read_b128 v[184:187], v231 offset:1024
	ds_read_b128 v[188:191], v231 offset:2048
	ds_read_b128 v[192:195], v231 offset:3072
	s_add_i32 s29, s5, 2
	s_nop 0
	s_add_i32 m0, s47, 0xc000
	ds_read_b128 v[196:199], v160
	ds_read_b128 v[200:203], v160 offset:1024
	ds_read_b128 v[204:207], v160 offset:2048
	ds_read_b128 v[208:211], v160 offset:3072
	ds_read_b128 v[212:215], v160 offset:4096
	ds_read_b128 v[216:219], v160 offset:5120
	ds_read_b128 v[220:223], v160 offset:6144
	ds_read_b128 v[224:227], v160 offset:7168
	global_load_lds_dwordx4 v144, s[86:87]
	s_add_i32 m0, s47, 0xe000
	s_nop 0
	global_load_lds_dwordx4 v142, s[86:87]
	s_waitcnt vmcnt(8)
	s_waitcnt lgkmcnt(0)
	s_barrier
	s_setprio 1
	s_waitcnt lgkmcnt(0)
	v_mfma_f32_16x16x32_bf16 v[122:125], v[164:167], v[196:199], v[122:125]
	v_mfma_f32_16x16x32_bf16 v[118:121], v[172:175], v[196:199], v[118:121]
	v_mfma_f32_16x16x32_bf16 v[110:113], v[164:167], v[204:207], v[110:113]
	v_mfma_f32_16x16x32_bf16 v[102:105], v[172:175], v[204:207], v[102:105]
	v_mfma_f32_16x16x32_bf16 v[94:97], v[164:167], v[212:215], v[94:97]
	v_mfma_f32_16x16x32_bf16 v[86:89], v[172:175], v[212:215], v[86:89]
	v_mfma_f32_16x16x32_bf16 v[78:81], v[164:167], v[220:223], v[78:81]
	v_mfma_f32_16x16x32_bf16 v[70:73], v[172:175], v[220:223], v[70:73]
	v_mfma_f32_16x16x32_bf16 v[122:125], v[168:171], v[200:203], v[122:125]
	v_mfma_f32_16x16x32_bf16 v[118:121], v[176:179], v[200:203], v[118:121]
	v_mfma_f32_16x16x32_bf16 v[110:113], v[168:171], v[208:211], v[110:113]
	v_mfma_f32_16x16x32_bf16 v[102:105], v[176:179], v[208:211], v[102:105]
	v_mfma_f32_16x16x32_bf16 v[94:97], v[168:171], v[216:219], v[94:97]
	v_mfma_f32_16x16x32_bf16 v[86:89], v[176:179], v[216:219], v[86:89]
	v_mfma_f32_16x16x32_bf16 v[78:81], v[168:171], v[224:227], v[78:81]
	v_mfma_f32_16x16x32_bf16 v[70:73], v[176:179], v[224:227], v[70:73]
	s_setprio 0
	s_setprio 1
	v_mfma_f32_16x16x32_bf16 v[126:129], v[180:183], v[196:199], v[126:129]
	v_mfma_f32_16x16x32_bf16 v[114:117], v[188:191], v[196:199], v[114:117]
	v_mfma_f32_16x16x32_bf16 v[106:109], v[180:183], v[204:207], v[106:109]
	v_mfma_f32_16x16x32_bf16 v[98:101], v[188:191], v[204:207], v[98:101]
	v_mfma_f32_16x16x32_bf16 v[90:93], v[180:183], v[212:215], v[90:93]
	v_mfma_f32_16x16x32_bf16 v[82:85], v[188:191], v[212:215], v[82:85]
	v_mfma_f32_16x16x32_bf16 v[74:77], v[180:183], v[220:223], v[74:77]
	v_mfma_f32_16x16x32_bf16 v[66:69], v[188:191], v[220:223], v[66:69]
	v_mfma_f32_16x16x32_bf16 v[126:129], v[184:187], v[200:203], v[126:129]
	v_mfma_f32_16x16x32_bf16 v[114:117], v[192:195], v[200:203], v[114:117]
	v_mfma_f32_16x16x32_bf16 v[106:109], v[184:187], v[208:211], v[106:109]
	v_mfma_f32_16x16x32_bf16 v[98:101], v[192:195], v[208:211], v[98:101]
	v_mfma_f32_16x16x32_bf16 v[90:93], v[184:187], v[216:219], v[90:93]
	v_mfma_f32_16x16x32_bf16 v[82:85], v[192:195], v[216:219], v[82:85]
	v_mfma_f32_16x16x32_bf16 v[74:77], v[184:187], v[224:227], v[74:77]
	v_mfma_f32_16x16x32_bf16 v[66:69], v[192:195], v[224:227], v[66:69]
	s_setprio 0
	s_barrier
	s_add_u32 s98, s96, 0x40000
	s_addc_u32 s99, s97, 0
	s_add_i32 s5, s74, s23
	s_mov_b32 m0, s5
	ds_read_b128 v[196:199], v160 offset:16384
	ds_read_b128 v[200:203], v160 offset:17408
	ds_read_b128 v[204:207], v160 offset:18432
	ds_read_b128 v[208:211], v160 offset:19456
	ds_read_b128 v[212:215], v160 offset:20480
	ds_read_b128 v[216:219], v160 offset:21504
	ds_read_b128 v[220:223], v160 offset:22528
	ds_read_b128 v[224:227], v160 offset:23552
	global_load_lds_dwordx4 v132, s[96:97]
	s_add_i32 m0, s5, 0x2000
	s_add_i32 s5, s75, s23
	global_load_lds_dwordx4 v136, s[96:97]
	s_mov_b32 m0, s5
	s_nop 0
	global_load_lds_dwordx4 v132, s[98:99]
	s_add_i32 m0, s5, 0x2000
	s_nop 0
	global_load_lds_dwordx4 v136, s[98:99]
	s_mov_b32 m0, s47
	s_nop 0
	global_load_lds_dwordx4 v130, s[94:95]
	s_mov_b32 m0, s56
	s_nop 0
	global_load_lds_dwordx4 v134, s[94:95]
	s_waitcnt vmcnt(8)
	s_waitcnt lgkmcnt(0)
	s_barrier
	s_setprio 1
	s_waitcnt lgkmcnt(0)
	v_mfma_f32_16x16x32_bf16 v[62:65], v[164:167], v[196:199], v[62:65]
	v_mfma_f32_16x16x32_bf16 v[54:57], v[172:175], v[196:199], v[54:57]
	v_mfma_f32_16x16x32_bf16 v[46:49], v[164:167], v[204:207], v[46:49]
	v_mfma_f32_16x16x32_bf16 v[38:41], v[172:175], v[204:207], v[38:41]
	v_mfma_f32_16x16x32_bf16 v[30:33], v[164:167], v[212:215], v[30:33]
	v_mfma_f32_16x16x32_bf16 v[22:25], v[172:175], v[212:215], v[22:25]
	v_mfma_f32_16x16x32_bf16 v[14:17], v[164:167], v[220:223], v[14:17]
	v_mfma_f32_16x16x32_bf16 v[6:9], v[172:175], v[220:223], v[6:9]
	v_mfma_f32_16x16x32_bf16 v[62:65], v[168:171], v[200:203], v[62:65]
	v_mfma_f32_16x16x32_bf16 v[54:57], v[176:179], v[200:203], v[54:57]
	v_mfma_f32_16x16x32_bf16 v[46:49], v[168:171], v[208:211], v[46:49]
	v_mfma_f32_16x16x32_bf16 v[38:41], v[176:179], v[208:211], v[38:41]
	v_mfma_f32_16x16x32_bf16 v[30:33], v[168:171], v[216:219], v[30:33]
	v_mfma_f32_16x16x32_bf16 v[22:25], v[176:179], v[216:219], v[22:25]
	v_mfma_f32_16x16x32_bf16 v[14:17], v[168:171], v[224:227], v[14:17]
	v_mfma_f32_16x16x32_bf16 v[6:9], v[176:179], v[224:227], v[6:9]
	s_setprio 0
	s_setprio 1
	v_mfma_f32_16x16x32_bf16 v[58:61], v[180:183], v[196:199], v[58:61]
	v_mfma_f32_16x16x32_bf16 v[50:53], v[188:191], v[196:199], v[50:53]
	v_mfma_f32_16x16x32_bf16 v[42:45], v[180:183], v[204:207], v[42:45]
	v_mfma_f32_16x16x32_bf16 v[34:37], v[188:191], v[204:207], v[34:37]
	v_mfma_f32_16x16x32_bf16 v[26:29], v[180:183], v[212:215], v[26:29]
	v_mfma_f32_16x16x32_bf16 v[18:21], v[188:191], v[212:215], v[18:21]
	v_mfma_f32_16x16x32_bf16 v[10:13], v[180:183], v[220:223], v[10:13]
	v_mfma_f32_16x16x32_bf16 v[2:5], v[188:191], v[220:223], v[2:5]
	v_mfma_f32_16x16x32_bf16 v[58:61], v[184:187], v[200:203], v[58:61]
	v_mfma_f32_16x16x32_bf16 v[50:53], v[192:195], v[200:203], v[50:53]
	v_mfma_f32_16x16x32_bf16 v[42:45], v[184:187], v[208:211], v[42:45]
	v_mfma_f32_16x16x32_bf16 v[34:37], v[192:195], v[208:211], v[34:37]
	v_mfma_f32_16x16x32_bf16 v[26:29], v[184:187], v[216:219], v[26:29]
	v_mfma_f32_16x16x32_bf16 v[18:21], v[192:195], v[216:219], v[18:21]
	v_mfma_f32_16x16x32_bf16 v[10:13], v[184:187], v[224:227], v[10:13]
	v_mfma_f32_16x16x32_bf16 v[2:5], v[192:195], v[224:227], v[2:5]
	s_setprio 0
	s_barrier
	s_add_u32 s98, s94, 0x40000
	s_addc_u32 s99, s95, 0
	s_add_i32 s5, 0, 0x18000
	s_add_i32 s45, 0, 0x1c000
	ds_read_b128 v[164:167], v232
	ds_read_b128 v[168:171], v232 offset:1024
	ds_read_b128 v[172:175], v232 offset:2048
	ds_read_b128 v[176:179], v232 offset:3072
	ds_read_b128 v[180:183], v233
	ds_read_b128 v[184:187], v233 offset:1024
	ds_read_b128 v[188:191], v233 offset:2048
	ds_read_b128 v[192:195], v233 offset:3072
	s_mov_b32 m0, s57
	ds_read_b128 v[196:199], v160 offset:32768
	ds_read_b128 v[200:203], v160 offset:33792
	ds_read_b128 v[204:207], v160 offset:34816
	ds_read_b128 v[208:211], v160 offset:35840
	ds_read_b128 v[212:215], v160 offset:36864
	ds_read_b128 v[216:219], v160 offset:37888
	ds_read_b128 v[220:223], v160 offset:38912
	ds_read_b128 v[224:227], v160 offset:39936
	global_load_lds_dwordx4 v130, s[98:99]
	s_mov_b32 m0, s58
	s_nop 0
	global_load_lds_dwordx4 v134, s[98:99]
	s_waitcnt vmcnt(8)
	s_waitcnt lgkmcnt(0)
	s_barrier
	s_setprio 1
	s_waitcnt lgkmcnt(0)
	v_mfma_f32_16x16x32_bf16 v[122:125], v[164:167], v[196:199], v[122:125]
	v_mfma_f32_16x16x32_bf16 v[118:121], v[172:175], v[196:199], v[118:121]
	v_mfma_f32_16x16x32_bf16 v[110:113], v[164:167], v[204:207], v[110:113]
	v_mfma_f32_16x16x32_bf16 v[102:105], v[172:175], v[204:207], v[102:105]
	v_mfma_f32_16x16x32_bf16 v[94:97], v[164:167], v[212:215], v[94:97]
	v_mfma_f32_16x16x32_bf16 v[86:89], v[172:175], v[212:215], v[86:89]
	v_mfma_f32_16x16x32_bf16 v[78:81], v[164:167], v[220:223], v[78:81]
	v_mfma_f32_16x16x32_bf16 v[70:73], v[172:175], v[220:223], v[70:73]
	v_mfma_f32_16x16x32_bf16 v[122:125], v[168:171], v[200:203], v[122:125]
	v_mfma_f32_16x16x32_bf16 v[118:121], v[176:179], v[200:203], v[118:121]
	v_mfma_f32_16x16x32_bf16 v[110:113], v[168:171], v[208:211], v[110:113]
	v_mfma_f32_16x16x32_bf16 v[102:105], v[176:179], v[208:211], v[102:105]
	v_mfma_f32_16x16x32_bf16 v[94:97], v[168:171], v[216:219], v[94:97]
	v_mfma_f32_16x16x32_bf16 v[86:89], v[176:179], v[216:219], v[86:89]
	v_mfma_f32_16x16x32_bf16 v[78:81], v[168:171], v[224:227], v[78:81]
	v_mfma_f32_16x16x32_bf16 v[70:73], v[176:179], v[224:227], v[70:73]
	s_setprio 0
	s_setprio 1
	v_mfma_f32_16x16x32_bf16 v[126:129], v[180:183], v[196:199], v[126:129]
	v_mfma_f32_16x16x32_bf16 v[114:117], v[188:191], v[196:199], v[114:117]
	v_mfma_f32_16x16x32_bf16 v[106:109], v[180:183], v[204:207], v[106:109]
	v_mfma_f32_16x16x32_bf16 v[98:101], v[188:191], v[204:207], v[98:101]
	v_mfma_f32_16x16x32_bf16 v[90:93], v[180:183], v[212:215], v[90:93]
	v_mfma_f32_16x16x32_bf16 v[82:85], v[188:191], v[212:215], v[82:85]
	v_mfma_f32_16x16x32_bf16 v[74:77], v[180:183], v[220:223], v[74:77]
	v_mfma_f32_16x16x32_bf16 v[66:69], v[188:191], v[220:223], v[66:69]
	v_mfma_f32_16x16x32_bf16 v[126:129], v[184:187], v[200:203], v[126:129]
	v_mfma_f32_16x16x32_bf16 v[114:117], v[192:195], v[200:203], v[114:117]
	v_mfma_f32_16x16x32_bf16 v[106:109], v[184:187], v[208:211], v[106:109]
	v_mfma_f32_16x16x32_bf16 v[98:101], v[192:195], v[208:211], v[98:101]
	v_mfma_f32_16x16x32_bf16 v[90:93], v[184:187], v[216:219], v[90:93]
	v_mfma_f32_16x16x32_bf16 v[82:85], v[192:195], v[216:219], v[82:85]
	v_mfma_f32_16x16x32_bf16 v[74:77], v[184:187], v[224:227], v[74:77]
	v_mfma_f32_16x16x32_bf16 v[66:69], v[192:195], v[224:227], v[66:69]
	s_setprio 0
	s_barrier
	s_add_u32 s96, s96, 0x80
	s_addc_u32 s97, s97, 0
	s_add_u32 s98, s96, 0x40000
	s_addc_u32 s99, s97, 0
	s_add_u32 s94, s94, 0x80
	s_addc_u32 s95, s95, 0
	s_add_i32 s5, s5, s23
	s_mov_b32 m0, s5
	ds_read_b128 v[196:199], v160 offset:49152
	ds_read_b128 v[200:203], v160 offset:50176
	ds_read_b128 v[204:207], v160 offset:51200
	ds_read_b128 v[208:211], v160 offset:52224
	ds_read_b128 v[212:215], v160 offset:53248
	ds_read_b128 v[216:219], v160 offset:54272
	ds_read_b128 v[220:223], v160 offset:55296
	ds_read_b128 v[224:227], v160 offset:56320
	global_load_lds_dwordx4 v132, s[96:97]
	s_add_i32 m0, s5, 0x2000
	s_add_i32 s5, s45, s23
	global_load_lds_dwordx4 v136, s[96:97]
	s_mov_b32 m0, s5
	s_nop 0
	global_load_lds_dwordx4 v132, s[98:99]
	s_add_i32 m0, s5, 0x2000
	s_nop 0
	global_load_lds_dwordx4 v136, s[98:99]
	s_mov_b32 m0, s64
	s_nop 0
	global_load_lds_dwordx4 v130, s[94:95]
	s_mov_b32 m0, s65
	s_nop 0
	global_load_lds_dwordx4 v134, s[94:95]
	s_waitcnt vmcnt(8)
	s_waitcnt lgkmcnt(0)
	s_barrier
	s_setprio 1
	s_waitcnt lgkmcnt(0)
	v_mfma_f32_16x16x32_bf16 v[62:65], v[164:167], v[196:199], v[62:65]
	v_mfma_f32_16x16x32_bf16 v[54:57], v[172:175], v[196:199], v[54:57]
	v_mfma_f32_16x16x32_bf16 v[46:49], v[164:167], v[204:207], v[46:49]
	v_mfma_f32_16x16x32_bf16 v[38:41], v[172:175], v[204:207], v[38:41]
	v_mfma_f32_16x16x32_bf16 v[30:33], v[164:167], v[212:215], v[30:33]
	v_mfma_f32_16x16x32_bf16 v[22:25], v[172:175], v[212:215], v[22:25]
	v_mfma_f32_16x16x32_bf16 v[14:17], v[164:167], v[220:223], v[14:17]
	v_mfma_f32_16x16x32_bf16 v[6:9], v[172:175], v[220:223], v[6:9]
	v_mfma_f32_16x16x32_bf16 v[62:65], v[168:171], v[200:203], v[62:65]
	v_mfma_f32_16x16x32_bf16 v[54:57], v[176:179], v[200:203], v[54:57]
	v_mfma_f32_16x16x32_bf16 v[46:49], v[168:171], v[208:211], v[46:49]
	v_mfma_f32_16x16x32_bf16 v[38:41], v[176:179], v[208:211], v[38:41]
	v_mfma_f32_16x16x32_bf16 v[30:33], v[168:171], v[216:219], v[30:33]
	v_mfma_f32_16x16x32_bf16 v[22:25], v[176:179], v[216:219], v[22:25]
	v_mfma_f32_16x16x32_bf16 v[14:17], v[168:171], v[224:227], v[14:17]
	v_mfma_f32_16x16x32_bf16 v[6:9], v[176:179], v[224:227], v[6:9]
	s_setprio 0
	s_setprio 1
	v_mfma_f32_16x16x32_bf16 v[58:61], v[180:183], v[196:199], v[58:61]
	v_mfma_f32_16x16x32_bf16 v[50:53], v[188:191], v[196:199], v[50:53]
	v_mfma_f32_16x16x32_bf16 v[42:45], v[180:183], v[204:207], v[42:45]
	v_mfma_f32_16x16x32_bf16 v[34:37], v[188:191], v[204:207], v[34:37]
	v_mfma_f32_16x16x32_bf16 v[26:29], v[180:183], v[212:215], v[26:29]
	v_mfma_f32_16x16x32_bf16 v[18:21], v[188:191], v[212:215], v[18:21]
	v_mfma_f32_16x16x32_bf16 v[10:13], v[180:183], v[220:223], v[10:13]
	v_mfma_f32_16x16x32_bf16 v[2:5], v[188:191], v[220:223], v[2:5]
	v_mfma_f32_16x16x32_bf16 v[58:61], v[184:187], v[200:203], v[58:61]
	v_mfma_f32_16x16x32_bf16 v[50:53], v[192:195], v[200:203], v[50:53]
	v_mfma_f32_16x16x32_bf16 v[42:45], v[184:187], v[208:211], v[42:45]
	v_mfma_f32_16x16x32_bf16 v[34:37], v[192:195], v[208:211], v[34:37]
	v_mfma_f32_16x16x32_bf16 v[26:29], v[184:187], v[216:219], v[26:29]
	v_mfma_f32_16x16x32_bf16 v[18:21], v[192:195], v[216:219], v[18:21]
	v_mfma_f32_16x16x32_bf16 v[10:13], v[184:187], v[224:227], v[10:13]
	v_mfma_f32_16x16x32_bf16 v[2:5], v[192:195], v[224:227], v[2:5]
	s_setprio 0
	s_barrier
	s_mov_b32 s5, s29
	s_add_u32 s88, s88, 0x100
	s_addc_u32 s89, s89, 0
	s_add_u32 s86, s86, 0x100
	s_addc_u32 s87, s87, 0
	s_cmp_ge_i32 s29, s101
	s_cbranch_scc0 .LBB0_1763

.LBB0_1942:
	v_cmp_gt_i32_e32 vcc, 1, v138
	s_cbranch_vccnz .LBB0_2004
	v_lshl_add_u64 v[152:153], v[2:3], 0, s[16:17]
	v_add_u32_e32 v154, -2, v138
	s_waitcnt lgkmcnt(0)
	v_lshl_add_u64 v[150:151], v[4:5], 0, s[20:21]
	s_mov_b32 s5, 0
	s_nop 0
	v_readfirstlane_b32 s86, v152
	v_readfirstlane_b32 s87, v153
	v_readfirstlane_b32 s88, v150
	v_readfirstlane_b32 s89, v151
	v_readfirstlane_b32 s90, v146
	v_readfirstlane_b32 s91, v147
	v_readfirstlane_b32 s92, v148
	v_readfirstlane_b32 s93, v149
	v_readfirstlane_b32 s100, v154
	v_readfirstlane_b32 s101, v138
	v_add_u32_e32 v230, s72, v141
	v_add_u32_e32 v231, s73, v141
	v_add_u32_e32 v232, 0x18000, v141
	v_add_u32_e32 v233, 0x1c000, v141
	s_add_u32 s98, s86, 0xfffc0080
	s_addc_u32 s99, s87, -1
	s_cmp_eq_u32 s5, s100
	s_cselect_b64 s[94:95], s[90:91], s[98:99]
	s_cselect_b64 s[96:97], s[92:93], s[88:89]
	ds_read_b128 v[164:167], v230
	ds_read_b128 v[168:171], v230 offset:1024
	ds_read_b128 v[172:175], v230 offset:2048
	ds_read_b128 v[176:179], v230 offset:3072
	ds_read_b128 v[180:183], v231
	ds_read_b128 v[184:187], v231 offset:1024
	ds_read_b128 v[188:191], v231 offset:2048
	ds_read_b128 v[192:195], v231 offset:3072
	s_add_i32 s45, s5, 2
	s_nop 0
	s_mov_b32 m0, s74
	ds_read_b128 v[196:199], v160
	ds_read_b128 v[200:203], v160 offset:1024
	ds_read_b128 v[204:207], v160 offset:2048
	ds_read_b128 v[208:211], v160 offset:3072
	ds_read_b128 v[212:215], v160 offset:4096
	ds_read_b128 v[216:219], v160 offset:5120
	ds_read_b128 v[220:223], v160 offset:6144
	ds_read_b128 v[224:227], v160 offset:7168
	global_load_lds_dwordx4 v144, s[86:87]
	s_mov_b32 m0, s75
	s_nop 0
	global_load_lds_dwordx4 v142, s[86:87]
	s_waitcnt vmcnt(8)
	s_waitcnt lgkmcnt(0)
	s_barrier
	s_setprio 1
	s_waitcnt lgkmcnt(0)
	v_mfma_f32_16x16x32_bf16 v[122:125], v[164:167], v[196:199], 0
	v_mfma_f32_16x16x32_bf16 v[118:121], v[172:175], v[196:199], 0
	v_mfma_f32_16x16x32_bf16 v[110:113], v[164:167], v[204:207], 0
	v_mfma_f32_16x16x32_bf16 v[102:105], v[172:175], v[204:207], 0
	v_mfma_f32_16x16x32_bf16 v[94:97], v[164:167], v[212:215], 0
	v_mfma_f32_16x16x32_bf16 v[86:89], v[172:175], v[212:215], 0
	v_mfma_f32_16x16x32_bf16 v[78:81], v[164:167], v[220:223], 0
	v_mfma_f32_16x16x32_bf16 v[70:73], v[172:175], v[220:223], 0
	v_mfma_f32_16x16x32_bf16 v[122:125], v[168:171], v[200:203], v[122:125]
	v_mfma_f32_16x16x32_bf16 v[118:121], v[176:179], v[200:203], v[118:121]
	v_mfma_f32_16x16x32_bf16 v[110:113], v[168:171], v[208:211], v[110:113]
	v_mfma_f32_16x16x32_bf16 v[102:105], v[176:179], v[208:211], v[102:105]
	v_mfma_f32_16x16x32_bf16 v[94:97], v[168:171], v[216:219], v[94:97]
	v_mfma_f32_16x16x32_bf16 v[86:89], v[176:179], v[216:219], v[86:89]
	v_mfma_f32_16x16x32_bf16 v[78:81], v[168:171], v[224:227], v[78:81]
	v_mfma_f32_16x16x32_bf16 v[70:73], v[176:179], v[224:227], v[70:73]
	s_setprio 0
	s_setprio 1
	v_mfma_f32_16x16x32_bf16 v[126:129], v[180:183], v[196:199], 0
	v_mfma_f32_16x16x32_bf16 v[114:117], v[188:191], v[196:199], 0
	v_mfma_f32_16x16x32_bf16 v[106:109], v[180:183], v[204:207], 0
	v_mfma_f32_16x16x32_bf16 v[98:101], v[188:191], v[204:207], 0
	v_mfma_f32_16x16x32_bf16 v[90:93], v[180:183], v[212:215], 0
	v_mfma_f32_16x16x32_bf16 v[82:85], v[188:191], v[212:215], 0
	v_mfma_f32_16x16x32_bf16 v[74:77], v[180:183], v[220:223], 0
	v_mfma_f32_16x16x32_bf16 v[66:69], v[188:191], v[220:223], 0
	v_mfma_f32_16x16x32_bf16 v[126:129], v[184:187], v[200:203], v[126:129]
	v_mfma_f32_16x16x32_bf16 v[114:117], v[192:195], v[200:203], v[114:117]
	v_mfma_f32_16x16x32_bf16 v[106:109], v[184:187], v[208:211], v[106:109]
	v_mfma_f32_16x16x32_bf16 v[98:101], v[192:195], v[208:211], v[98:101]
	v_mfma_f32_16x16x32_bf16 v[90:93], v[184:187], v[216:219], v[90:93]
	v_mfma_f32_16x16x32_bf16 v[82:85], v[192:195], v[216:219], v[82:85]
	v_mfma_f32_16x16x32_bf16 v[74:77], v[184:187], v[224:227], v[74:77]
	v_mfma_f32_16x16x32_bf16 v[66:69], v[192:195], v[224:227], v[66:69]
	s_setprio 0
	s_barrier
	s_add_u32 s98, s96, 0x40000
	s_addc_u32 s99, s97, 0
	s_mov_b32 m0, s76
	ds_read_b128 v[196:199], v160 offset:16384
	ds_read_b128 v[200:203], v160 offset:17408
	ds_read_b128 v[204:207], v160 offset:18432
	ds_read_b128 v[208:211], v160 offset:19456
	ds_read_b128 v[212:215], v160 offset:20480
	ds_read_b128 v[216:219], v160 offset:21504
	ds_read_b128 v[220:223], v160 offset:22528
	ds_read_b128 v[224:227], v160 offset:23552
	global_load_lds_dwordx4 v132, s[96:97]
	s_mov_b32 m0, s77
	s_add_i32 s5, s73, s25
	global_load_lds_dwordx4 v136, s[96:97]
	s_mov_b32 m0, s5
	s_nop 0
	global_load_lds_dwordx4 v132, s[98:99]
	s_add_i32 m0, s5, 0x2000
	s_nop 0
	global_load_lds_dwordx4 v136, s[98:99]
	s_mov_b32 m0, s49
	s_nop 0
	global_load_lds_dwordx4 v130, s[94:95]
	s_mov_b32 m0, s58
	s_nop 0
	global_load_lds_dwordx4 v134, s[94:95]
	s_waitcnt vmcnt(8)
	s_waitcnt lgkmcnt(0)
	s_barrier
	s_setprio 1
	s_waitcnt lgkmcnt(0)
	v_mfma_f32_16x16x32_bf16 v[62:65], v[164:167], v[196:199], 0
	v_mfma_f32_16x16x32_bf16 v[54:57], v[172:175], v[196:199], 0
	v_mfma_f32_16x16x32_bf16 v[46:49], v[164:167], v[204:207], 0
	v_mfma_f32_16x16x32_bf16 v[38:41], v[172:175], v[204:207], 0
	v_mfma_f32_16x16x32_bf16 v[30:33], v[164:167], v[212:215], 0
	v_mfma_f32_16x16x32_bf16 v[22:25], v[172:175], v[212:215], 0
	v_mfma_f32_16x16x32_bf16 v[14:17], v[164:167], v[220:223], 0
	v_mfma_f32_16x16x32_bf16 v[6:9], v[172:175], v[220:223], 0
	v_mfma_f32_16x16x32_bf16 v[62:65], v[168:171], v[200:203], v[62:65]
	v_mfma_f32_16x16x32_bf16 v[54:57], v[176:179], v[200:203], v[54:57]
	v_mfma_f32_16x16x32_bf16 v[46:49], v[168:171], v[208:211], v[46:49]
	v_mfma_f32_16x16x32_bf16 v[38:41], v[176:179], v[208:211], v[38:41]
	v_mfma_f32_16x16x32_bf16 v[30:33], v[168:171], v[216:219], v[30:33]
	v_mfma_f32_16x16x32_bf16 v[22:25], v[176:179], v[216:219], v[22:25]
	v_mfma_f32_16x16x32_bf16 v[14:17], v[168:171], v[224:227], v[14:17]
	v_mfma_f32_16x16x32_bf16 v[6:9], v[176:179], v[224:227], v[6:9]
	s_setprio 0
	s_setprio 1
	v_mfma_f32_16x16x32_bf16 v[58:61], v[180:183], v[196:199], 0
	v_mfma_f32_16x16x32_bf16 v[50:53], v[188:191], v[196:199], 0
	v_mfma_f32_16x16x32_bf16 v[42:45], v[180:183], v[204:207], 0
	v_mfma_f32_16x16x32_bf16 v[34:37], v[188:191], v[204:207], 0
	v_mfma_f32_16x16x32_bf16 v[26:29], v[180:183], v[212:215], 0
	v_mfma_f32_16x16x32_bf16 v[18:21], v[188:191], v[212:215], 0
	v_mfma_f32_16x16x32_bf16 v[10:13], v[180:183], v[220:223], 0
	v_mfma_f32_16x16x32_bf16 v[2:5], v[188:191], v[220:223], 0
	v_mfma_f32_16x16x32_bf16 v[58:61], v[184:187], v[200:203], v[58:61]
	v_mfma_f32_16x16x32_bf16 v[50:53], v[192:195], v[200:203], v[50:53]
	v_mfma_f32_16x16x32_bf16 v[42:45], v[184:187], v[208:211], v[42:45]
	v_mfma_f32_16x16x32_bf16 v[34:37], v[192:195], v[208:211], v[34:37]
	v_mfma_f32_16x16x32_bf16 v[26:29], v[184:187], v[216:219], v[26:29]
	v_mfma_f32_16x16x32_bf16 v[18:21], v[192:195], v[216:219], v[18:21]
	v_mfma_f32_16x16x32_bf16 v[10:13], v[184:187], v[224:227], v[10:13]
	v_mfma_f32_16x16x32_bf16 v[2:5], v[192:195], v[224:227], v[2:5]
	s_setprio 0
	s_barrier
	s_add_u32 s98, s94, 0x40000
	s_addc_u32 s99, s95, 0
	s_add_i32 s5, 0, 0x18000
	s_add_i32 s47, 0, 0x1c000
	ds_read_b128 v[164:167], v232
	ds_read_b128 v[168:171], v232 offset:1024
	ds_read_b128 v[172:175], v232 offset:2048
	ds_read_b128 v[176:179], v232 offset:3072
	ds_read_b128 v[180:183], v233
	ds_read_b128 v[184:187], v233 offset:1024
	ds_read_b128 v[188:191], v233 offset:2048
	ds_read_b128 v[192:195], v233 offset:3072
	s_mov_b32 m0, s59
	ds_read_b128 v[196:199], v160 offset:32768
	ds_read_b128 v[200:203], v160 offset:33792
	ds_read_b128 v[204:207], v160 offset:34816
	ds_read_b128 v[208:211], v160 offset:35840
	ds_read_b128 v[212:215], v160 offset:36864
	ds_read_b128 v[216:219], v160 offset:37888
	ds_read_b128 v[220:223], v160 offset:38912
	ds_read_b128 v[224:227], v160 offset:39936
	global_load_lds_dwordx4 v130, s[98:99]
	s_mov_b32 m0, s60
	s_nop 0
	global_load_lds_dwordx4 v134, s[98:99]
	s_waitcnt vmcnt(8)
	s_waitcnt lgkmcnt(0)
	s_barrier
	s_setprio 1
	s_waitcnt lgkmcnt(0)
	v_mfma_f32_16x16x32_bf16 v[122:125], v[164:167], v[196:199], v[122:125]
	v_mfma_f32_16x16x32_bf16 v[118:121], v[172:175], v[196:199], v[118:121]
	v_mfma_f32_16x16x32_bf16 v[110:113], v[164:167], v[204:207], v[110:113]
	v_mfma_f32_16x16x32_bf16 v[102:105], v[172:175], v[204:207], v[102:105]
	v_mfma_f32_16x16x32_bf16 v[94:97], v[164:167], v[212:215], v[94:97]
	v_mfma_f32_16x16x32_bf16 v[86:89], v[172:175], v[212:215], v[86:89]
	v_mfma_f32_16x16x32_bf16 v[78:81], v[164:167], v[220:223], v[78:81]
	v_mfma_f32_16x16x32_bf16 v[70:73], v[172:175], v[220:223], v[70:73]
	v_mfma_f32_16x16x32_bf16 v[122:125], v[168:171], v[200:203], v[122:125]
	v_mfma_f32_16x16x32_bf16 v[118:121], v[176:179], v[200:203], v[118:121]
	v_mfma_f32_16x16x32_bf16 v[110:113], v[168:171], v[208:211], v[110:113]
	v_mfma_f32_16x16x32_bf16 v[102:105], v[176:179], v[208:211], v[102:105]
	v_mfma_f32_16x16x32_bf16 v[94:97], v[168:171], v[216:219], v[94:97]
	v_mfma_f32_16x16x32_bf16 v[86:89], v[176:179], v[216:219], v[86:89]
	v_mfma_f32_16x16x32_bf16 v[78:81], v[168:171], v[224:227], v[78:81]
	v_mfma_f32_16x16x32_bf16 v[70:73], v[176:179], v[224:227], v[70:73]
	s_setprio 0
	s_setprio 1
	v_mfma_f32_16x16x32_bf16 v[126:129], v[180:183], v[196:199], v[126:129]
	v_mfma_f32_16x16x32_bf16 v[114:117], v[188:191], v[196:199], v[114:117]
	v_mfma_f32_16x16x32_bf16 v[106:109], v[180:183], v[204:207], v[106:109]
	v_mfma_f32_16x16x32_bf16 v[98:101], v[188:191], v[204:207], v[98:101]
	v_mfma_f32_16x16x32_bf16 v[90:93], v[180:183], v[212:215], v[90:93]
	v_mfma_f32_16x16x32_bf16 v[82:85], v[188:191], v[212:215], v[82:85]
	v_mfma_f32_16x16x32_bf16 v[74:77], v[180:183], v[220:223], v[74:77]
	v_mfma_f32_16x16x32_bf16 v[66:69], v[188:191], v[220:223], v[66:69]
	v_mfma_f32_16x16x32_bf16 v[126:129], v[184:187], v[200:203], v[126:129]
	v_mfma_f32_16x16x32_bf16 v[114:117], v[192:195], v[200:203], v[114:117]
	v_mfma_f32_16x16x32_bf16 v[106:109], v[184:187], v[208:211], v[106:109]
	v_mfma_f32_16x16x32_bf16 v[98:101], v[192:195], v[208:211], v[98:101]
	v_mfma_f32_16x16x32_bf16 v[90:93], v[184:187], v[216:219], v[90:93]
	v_mfma_f32_16x16x32_bf16 v[82:85], v[192:195], v[216:219], v[82:85]
	v_mfma_f32_16x16x32_bf16 v[74:77], v[184:187], v[224:227], v[74:77]
	v_mfma_f32_16x16x32_bf16 v[66:69], v[192:195], v[224:227], v[66:69]
	s_setprio 0
	s_barrier
	s_add_u32 s96, s96, 0x80
	s_addc_u32 s97, s97, 0
	s_add_u32 s98, s96, 0x40000
	s_addc_u32 s99, s97, 0
	s_add_u32 s94, s94, 0x80
	s_addc_u32 s95, s95, 0
	s_add_i32 s5, s5, s25
	s_mov_b32 m0, s5
	ds_read_b128 v[196:199], v160 offset:49152
	ds_read_b128 v[200:203], v160 offset:50176
	ds_read_b128 v[204:207], v160 offset:51200
	ds_read_b128 v[208:211], v160 offset:52224
	ds_read_b128 v[212:215], v160 offset:53248
	ds_read_b128 v[216:219], v160 offset:54272
	ds_read_b128 v[220:223], v160 offset:55296
	ds_read_b128 v[224:227], v160 offset:56320
	global_load_lds_dwordx4 v132, s[96:97]
	s_add_i32 m0, s5, 0x2000
	s_add_i32 s5, s47, s25
	global_load_lds_dwordx4 v136, s[96:97]
	s_mov_b32 m0, s5
	s_nop 0
	global_load_lds_dwordx4 v132, s[98:99]
	s_add_i32 m0, s5, 0x2000
	s_nop 0
	global_load_lds_dwordx4 v136, s[98:99]
	s_mov_b32 m0, s61
	s_nop 0
	global_load_lds_dwordx4 v130, s[94:95]
	s_mov_b32 m0, s62
	s_nop 0
	global_load_lds_dwordx4 v134, s[94:95]
	s_waitcnt vmcnt(8)
	s_waitcnt lgkmcnt(0)
	s_barrier
	s_setprio 1
	s_waitcnt lgkmcnt(0)
	v_mfma_f32_16x16x32_bf16 v[62:65], v[164:167], v[196:199], v[62:65]
	v_mfma_f32_16x16x32_bf16 v[54:57], v[172:175], v[196:199], v[54:57]
	v_mfma_f32_16x16x32_bf16 v[46:49], v[164:167], v[204:207], v[46:49]
	v_mfma_f32_16x16x32_bf16 v[38:41], v[172:175], v[204:207], v[38:41]
	v_mfma_f32_16x16x32_bf16 v[30:33], v[164:167], v[212:215], v[30:33]
	v_mfma_f32_16x16x32_bf16 v[22:25], v[172:175], v[212:215], v[22:25]
	v_mfma_f32_16x16x32_bf16 v[14:17], v[164:167], v[220:223], v[14:17]
	v_mfma_f32_16x16x32_bf16 v[6:9], v[172:175], v[220:223], v[6:9]
	v_mfma_f32_16x16x32_bf16 v[62:65], v[168:171], v[200:203], v[62:65]
	v_mfma_f32_16x16x32_bf16 v[54:57], v[176:179], v[200:203], v[54:57]
	v_mfma_f32_16x16x32_bf16 v[46:49], v[168:171], v[208:211], v[46:49]
	v_mfma_f32_16x16x32_bf16 v[38:41], v[176:179], v[208:211], v[38:41]
	v_mfma_f32_16x16x32_bf16 v[30:33], v[168:171], v[216:219], v[30:33]
	v_mfma_f32_16x16x32_bf16 v[22:25], v[176:179], v[216:219], v[22:25]
	v_mfma_f32_16x16x32_bf16 v[14:17], v[168:171], v[224:227], v[14:17]
	v_mfma_f32_16x16x32_bf16 v[6:9], v[176:179], v[224:227], v[6:9]
	s_setprio 0
	s_setprio 1
	v_mfma_f32_16x16x32_bf16 v[58:61], v[180:183], v[196:199], v[58:61]
	v_mfma_f32_16x16x32_bf16 v[50:53], v[188:191], v[196:199], v[50:53]
	v_mfma_f32_16x16x32_bf16 v[42:45], v[180:183], v[204:207], v[42:45]
	v_mfma_f32_16x16x32_bf16 v[34:37], v[188:191], v[204:207], v[34:37]
	v_mfma_f32_16x16x32_bf16 v[26:29], v[180:183], v[212:215], v[26:29]
	v_mfma_f32_16x16x32_bf16 v[18:21], v[188:191], v[212:215], v[18:21]
	v_mfma_f32_16x16x32_bf16 v[10:13], v[180:183], v[220:223], v[10:13]
	v_mfma_f32_16x16x32_bf16 v[2:5], v[188:191], v[220:223], v[2:5]
	v_mfma_f32_16x16x32_bf16 v[58:61], v[184:187], v[200:203], v[58:61]
	v_mfma_f32_16x16x32_bf16 v[50:53], v[192:195], v[200:203], v[50:53]
	v_mfma_f32_16x16x32_bf16 v[42:45], v[184:187], v[208:211], v[42:45]
	v_mfma_f32_16x16x32_bf16 v[34:37], v[192:195], v[208:211], v[34:37]
	v_mfma_f32_16x16x32_bf16 v[26:29], v[184:187], v[216:219], v[26:29]
	v_mfma_f32_16x16x32_bf16 v[18:21], v[192:195], v[216:219], v[18:21]
	v_mfma_f32_16x16x32_bf16 v[10:13], v[184:187], v[224:227], v[10:13]
	v_mfma_f32_16x16x32_bf16 v[2:5], v[192:195], v[224:227], v[2:5]
	s_setprio 0
	s_barrier
	s_mov_b32 s5, s45
	s_add_u32 s88, s88, 0x100
	s_addc_u32 s89, s89, 0
	s_add_u32 s86, s86, 0x100
	s_addc_u32 s87, s87, 0
	s_cmp_ge_i32 s45, s101
	s_cbranch_scc1 .Lmy_kexit_10
.LBB0_1944:
	s_add_u32 s98, s86, 0xfffc0080
	s_addc_u32 s99, s87, -1
	s_cmp_eq_u32 s5, s100
	s_cselect_b64 s[94:95], s[90:91], s[98:99]
	s_cselect_b64 s[96:97], s[92:93], s[88:89]
	ds_read_b128 v[164:167], v230
	ds_read_b128 v[168:171], v230 offset:1024
	ds_read_b128 v[172:175], v230 offset:2048
	ds_read_b128 v[176:179], v230 offset:3072
	ds_read_b128 v[180:183], v231
	ds_read_b128 v[184:187], v231 offset:1024
	ds_read_b128 v[188:191], v231 offset:2048
	ds_read_b128 v[192:195], v231 offset:3072
	s_add_i32 s45, s5, 2
	s_nop 0
	s_mov_b32 m0, s74
	ds_read_b128 v[196:199], v160
	ds_read_b128 v[200:203], v160 offset:1024
	ds_read_b128 v[204:207], v160 offset:2048
	ds_read_b128 v[208:211], v160 offset:3072
	ds_read_b128 v[212:215], v160 offset:4096
	ds_read_b128 v[216:219], v160 offset:5120
	ds_read_b128 v[220:223], v160 offset:6144
	ds_read_b128 v[224:227], v160 offset:7168
	global_load_lds_dwordx4 v144, s[86:87]
	s_mov_b32 m0, s75
	s_nop 0
	global_load_lds_dwordx4 v142, s[86:87]
	s_waitcnt vmcnt(8)
	s_waitcnt lgkmcnt(0)
	s_barrier
	s_setprio 1
	s_waitcnt lgkmcnt(0)
	v_mfma_f32_16x16x32_bf16 v[122:125], v[164:167], v[196:199], v[122:125]
	v_mfma_f32_16x16x32_bf16 v[118:121], v[172:175], v[196:199], v[118:121]
	v_mfma_f32_16x16x32_bf16 v[110:113], v[164:167], v[204:207], v[110:113]
	v_mfma_f32_16x16x32_bf16 v[102:105], v[172:175], v[204:207], v[102:105]
	v_mfma_f32_16x16x32_bf16 v[94:97], v[164:167], v[212:215], v[94:97]
	v_mfma_f32_16x16x32_bf16 v[86:89], v[172:175], v[212:215], v[86:89]
	v_mfma_f32_16x16x32_bf16 v[78:81], v[164:167], v[220:223], v[78:81]
	v_mfma_f32_16x16x32_bf16 v[70:73], v[172:175], v[220:223], v[70:73]
	v_mfma_f32_16x16x32_bf16 v[122:125], v[168:171], v[200:203], v[122:125]
	v_mfma_f32_16x16x32_bf16 v[118:121], v[176:179], v[200:203], v[118:121]
	v_mfma_f32_16x16x32_bf16 v[110:113], v[168:171], v[208:211], v[110:113]
	v_mfma_f32_16x16x32_bf16 v[102:105], v[176:179], v[208:211], v[102:105]
	v_mfma_f32_16x16x32_bf16 v[94:97], v[168:171], v[216:219], v[94:97]
	v_mfma_f32_16x16x32_bf16 v[86:89], v[176:179], v[216:219], v[86:89]
	v_mfma_f32_16x16x32_bf16 v[78:81], v[168:171], v[224:227], v[78:81]
	v_mfma_f32_16x16x32_bf16 v[70:73], v[176:179], v[224:227], v[70:73]
	s_setprio 0
	s_setprio 1
	v_mfma_f32_16x16x32_bf16 v[126:129], v[180:183], v[196:199], v[126:129]
	v_mfma_f32_16x16x32_bf16 v[114:117], v[188:191], v[196:199], v[114:117]
	v_mfma_f32_16x16x32_bf16 v[106:109], v[180:183], v[204:207], v[106:109]
	v_mfma_f32_16x16x32_bf16 v[98:101], v[188:191], v[204:207], v[98:101]
	v_mfma_f32_16x16x32_bf16 v[90:93], v[180:183], v[212:215], v[90:93]
	v_mfma_f32_16x16x32_bf16 v[82:85], v[188:191], v[212:215], v[82:85]
	v_mfma_f32_16x16x32_bf16 v[74:77], v[180:183], v[220:223], v[74:77]
	v_mfma_f32_16x16x32_bf16 v[66:69], v[188:191], v[220:223], v[66:69]
	v_mfma_f32_16x16x32_bf16 v[126:129], v[184:187], v[200:203], v[126:129]
	v_mfma_f32_16x16x32_bf16 v[114:117], v[192:195], v[200:203], v[114:117]
	v_mfma_f32_16x16x32_bf16 v[106:109], v[184:187], v[208:211], v[106:109]
	v_mfma_f32_16x16x32_bf16 v[98:101], v[192:195], v[208:211], v[98:101]
	v_mfma_f32_16x16x32_bf16 v[90:93], v[184:187], v[216:219], v[90:93]
	v_mfma_f32_16x16x32_bf16 v[82:85], v[192:195], v[216:219], v[82:85]
	v_mfma_f32_16x16x32_bf16 v[74:77], v[184:187], v[224:227], v[74:77]
	v_mfma_f32_16x16x32_bf16 v[66:69], v[192:195], v[224:227], v[66:69]
	s_setprio 0
	s_barrier
	s_add_u32 s98, s96, 0x40000
	s_addc_u32 s99, s97, 0
	s_mov_b32 m0, s76
	ds_read_b128 v[196:199], v160 offset:16384
	ds_read_b128 v[200:203], v160 offset:17408
	ds_read_b128 v[204:207], v160 offset:18432
	ds_read_b128 v[208:211], v160 offset:19456
	ds_read_b128 v[212:215], v160 offset:20480
	ds_read_b128 v[216:219], v160 offset:21504
	ds_read_b128 v[220:223], v160 offset:22528
	ds_read_b128 v[224:227], v160 offset:23552
	global_load_lds_dwordx4 v132, s[96:97]
	s_mov_b32 m0, s77
	s_add_i32 s5, s73, s25
	global_load_lds_dwordx4 v136, s[96:97]
	s_mov_b32 m0, s5
	s_nop 0
	global_load_lds_dwordx4 v132, s[98:99]
	s_add_i32 m0, s5, 0x2000
	s_nop 0
	global_load_lds_dwordx4 v136, s[98:99]
	s_mov_b32 m0, s49
	s_nop 0
	global_load_lds_dwordx4 v130, s[94:95]
	s_mov_b32 m0, s58
	s_nop 0
	global_load_lds_dwordx4 v134, s[94:95]
	s_waitcnt vmcnt(8)
	s_waitcnt lgkmcnt(0)
	s_barrier
	s_setprio 1
	s_waitcnt lgkmcnt(0)
	v_mfma_f32_16x16x32_bf16 v[62:65], v[164:167], v[196:199], v[62:65]
	v_mfma_f32_16x16x32_bf16 v[54:57], v[172:175], v[196:199], v[54:57]
	v_mfma_f32_16x16x32_bf16 v[46:49], v[164:167], v[204:207], v[46:49]
	v_mfma_f32_16x16x32_bf16 v[38:41], v[172:175], v[204:207], v[38:41]
	v_mfma_f32_16x16x32_bf16 v[30:33], v[164:167], v[212:215], v[30:33]
	v_mfma_f32_16x16x32_bf16 v[22:25], v[172:175], v[212:215], v[22:25]
	v_mfma_f32_16x16x32_bf16 v[14:17], v[164:167], v[220:223], v[14:17]
	v_mfma_f32_16x16x32_bf16 v[6:9], v[172:175], v[220:223], v[6:9]
	v_mfma_f32_16x16x32_bf16 v[62:65], v[168:171], v[200:203], v[62:65]
	v_mfma_f32_16x16x32_bf16 v[54:57], v[176:179], v[200:203], v[54:57]
	v_mfma_f32_16x16x32_bf16 v[46:49], v[168:171], v[208:211], v[46:49]
	v_mfma_f32_16x16x32_bf16 v[38:41], v[176:179], v[208:211], v[38:41]
	v_mfma_f32_16x16x32_bf16 v[30:33], v[168:171], v[216:219], v[30:33]
	v_mfma_f32_16x16x32_bf16 v[22:25], v[176:179], v[216:219], v[22:25]
	v_mfma_f32_16x16x32_bf16 v[14:17], v[168:171], v[224:227], v[14:17]
	v_mfma_f32_16x16x32_bf16 v[6:9], v[176:179], v[224:227], v[6:9]
	s_setprio 0
	s_setprio 1
	v_mfma_f32_16x16x32_bf16 v[58:61], v[180:183], v[196:199], v[58:61]
	v_mfma_f32_16x16x32_bf16 v[50:53], v[188:191], v[196:199], v[50:53]
	v_mfma_f32_16x16x32_bf16 v[42:45], v[180:183], v[204:207], v[42:45]
	v_mfma_f32_16x16x32_bf16 v[34:37], v[188:191], v[204:207], v[34:37]
	v_mfma_f32_16x16x32_bf16 v[26:29], v[180:183], v[212:215], v[26:29]
	v_mfma_f32_16x16x32_bf16 v[18:21], v[188:191], v[212:215], v[18:21]
	v_mfma_f32_16x16x32_bf16 v[10:13], v[180:183], v[220:223], v[10:13]
	v_mfma_f32_16x16x32_bf16 v[2:5], v[188:191], v[220:223], v[2:5]
	v_mfma_f32_16x16x32_bf16 v[58:61], v[184:187], v[200:203], v[58:61]
	v_mfma_f32_16x16x32_bf16 v[50:53], v[192:195], v[200:203], v[50:53]
	v_mfma_f32_16x16x32_bf16 v[42:45], v[184:187], v[208:211], v[42:45]
	v_mfma_f32_16x16x32_bf16 v[34:37], v[192:195], v[208:211], v[34:37]
	v_mfma_f32_16x16x32_bf16 v[26:29], v[184:187], v[216:219], v[26:29]
	v_mfma_f32_16x16x32_bf16 v[18:21], v[192:195], v[216:219], v[18:21]
	v_mfma_f32_16x16x32_bf16 v[10:13], v[184:187], v[224:227], v[10:13]
	v_mfma_f32_16x16x32_bf16 v[2:5], v[192:195], v[224:227], v[2:5]
	s_setprio 0
	s_barrier
	s_add_u32 s98, s94, 0x40000
	s_addc_u32 s99, s95, 0
	s_add_i32 s5, 0, 0x18000
	s_add_i32 s47, 0, 0x1c000
	ds_read_b128 v[164:167], v232
	ds_read_b128 v[168:171], v232 offset:1024
	ds_read_b128 v[172:175], v232 offset:2048
	ds_read_b128 v[176:179], v232 offset:3072
	ds_read_b128 v[180:183], v233
	ds_read_b128 v[184:187], v233 offset:1024
	ds_read_b128 v[188:191], v233 offset:2048
	ds_read_b128 v[192:195], v233 offset:3072
	s_mov_b32 m0, s59
	ds_read_b128 v[196:199], v160 offset:32768
	ds_read_b128 v[200:203], v160 offset:33792
	ds_read_b128 v[204:207], v160 offset:34816
	ds_read_b128 v[208:211], v160 offset:35840
	ds_read_b128 v[212:215], v160 offset:36864
	ds_read_b128 v[216:219], v160 offset:37888
	ds_read_b128 v[220:223], v160 offset:38912
	ds_read_b128 v[224:227], v160 offset:39936
	global_load_lds_dwordx4 v130, s[98:99]
	s_mov_b32 m0, s60
	s_nop 0
	global_load_lds_dwordx4 v134, s[98:99]
	s_waitcnt vmcnt(8)
	s_waitcnt lgkmcnt(0)
	s_barrier
	s_setprio 1
	s_waitcnt lgkmcnt(0)
	v_mfma_f32_16x16x32_bf16 v[122:125], v[164:167], v[196:199], v[122:125]
	v_mfma_f32_16x16x32_bf16 v[118:121], v[172:175], v[196:199], v[118:121]
	v_mfma_f32_16x16x32_bf16 v[110:113], v[164:167], v[204:207], v[110:113]
	v_mfma_f32_16x16x32_bf16 v[102:105], v[172:175], v[204:207], v[102:105]
	v_mfma_f32_16x16x32_bf16 v[94:97], v[164:167], v[212:215], v[94:97]
	v_mfma_f32_16x16x32_bf16 v[86:89], v[172:175], v[212:215], v[86:89]
	v_mfma_f32_16x16x32_bf16 v[78:81], v[164:167], v[220:223], v[78:81]
	v_mfma_f32_16x16x32_bf16 v[70:73], v[172:175], v[220:223], v[70:73]
	v_mfma_f32_16x16x32_bf16 v[122:125], v[168:171], v[200:203], v[122:125]
	v_mfma_f32_16x16x32_bf16 v[118:121], v[176:179], v[200:203], v[118:121]
	v_mfma_f32_16x16x32_bf16 v[110:113], v[168:171], v[208:211], v[110:113]
	v_mfma_f32_16x16x32_bf16 v[102:105], v[176:179], v[208:211], v[102:105]
	v_mfma_f32_16x16x32_bf16 v[94:97], v[168:171], v[216:219], v[94:97]
	v_mfma_f32_16x16x32_bf16 v[86:89], v[176:179], v[216:219], v[86:89]
	v_mfma_f32_16x16x32_bf16 v[78:81], v[168:171], v[224:227], v[78:81]
	v_mfma_f32_16x16x32_bf16 v[70:73], v[176:179], v[224:227], v[70:73]
	s_setprio 0
	s_setprio 1
	v_mfma_f32_16x16x32_bf16 v[126:129], v[180:183], v[196:199], v[126:129]
	v_mfma_f32_16x16x32_bf16 v[114:117], v[188:191], v[196:199], v[114:117]
	v_mfma_f32_16x16x32_bf16 v[106:109], v[180:183], v[204:207], v[106:109]
	v_mfma_f32_16x16x32_bf16 v[98:101], v[188:191], v[204:207], v[98:101]
	v_mfma_f32_16x16x32_bf16 v[90:93], v[180:183], v[212:215], v[90:93]
	v_mfma_f32_16x16x32_bf16 v[82:85], v[188:191], v[212:215], v[82:85]
	v_mfma_f32_16x16x32_bf16 v[74:77], v[180:183], v[220:223], v[74:77]
	v_mfma_f32_16x16x32_bf16 v[66:69], v[188:191], v[220:223], v[66:69]
	v_mfma_f32_16x16x32_bf16 v[126:129], v[184:187], v[200:203], v[126:129]
	v_mfma_f32_16x16x32_bf16 v[114:117], v[192:195], v[200:203], v[114:117]
	v_mfma_f32_16x16x32_bf16 v[106:109], v[184:187], v[208:211], v[106:109]
	v_mfma_f32_16x16x32_bf16 v[98:101], v[192:195], v[208:211], v[98:101]
	v_mfma_f32_16x16x32_bf16 v[90:93], v[184:187], v[216:219], v[90:93]
	v_mfma_f32_16x16x32_bf16 v[82:85], v[192:195], v[216:219], v[82:85]
	v_mfma_f32_16x16x32_bf16 v[74:77], v[184:187], v[224:227], v[74:77]
	v_mfma_f32_16x16x32_bf16 v[66:69], v[192:195], v[224:227], v[66:69]
	s_setprio 0
	s_barrier
	s_add_u32 s96, s96, 0x80
	s_addc_u32 s97, s97, 0
	s_add_u32 s98, s96, 0x40000
	s_addc_u32 s99, s97, 0
	s_add_u32 s94, s94, 0x80
	s_addc_u32 s95, s95, 0
	s_add_i32 s5, s5, s25
	s_mov_b32 m0, s5
	ds_read_b128 v[196:199], v160 offset:49152
	ds_read_b128 v[200:203], v160 offset:50176
	ds_read_b128 v[204:207], v160 offset:51200
	ds_read_b128 v[208:211], v160 offset:52224
	ds_read_b128 v[212:215], v160 offset:53248
	ds_read_b128 v[216:219], v160 offset:54272
	ds_read_b128 v[220:223], v160 offset:55296
	ds_read_b128 v[224:227], v160 offset:56320
	global_load_lds_dwordx4 v132, s[96:97]
	s_add_i32 m0, s5, 0x2000
	s_add_i32 s5, s47, s25
	global_load_lds_dwordx4 v136, s[96:97]
	s_mov_b32 m0, s5
	s_nop 0
	global_load_lds_dwordx4 v132, s[98:99]
	s_add_i32 m0, s5, 0x2000
	s_nop 0
	global_load_lds_dwordx4 v136, s[98:99]
	s_mov_b32 m0, s61
	s_nop 0
	global_load_lds_dwordx4 v130, s[94:95]
	s_mov_b32 m0, s62
	s_nop 0
	global_load_lds_dwordx4 v134, s[94:95]
	s_waitcnt vmcnt(8)
	s_waitcnt lgkmcnt(0)
	s_barrier
	s_setprio 1
	s_waitcnt lgkmcnt(0)
	v_mfma_f32_16x16x32_bf16 v[62:65], v[164:167], v[196:199], v[62:65]
	v_mfma_f32_16x16x32_bf16 v[54:57], v[172:175], v[196:199], v[54:57]
	v_mfma_f32_16x16x32_bf16 v[46:49], v[164:167], v[204:207], v[46:49]
	v_mfma_f32_16x16x32_bf16 v[38:41], v[172:175], v[204:207], v[38:41]
	v_mfma_f32_16x16x32_bf16 v[30:33], v[164:167], v[212:215], v[30:33]
	v_mfma_f32_16x16x32_bf16 v[22:25], v[172:175], v[212:215], v[22:25]
	v_mfma_f32_16x16x32_bf16 v[14:17], v[164:167], v[220:223], v[14:17]
	v_mfma_f32_16x16x32_bf16 v[6:9], v[172:175], v[220:223], v[6:9]
	v_mfma_f32_16x16x32_bf16 v[62:65], v[168:171], v[200:203], v[62:65]
	v_mfma_f32_16x16x32_bf16 v[54:57], v[176:179], v[200:203], v[54:57]
	v_mfma_f32_16x16x32_bf16 v[46:49], v[168:171], v[208:211], v[46:49]
	v_mfma_f32_16x16x32_bf16 v[38:41], v[176:179], v[208:211], v[38:41]
	v_mfma_f32_16x16x32_bf16 v[30:33], v[168:171], v[216:219], v[30:33]
	v_mfma_f32_16x16x32_bf16 v[22:25], v[176:179], v[216:219], v[22:25]
	v_mfma_f32_16x16x32_bf16 v[14:17], v[168:171], v[224:227], v[14:17]
	v_mfma_f32_16x16x32_bf16 v[6:9], v[176:179], v[224:227], v[6:9]
	s_setprio 0
	s_setprio 1
	v_mfma_f32_16x16x32_bf16 v[58:61], v[180:183], v[196:199], v[58:61]
	v_mfma_f32_16x16x32_bf16 v[50:53], v[188:191], v[196:199], v[50:53]
	v_mfma_f32_16x16x32_bf16 v[42:45], v[180:183], v[204:207], v[42:45]
	v_mfma_f32_16x16x32_bf16 v[34:37], v[188:191], v[204:207], v[34:37]
	v_mfma_f32_16x16x32_bf16 v[26:29], v[180:183], v[212:215], v[26:29]
	v_mfma_f32_16x16x32_bf16 v[18:21], v[188:191], v[212:215], v[18:21]
	v_mfma_f32_16x16x32_bf16 v[10:13], v[180:183], v[220:223], v[10:13]
	v_mfma_f32_16x16x32_bf16 v[2:5], v[188:191], v[220:223], v[2:5]
	v_mfma_f32_16x16x32_bf16 v[58:61], v[184:187], v[200:203], v[58:61]
	v_mfma_f32_16x16x32_bf16 v[50:53], v[192:195], v[200:203], v[50:53]
	v_mfma_f32_16x16x32_bf16 v[42:45], v[184:187], v[208:211], v[42:45]
	v_mfma_f32_16x16x32_bf16 v[34:37], v[192:195], v[208:211], v[34:37]
	v_mfma_f32_16x16x32_bf16 v[26:29], v[184:187], v[216:219], v[26:29]
	v_mfma_f32_16x16x32_bf16 v[18:21], v[192:195], v[216:219], v[18:21]
	v_mfma_f32_16x16x32_bf16 v[10:13], v[184:187], v[224:227], v[10:13]
	v_mfma_f32_16x16x32_bf16 v[2:5], v[192:195], v[224:227], v[2:5]
	s_setprio 0
	s_barrier
	s_mov_b32 s5, s45
	s_add_u32 s88, s88, 0x100
	s_addc_u32 s89, s89, 0
	s_add_u32 s86, s86, 0x100
	s_addc_u32 s87, s87, 0
	s_cmp_ge_i32 s45, s101
	s_cbranch_scc0 .LBB0_1944

.LBB0_2073:
	v_cmp_gt_i32_e32 vcc, 1, v156
	s_cbranch_vccnz .LBB0_2135
	v_lshl_add_u64 v[152:153], v[2:3], 0, s[18:19]
	v_add_u32_e32 v138, -2, v156
	s_mov_b32 s4, 0
	s_nop 0
	v_readfirstlane_b32 s86, v150
	v_readfirstlane_b32 s87, v151
	v_readfirstlane_b32 s88, v152
	v_readfirstlane_b32 s89, v153
	v_readfirstlane_b32 s90, v146
	v_readfirstlane_b32 s91, v147
	v_readfirstlane_b32 s92, v148
	v_readfirstlane_b32 s93, v149
	v_readfirstlane_b32 s100, v138
	v_readfirstlane_b32 s101, v156
	v_add_u32_e32 v230, s65, v141
	v_add_u32_e32 v231, s66, v141
	v_add_u32_e32 v232, 0x18000, v141
	v_add_u32_e32 v233, 0x1c000, v141
	s_add_u32 s98, s86, 0x100
	s_addc_u32 s99, s87, 0
	s_cmp_eq_u32 s4, s100
	s_cselect_b64 s[94:95], s[90:91], s[98:99]
	s_cselect_b64 s[96:97], s[92:93], s[88:89]
	ds_read_b128 v[164:167], v230
	ds_read_b128 v[168:171], v230 offset:1024
	ds_read_b128 v[172:175], v230 offset:2048
	ds_read_b128 v[176:179], v230 offset:3072
	ds_read_b128 v[180:183], v231
	ds_read_b128 v[184:187], v231 offset:1024
	ds_read_b128 v[188:191], v231 offset:2048
	ds_read_b128 v[192:195], v231 offset:3072
	s_add_i32 s5, s4, 2
	s_nop 0
	s_add_i32 m0, s44, 0xc000
	ds_read_b128 v[196:199], v160
	ds_read_b128 v[200:203], v160 offset:1024
	ds_read_b128 v[204:207], v160 offset:2048
	ds_read_b128 v[208:211], v160 offset:3072
	ds_read_b128 v[212:215], v160 offset:4096
	ds_read_b128 v[216:219], v160 offset:5120
	ds_read_b128 v[220:223], v160 offset:6144
	ds_read_b128 v[224:227], v160 offset:7168
	global_load_lds_dwordx4 v144, s[86:87]
	s_add_i32 m0, s44, 0xe000
	s_nop 0
	global_load_lds_dwordx4 v142, s[86:87]
	s_waitcnt vmcnt(8)
	s_waitcnt lgkmcnt(0)
	s_barrier
	s_setprio 1
	s_waitcnt lgkmcnt(0)
	v_mfma_f32_16x16x32_bf16 v[122:125], v[164:167], v[196:199], 0
	v_mfma_f32_16x16x32_bf16 v[118:121], v[172:175], v[196:199], 0
	v_mfma_f32_16x16x32_bf16 v[110:113], v[164:167], v[204:207], 0
	v_mfma_f32_16x16x32_bf16 v[102:105], v[172:175], v[204:207], 0
	v_mfma_f32_16x16x32_bf16 v[94:97], v[164:167], v[212:215], 0
	v_mfma_f32_16x16x32_bf16 v[86:89], v[172:175], v[212:215], 0
	v_mfma_f32_16x16x32_bf16 v[78:81], v[164:167], v[220:223], 0
	v_mfma_f32_16x16x32_bf16 v[70:73], v[172:175], v[220:223], 0
	v_mfma_f32_16x16x32_bf16 v[122:125], v[168:171], v[200:203], v[122:125]
	v_mfma_f32_16x16x32_bf16 v[118:121], v[176:179], v[200:203], v[118:121]
	v_mfma_f32_16x16x32_bf16 v[110:113], v[168:171], v[208:211], v[110:113]
	v_mfma_f32_16x16x32_bf16 v[102:105], v[176:179], v[208:211], v[102:105]
	v_mfma_f32_16x16x32_bf16 v[94:97], v[168:171], v[216:219], v[94:97]
	v_mfma_f32_16x16x32_bf16 v[86:89], v[176:179], v[216:219], v[86:89]
	v_mfma_f32_16x16x32_bf16 v[78:81], v[168:171], v[224:227], v[78:81]
	v_mfma_f32_16x16x32_bf16 v[70:73], v[176:179], v[224:227], v[70:73]
	s_setprio 0
	s_setprio 1
	v_mfma_f32_16x16x32_bf16 v[126:129], v[180:183], v[196:199], 0
	v_mfma_f32_16x16x32_bf16 v[114:117], v[188:191], v[196:199], 0
	v_mfma_f32_16x16x32_bf16 v[106:109], v[180:183], v[204:207], 0
	v_mfma_f32_16x16x32_bf16 v[98:101], v[188:191], v[204:207], 0
	v_mfma_f32_16x16x32_bf16 v[90:93], v[180:183], v[212:215], 0
	v_mfma_f32_16x16x32_bf16 v[82:85], v[188:191], v[212:215], 0
	v_mfma_f32_16x16x32_bf16 v[74:77], v[180:183], v[220:223], 0
	v_mfma_f32_16x16x32_bf16 v[66:69], v[188:191], v[220:223], 0
	v_mfma_f32_16x16x32_bf16 v[126:129], v[184:187], v[200:203], v[126:129]
	v_mfma_f32_16x16x32_bf16 v[114:117], v[192:195], v[200:203], v[114:117]
	v_mfma_f32_16x16x32_bf16 v[106:109], v[184:187], v[208:211], v[106:109]
	v_mfma_f32_16x16x32_bf16 v[98:101], v[192:195], v[208:211], v[98:101]
	v_mfma_f32_16x16x32_bf16 v[90:93], v[184:187], v[216:219], v[90:93]
	v_mfma_f32_16x16x32_bf16 v[82:85], v[192:195], v[216:219], v[82:85]
	v_mfma_f32_16x16x32_bf16 v[74:77], v[184:187], v[224:227], v[74:77]
	v_mfma_f32_16x16x32_bf16 v[66:69], v[192:195], v[224:227], v[66:69]
	s_setprio 0
	s_barrier
	s_add_u32 s98, s96, 0xb0000
	s_addc_u32 s99, s97, 0
	s_add_i32 s4, s65, s21
	s_mov_b32 m0, s4
	ds_read_b128 v[196:199], v160 offset:16384
	ds_read_b128 v[200:203], v160 offset:17408
	ds_read_b128 v[204:207], v160 offset:18432
	ds_read_b128 v[208:211], v160 offset:19456
	ds_read_b128 v[212:215], v160 offset:20480
	ds_read_b128 v[216:219], v160 offset:21504
	ds_read_b128 v[220:223], v160 offset:22528
	ds_read_b128 v[224:227], v160 offset:23552
	global_load_lds_dwordx4 v132, s[96:97]
	s_add_i32 m0, s4, 0x2000
	s_add_i32 s4, s66, s21
	global_load_lds_dwordx4 v136, s[96:97]
	s_mov_b32 m0, s4
	s_nop 0
	global_load_lds_dwordx4 v132, s[98:99]
	s_add_i32 m0, s4, 0x2000
	s_nop 0
	global_load_lds_dwordx4 v136, s[98:99]
	s_mov_b32 m0, s44
	s_nop 0
	global_load_lds_dwordx4 v130, s[94:95]
	s_mov_b32 m0, s45
	s_nop 0
	global_load_lds_dwordx4 v134, s[94:95]
	s_waitcnt vmcnt(8)
	s_waitcnt lgkmcnt(0)
	s_barrier
	s_setprio 1
	s_waitcnt lgkmcnt(0)
	v_mfma_f32_16x16x32_bf16 v[62:65], v[164:167], v[196:199], 0
	v_mfma_f32_16x16x32_bf16 v[54:57], v[172:175], v[196:199], 0
	v_mfma_f32_16x16x32_bf16 v[46:49], v[164:167], v[204:207], 0
	v_mfma_f32_16x16x32_bf16 v[38:41], v[172:175], v[204:207], 0
	v_mfma_f32_16x16x32_bf16 v[30:33], v[164:167], v[212:215], 0
	v_mfma_f32_16x16x32_bf16 v[22:25], v[172:175], v[212:215], 0
	v_mfma_f32_16x16x32_bf16 v[14:17], v[164:167], v[220:223], 0
	v_mfma_f32_16x16x32_bf16 v[6:9], v[172:175], v[220:223], 0
	v_mfma_f32_16x16x32_bf16 v[62:65], v[168:171], v[200:203], v[62:65]
	v_mfma_f32_16x16x32_bf16 v[54:57], v[176:179], v[200:203], v[54:57]
	v_mfma_f32_16x16x32_bf16 v[46:49], v[168:171], v[208:211], v[46:49]
	v_mfma_f32_16x16x32_bf16 v[38:41], v[176:179], v[208:211], v[38:41]
	v_mfma_f32_16x16x32_bf16 v[30:33], v[168:171], v[216:219], v[30:33]
	v_mfma_f32_16x16x32_bf16 v[22:25], v[176:179], v[216:219], v[22:25]
	v_mfma_f32_16x16x32_bf16 v[14:17], v[168:171], v[224:227], v[14:17]
	v_mfma_f32_16x16x32_bf16 v[6:9], v[176:179], v[224:227], v[6:9]
	s_setprio 0
	s_setprio 1
	v_mfma_f32_16x16x32_bf16 v[58:61], v[180:183], v[196:199], 0
	v_mfma_f32_16x16x32_bf16 v[50:53], v[188:191], v[196:199], 0
	v_mfma_f32_16x16x32_bf16 v[42:45], v[180:183], v[204:207], 0
	v_mfma_f32_16x16x32_bf16 v[34:37], v[188:191], v[204:207], 0
	v_mfma_f32_16x16x32_bf16 v[26:29], v[180:183], v[212:215], 0
	v_mfma_f32_16x16x32_bf16 v[18:21], v[188:191], v[212:215], 0
	v_mfma_f32_16x16x32_bf16 v[10:13], v[180:183], v[220:223], 0
	v_mfma_f32_16x16x32_bf16 v[2:5], v[188:191], v[220:223], 0
	v_mfma_f32_16x16x32_bf16 v[58:61], v[184:187], v[200:203], v[58:61]
	v_mfma_f32_16x16x32_bf16 v[50:53], v[192:195], v[200:203], v[50:53]
	v_mfma_f32_16x16x32_bf16 v[42:45], v[184:187], v[208:211], v[42:45]
	v_mfma_f32_16x16x32_bf16 v[34:37], v[192:195], v[208:211], v[34:37]
	v_mfma_f32_16x16x32_bf16 v[26:29], v[184:187], v[216:219], v[26:29]
	v_mfma_f32_16x16x32_bf16 v[18:21], v[192:195], v[216:219], v[18:21]
	v_mfma_f32_16x16x32_bf16 v[10:13], v[184:187], v[224:227], v[10:13]
	v_mfma_f32_16x16x32_bf16 v[2:5], v[192:195], v[224:227], v[2:5]
	s_setprio 0
	s_barrier
	s_add_u32 s98, s94, 0xb0000
	s_addc_u32 s99, s95, 0
	s_add_i32 s4, 0, 0x18000
	s_add_i32 s25, 0, 0x1c000
	ds_read_b128 v[164:167], v232
	ds_read_b128 v[168:171], v232 offset:1024
	ds_read_b128 v[172:175], v232 offset:2048
	ds_read_b128 v[176:179], v232 offset:3072
	ds_read_b128 v[180:183], v233
	ds_read_b128 v[184:187], v233 offset:1024
	ds_read_b128 v[188:191], v233 offset:2048
	ds_read_b128 v[192:195], v233 offset:3072
	s_mov_b32 m0, s46
	ds_read_b128 v[196:199], v160 offset:32768
	ds_read_b128 v[200:203], v160 offset:33792
	ds_read_b128 v[204:207], v160 offset:34816
	ds_read_b128 v[208:211], v160 offset:35840
	ds_read_b128 v[212:215], v160 offset:36864
	ds_read_b128 v[216:219], v160 offset:37888
	ds_read_b128 v[220:223], v160 offset:38912
	ds_read_b128 v[224:227], v160 offset:39936
	global_load_lds_dwordx4 v130, s[98:99]
	s_mov_b32 m0, s47
	s_nop 0
	global_load_lds_dwordx4 v134, s[98:99]
	s_waitcnt vmcnt(8)
	s_waitcnt lgkmcnt(0)
	s_barrier
	s_setprio 1
	s_waitcnt lgkmcnt(0)
	v_mfma_f32_16x16x32_bf16 v[122:125], v[164:167], v[196:199], v[122:125]
	v_mfma_f32_16x16x32_bf16 v[118:121], v[172:175], v[196:199], v[118:121]
	v_mfma_f32_16x16x32_bf16 v[110:113], v[164:167], v[204:207], v[110:113]
	v_mfma_f32_16x16x32_bf16 v[102:105], v[172:175], v[204:207], v[102:105]
	v_mfma_f32_16x16x32_bf16 v[94:97], v[164:167], v[212:215], v[94:97]
	v_mfma_f32_16x16x32_bf16 v[86:89], v[172:175], v[212:215], v[86:89]
	v_mfma_f32_16x16x32_bf16 v[78:81], v[164:167], v[220:223], v[78:81]
	v_mfma_f32_16x16x32_bf16 v[70:73], v[172:175], v[220:223], v[70:73]
	v_mfma_f32_16x16x32_bf16 v[122:125], v[168:171], v[200:203], v[122:125]
	v_mfma_f32_16x16x32_bf16 v[118:121], v[176:179], v[200:203], v[118:121]
	v_mfma_f32_16x16x32_bf16 v[110:113], v[168:171], v[208:211], v[110:113]
	v_mfma_f32_16x16x32_bf16 v[102:105], v[176:179], v[208:211], v[102:105]
	v_mfma_f32_16x16x32_bf16 v[94:97], v[168:171], v[216:219], v[94:97]
	v_mfma_f32_16x16x32_bf16 v[86:89], v[176:179], v[216:219], v[86:89]
	v_mfma_f32_16x16x32_bf16 v[78:81], v[168:171], v[224:227], v[78:81]
	v_mfma_f32_16x16x32_bf16 v[70:73], v[176:179], v[224:227], v[70:73]
	s_setprio 0
	s_setprio 1
	v_mfma_f32_16x16x32_bf16 v[126:129], v[180:183], v[196:199], v[126:129]
	v_mfma_f32_16x16x32_bf16 v[114:117], v[188:191], v[196:199], v[114:117]
	v_mfma_f32_16x16x32_bf16 v[106:109], v[180:183], v[204:207], v[106:109]
	v_mfma_f32_16x16x32_bf16 v[98:101], v[188:191], v[204:207], v[98:101]
	v_mfma_f32_16x16x32_bf16 v[90:93], v[180:183], v[212:215], v[90:93]
	v_mfma_f32_16x16x32_bf16 v[82:85], v[188:191], v[212:215], v[82:85]
	v_mfma_f32_16x16x32_bf16 v[74:77], v[180:183], v[220:223], v[74:77]
	v_mfma_f32_16x16x32_bf16 v[66:69], v[188:191], v[220:223], v[66:69]
	v_mfma_f32_16x16x32_bf16 v[126:129], v[184:187], v[200:203], v[126:129]
	v_mfma_f32_16x16x32_bf16 v[114:117], v[192:195], v[200:203], v[114:117]
	v_mfma_f32_16x16x32_bf16 v[106:109], v[184:187], v[208:211], v[106:109]
	v_mfma_f32_16x16x32_bf16 v[98:101], v[192:195], v[208:211], v[98:101]
	v_mfma_f32_16x16x32_bf16 v[90:93], v[184:187], v[216:219], v[90:93]
	v_mfma_f32_16x16x32_bf16 v[82:85], v[192:195], v[216:219], v[82:85]
	v_mfma_f32_16x16x32_bf16 v[74:77], v[184:187], v[224:227], v[74:77]
	v_mfma_f32_16x16x32_bf16 v[66:69], v[192:195], v[224:227], v[66:69]
	s_setprio 0
	s_barrier
	s_add_u32 s96, s96, 0x80
	s_addc_u32 s97, s97, 0
	s_add_u32 s98, s96, 0xb0000
	s_addc_u32 s99, s97, 0
	s_add_u32 s94, s94, 0x80
	s_addc_u32 s95, s95, 0
	s_add_i32 s4, s4, s21
	s_mov_b32 m0, s4
	ds_read_b128 v[196:199], v160 offset:49152
	ds_read_b128 v[200:203], v160 offset:50176
	ds_read_b128 v[204:207], v160 offset:51200
	ds_read_b128 v[208:211], v160 offset:52224
	ds_read_b128 v[212:215], v160 offset:53248
	ds_read_b128 v[216:219], v160 offset:54272
	ds_read_b128 v[220:223], v160 offset:55296
	ds_read_b128 v[224:227], v160 offset:56320
	global_load_lds_dwordx4 v132, s[96:97]
	s_add_i32 m0, s4, 0x2000
	s_add_i32 s4, s25, s21
	global_load_lds_dwordx4 v136, s[96:97]
	s_mov_b32 m0, s4
	s_nop 0
	global_load_lds_dwordx4 v132, s[98:99]
	s_add_i32 m0, s4, 0x2000
	s_nop 0
	global_load_lds_dwordx4 v136, s[98:99]
	s_mov_b32 m0, s57
	s_nop 0
	global_load_lds_dwordx4 v130, s[94:95]
	s_mov_b32 m0, s58
	s_nop 0
	global_load_lds_dwordx4 v134, s[94:95]
	s_waitcnt vmcnt(8)
	s_waitcnt lgkmcnt(0)
	s_barrier
	s_setprio 1
	s_waitcnt lgkmcnt(0)
	v_mfma_f32_16x16x32_bf16 v[62:65], v[164:167], v[196:199], v[62:65]
	v_mfma_f32_16x16x32_bf16 v[54:57], v[172:175], v[196:199], v[54:57]
	v_mfma_f32_16x16x32_bf16 v[46:49], v[164:167], v[204:207], v[46:49]
	v_mfma_f32_16x16x32_bf16 v[38:41], v[172:175], v[204:207], v[38:41]
	v_mfma_f32_16x16x32_bf16 v[30:33], v[164:167], v[212:215], v[30:33]
	v_mfma_f32_16x16x32_bf16 v[22:25], v[172:175], v[212:215], v[22:25]
	v_mfma_f32_16x16x32_bf16 v[14:17], v[164:167], v[220:223], v[14:17]
	v_mfma_f32_16x16x32_bf16 v[6:9], v[172:175], v[220:223], v[6:9]
	v_mfma_f32_16x16x32_bf16 v[62:65], v[168:171], v[200:203], v[62:65]
	v_mfma_f32_16x16x32_bf16 v[54:57], v[176:179], v[200:203], v[54:57]
	v_mfma_f32_16x16x32_bf16 v[46:49], v[168:171], v[208:211], v[46:49]
	v_mfma_f32_16x16x32_bf16 v[38:41], v[176:179], v[208:211], v[38:41]
	v_mfma_f32_16x16x32_bf16 v[30:33], v[168:171], v[216:219], v[30:33]
	v_mfma_f32_16x16x32_bf16 v[22:25], v[176:179], v[216:219], v[22:25]
	v_mfma_f32_16x16x32_bf16 v[14:17], v[168:171], v[224:227], v[14:17]
	v_mfma_f32_16x16x32_bf16 v[6:9], v[176:179], v[224:227], v[6:9]
	s_setprio 0
	s_setprio 1
	v_mfma_f32_16x16x32_bf16 v[58:61], v[180:183], v[196:199], v[58:61]
	v_mfma_f32_16x16x32_bf16 v[50:53], v[188:191], v[196:199], v[50:53]
	v_mfma_f32_16x16x32_bf16 v[42:45], v[180:183], v[204:207], v[42:45]
	v_mfma_f32_16x16x32_bf16 v[34:37], v[188:191], v[204:207], v[34:37]
	v_mfma_f32_16x16x32_bf16 v[26:29], v[180:183], v[212:215], v[26:29]
	v_mfma_f32_16x16x32_bf16 v[18:21], v[188:191], v[212:215], v[18:21]
	v_mfma_f32_16x16x32_bf16 v[10:13], v[180:183], v[220:223], v[10:13]
	v_mfma_f32_16x16x32_bf16 v[2:5], v[188:191], v[220:223], v[2:5]
	v_mfma_f32_16x16x32_bf16 v[58:61], v[184:187], v[200:203], v[58:61]
	v_mfma_f32_16x16x32_bf16 v[50:53], v[192:195], v[200:203], v[50:53]
	v_mfma_f32_16x16x32_bf16 v[42:45], v[184:187], v[208:211], v[42:45]
	v_mfma_f32_16x16x32_bf16 v[34:37], v[192:195], v[208:211], v[34:37]
	v_mfma_f32_16x16x32_bf16 v[26:29], v[184:187], v[216:219], v[26:29]
	v_mfma_f32_16x16x32_bf16 v[18:21], v[192:195], v[216:219], v[18:21]
	v_mfma_f32_16x16x32_bf16 v[10:13], v[184:187], v[224:227], v[10:13]
	v_mfma_f32_16x16x32_bf16 v[2:5], v[192:195], v[224:227], v[2:5]
	s_setprio 0
	s_barrier
	s_mov_b32 s4, s5
	s_add_u32 s88, s88, 0x100
	s_addc_u32 s89, s89, 0
	s_add_u32 s86, s86, 0x100
	s_addc_u32 s87, s87, 0
	s_cmp_ge_i32 s5, s101
	s_cbranch_scc1 .Lmy_kexit_11
.LBB0_2075:
	s_add_u32 s98, s86, 0x100
	s_addc_u32 s99, s87, 0
	s_cmp_eq_u32 s4, s100
	s_cselect_b64 s[94:95], s[90:91], s[98:99]
	s_cselect_b64 s[96:97], s[92:93], s[88:89]
	ds_read_b128 v[164:167], v230
	ds_read_b128 v[168:171], v230 offset:1024
	ds_read_b128 v[172:175], v230 offset:2048
	ds_read_b128 v[176:179], v230 offset:3072
	ds_read_b128 v[180:183], v231
	ds_read_b128 v[184:187], v231 offset:1024
	ds_read_b128 v[188:191], v231 offset:2048
	ds_read_b128 v[192:195], v231 offset:3072
	s_add_i32 s5, s4, 2
	s_nop 0
	s_add_i32 m0, s44, 0xc000
	ds_read_b128 v[196:199], v160
	ds_read_b128 v[200:203], v160 offset:1024
	ds_read_b128 v[204:207], v160 offset:2048
	ds_read_b128 v[208:211], v160 offset:3072
	ds_read_b128 v[212:215], v160 offset:4096
	ds_read_b128 v[216:219], v160 offset:5120
	ds_read_b128 v[220:223], v160 offset:6144
	ds_read_b128 v[224:227], v160 offset:7168
	global_load_lds_dwordx4 v144, s[86:87]
	s_add_i32 m0, s44, 0xe000
	s_nop 0
	global_load_lds_dwordx4 v142, s[86:87]
	s_waitcnt vmcnt(8)
	s_waitcnt lgkmcnt(0)
	s_barrier
	s_setprio 1
	s_waitcnt lgkmcnt(0)
	v_mfma_f32_16x16x32_bf16 v[122:125], v[164:167], v[196:199], v[122:125]
	v_mfma_f32_16x16x32_bf16 v[118:121], v[172:175], v[196:199], v[118:121]
	v_mfma_f32_16x16x32_bf16 v[110:113], v[164:167], v[204:207], v[110:113]
	v_mfma_f32_16x16x32_bf16 v[102:105], v[172:175], v[204:207], v[102:105]
	v_mfma_f32_16x16x32_bf16 v[94:97], v[164:167], v[212:215], v[94:97]
	v_mfma_f32_16x16x32_bf16 v[86:89], v[172:175], v[212:215], v[86:89]
	v_mfma_f32_16x16x32_bf16 v[78:81], v[164:167], v[220:223], v[78:81]
	v_mfma_f32_16x16x32_bf16 v[70:73], v[172:175], v[220:223], v[70:73]
	v_mfma_f32_16x16x32_bf16 v[122:125], v[168:171], v[200:203], v[122:125]
	v_mfma_f32_16x16x32_bf16 v[118:121], v[176:179], v[200:203], v[118:121]
	v_mfma_f32_16x16x32_bf16 v[110:113], v[168:171], v[208:211], v[110:113]
	v_mfma_f32_16x16x32_bf16 v[102:105], v[176:179], v[208:211], v[102:105]
	v_mfma_f32_16x16x32_bf16 v[94:97], v[168:171], v[216:219], v[94:97]
	v_mfma_f32_16x16x32_bf16 v[86:89], v[176:179], v[216:219], v[86:89]
	v_mfma_f32_16x16x32_bf16 v[78:81], v[168:171], v[224:227], v[78:81]
	v_mfma_f32_16x16x32_bf16 v[70:73], v[176:179], v[224:227], v[70:73]
	s_setprio 0
	s_setprio 1
	v_mfma_f32_16x16x32_bf16 v[126:129], v[180:183], v[196:199], v[126:129]
	v_mfma_f32_16x16x32_bf16 v[114:117], v[188:191], v[196:199], v[114:117]
	v_mfma_f32_16x16x32_bf16 v[106:109], v[180:183], v[204:207], v[106:109]
	v_mfma_f32_16x16x32_bf16 v[98:101], v[188:191], v[204:207], v[98:101]
	v_mfma_f32_16x16x32_bf16 v[90:93], v[180:183], v[212:215], v[90:93]
	v_mfma_f32_16x16x32_bf16 v[82:85], v[188:191], v[212:215], v[82:85]
	v_mfma_f32_16x16x32_bf16 v[74:77], v[180:183], v[220:223], v[74:77]
	v_mfma_f32_16x16x32_bf16 v[66:69], v[188:191], v[220:223], v[66:69]
	v_mfma_f32_16x16x32_bf16 v[126:129], v[184:187], v[200:203], v[126:129]
	v_mfma_f32_16x16x32_bf16 v[114:117], v[192:195], v[200:203], v[114:117]
	v_mfma_f32_16x16x32_bf16 v[106:109], v[184:187], v[208:211], v[106:109]
	v_mfma_f32_16x16x32_bf16 v[98:101], v[192:195], v[208:211], v[98:101]
	v_mfma_f32_16x16x32_bf16 v[90:93], v[184:187], v[216:219], v[90:93]
	v_mfma_f32_16x16x32_bf16 v[82:85], v[192:195], v[216:219], v[82:85]
	v_mfma_f32_16x16x32_bf16 v[74:77], v[184:187], v[224:227], v[74:77]
	v_mfma_f32_16x16x32_bf16 v[66:69], v[192:195], v[224:227], v[66:69]
	s_setprio 0
	s_barrier
	s_add_u32 s98, s96, 0xb0000
	s_addc_u32 s99, s97, 0
	s_add_i32 s4, s65, s21
	s_mov_b32 m0, s4
	ds_read_b128 v[196:199], v160 offset:16384
	ds_read_b128 v[200:203], v160 offset:17408
	ds_read_b128 v[204:207], v160 offset:18432
	ds_read_b128 v[208:211], v160 offset:19456
	ds_read_b128 v[212:215], v160 offset:20480
	ds_read_b128 v[216:219], v160 offset:21504
	ds_read_b128 v[220:223], v160 offset:22528
	ds_read_b128 v[224:227], v160 offset:23552
	global_load_lds_dwordx4 v132, s[96:97]
	s_add_i32 m0, s4, 0x2000
	s_add_i32 s4, s66, s21
	global_load_lds_dwordx4 v136, s[96:97]
	s_mov_b32 m0, s4
	s_nop 0
	global_load_lds_dwordx4 v132, s[98:99]
	s_add_i32 m0, s4, 0x2000
	s_nop 0
	global_load_lds_dwordx4 v136, s[98:99]
	s_mov_b32 m0, s44
	s_nop 0
	global_load_lds_dwordx4 v130, s[94:95]
	s_mov_b32 m0, s45
	s_nop 0
	global_load_lds_dwordx4 v134, s[94:95]
	s_waitcnt vmcnt(8)
	s_waitcnt lgkmcnt(0)
	s_barrier
	s_setprio 1
	s_waitcnt lgkmcnt(0)
	v_mfma_f32_16x16x32_bf16 v[62:65], v[164:167], v[196:199], v[62:65]
	v_mfma_f32_16x16x32_bf16 v[54:57], v[172:175], v[196:199], v[54:57]
	v_mfma_f32_16x16x32_bf16 v[46:49], v[164:167], v[204:207], v[46:49]
	v_mfma_f32_16x16x32_bf16 v[38:41], v[172:175], v[204:207], v[38:41]
	v_mfma_f32_16x16x32_bf16 v[30:33], v[164:167], v[212:215], v[30:33]
	v_mfma_f32_16x16x32_bf16 v[22:25], v[172:175], v[212:215], v[22:25]
	v_mfma_f32_16x16x32_bf16 v[14:17], v[164:167], v[220:223], v[14:17]
	v_mfma_f32_16x16x32_bf16 v[6:9], v[172:175], v[220:223], v[6:9]
	v_mfma_f32_16x16x32_bf16 v[62:65], v[168:171], v[200:203], v[62:65]
	v_mfma_f32_16x16x32_bf16 v[54:57], v[176:179], v[200:203], v[54:57]
	v_mfma_f32_16x16x32_bf16 v[46:49], v[168:171], v[208:211], v[46:49]
	v_mfma_f32_16x16x32_bf16 v[38:41], v[176:179], v[208:211], v[38:41]
	v_mfma_f32_16x16x32_bf16 v[30:33], v[168:171], v[216:219], v[30:33]
	v_mfma_f32_16x16x32_bf16 v[22:25], v[176:179], v[216:219], v[22:25]
	v_mfma_f32_16x16x32_bf16 v[14:17], v[168:171], v[224:227], v[14:17]
	v_mfma_f32_16x16x32_bf16 v[6:9], v[176:179], v[224:227], v[6:9]
	s_setprio 0
	s_setprio 1
	v_mfma_f32_16x16x32_bf16 v[58:61], v[180:183], v[196:199], v[58:61]
	v_mfma_f32_16x16x32_bf16 v[50:53], v[188:191], v[196:199], v[50:53]
	v_mfma_f32_16x16x32_bf16 v[42:45], v[180:183], v[204:207], v[42:45]
	v_mfma_f32_16x16x32_bf16 v[34:37], v[188:191], v[204:207], v[34:37]
	v_mfma_f32_16x16x32_bf16 v[26:29], v[180:183], v[212:215], v[26:29]
	v_mfma_f32_16x16x32_bf16 v[18:21], v[188:191], v[212:215], v[18:21]
	v_mfma_f32_16x16x32_bf16 v[10:13], v[180:183], v[220:223], v[10:13]
	v_mfma_f32_16x16x32_bf16 v[2:5], v[188:191], v[220:223], v[2:5]
	v_mfma_f32_16x16x32_bf16 v[58:61], v[184:187], v[200:203], v[58:61]
	v_mfma_f32_16x16x32_bf16 v[50:53], v[192:195], v[200:203], v[50:53]
	v_mfma_f32_16x16x32_bf16 v[42:45], v[184:187], v[208:211], v[42:45]
	v_mfma_f32_16x16x32_bf16 v[34:37], v[192:195], v[208:211], v[34:37]
	v_mfma_f32_16x16x32_bf16 v[26:29], v[184:187], v[216:219], v[26:29]
	v_mfma_f32_16x16x32_bf16 v[18:21], v[192:195], v[216:219], v[18:21]
	v_mfma_f32_16x16x32_bf16 v[10:13], v[184:187], v[224:227], v[10:13]
	v_mfma_f32_16x16x32_bf16 v[2:5], v[192:195], v[224:227], v[2:5]
	s_setprio 0
	s_barrier
	s_add_u32 s98, s94, 0xb0000
	s_addc_u32 s99, s95, 0
	s_add_i32 s4, 0, 0x18000
	s_add_i32 s25, 0, 0x1c000
	ds_read_b128 v[164:167], v232
	ds_read_b128 v[168:171], v232 offset:1024
	ds_read_b128 v[172:175], v232 offset:2048
	ds_read_b128 v[176:179], v232 offset:3072
	ds_read_b128 v[180:183], v233
	ds_read_b128 v[184:187], v233 offset:1024
	ds_read_b128 v[188:191], v233 offset:2048
	ds_read_b128 v[192:195], v233 offset:3072
	s_mov_b32 m0, s46
	ds_read_b128 v[196:199], v160 offset:32768
	ds_read_b128 v[200:203], v160 offset:33792
	ds_read_b128 v[204:207], v160 offset:34816
	ds_read_b128 v[208:211], v160 offset:35840
	ds_read_b128 v[212:215], v160 offset:36864
	ds_read_b128 v[216:219], v160 offset:37888
	ds_read_b128 v[220:223], v160 offset:38912
	ds_read_b128 v[224:227], v160 offset:39936
	global_load_lds_dwordx4 v130, s[98:99]
	s_mov_b32 m0, s47
	s_nop 0
	global_load_lds_dwordx4 v134, s[98:99]
	s_waitcnt vmcnt(8)
	s_waitcnt lgkmcnt(0)
	s_barrier
	s_setprio 1
	s_waitcnt lgkmcnt(0)
	v_mfma_f32_16x16x32_bf16 v[122:125], v[164:167], v[196:199], v[122:125]
	v_mfma_f32_16x16x32_bf16 v[118:121], v[172:175], v[196:199], v[118:121]
	v_mfma_f32_16x16x32_bf16 v[110:113], v[164:167], v[204:207], v[110:113]
	v_mfma_f32_16x16x32_bf16 v[102:105], v[172:175], v[204:207], v[102:105]
	v_mfma_f32_16x16x32_bf16 v[94:97], v[164:167], v[212:215], v[94:97]
	v_mfma_f32_16x16x32_bf16 v[86:89], v[172:175], v[212:215], v[86:89]
	v_mfma_f32_16x16x32_bf16 v[78:81], v[164:167], v[220:223], v[78:81]
	v_mfma_f32_16x16x32_bf16 v[70:73], v[172:175], v[220:223], v[70:73]
	v_mfma_f32_16x16x32_bf16 v[122:125], v[168:171], v[200:203], v[122:125]
	v_mfma_f32_16x16x32_bf16 v[118:121], v[176:179], v[200:203], v[118:121]
	v_mfma_f32_16x16x32_bf16 v[110:113], v[168:171], v[208:211], v[110:113]
	v_mfma_f32_16x16x32_bf16 v[102:105], v[176:179], v[208:211], v[102:105]
	v_mfma_f32_16x16x32_bf16 v[94:97], v[168:171], v[216:219], v[94:97]
	v_mfma_f32_16x16x32_bf16 v[86:89], v[176:179], v[216:219], v[86:89]
	v_mfma_f32_16x16x32_bf16 v[78:81], v[168:171], v[224:227], v[78:81]
	v_mfma_f32_16x16x32_bf16 v[70:73], v[176:179], v[224:227], v[70:73]
	s_setprio 0
	s_setprio 1
	v_mfma_f32_16x16x32_bf16 v[126:129], v[180:183], v[196:199], v[126:129]
	v_mfma_f32_16x16x32_bf16 v[114:117], v[188:191], v[196:199], v[114:117]
	v_mfma_f32_16x16x32_bf16 v[106:109], v[180:183], v[204:207], v[106:109]
	v_mfma_f32_16x16x32_bf16 v[98:101], v[188:191], v[204:207], v[98:101]
	v_mfma_f32_16x16x32_bf16 v[90:93], v[180:183], v[212:215], v[90:93]
	v_mfma_f32_16x16x32_bf16 v[82:85], v[188:191], v[212:215], v[82:85]
	v_mfma_f32_16x16x32_bf16 v[74:77], v[180:183], v[220:223], v[74:77]
	v_mfma_f32_16x16x32_bf16 v[66:69], v[188:191], v[220:223], v[66:69]
	v_mfma_f32_16x16x32_bf16 v[126:129], v[184:187], v[200:203], v[126:129]
	v_mfma_f32_16x16x32_bf16 v[114:117], v[192:195], v[200:203], v[114:117]
	v_mfma_f32_16x16x32_bf16 v[106:109], v[184:187], v[208:211], v[106:109]
	v_mfma_f32_16x16x32_bf16 v[98:101], v[192:195], v[208:211], v[98:101]
	v_mfma_f32_16x16x32_bf16 v[90:93], v[184:187], v[216:219], v[90:93]
	v_mfma_f32_16x16x32_bf16 v[82:85], v[192:195], v[216:219], v[82:85]
	v_mfma_f32_16x16x32_bf16 v[74:77], v[184:187], v[224:227], v[74:77]
	v_mfma_f32_16x16x32_bf16 v[66:69], v[192:195], v[224:227], v[66:69]
	s_setprio 0
	s_barrier
	s_add_u32 s96, s96, 0x80
	s_addc_u32 s97, s97, 0
	s_add_u32 s98, s96, 0xb0000
	s_addc_u32 s99, s97, 0
	s_add_u32 s94, s94, 0x80
	s_addc_u32 s95, s95, 0
	s_add_i32 s4, s4, s21
	s_mov_b32 m0, s4
	ds_read_b128 v[196:199], v160 offset:49152
	ds_read_b128 v[200:203], v160 offset:50176
	ds_read_b128 v[204:207], v160 offset:51200
	ds_read_b128 v[208:211], v160 offset:52224
	ds_read_b128 v[212:215], v160 offset:53248
	ds_read_b128 v[216:219], v160 offset:54272
	ds_read_b128 v[220:223], v160 offset:55296
	ds_read_b128 v[224:227], v160 offset:56320
	global_load_lds_dwordx4 v132, s[96:97]
	s_add_i32 m0, s4, 0x2000
	s_add_i32 s4, s25, s21
	global_load_lds_dwordx4 v136, s[96:97]
	s_mov_b32 m0, s4
	s_nop 0
	global_load_lds_dwordx4 v132, s[98:99]
	s_add_i32 m0, s4, 0x2000
	s_nop 0
	global_load_lds_dwordx4 v136, s[98:99]
	s_mov_b32 m0, s57
	s_nop 0
	global_load_lds_dwordx4 v130, s[94:95]
	s_mov_b32 m0, s58
	s_nop 0
	global_load_lds_dwordx4 v134, s[94:95]
	s_waitcnt vmcnt(8)
	s_waitcnt lgkmcnt(0)
	s_barrier
	s_setprio 1
	s_waitcnt lgkmcnt(0)
	v_mfma_f32_16x16x32_bf16 v[62:65], v[164:167], v[196:199], v[62:65]
	v_mfma_f32_16x16x32_bf16 v[54:57], v[172:175], v[196:199], v[54:57]
	v_mfma_f32_16x16x32_bf16 v[46:49], v[164:167], v[204:207], v[46:49]
	v_mfma_f32_16x16x32_bf16 v[38:41], v[172:175], v[204:207], v[38:41]
	v_mfma_f32_16x16x32_bf16 v[30:33], v[164:167], v[212:215], v[30:33]
	v_mfma_f32_16x16x32_bf16 v[22:25], v[172:175], v[212:215], v[22:25]
	v_mfma_f32_16x16x32_bf16 v[14:17], v[164:167], v[220:223], v[14:17]
	v_mfma_f32_16x16x32_bf16 v[6:9], v[172:175], v[220:223], v[6:9]
	v_mfma_f32_16x16x32_bf16 v[62:65], v[168:171], v[200:203], v[62:65]
	v_mfma_f32_16x16x32_bf16 v[54:57], v[176:179], v[200:203], v[54:57]
	v_mfma_f32_16x16x32_bf16 v[46:49], v[168:171], v[208:211], v[46:49]
	v_mfma_f32_16x16x32_bf16 v[38:41], v[176:179], v[208:211], v[38:41]
	v_mfma_f32_16x16x32_bf16 v[30:33], v[168:171], v[216:219], v[30:33]
	v_mfma_f32_16x16x32_bf16 v[22:25], v[176:179], v[216:219], v[22:25]
	v_mfma_f32_16x16x32_bf16 v[14:17], v[168:171], v[224:227], v[14:17]
	v_mfma_f32_16x16x32_bf16 v[6:9], v[176:179], v[224:227], v[6:9]
	s_setprio 0
	s_setprio 1
	v_mfma_f32_16x16x32_bf16 v[58:61], v[180:183], v[196:199], v[58:61]
	v_mfma_f32_16x16x32_bf16 v[50:53], v[188:191], v[196:199], v[50:53]
	v_mfma_f32_16x16x32_bf16 v[42:45], v[180:183], v[204:207], v[42:45]
	v_mfma_f32_16x16x32_bf16 v[34:37], v[188:191], v[204:207], v[34:37]
	v_mfma_f32_16x16x32_bf16 v[26:29], v[180:183], v[212:215], v[26:29]
	v_mfma_f32_16x16x32_bf16 v[18:21], v[188:191], v[212:215], v[18:21]
	v_mfma_f32_16x16x32_bf16 v[10:13], v[180:183], v[220:223], v[10:13]
	v_mfma_f32_16x16x32_bf16 v[2:5], v[188:191], v[220:223], v[2:5]
	v_mfma_f32_16x16x32_bf16 v[58:61], v[184:187], v[200:203], v[58:61]
	v_mfma_f32_16x16x32_bf16 v[50:53], v[192:195], v[200:203], v[50:53]
	v_mfma_f32_16x16x32_bf16 v[42:45], v[184:187], v[208:211], v[42:45]
	v_mfma_f32_16x16x32_bf16 v[34:37], v[192:195], v[208:211], v[34:37]
	v_mfma_f32_16x16x32_bf16 v[26:29], v[184:187], v[216:219], v[26:29]
	v_mfma_f32_16x16x32_bf16 v[18:21], v[192:195], v[216:219], v[18:21]
	v_mfma_f32_16x16x32_bf16 v[10:13], v[184:187], v[224:227], v[10:13]
	v_mfma_f32_16x16x32_bf16 v[2:5], v[192:195], v[224:227], v[2:5]
	s_setprio 0
	s_barrier
	s_mov_b32 s4, s5
	s_add_u32 s88, s88, 0x100
	s_addc_u32 s89, s89, 0
	s_add_u32 s86, s86, 0x100
	s_addc_u32 s87, s87, 0
	s_cmp_ge_i32 s5, s101
	s_cbranch_scc0 .LBB0_2075
